# GEMM K-loops: K=2 late pre-MFMA barrier + all s_setprio removed from the K-loops (A/B of the priority flips)
# baseline (speedup 1.0000x reference)
.LBB0_408:
	ds_read_b128 v[34:37], v196
	ds_read_b128 v[38:41], v196 offset:1024
	ds_read_b128 v[42:45], v196 offset:2048
	ds_read_b128 v[46:49], v196 offset:3072
	ds_read_b128 v[146:149], v197
	ds_read_b128 v[150:153], v197 offset:1024
	ds_read_b128 v[184:187], v197 offset:2048
	ds_read_b128 v[188:191], v197 offset:3072
	s_add_i32 s11, s6, 2
	s_add_u32 s12, s4, 0x80
	s_addc_u32 s7, s5, 0
	s_cmp_eq_u32 s27, s6
	s_cselect_b32 s6, s54, s12
	s_cselect_b32 s7, s55, s7
	s_cselect_b32 s13, s61, s9
	s_cselect_b32 s12, s60, s8
	v_lshl_add_u64 v[192:193], s[4:5], 0, v[174:175]
	s_add_i32 m0, s88, 0xc000
	ds_read_b128 v[200:203], v198
	ds_read_b128 v[204:207], v198 offset:1024
	ds_read_b128 v[208:211], v198 offset:2048
	ds_read_b128 v[212:215], v198 offset:3072
	ds_read_b128 v[216:219], v198 offset:4096
	ds_read_b128 v[220:223], v198 offset:5120
	ds_read_b128 v[224:227], v198 offset:6144
	ds_read_b128 v[228:231], v198 offset:7168
	global_load_lds_dwordx4 v[192:193], off
	v_lshl_add_u64 v[192:193], s[4:5], 0, v[176:177]
	s_add_i32 m0, s88, 0xe000
	s_nop 0
	global_load_lds_dwordx4 v[192:193], off
	s_waitcnt vmcnt(8)
	s_waitcnt lgkmcnt(0)
	s_waitcnt lgkmcnt(0)
	v_mfma_f32_16x16x32_bf16 v[142:145], v[34:37], v[200:203], v[142:145]
	v_mfma_f32_16x16x32_bf16 v[138:141], v[42:45], v[200:203], v[138:141]
	s_barrier
	v_mfma_f32_16x16x32_bf16 v[126:129], v[34:37], v[208:211], v[126:129]
	v_mfma_f32_16x16x32_bf16 v[122:125], v[42:45], v[208:211], v[122:125]
	v_mfma_f32_16x16x32_bf16 v[110:113], v[34:37], v[216:219], v[110:113]
	v_mfma_f32_16x16x32_bf16 v[106:109], v[42:45], v[216:219], v[106:109]
	v_mfma_f32_16x16x32_bf16 v[94:97], v[34:37], v[224:227], v[94:97]
	v_mfma_f32_16x16x32_bf16 v[90:93], v[42:45], v[224:227], v[90:93]
	v_mfma_f32_16x16x32_bf16 v[142:145], v[38:41], v[204:207], v[142:145]
	v_mfma_f32_16x16x32_bf16 v[138:141], v[46:49], v[204:207], v[138:141]
	v_mfma_f32_16x16x32_bf16 v[126:129], v[38:41], v[212:215], v[126:129]
	v_mfma_f32_16x16x32_bf16 v[122:125], v[46:49], v[212:215], v[122:125]
	v_mfma_f32_16x16x32_bf16 v[110:113], v[38:41], v[220:223], v[110:113]
	v_mfma_f32_16x16x32_bf16 v[106:109], v[46:49], v[220:223], v[106:109]
	v_mfma_f32_16x16x32_bf16 v[94:97], v[38:41], v[228:231], v[94:97]
	v_mfma_f32_16x16x32_bf16 v[90:93], v[46:49], v[228:231], v[90:93]
	v_mfma_f32_16x16x32_bf16 v[134:137], v[146:149], v[200:203], v[134:137]
	v_mfma_f32_16x16x32_bf16 v[130:133], v[184:187], v[200:203], v[130:133]
	v_mfma_f32_16x16x32_bf16 v[118:121], v[146:149], v[208:211], v[118:121]
	v_mfma_f32_16x16x32_bf16 v[114:117], v[184:187], v[208:211], v[114:117]
	v_mfma_f32_16x16x32_bf16 v[102:105], v[146:149], v[216:219], v[102:105]
	v_mfma_f32_16x16x32_bf16 v[98:101], v[184:187], v[216:219], v[98:101]
	v_mfma_f32_16x16x32_bf16 v[86:89], v[146:149], v[224:227], v[86:89]
	v_mfma_f32_16x16x32_bf16 v[82:85], v[184:187], v[224:227], v[82:85]
	v_mfma_f32_16x16x32_bf16 v[134:137], v[150:153], v[204:207], v[134:137]
	v_mfma_f32_16x16x32_bf16 v[130:133], v[188:191], v[204:207], v[130:133]
	v_mfma_f32_16x16x32_bf16 v[118:121], v[150:153], v[212:215], v[118:121]
	v_mfma_f32_16x16x32_bf16 v[114:117], v[188:191], v[212:215], v[114:117]
	v_mfma_f32_16x16x32_bf16 v[102:105], v[150:153], v[220:223], v[102:105]
	v_mfma_f32_16x16x32_bf16 v[98:101], v[188:191], v[220:223], v[98:101]
	v_mfma_f32_16x16x32_bf16 v[86:89], v[150:153], v[228:231], v[86:89]
	v_mfma_f32_16x16x32_bf16 v[82:85], v[188:191], v[228:231], v[82:85]
	s_barrier
	s_add_i32 s24, s84, s81
	v_lshl_add_u64 v[192:193], s[12:13], 0, v[156:157]
	s_mov_b32 m0, s24
	ds_read_b128 v[200:203], v198 offset:16384
	ds_read_b128 v[204:207], v198 offset:17408
	ds_read_b128 v[208:211], v198 offset:18432
	ds_read_b128 v[212:215], v198 offset:19456
	ds_read_b128 v[216:219], v198 offset:20480
	ds_read_b128 v[220:223], v198 offset:21504
	ds_read_b128 v[224:227], v198 offset:22528
	ds_read_b128 v[228:231], v198 offset:23552
	global_load_lds_dwordx4 v[192:193], off
	s_add_i32 m0, s24, 0x2000
	v_lshl_add_u64 v[232:233], s[12:13], 0, v[160:161]
	s_add_u32 s12, s12, s20
	s_addc_u32 s13, s13, s21
	s_add_i32 s24, s85, s81
	global_load_lds_dwordx4 v[232:233], off
	v_lshl_add_u64 v[234:235], s[12:13], 0, v[156:157]
	s_mov_b32 m0, s24
	v_lshl_add_u64 v[236:237], s[12:13], 0, v[160:161]
	global_load_lds_dwordx4 v[234:235], off
	s_add_i32 m0, s24, 0x2000
	v_lshl_add_u64 v[238:239], s[6:7], 0, v[154:155]
	global_load_lds_dwordx4 v[236:237], off
	s_mov_b32 m0, s88
	v_lshl_add_u64 v[240:241], s[6:7], 0, v[158:159]
	global_load_lds_dwordx4 v[238:239], off
	s_mov_b32 m0, s90
	s_nop 0
	global_load_lds_dwordx4 v[240:241], off
	s_waitcnt vmcnt(8)
	s_waitcnt lgkmcnt(0)
	s_waitcnt lgkmcnt(0)
	v_mfma_f32_16x16x32_bf16 v[78:81], v[34:37], v[200:203], v[78:81]
	v_mfma_f32_16x16x32_bf16 v[74:77], v[42:45], v[200:203], v[74:77]
	s_barrier
	v_mfma_f32_16x16x32_bf16 v[62:65], v[34:37], v[208:211], v[62:65]
	v_mfma_f32_16x16x32_bf16 v[58:61], v[42:45], v[208:211], v[58:61]
	v_mfma_f32_16x16x32_bf16 v[30:33], v[34:37], v[216:219], v[30:33]
	v_mfma_f32_16x16x32_bf16 v[26:29], v[42:45], v[216:219], v[26:29]
	v_mfma_f32_16x16x32_bf16 v[14:17], v[34:37], v[224:227], v[14:17]
	v_mfma_f32_16x16x32_bf16 v[10:13], v[42:45], v[224:227], v[10:13]
	v_mfma_f32_16x16x32_bf16 v[78:81], v[38:41], v[204:207], v[78:81]
	v_mfma_f32_16x16x32_bf16 v[74:77], v[46:49], v[204:207], v[74:77]
	v_mfma_f32_16x16x32_bf16 v[62:65], v[38:41], v[212:215], v[62:65]
	v_mfma_f32_16x16x32_bf16 v[58:61], v[46:49], v[212:215], v[58:61]
	v_mfma_f32_16x16x32_bf16 v[30:33], v[38:41], v[220:223], v[30:33]
	v_mfma_f32_16x16x32_bf16 v[26:29], v[46:49], v[220:223], v[26:29]
	v_mfma_f32_16x16x32_bf16 v[14:17], v[38:41], v[228:231], v[14:17]
	v_mfma_f32_16x16x32_bf16 v[10:13], v[46:49], v[228:231], v[10:13]
	v_mfma_f32_16x16x32_bf16 v[22:25], v[146:149], v[216:219], v[22:25]
	v_mfma_f32_16x16x32_bf16 v[18:21], v[184:187], v[216:219], v[18:21]
	v_mfma_f32_16x16x32_bf16 v[6:9], v[146:149], v[224:227], v[6:9]
	v_mfma_f32_16x16x32_bf16 v[2:5], v[184:187], v[224:227], v[2:5]
	v_mfma_f32_16x16x32_bf16 v[34:37], v[146:149], v[200:203], v[70:73]
	v_mfma_f32_16x16x32_bf16 v[38:41], v[184:187], v[200:203], v[66:69]
	v_mfma_f32_16x16x32_bf16 v[42:45], v[146:149], v[208:211], v[54:57]
	v_mfma_f32_16x16x32_bf16 v[46:49], v[184:187], v[208:211], v[50:53]
	v_mfma_f32_16x16x32_bf16 v[22:25], v[150:153], v[220:223], v[22:25]
	v_mfma_f32_16x16x32_bf16 v[18:21], v[188:191], v[220:223], v[18:21]
	v_mfma_f32_16x16x32_bf16 v[6:9], v[150:153], v[228:231], v[6:9]
	v_mfma_f32_16x16x32_bf16 v[2:5], v[188:191], v[228:231], v[2:5]
	v_mfma_f32_16x16x32_bf16 v[34:37], v[150:153], v[204:207], v[34:37]
	v_mfma_f32_16x16x32_bf16 v[38:41], v[188:191], v[204:207], v[38:41]
	v_mfma_f32_16x16x32_bf16 v[42:45], v[150:153], v[212:215], v[42:45]
	v_mfma_f32_16x16x32_bf16 v[46:49], v[188:191], v[212:215], v[46:49]
	s_barrier
	s_add_i32 s12, 0, 0x18000
	s_add_i32 s13, 0, 0x1c000
	v_add_u32_e32 v70, s12, v194
	v_add_u32_e32 v162, s13, v194
	ds_read_b128 v[50:53], v70
	ds_read_b128 v[54:57], v70 offset:1024
	ds_read_b128 v[66:69], v70 offset:2048
	ds_read_b128 v[70:73], v70 offset:3072
	ds_read_b128 v[146:149], v162
	ds_read_b128 v[150:153], v162 offset:1024
	ds_read_b128 v[184:187], v162 offset:2048
	ds_read_b128 v[188:191], v162 offset:3072
	s_add_u32 s6, s6, s20
	s_addc_u32 s7, s7, s21
	s_mov_b32 m0, s91
	v_lshl_add_u64 v[242:243], s[6:7], 0, v[154:155]
	ds_read_b128 v[200:203], v198 offset:32768
	ds_read_b128 v[204:207], v198 offset:33792
	ds_read_b128 v[208:211], v198 offset:34816
	ds_read_b128 v[212:215], v198 offset:35840
	ds_read_b128 v[216:219], v198 offset:36864
	ds_read_b128 v[220:223], v198 offset:37888
	ds_read_b128 v[224:227], v198 offset:38912
	ds_read_b128 v[228:231], v198 offset:39936
	global_load_lds_dwordx4 v[242:243], off
	v_lshl_add_u64 v[242:243], s[6:7], 0, v[158:159]
	s_mov_b32 m0, s95
	s_nop 0
	global_load_lds_dwordx4 v[242:243], off
	s_waitcnt vmcnt(8)
	s_waitcnt lgkmcnt(0)
	s_waitcnt lgkmcnt(0)
	v_mfma_f32_16x16x32_bf16 v[142:145], v[50:53], v[200:203], v[142:145]
	v_mfma_f32_16x16x32_bf16 v[138:141], v[66:69], v[200:203], v[138:141]
	s_barrier
	v_mfma_f32_16x16x32_bf16 v[126:129], v[50:53], v[208:211], v[126:129]
	v_mfma_f32_16x16x32_bf16 v[122:125], v[66:69], v[208:211], v[122:125]
	v_mfma_f32_16x16x32_bf16 v[110:113], v[50:53], v[216:219], v[110:113]
	v_mfma_f32_16x16x32_bf16 v[106:109], v[66:69], v[216:219], v[106:109]
	v_mfma_f32_16x16x32_bf16 v[94:97], v[50:53], v[224:227], v[94:97]
	v_mfma_f32_16x16x32_bf16 v[90:93], v[66:69], v[224:227], v[90:93]
	v_mfma_f32_16x16x32_bf16 v[142:145], v[54:57], v[204:207], v[142:145]
	v_mfma_f32_16x16x32_bf16 v[138:141], v[70:73], v[204:207], v[138:141]
	v_mfma_f32_16x16x32_bf16 v[126:129], v[54:57], v[212:215], v[126:129]
	v_mfma_f32_16x16x32_bf16 v[122:125], v[70:73], v[212:215], v[122:125]
	v_mfma_f32_16x16x32_bf16 v[110:113], v[54:57], v[220:223], v[110:113]
	v_mfma_f32_16x16x32_bf16 v[106:109], v[70:73], v[220:223], v[106:109]
	v_mfma_f32_16x16x32_bf16 v[94:97], v[54:57], v[228:231], v[94:97]
	v_mfma_f32_16x16x32_bf16 v[90:93], v[70:73], v[228:231], v[90:93]
	v_mfma_f32_16x16x32_bf16 v[134:137], v[146:149], v[200:203], v[134:137]
	v_mfma_f32_16x16x32_bf16 v[130:133], v[184:187], v[200:203], v[130:133]
	v_mfma_f32_16x16x32_bf16 v[118:121], v[146:149], v[208:211], v[118:121]
	v_mfma_f32_16x16x32_bf16 v[114:117], v[184:187], v[208:211], v[114:117]
	v_mfma_f32_16x16x32_bf16 v[102:105], v[146:149], v[216:219], v[102:105]
	v_mfma_f32_16x16x32_bf16 v[98:101], v[184:187], v[216:219], v[98:101]
	v_mfma_f32_16x16x32_bf16 v[86:89], v[146:149], v[224:227], v[86:89]
	v_mfma_f32_16x16x32_bf16 v[82:85], v[184:187], v[224:227], v[82:85]
	v_mfma_f32_16x16x32_bf16 v[134:137], v[150:153], v[204:207], v[134:137]
	v_mfma_f32_16x16x32_bf16 v[130:133], v[188:191], v[204:207], v[130:133]
	v_mfma_f32_16x16x32_bf16 v[118:121], v[150:153], v[212:215], v[118:121]
	v_mfma_f32_16x16x32_bf16 v[114:117], v[188:191], v[212:215], v[114:117]
	v_mfma_f32_16x16x32_bf16 v[102:105], v[150:153], v[220:223], v[102:105]
	v_mfma_f32_16x16x32_bf16 v[98:101], v[188:191], v[220:223], v[98:101]
	v_mfma_f32_16x16x32_bf16 v[86:89], v[150:153], v[228:231], v[86:89]
	v_mfma_f32_16x16x32_bf16 v[82:85], v[188:191], v[228:231], v[82:85]
	s_barrier
	s_add_i32 s6, s12, s81
	v_lshl_add_u64 v[192:193], v[192:193], 0, s[44:45]
	s_mov_b32 m0, s6
	ds_read_b128 v[200:203], v198 offset:49152
	ds_read_b128 v[204:207], v198 offset:50176
	ds_read_b128 v[208:211], v198 offset:51200
	ds_read_b128 v[212:215], v198 offset:52224
	ds_read_b128 v[216:219], v198 offset:53248
	ds_read_b128 v[220:223], v198 offset:54272
	ds_read_b128 v[224:227], v198 offset:55296
	ds_read_b128 v[228:231], v198 offset:56320
	global_load_lds_dwordx4 v[192:193], off
	v_lshl_add_u64 v[192:193], v[232:233], 0, s[44:45]
	s_add_i32 m0, s6, 0x2000
	s_add_i32 s6, s13, s81
	global_load_lds_dwordx4 v[192:193], off
	v_lshl_add_u64 v[192:193], v[234:235], 0, s[44:45]
	s_mov_b32 m0, s6
	s_nop 0
	global_load_lds_dwordx4 v[192:193], off
	v_lshl_add_u64 v[192:193], v[236:237], 0, s[44:45]
	s_add_i32 m0, s6, 0x2000
	s_nop 0
	global_load_lds_dwordx4 v[192:193], off
	v_lshl_add_u64 v[192:193], v[238:239], 0, s[44:45]
	s_mov_b32 m0, s17
	s_nop 0
	global_load_lds_dwordx4 v[192:193], off
	v_lshl_add_u64 v[192:193], v[240:241], 0, s[44:45]
	s_mov_b32 m0, s94
	s_nop 0
	global_load_lds_dwordx4 v[192:193], off
	s_waitcnt vmcnt(8)
	s_waitcnt lgkmcnt(0)
	s_waitcnt lgkmcnt(0)
	v_mfma_f32_16x16x32_bf16 v[78:81], v[50:53], v[200:203], v[78:81]
	v_mfma_f32_16x16x32_bf16 v[74:77], v[66:69], v[200:203], v[74:77]
	s_barrier
	v_mfma_f32_16x16x32_bf16 v[62:65], v[50:53], v[208:211], v[62:65]
	v_mfma_f32_16x16x32_bf16 v[58:61], v[66:69], v[208:211], v[58:61]
	v_mfma_f32_16x16x32_bf16 v[30:33], v[50:53], v[216:219], v[30:33]
	v_mfma_f32_16x16x32_bf16 v[26:29], v[66:69], v[216:219], v[26:29]
	v_mfma_f32_16x16x32_bf16 v[14:17], v[50:53], v[224:227], v[14:17]
	v_mfma_f32_16x16x32_bf16 v[10:13], v[66:69], v[224:227], v[10:13]
	v_mfma_f32_16x16x32_bf16 v[78:81], v[54:57], v[204:207], v[78:81]
	v_mfma_f32_16x16x32_bf16 v[74:77], v[70:73], v[204:207], v[74:77]
	v_mfma_f32_16x16x32_bf16 v[62:65], v[54:57], v[212:215], v[62:65]
	v_mfma_f32_16x16x32_bf16 v[58:61], v[70:73], v[212:215], v[58:61]
	v_mfma_f32_16x16x32_bf16 v[30:33], v[54:57], v[220:223], v[30:33]
	v_mfma_f32_16x16x32_bf16 v[26:29], v[70:73], v[220:223], v[26:29]
	v_mfma_f32_16x16x32_bf16 v[14:17], v[54:57], v[228:231], v[14:17]
	v_mfma_f32_16x16x32_bf16 v[10:13], v[70:73], v[228:231], v[10:13]
	v_mfma_f32_16x16x32_bf16 v[34:37], v[146:149], v[200:203], v[34:37]
	v_mfma_f32_16x16x32_bf16 v[70:73], v[150:153], v[204:207], v[34:37]
	v_mfma_f32_16x16x32_bf16 v[34:37], v[184:187], v[200:203], v[38:41]
	v_mfma_f32_16x16x32_bf16 v[66:69], v[188:191], v[204:207], v[34:37]
	v_mfma_f32_16x16x32_bf16 v[34:37], v[146:149], v[208:211], v[42:45]
	v_mfma_f32_16x16x32_bf16 v[54:57], v[150:153], v[212:215], v[34:37]
	v_mfma_f32_16x16x32_bf16 v[34:37], v[184:187], v[208:211], v[46:49]
	v_mfma_f32_16x16x32_bf16 v[22:25], v[146:149], v[216:219], v[22:25]
	v_mfma_f32_16x16x32_bf16 v[18:21], v[184:187], v[216:219], v[18:21]
	v_mfma_f32_16x16x32_bf16 v[6:9], v[146:149], v[224:227], v[6:9]
	v_mfma_f32_16x16x32_bf16 v[2:5], v[184:187], v[224:227], v[2:5]
	v_mfma_f32_16x16x32_bf16 v[50:53], v[188:191], v[212:215], v[34:37]
	v_mfma_f32_16x16x32_bf16 v[22:25], v[150:153], v[220:223], v[22:25]
	v_mfma_f32_16x16x32_bf16 v[18:21], v[188:191], v[220:223], v[18:21]
	v_mfma_f32_16x16x32_bf16 v[6:9], v[150:153], v[228:231], v[6:9]
	v_mfma_f32_16x16x32_bf16 v[2:5], v[188:191], v[228:231], v[2:5]
	s_barrier
	s_add_u32 s4, s4, 0x100
	s_addc_u32 s5, s5, 0
	s_add_u32 s8, s8, 0x100
	s_addc_u32 s9, s9, 0
	s_cmp_ge_i32 s11, s26
	s_mov_b32 s6, s11
	s_cbranch_scc0 .LBB0_408

.LBB0_895:
	v_add_u32_e32 v158, s84, v227
	v_add_u32_e32 v174, s85, v227
	ds_read_b128 v[146:149], v158
	ds_read_b128 v[150:153], v158 offset:1024
	ds_read_b128 v[154:157], v158 offset:2048
	ds_read_b128 v[158:161], v158 offset:3072
	ds_read_b128 v[162:165], v174
	ds_read_b128 v[166:169], v174 offset:1024
	ds_read_b128 v[170:173], v174 offset:2048
	ds_read_b128 v[174:177], v174 offset:3072
	s_add_i32 s16, s50, 2
	s_add_u32 s17, s46, 0x80
	s_addc_u32 s51, s47, 0
	s_cmp_eq_u32 s81, s50
	s_cselect_b32 s50, s4, s17
	s_cselect_b32 s51, s5, s51
	s_cselect_b32 s55, s45, vcc_hi
	s_cselect_b32 s54, s44, vcc_lo
	v_lshl_add_u64 v[210:211], s[46:47], 0, v[138:139]
	s_add_i32 m0, s63, 0xc000
	ds_read_b128 v[178:181], v229
	ds_read_b128 v[182:185], v229 offset:1024
	ds_read_b128 v[186:189], v229 offset:2048
	ds_read_b128 v[190:193], v229 offset:3072
	ds_read_b128 v[194:197], v229 offset:4096
	ds_read_b128 v[198:201], v229 offset:5120
	ds_read_b128 v[202:205], v229 offset:6144
	ds_read_b128 v[206:209], v229 offset:7168
	global_load_lds_dwordx4 v[210:211], off
	v_lshl_add_u64 v[210:211], s[46:47], 0, v[140:141]
	s_add_i32 m0, s63, 0xe000
	s_nop 0
	global_load_lds_dwordx4 v[210:211], off
	s_waitcnt vmcnt(8)
	s_waitcnt lgkmcnt(0)
	s_waitcnt lgkmcnt(0)
	v_mfma_i32_16x16x64_i8 v[126:129], v[146:149], v[178:181], v[126:129]
	v_mfma_i32_16x16x64_i8 v[122:125], v[154:157], v[178:181], v[122:125]
	s_barrier
	v_mfma_i32_16x16x64_i8 v[118:121], v[146:149], v[186:189], v[118:121]
	v_mfma_i32_16x16x64_i8 v[114:117], v[154:157], v[186:189], v[114:117]
	v_mfma_i32_16x16x64_i8 v[106:109], v[146:149], v[194:197], v[106:109]
	v_mfma_i32_16x16x64_i8 v[98:101], v[154:157], v[194:197], v[98:101]
	v_mfma_i32_16x16x64_i8 v[90:93], v[146:149], v[202:205], v[90:93]
	v_mfma_i32_16x16x64_i8 v[82:85], v[154:157], v[202:205], v[82:85]
	v_mfma_i32_16x16x64_i8 v[126:129], v[150:153], v[182:185], v[126:129]
	v_mfma_i32_16x16x64_i8 v[122:125], v[158:161], v[182:185], v[122:125]
	v_mfma_i32_16x16x64_i8 v[118:121], v[150:153], v[190:193], v[118:121]
	v_mfma_i32_16x16x64_i8 v[114:117], v[158:161], v[190:193], v[114:117]
	v_mfma_i32_16x16x64_i8 v[106:109], v[150:153], v[198:201], v[106:109]
	v_mfma_i32_16x16x64_i8 v[98:101], v[158:161], v[198:201], v[98:101]
	v_mfma_i32_16x16x64_i8 v[90:93], v[150:153], v[206:209], v[90:93]
	v_mfma_i32_16x16x64_i8 v[82:85], v[158:161], v[206:209], v[82:85]
	v_mfma_i32_16x16x64_i8 v[110:113], v[162:165], v[178:181], v[110:113]
	v_mfma_i32_16x16x64_i8 v[102:105], v[170:173], v[178:181], v[102:105]
	v_mfma_i32_16x16x64_i8 v[94:97], v[162:165], v[186:189], v[94:97]
	v_mfma_i32_16x16x64_i8 v[86:89], v[170:173], v[186:189], v[86:89]
	v_mfma_i32_16x16x64_i8 v[78:81], v[162:165], v[194:197], v[78:81]
	v_mfma_i32_16x16x64_i8 v[74:77], v[170:173], v[194:197], v[74:77]
	v_mfma_i32_16x16x64_i8 v[70:73], v[162:165], v[202:205], v[70:73]
	v_mfma_i32_16x16x64_i8 v[66:69], v[170:173], v[202:205], v[66:69]
	v_mfma_i32_16x16x64_i8 v[110:113], v[166:169], v[182:185], v[110:113]
	v_mfma_i32_16x16x64_i8 v[102:105], v[174:177], v[182:185], v[102:105]
	v_mfma_i32_16x16x64_i8 v[94:97], v[166:169], v[190:193], v[94:97]
	v_mfma_i32_16x16x64_i8 v[86:89], v[174:177], v[190:193], v[86:89]
	v_mfma_i32_16x16x64_i8 v[78:81], v[166:169], v[198:201], v[78:81]
	v_mfma_i32_16x16x64_i8 v[74:77], v[174:177], v[198:201], v[74:77]
	v_mfma_i32_16x16x64_i8 v[70:73], v[166:169], v[206:209], v[70:73]
	v_mfma_i32_16x16x64_i8 v[66:69], v[174:177], v[206:209], v[66:69]
	s_barrier
	s_add_i32 s17, s84, s62
	v_lshl_add_u64 v[210:211], s[54:55], 0, v[132:133]
	s_mov_b32 m0, s17
	ds_read_b128 v[178:181], v229 offset:16384
	ds_read_b128 v[182:185], v229 offset:17408
	ds_read_b128 v[186:189], v229 offset:18432
	ds_read_b128 v[190:193], v229 offset:19456
	ds_read_b128 v[194:197], v229 offset:20480
	ds_read_b128 v[198:201], v229 offset:21504
	ds_read_b128 v[202:205], v229 offset:22528
	ds_read_b128 v[206:209], v229 offset:23552
	global_load_lds_dwordx4 v[210:211], off
	s_add_i32 m0, s17, 0x2000
	v_lshl_add_u64 v[212:213], s[54:55], 0, v[136:137]
	s_add_u32 s54, s54, s8
	s_addc_u32 s55, s55, s9
	s_add_i32 s17, s85, s62
	global_load_lds_dwordx4 v[212:213], off
	v_lshl_add_u64 v[214:215], s[54:55], 0, v[132:133]
	s_mov_b32 m0, s17
	v_lshl_add_u64 v[216:217], s[54:55], 0, v[136:137]
	global_load_lds_dwordx4 v[214:215], off
	s_add_i32 m0, s17, 0x2000
	v_lshl_add_u64 v[218:219], s[50:51], 0, v[130:131]
	global_load_lds_dwordx4 v[216:217], off
	s_mov_b32 m0, s63
	v_lshl_add_u64 v[220:221], s[50:51], 0, v[134:135]
	global_load_lds_dwordx4 v[218:219], off
	s_mov_b32 m0, s64
	s_nop 0
	global_load_lds_dwordx4 v[220:221], off
	s_waitcnt vmcnt(8)
	s_waitcnt lgkmcnt(0)
	s_waitcnt lgkmcnt(0)
	v_mfma_i32_16x16x64_i8 v[62:65], v[146:149], v[178:181], v[62:65]
	v_mfma_i32_16x16x64_i8 v[58:61], v[154:157], v[178:181], v[58:61]
	s_barrier
	v_mfma_i32_16x16x64_i8 v[54:57], v[146:149], v[186:189], v[54:57]
	v_mfma_i32_16x16x64_i8 v[50:53], v[154:157], v[186:189], v[50:53]
	v_mfma_i32_16x16x64_i8 v[42:45], v[146:149], v[194:197], v[42:45]
	v_mfma_i32_16x16x64_i8 v[34:37], v[154:157], v[194:197], v[34:37]
	v_mfma_i32_16x16x64_i8 v[26:29], v[146:149], v[202:205], v[26:29]
	v_mfma_i32_16x16x64_i8 v[18:21], v[154:157], v[202:205], v[18:21]
	v_mfma_i32_16x16x64_i8 v[62:65], v[150:153], v[182:185], v[62:65]
	v_mfma_i32_16x16x64_i8 v[58:61], v[158:161], v[182:185], v[58:61]
	v_mfma_i32_16x16x64_i8 v[54:57], v[150:153], v[190:193], v[54:57]
	v_mfma_i32_16x16x64_i8 v[50:53], v[158:161], v[190:193], v[50:53]
	v_mfma_i32_16x16x64_i8 v[42:45], v[150:153], v[198:201], v[42:45]
	v_mfma_i32_16x16x64_i8 v[34:37], v[158:161], v[198:201], v[34:37]
	v_mfma_i32_16x16x64_i8 v[26:29], v[150:153], v[206:209], v[26:29]
	v_mfma_i32_16x16x64_i8 v[18:21], v[158:161], v[206:209], v[18:21]
	v_mfma_i32_16x16x64_i8 v[46:49], v[162:165], v[178:181], v[46:49]
	v_mfma_i32_16x16x64_i8 v[38:41], v[170:173], v[178:181], v[38:41]
	v_mfma_i32_16x16x64_i8 v[30:33], v[162:165], v[186:189], v[30:33]
	v_mfma_i32_16x16x64_i8 v[22:25], v[170:173], v[186:189], v[22:25]
	v_mfma_i32_16x16x64_i8 v[14:17], v[162:165], v[194:197], v[14:17]
	v_mfma_i32_16x16x64_i8 v[10:13], v[170:173], v[194:197], v[10:13]
	v_mfma_i32_16x16x64_i8 v[6:9], v[162:165], v[202:205], v[6:9]
	v_mfma_i32_16x16x64_i8 v[2:5], v[170:173], v[202:205], v[2:5]
	v_mfma_i32_16x16x64_i8 v[46:49], v[166:169], v[182:185], v[46:49]
	v_mfma_i32_16x16x64_i8 v[38:41], v[174:177], v[182:185], v[38:41]
	v_mfma_i32_16x16x64_i8 v[30:33], v[166:169], v[190:193], v[30:33]
	v_mfma_i32_16x16x64_i8 v[22:25], v[174:177], v[190:193], v[22:25]
	v_mfma_i32_16x16x64_i8 v[14:17], v[166:169], v[198:201], v[14:17]
	v_mfma_i32_16x16x64_i8 v[10:13], v[174:177], v[198:201], v[10:13]
	v_mfma_i32_16x16x64_i8 v[6:9], v[166:169], v[206:209], v[6:9]
	v_mfma_i32_16x16x64_i8 v[2:5], v[174:177], v[206:209], v[2:5]
	s_barrier
	s_add_i32 s17, 0, 0x18000
	s_add_i32 s54, 0, 0x1c000
	v_add_u32_e32 v158, s17, v227
	v_add_u32_e32 v174, s54, v227
	ds_read_b128 v[146:149], v158
	ds_read_b128 v[150:153], v158 offset:1024
	ds_read_b128 v[154:157], v158 offset:2048
	ds_read_b128 v[158:161], v158 offset:3072
	ds_read_b128 v[162:165], v174
	ds_read_b128 v[166:169], v174 offset:1024
	ds_read_b128 v[170:173], v174 offset:2048
	ds_read_b128 v[174:177], v174 offset:3072
	s_add_u32 s50, s50, s8
	s_addc_u32 s51, s51, s9
	s_mov_b32 m0, s65
	v_lshl_add_u64 v[222:223], s[50:51], 0, v[130:131]
	ds_read_b128 v[178:181], v229 offset:32768
	ds_read_b128 v[182:185], v229 offset:33792
	ds_read_b128 v[186:189], v229 offset:34816
	ds_read_b128 v[190:193], v229 offset:35840
	ds_read_b128 v[194:197], v229 offset:36864
	ds_read_b128 v[198:201], v229 offset:37888
	ds_read_b128 v[202:205], v229 offset:38912
	ds_read_b128 v[206:209], v229 offset:39936
	global_load_lds_dwordx4 v[222:223], off
	v_lshl_add_u64 v[222:223], s[50:51], 0, v[134:135]
	s_mov_b32 m0, s86
	s_nop 0
	global_load_lds_dwordx4 v[222:223], off
	s_waitcnt vmcnt(8)
	s_waitcnt lgkmcnt(0)
	s_waitcnt lgkmcnt(0)
	v_mfma_i32_16x16x64_i8 v[126:129], v[146:149], v[178:181], v[126:129]
	v_mfma_i32_16x16x64_i8 v[122:125], v[154:157], v[178:181], v[122:125]
	s_barrier
	v_mfma_i32_16x16x64_i8 v[118:121], v[146:149], v[186:189], v[118:121]
	v_mfma_i32_16x16x64_i8 v[114:117], v[154:157], v[186:189], v[114:117]
	v_mfma_i32_16x16x64_i8 v[106:109], v[146:149], v[194:197], v[106:109]
	v_mfma_i32_16x16x64_i8 v[98:101], v[154:157], v[194:197], v[98:101]
	v_mfma_i32_16x16x64_i8 v[90:93], v[146:149], v[202:205], v[90:93]
	v_mfma_i32_16x16x64_i8 v[82:85], v[154:157], v[202:205], v[82:85]
	v_mfma_i32_16x16x64_i8 v[126:129], v[150:153], v[182:185], v[126:129]
	v_mfma_i32_16x16x64_i8 v[122:125], v[158:161], v[182:185], v[122:125]
	v_mfma_i32_16x16x64_i8 v[118:121], v[150:153], v[190:193], v[118:121]
	v_mfma_i32_16x16x64_i8 v[114:117], v[158:161], v[190:193], v[114:117]
	v_mfma_i32_16x16x64_i8 v[106:109], v[150:153], v[198:201], v[106:109]
	v_mfma_i32_16x16x64_i8 v[98:101], v[158:161], v[198:201], v[98:101]
	v_mfma_i32_16x16x64_i8 v[90:93], v[150:153], v[206:209], v[90:93]
	v_mfma_i32_16x16x64_i8 v[82:85], v[158:161], v[206:209], v[82:85]
	v_mfma_i32_16x16x64_i8 v[110:113], v[162:165], v[178:181], v[110:113]
	v_mfma_i32_16x16x64_i8 v[102:105], v[170:173], v[178:181], v[102:105]
	v_mfma_i32_16x16x64_i8 v[94:97], v[162:165], v[186:189], v[94:97]
	v_mfma_i32_16x16x64_i8 v[86:89], v[170:173], v[186:189], v[86:89]
	v_mfma_i32_16x16x64_i8 v[78:81], v[162:165], v[194:197], v[78:81]
	v_mfma_i32_16x16x64_i8 v[74:77], v[170:173], v[194:197], v[74:77]
	v_mfma_i32_16x16x64_i8 v[70:73], v[162:165], v[202:205], v[70:73]
	v_mfma_i32_16x16x64_i8 v[66:69], v[170:173], v[202:205], v[66:69]
	v_mfma_i32_16x16x64_i8 v[110:113], v[166:169], v[182:185], v[110:113]
	v_mfma_i32_16x16x64_i8 v[102:105], v[174:177], v[182:185], v[102:105]
	v_mfma_i32_16x16x64_i8 v[94:97], v[166:169], v[190:193], v[94:97]
	v_mfma_i32_16x16x64_i8 v[86:89], v[174:177], v[190:193], v[86:89]
	v_mfma_i32_16x16x64_i8 v[78:81], v[166:169], v[198:201], v[78:81]
	v_mfma_i32_16x16x64_i8 v[74:77], v[174:177], v[198:201], v[74:77]
	v_mfma_i32_16x16x64_i8 v[70:73], v[166:169], v[206:209], v[70:73]
	v_mfma_i32_16x16x64_i8 v[66:69], v[174:177], v[206:209], v[66:69]
	s_barrier
	s_add_i32 s17, s17, s62
	v_lshl_add_u64 v[210:211], v[210:211], 0, s[36:37]
	s_mov_b32 m0, s17
	ds_read_b128 v[178:181], v229 offset:49152
	ds_read_b128 v[182:185], v229 offset:50176
	ds_read_b128 v[186:189], v229 offset:51200
	ds_read_b128 v[190:193], v229 offset:52224
	ds_read_b128 v[194:197], v229 offset:53248
	ds_read_b128 v[198:201], v229 offset:54272
	ds_read_b128 v[202:205], v229 offset:55296
	ds_read_b128 v[206:209], v229 offset:56320
	global_load_lds_dwordx4 v[210:211], off
	v_lshl_add_u64 v[210:211], v[212:213], 0, s[36:37]
	s_add_i32 m0, s17, 0x2000
	s_add_i32 s17, s54, s62
	global_load_lds_dwordx4 v[210:211], off
	v_lshl_add_u64 v[210:211], v[214:215], 0, s[36:37]
	s_mov_b32 m0, s17
	s_nop 0
	global_load_lds_dwordx4 v[210:211], off
	v_lshl_add_u64 v[210:211], v[216:217], 0, s[36:37]
	s_add_i32 m0, s17, 0x2000
	s_nop 0
	global_load_lds_dwordx4 v[210:211], off
	v_lshl_add_u64 v[210:211], v[218:219], 0, s[36:37]
	s_mov_b32 m0, s95
	s_nop 0
	global_load_lds_dwordx4 v[210:211], off
	v_lshl_add_u64 v[210:211], v[220:221], 0, s[36:37]
	s_mov_b32 m0, s80
	s_nop 0
	global_load_lds_dwordx4 v[210:211], off
	s_waitcnt vmcnt(8)
	s_waitcnt lgkmcnt(0)
	s_waitcnt lgkmcnt(0)
	v_mfma_i32_16x16x64_i8 v[62:65], v[146:149], v[178:181], v[62:65]
	v_mfma_i32_16x16x64_i8 v[58:61], v[154:157], v[178:181], v[58:61]
	s_barrier
	v_mfma_i32_16x16x64_i8 v[54:57], v[146:149], v[186:189], v[54:57]
	v_mfma_i32_16x16x64_i8 v[50:53], v[154:157], v[186:189], v[50:53]
	v_mfma_i32_16x16x64_i8 v[42:45], v[146:149], v[194:197], v[42:45]
	v_mfma_i32_16x16x64_i8 v[34:37], v[154:157], v[194:197], v[34:37]
	v_mfma_i32_16x16x64_i8 v[26:29], v[146:149], v[202:205], v[26:29]
	v_mfma_i32_16x16x64_i8 v[18:21], v[154:157], v[202:205], v[18:21]
	v_mfma_i32_16x16x64_i8 v[62:65], v[150:153], v[182:185], v[62:65]
	v_mfma_i32_16x16x64_i8 v[58:61], v[158:161], v[182:185], v[58:61]
	v_mfma_i32_16x16x64_i8 v[54:57], v[150:153], v[190:193], v[54:57]
	v_mfma_i32_16x16x64_i8 v[50:53], v[158:161], v[190:193], v[50:53]
	v_mfma_i32_16x16x64_i8 v[42:45], v[150:153], v[198:201], v[42:45]
	v_mfma_i32_16x16x64_i8 v[34:37], v[158:161], v[198:201], v[34:37]
	v_mfma_i32_16x16x64_i8 v[26:29], v[150:153], v[206:209], v[26:29]
	v_mfma_i32_16x16x64_i8 v[18:21], v[158:161], v[206:209], v[18:21]
	v_mfma_i32_16x16x64_i8 v[46:49], v[162:165], v[178:181], v[46:49]
	v_mfma_i32_16x16x64_i8 v[38:41], v[170:173], v[178:181], v[38:41]
	v_mfma_i32_16x16x64_i8 v[30:33], v[162:165], v[186:189], v[30:33]
	v_mfma_i32_16x16x64_i8 v[22:25], v[170:173], v[186:189], v[22:25]
	v_mfma_i32_16x16x64_i8 v[14:17], v[162:165], v[194:197], v[14:17]
	v_mfma_i32_16x16x64_i8 v[10:13], v[170:173], v[194:197], v[10:13]
	v_mfma_i32_16x16x64_i8 v[6:9], v[162:165], v[202:205], v[6:9]
	v_mfma_i32_16x16x64_i8 v[2:5], v[170:173], v[202:205], v[2:5]
	v_mfma_i32_16x16x64_i8 v[46:49], v[166:169], v[182:185], v[46:49]
	v_mfma_i32_16x16x64_i8 v[38:41], v[174:177], v[182:185], v[38:41]
	v_mfma_i32_16x16x64_i8 v[30:33], v[166:169], v[190:193], v[30:33]
	v_mfma_i32_16x16x64_i8 v[22:25], v[174:177], v[190:193], v[22:25]
	v_mfma_i32_16x16x64_i8 v[14:17], v[166:169], v[198:201], v[14:17]
	v_mfma_i32_16x16x64_i8 v[10:13], v[174:177], v[198:201], v[10:13]
	v_mfma_i32_16x16x64_i8 v[6:9], v[166:169], v[206:209], v[6:9]
	v_mfma_i32_16x16x64_i8 v[2:5], v[174:177], v[206:209], v[2:5]
	s_barrier
	s_add_u32 s46, s46, 0x100
	s_addc_u32 s47, s47, 0
	s_add_u32 vcc_lo, vcc_lo, 0x100
	s_addc_u32 vcc_hi, vcc_hi, 0
	s_cmp_ge_i32 s16, s90
	s_mov_b32 s50, s16
	s_cbranch_scc0 .LBB0_895
	v_cvt_f32_i32_e32 v220, v126
	v_cvt_f32_i32_e32 v221, v127
	v_cvt_f32_i32_e32 v218, v128
	v_cvt_f32_i32_e32 v219, v129
	v_cvt_f32_i32_e32 v224, v122
	v_cvt_f32_i32_e32 v225, v123
	v_cvt_f32_i32_e32 v222, v124
	v_cvt_f32_i32_e32 v223, v125
	v_cvt_f32_i32_e32 v212, v110
	v_cvt_f32_i32_e32 v213, v111
	v_cvt_f32_i32_e32 v210, v112
	v_cvt_f32_i32_e32 v211, v113
	v_cvt_f32_i32_e32 v216, v102
	v_cvt_f32_i32_e32 v217, v103
	v_cvt_f32_i32_e32 v214, v104
	v_cvt_f32_i32_e32 v215, v105
	v_cvt_f32_i32_e32 v204, v118
	v_cvt_f32_i32_e32 v205, v119
	v_cvt_f32_i32_e32 v202, v120
	v_cvt_f32_i32_e32 v203, v121
	v_cvt_f32_i32_e32 v208, v114
	v_cvt_f32_i32_e32 v209, v115
	v_cvt_f32_i32_e32 v206, v116
	v_cvt_f32_i32_e32 v207, v117
	v_cvt_f32_i32_e32 v198, v94
	v_cvt_f32_i32_e32 v199, v95
	v_cvt_f32_i32_e32 v194, v96
	v_cvt_f32_i32_e32 v195, v97
	v_cvt_f32_i32_e32 v200, v86
	v_cvt_f32_i32_e32 v201, v87
	v_cvt_f32_i32_e32 v196, v88
	v_cvt_f32_i32_e32 v197, v89
	v_cvt_f32_i32_e32 v188, v106
	v_cvt_f32_i32_e32 v189, v107
	v_cvt_f32_i32_e32 v186, v108
	v_cvt_f32_i32_e32 v187, v109
	v_cvt_f32_i32_e32 v192, v98
	v_cvt_f32_i32_e32 v193, v99
	v_cvt_f32_i32_e32 v190, v100
	v_cvt_f32_i32_e32 v191, v101
	v_cvt_f32_i32_e32 v182, v78
	v_cvt_f32_i32_e32 v183, v79
	v_cvt_f32_i32_e32 v178, v80
	v_cvt_f32_i32_e32 v179, v81
	v_cvt_f32_i32_e32 v184, v74
	v_cvt_f32_i32_e32 v185, v75
	v_cvt_f32_i32_e32 v180, v76
	v_cvt_f32_i32_e32 v181, v77
	v_cvt_f32_i32_e32 v170, v90
	v_cvt_f32_i32_e32 v171, v91
	v_cvt_f32_i32_e32 v168, v92
	v_cvt_f32_i32_e32 v169, v93
	v_cvt_f32_i32_e32 v174, v82
	v_cvt_f32_i32_e32 v175, v83
	v_cvt_f32_i32_e32 v172, v84
	v_cvt_f32_i32_e32 v173, v85
	v_cvt_f32_i32_e32 v164, v70
	v_cvt_f32_i32_e32 v165, v71
	v_cvt_f32_i32_e32 v160, v72
	v_cvt_f32_i32_e32 v161, v73
	v_cvt_f32_i32_e32 v166, v66
	v_cvt_f32_i32_e32 v167, v67
	v_cvt_f32_i32_e32 v162, v68
	v_cvt_f32_i32_e32 v163, v69
	v_cvt_f32_i32_e32 v154, v62
	v_cvt_f32_i32_e32 v155, v63
	v_cvt_f32_i32_e32 v152, v64
	v_cvt_f32_i32_e32 v153, v65
	v_cvt_f32_i32_e32 v158, v58
	v_cvt_f32_i32_e32 v159, v59
	v_cvt_f32_i32_e32 v156, v60
	v_cvt_f32_i32_e32 v157, v61
	v_cvt_f32_i32_e32 v148, v46
	v_cvt_f32_i32_e32 v149, v47
	v_cvt_f32_i32_e32 v128, v48
	v_cvt_f32_i32_e32 v129, v49
	v_cvt_f32_i32_e32 v150, v38
	v_cvt_f32_i32_e32 v151, v39
	v_cvt_f32_i32_e32 v146, v40
	v_cvt_f32_i32_e32 v147, v41
	v_cvt_f32_i32_e32 v122, v54
	v_cvt_f32_i32_e32 v123, v55
	v_cvt_f32_i32_e32 v120, v56
	v_cvt_f32_i32_e32 v121, v57
	v_cvt_f32_i32_e32 v126, v50
	v_cvt_f32_i32_e32 v127, v51
	v_cvt_f32_i32_e32 v124, v52
	v_cvt_f32_i32_e32 v125, v53
	v_cvt_f32_i32_e32 v114, v30
	v_cvt_f32_i32_e32 v115, v31
	v_cvt_f32_i32_e32 v110, v32
	v_cvt_f32_i32_e32 v111, v33
	v_cvt_f32_i32_e32 v116, v22
	v_cvt_f32_i32_e32 v117, v23
	v_cvt_f32_i32_e32 v112, v24
	v_cvt_f32_i32_e32 v113, v25
	v_cvt_f32_i32_e32 v102, v42
	v_cvt_f32_i32_e32 v103, v43
	v_cvt_f32_i32_e32 v100, v44
	v_cvt_f32_i32_e32 v101, v45
	v_cvt_f32_i32_e32 v106, v34
	v_cvt_f32_i32_e32 v107, v35
	v_cvt_f32_i32_e32 v104, v36
	v_cvt_f32_i32_e32 v105, v37
	v_cvt_f32_i32_e32 v96, v14
	v_cvt_f32_i32_e32 v97, v15
	v_cvt_f32_i32_e32 v92, v16
	v_cvt_f32_i32_e32 v93, v17
	v_cvt_f32_i32_e32 v98, v10
	v_cvt_f32_i32_e32 v99, v11
	v_cvt_f32_i32_e32 v94, v12
	v_cvt_f32_i32_e32 v95, v13
	v_cvt_f32_i32_e32 v52, v26
	v_cvt_f32_i32_e32 v53, v27
	v_cvt_f32_i32_e32 v50, v28
	v_cvt_f32_i32_e32 v51, v29
	v_cvt_f32_i32_e32 v56, v18
	v_cvt_f32_i32_e32 v57, v19
	v_cvt_f32_i32_e32 v54, v20
	v_cvt_f32_i32_e32 v55, v21
	v_cvt_f32_i32_e32 v46, v6
	v_cvt_f32_i32_e32 v47, v7
	v_cvt_f32_i32_e32 v42, v8
	v_cvt_f32_i32_e32 v43, v9
	v_cvt_f32_i32_e32 v48, v2
	v_cvt_f32_i32_e32 v49, v3
	v_cvt_f32_i32_e32 v44, v4
	v_cvt_f32_i32_e32 v45, v5

.LBB0_1087:
	v_add_u32_e32 v138, s80, v188
	ds_read_b128 v[148:151], v138
	ds_read_b128 v[152:155], v138 offset:1024
	ds_read_b128 v[156:159], v138 offset:2048
	ds_read_b128 v[160:163], v138 offset:3072
	v_add_u32_e32 v138, s81, v188
	ds_read_b128 v[164:167], v138
	ds_read_b128 v[168:171], v138 offset:1024
	ds_read_b128 v[172:175], v138 offset:2048
	ds_read_b128 v[176:179], v138 offset:3072
	s_add_i32 s84, s34, 2
	s_add_u32 s85, s30, 0x80
	s_addc_u32 s35, s31, 0
	s_cmp_eq_u32 s64, s34
	s_cselect_b32 s34, s2, s85
	s_cselect_b32 s35, s3, s35
	s_cselect_b32 s87, s29, s39
	s_cselect_b32 s86, s28, s38
	v_lshl_add_u64 v[184:185], s[30:31], 0, v[140:141]
	s_add_i32 m0, s50, 0xc000
	ds_read_b128 v[180:183], v189
	ds_read_b128 v[190:193], v189 offset:1024
	ds_read_b128 v[194:197], v189 offset:2048
	ds_read_b128 v[198:201], v189 offset:3072
	ds_read_b128 v[202:205], v189 offset:4096
	ds_read_b128 v[206:209], v189 offset:5120
	ds_read_b128 v[210:213], v189 offset:6144
	ds_read_b128 v[214:217], v189 offset:7168
	global_load_lds_dwordx4 v[184:185], off
	v_lshl_add_u64 v[184:185], s[30:31], 0, v[142:143]
	s_add_i32 m0, s50, 0xe000
	s_nop 0
	global_load_lds_dwordx4 v[184:185], off
	s_waitcnt vmcnt(8)
	s_waitcnt lgkmcnt(0)
	s_waitcnt lgkmcnt(0)
	v_mfma_i32_16x16x64_i8 v[126:129], v[148:151], v[180:183], v[126:129]
	v_mfma_i32_16x16x64_i8 v[122:125], v[156:159], v[180:183], v[122:125]
	s_barrier
	v_mfma_i32_16x16x64_i8 v[118:121], v[148:151], v[194:197], v[118:121]
	v_mfma_i32_16x16x64_i8 v[114:117], v[156:159], v[194:197], v[114:117]
	v_mfma_i32_16x16x64_i8 v[106:109], v[148:151], v[202:205], v[106:109]
	v_mfma_i32_16x16x64_i8 v[98:101], v[156:159], v[202:205], v[98:101]
	v_mfma_i32_16x16x64_i8 v[90:93], v[148:151], v[210:213], v[90:93]
	v_mfma_i32_16x16x64_i8 v[82:85], v[156:159], v[210:213], v[82:85]
	v_mfma_i32_16x16x64_i8 v[126:129], v[152:155], v[190:193], v[126:129]
	v_mfma_i32_16x16x64_i8 v[122:125], v[160:163], v[190:193], v[122:125]
	v_mfma_i32_16x16x64_i8 v[118:121], v[152:155], v[198:201], v[118:121]
	v_mfma_i32_16x16x64_i8 v[114:117], v[160:163], v[198:201], v[114:117]
	v_mfma_i32_16x16x64_i8 v[106:109], v[152:155], v[206:209], v[106:109]
	v_mfma_i32_16x16x64_i8 v[98:101], v[160:163], v[206:209], v[98:101]
	v_mfma_i32_16x16x64_i8 v[90:93], v[152:155], v[214:217], v[90:93]
	v_mfma_i32_16x16x64_i8 v[82:85], v[160:163], v[214:217], v[82:85]
	v_mfma_i32_16x16x64_i8 v[110:113], v[164:167], v[180:183], v[110:113]
	v_mfma_i32_16x16x64_i8 v[102:105], v[172:175], v[180:183], v[102:105]
	v_mfma_i32_16x16x64_i8 v[94:97], v[164:167], v[194:197], v[94:97]
	v_mfma_i32_16x16x64_i8 v[86:89], v[172:175], v[194:197], v[86:89]
	v_mfma_i32_16x16x64_i8 v[78:81], v[164:167], v[202:205], v[78:81]
	v_mfma_i32_16x16x64_i8 v[74:77], v[172:175], v[202:205], v[74:77]
	v_mfma_i32_16x16x64_i8 v[70:73], v[164:167], v[210:213], v[70:73]
	v_mfma_i32_16x16x64_i8 v[66:69], v[172:175], v[210:213], v[66:69]
	v_mfma_i32_16x16x64_i8 v[110:113], v[168:171], v[190:193], v[110:113]
	v_mfma_i32_16x16x64_i8 v[102:105], v[176:179], v[190:193], v[102:105]
	v_mfma_i32_16x16x64_i8 v[94:97], v[168:171], v[198:201], v[94:97]
	v_mfma_i32_16x16x64_i8 v[86:89], v[176:179], v[198:201], v[86:89]
	v_mfma_i32_16x16x64_i8 v[78:81], v[168:171], v[206:209], v[78:81]
	v_mfma_i32_16x16x64_i8 v[74:77], v[176:179], v[206:209], v[74:77]
	v_mfma_i32_16x16x64_i8 v[70:73], v[168:171], v[214:217], v[70:73]
	v_mfma_i32_16x16x64_i8 v[66:69], v[176:179], v[214:217], v[66:69]
	s_barrier
	s_add_i32 s85, s80, s47
	v_lshl_add_u64 v[184:185], s[86:87], 0, v[132:133]
	s_mov_b32 m0, s85
	ds_read_b128 v[180:183], v189 offset:16384
	ds_read_b128 v[190:193], v189 offset:17408
	ds_read_b128 v[194:197], v189 offset:18432
	ds_read_b128 v[198:201], v189 offset:19456
	ds_read_b128 v[202:205], v189 offset:20480
	ds_read_b128 v[206:209], v189 offset:21504
	ds_read_b128 v[210:213], v189 offset:22528
	ds_read_b128 v[214:217], v189 offset:23552
	global_load_lds_dwordx4 v[184:185], off
	s_add_i32 m0, s85, 0x2000
	v_lshl_add_u64 v[218:219], s[86:87], 0, v[136:137]
	s_add_u32 s86, s86, s6
	s_addc_u32 s87, s87, s7
	s_add_i32 s85, s81, s47
	global_load_lds_dwordx4 v[218:219], off
	v_lshl_add_u64 v[220:221], s[86:87], 0, v[132:133]
	s_mov_b32 m0, s85
	v_lshl_add_u64 v[222:223], s[86:87], 0, v[136:137]
	global_load_lds_dwordx4 v[220:221], off
	s_add_i32 m0, s85, 0x2000
	v_lshl_add_u64 v[224:225], s[34:35], 0, v[130:131]
	global_load_lds_dwordx4 v[222:223], off
	s_mov_b32 m0, s50
	v_lshl_add_u64 v[226:227], s[34:35], 0, v[134:135]
	global_load_lds_dwordx4 v[224:225], off
	s_mov_b32 m0, s51
	s_nop 0
	global_load_lds_dwordx4 v[226:227], off
	s_waitcnt vmcnt(8)
	s_waitcnt lgkmcnt(0)
	s_waitcnt lgkmcnt(0)
	v_mfma_i32_16x16x64_i8 v[62:65], v[148:151], v[180:183], v[62:65]
	v_mfma_i32_16x16x64_i8 v[58:61], v[156:159], v[180:183], v[58:61]
	s_barrier
	v_mfma_i32_16x16x64_i8 v[54:57], v[148:151], v[194:197], v[54:57]
	v_mfma_i32_16x16x64_i8 v[50:53], v[156:159], v[194:197], v[50:53]
	v_mfma_i32_16x16x64_i8 v[42:45], v[148:151], v[202:205], v[42:45]
	v_mfma_i32_16x16x64_i8 v[34:37], v[156:159], v[202:205], v[34:37]
	v_mfma_i32_16x16x64_i8 v[26:29], v[148:151], v[210:213], v[26:29]
	v_mfma_i32_16x16x64_i8 v[18:21], v[156:159], v[210:213], v[18:21]
	v_mfma_i32_16x16x64_i8 v[62:65], v[152:155], v[190:193], v[62:65]
	v_mfma_i32_16x16x64_i8 v[58:61], v[160:163], v[190:193], v[58:61]
	v_mfma_i32_16x16x64_i8 v[54:57], v[152:155], v[198:201], v[54:57]
	v_mfma_i32_16x16x64_i8 v[50:53], v[160:163], v[198:201], v[50:53]
	v_mfma_i32_16x16x64_i8 v[42:45], v[152:155], v[206:209], v[42:45]
	v_mfma_i32_16x16x64_i8 v[34:37], v[160:163], v[206:209], v[34:37]
	v_mfma_i32_16x16x64_i8 v[26:29], v[152:155], v[214:217], v[26:29]
	v_mfma_i32_16x16x64_i8 v[18:21], v[160:163], v[214:217], v[18:21]
	v_mfma_i32_16x16x64_i8 v[46:49], v[164:167], v[180:183], v[46:49]
	v_mfma_i32_16x16x64_i8 v[38:41], v[172:175], v[180:183], v[38:41]
	v_mfma_i32_16x16x64_i8 v[30:33], v[164:167], v[194:197], v[30:33]
	v_mfma_i32_16x16x64_i8 v[22:25], v[172:175], v[194:197], v[22:25]
	v_mfma_i32_16x16x64_i8 v[14:17], v[164:167], v[202:205], v[14:17]
	v_mfma_i32_16x16x64_i8 v[10:13], v[172:175], v[202:205], v[10:13]
	v_mfma_i32_16x16x64_i8 v[6:9], v[164:167], v[210:213], v[6:9]
	v_mfma_i32_16x16x64_i8 v[2:5], v[172:175], v[210:213], v[2:5]
	v_mfma_i32_16x16x64_i8 v[46:49], v[168:171], v[190:193], v[46:49]
	v_mfma_i32_16x16x64_i8 v[38:41], v[176:179], v[190:193], v[38:41]
	v_mfma_i32_16x16x64_i8 v[30:33], v[168:171], v[198:201], v[30:33]
	v_mfma_i32_16x16x64_i8 v[22:25], v[176:179], v[198:201], v[22:25]
	v_mfma_i32_16x16x64_i8 v[14:17], v[168:171], v[206:209], v[14:17]
	v_mfma_i32_16x16x64_i8 v[10:13], v[176:179], v[206:209], v[10:13]
	v_mfma_i32_16x16x64_i8 v[6:9], v[168:171], v[214:217], v[6:9]
	v_mfma_i32_16x16x64_i8 v[2:5], v[176:179], v[214:217], v[2:5]
	s_barrier
	s_add_i32 s85, 0, 0x18000
	v_add_u32_e32 v138, s85, v188
	s_add_i32 s86, 0, 0x1c000
	ds_read_b128 v[148:151], v138
	ds_read_b128 v[152:155], v138 offset:1024
	ds_read_b128 v[156:159], v138 offset:2048
	ds_read_b128 v[160:163], v138 offset:3072
	v_add_u32_e32 v138, s86, v188
	ds_read_b128 v[164:167], v138
	ds_read_b128 v[168:171], v138 offset:1024
	ds_read_b128 v[172:175], v138 offset:2048
	ds_read_b128 v[176:179], v138 offset:3072
	s_add_u32 s34, s34, s6
	s_addc_u32 s35, s35, s7
	s_mov_b32 m0, s54
	v_lshl_add_u64 v[228:229], s[34:35], 0, v[130:131]
	ds_read_b128 v[180:183], v189 offset:32768
	ds_read_b128 v[190:193], v189 offset:33792
	ds_read_b128 v[194:197], v189 offset:34816
	ds_read_b128 v[198:201], v189 offset:35840
	ds_read_b128 v[202:205], v189 offset:36864
	ds_read_b128 v[206:209], v189 offset:37888
	ds_read_b128 v[210:213], v189 offset:38912
	ds_read_b128 v[214:217], v189 offset:39936
	global_load_lds_dwordx4 v[228:229], off
	v_lshl_add_u64 v[228:229], s[34:35], 0, v[134:135]
	s_mov_b32 m0, s55
	s_nop 0
	global_load_lds_dwordx4 v[228:229], off
	s_waitcnt vmcnt(8)
	s_waitcnt lgkmcnt(0)
	s_waitcnt lgkmcnt(0)
	v_mfma_i32_16x16x64_i8 v[126:129], v[148:151], v[180:183], v[126:129]
	v_mfma_i32_16x16x64_i8 v[122:125], v[156:159], v[180:183], v[122:125]
	s_barrier
	v_mfma_i32_16x16x64_i8 v[118:121], v[148:151], v[194:197], v[118:121]
	v_mfma_i32_16x16x64_i8 v[114:117], v[156:159], v[194:197], v[114:117]
	v_mfma_i32_16x16x64_i8 v[106:109], v[148:151], v[202:205], v[106:109]
	v_mfma_i32_16x16x64_i8 v[98:101], v[156:159], v[202:205], v[98:101]
	v_mfma_i32_16x16x64_i8 v[90:93], v[148:151], v[210:213], v[90:93]
	v_mfma_i32_16x16x64_i8 v[82:85], v[156:159], v[210:213], v[82:85]
	v_mfma_i32_16x16x64_i8 v[126:129], v[152:155], v[190:193], v[126:129]
	v_mfma_i32_16x16x64_i8 v[122:125], v[160:163], v[190:193], v[122:125]
	v_mfma_i32_16x16x64_i8 v[118:121], v[152:155], v[198:201], v[118:121]
	v_mfma_i32_16x16x64_i8 v[114:117], v[160:163], v[198:201], v[114:117]
	v_mfma_i32_16x16x64_i8 v[106:109], v[152:155], v[206:209], v[106:109]
	v_mfma_i32_16x16x64_i8 v[98:101], v[160:163], v[206:209], v[98:101]
	v_mfma_i32_16x16x64_i8 v[90:93], v[152:155], v[214:217], v[90:93]
	v_mfma_i32_16x16x64_i8 v[82:85], v[160:163], v[214:217], v[82:85]
	v_mfma_i32_16x16x64_i8 v[110:113], v[164:167], v[180:183], v[110:113]
	v_mfma_i32_16x16x64_i8 v[102:105], v[172:175], v[180:183], v[102:105]
	v_mfma_i32_16x16x64_i8 v[94:97], v[164:167], v[194:197], v[94:97]
	v_mfma_i32_16x16x64_i8 v[86:89], v[172:175], v[194:197], v[86:89]
	v_mfma_i32_16x16x64_i8 v[78:81], v[164:167], v[202:205], v[78:81]
	v_mfma_i32_16x16x64_i8 v[74:77], v[172:175], v[202:205], v[74:77]
	v_mfma_i32_16x16x64_i8 v[70:73], v[164:167], v[210:213], v[70:73]
	v_mfma_i32_16x16x64_i8 v[66:69], v[172:175], v[210:213], v[66:69]
	v_mfma_i32_16x16x64_i8 v[110:113], v[168:171], v[190:193], v[110:113]
	v_mfma_i32_16x16x64_i8 v[102:105], v[176:179], v[190:193], v[102:105]
	v_mfma_i32_16x16x64_i8 v[94:97], v[168:171], v[198:201], v[94:97]
	v_mfma_i32_16x16x64_i8 v[86:89], v[176:179], v[198:201], v[86:89]
	v_mfma_i32_16x16x64_i8 v[78:81], v[168:171], v[206:209], v[78:81]
	v_mfma_i32_16x16x64_i8 v[74:77], v[176:179], v[206:209], v[74:77]
	v_mfma_i32_16x16x64_i8 v[70:73], v[168:171], v[214:217], v[70:73]
	v_mfma_i32_16x16x64_i8 v[66:69], v[176:179], v[214:217], v[66:69]
	s_barrier
	s_add_i32 s34, s85, s47
	v_lshl_add_u64 v[184:185], v[184:185], 0, s[22:23]
	s_mov_b32 m0, s34
	ds_read_b128 v[180:183], v189 offset:49152
	ds_read_b128 v[190:193], v189 offset:50176
	ds_read_b128 v[194:197], v189 offset:51200
	ds_read_b128 v[198:201], v189 offset:52224
	ds_read_b128 v[202:205], v189 offset:53248
	ds_read_b128 v[206:209], v189 offset:54272
	ds_read_b128 v[210:213], v189 offset:55296
	ds_read_b128 v[214:217], v189 offset:56320
	global_load_lds_dwordx4 v[184:185], off
	v_lshl_add_u64 v[184:185], v[218:219], 0, s[22:23]
	s_add_i32 m0, s34, 0x2000
	s_add_i32 s34, s86, s47
	global_load_lds_dwordx4 v[184:185], off
	v_lshl_add_u64 v[184:185], v[220:221], 0, s[22:23]
	s_mov_b32 m0, s34
	s_nop 0
	global_load_lds_dwordx4 v[184:185], off
	v_lshl_add_u64 v[184:185], v[222:223], 0, s[22:23]
	s_add_i32 m0, s34, 0x2000
	s_nop 0
	global_load_lds_dwordx4 v[184:185], off
	v_lshl_add_u64 v[184:185], v[224:225], 0, s[22:23]
	s_mov_b32 m0, s59
	s_nop 0
	global_load_lds_dwordx4 v[184:185], off
	v_lshl_add_u64 v[184:185], v[226:227], 0, s[22:23]
	s_mov_b32 m0, s60
	s_nop 0
	global_load_lds_dwordx4 v[184:185], off
	s_waitcnt vmcnt(8)
	s_waitcnt lgkmcnt(0)
	s_waitcnt lgkmcnt(0)
	v_mfma_i32_16x16x64_i8 v[62:65], v[148:151], v[180:183], v[62:65]
	v_mfma_i32_16x16x64_i8 v[58:61], v[156:159], v[180:183], v[58:61]
	s_barrier
	v_mfma_i32_16x16x64_i8 v[54:57], v[148:151], v[194:197], v[54:57]
	v_mfma_i32_16x16x64_i8 v[50:53], v[156:159], v[194:197], v[50:53]
	v_mfma_i32_16x16x64_i8 v[42:45], v[148:151], v[202:205], v[42:45]
	v_mfma_i32_16x16x64_i8 v[34:37], v[156:159], v[202:205], v[34:37]
	v_mfma_i32_16x16x64_i8 v[26:29], v[148:151], v[210:213], v[26:29]
	v_mfma_i32_16x16x64_i8 v[18:21], v[156:159], v[210:213], v[18:21]
	v_mfma_i32_16x16x64_i8 v[62:65], v[152:155], v[190:193], v[62:65]
	v_mfma_i32_16x16x64_i8 v[58:61], v[160:163], v[190:193], v[58:61]
	v_mfma_i32_16x16x64_i8 v[54:57], v[152:155], v[198:201], v[54:57]
	v_mfma_i32_16x16x64_i8 v[50:53], v[160:163], v[198:201], v[50:53]
	v_mfma_i32_16x16x64_i8 v[42:45], v[152:155], v[206:209], v[42:45]
	v_mfma_i32_16x16x64_i8 v[34:37], v[160:163], v[206:209], v[34:37]
	v_mfma_i32_16x16x64_i8 v[26:29], v[152:155], v[214:217], v[26:29]
	v_mfma_i32_16x16x64_i8 v[18:21], v[160:163], v[214:217], v[18:21]
	v_mfma_i32_16x16x64_i8 v[46:49], v[164:167], v[180:183], v[46:49]
	v_mfma_i32_16x16x64_i8 v[38:41], v[172:175], v[180:183], v[38:41]
	v_mfma_i32_16x16x64_i8 v[30:33], v[164:167], v[194:197], v[30:33]
	v_mfma_i32_16x16x64_i8 v[22:25], v[172:175], v[194:197], v[22:25]
	v_mfma_i32_16x16x64_i8 v[14:17], v[164:167], v[202:205], v[14:17]
	v_mfma_i32_16x16x64_i8 v[10:13], v[172:175], v[202:205], v[10:13]
	v_mfma_i32_16x16x64_i8 v[6:9], v[164:167], v[210:213], v[6:9]
	v_mfma_i32_16x16x64_i8 v[2:5], v[172:175], v[210:213], v[2:5]
	v_mfma_i32_16x16x64_i8 v[46:49], v[168:171], v[190:193], v[46:49]
	v_mfma_i32_16x16x64_i8 v[38:41], v[176:179], v[190:193], v[38:41]
	v_mfma_i32_16x16x64_i8 v[30:33], v[168:171], v[198:201], v[30:33]
	v_mfma_i32_16x16x64_i8 v[22:25], v[176:179], v[198:201], v[22:25]
	v_mfma_i32_16x16x64_i8 v[14:17], v[168:171], v[206:209], v[14:17]
	v_mfma_i32_16x16x64_i8 v[10:13], v[176:179], v[206:209], v[10:13]
	v_mfma_i32_16x16x64_i8 v[6:9], v[168:171], v[214:217], v[6:9]
	v_mfma_i32_16x16x64_i8 v[2:5], v[176:179], v[214:217], v[2:5]
	s_barrier
	s_add_u32 s30, s30, 0x100
	s_addc_u32 s31, s31, 0
	s_add_u32 s38, s38, 0x100
	s_addc_u32 s39, s39, 0
	s_cmp_ge_i32 s84, s61
	s_mov_b32 s34, s84
	s_cbranch_scc0 .LBB0_1087
	v_cvt_f32_i32_e32 v172, v126
	v_cvt_f32_i32_e32 v173, v127
	v_cvt_f32_i32_e32 v170, v128
	v_cvt_f32_i32_e32 v171, v129
	v_cvt_f32_i32_e32 v174, v122
	v_cvt_f32_i32_e32 v175, v123
	v_cvt_f32_i32_e32 v176, v124
	v_cvt_f32_i32_e32 v177, v125
	v_cvt_f32_i32_e32 v180, v110
	v_cvt_f32_i32_e32 v181, v111
	v_cvt_f32_i32_e32 v182, v112
	v_cvt_f32_i32_e32 v183, v113
	v_cvt_f32_i32_e32 v178, v102
	v_cvt_f32_i32_e32 v179, v103
	v_cvt_f32_i32_e32 v184, v104
	v_cvt_f32_i32_e32 v185, v105
	v_cvt_f32_i32_e32 v152, v118
	v_cvt_f32_i32_e32 v153, v119
	v_cvt_f32_i32_e32 v154, v120
	v_cvt_f32_i32_e32 v155, v121
	v_cvt_f32_i32_e32 v156, v114
	v_cvt_f32_i32_e32 v157, v115
	v_cvt_f32_i32_e32 v158, v116
	v_cvt_f32_i32_e32 v159, v117
	v_cvt_f32_i32_e32 v160, v94
	v_cvt_f32_i32_e32 v161, v95
	v_cvt_f32_i32_e32 v162, v96
	v_cvt_f32_i32_e32 v163, v97
	v_cvt_f32_i32_e32 v164, v86
	v_cvt_f32_i32_e32 v165, v87
	v_cvt_f32_i32_e32 v166, v88
	v_cvt_f32_i32_e32 v167, v89
	v_cvt_f32_i32_e32 v118, v106
	v_cvt_f32_i32_e32 v119, v107
	v_cvt_f32_i32_e32 v120, v108
	v_cvt_f32_i32_e32 v121, v109
	v_cvt_f32_i32_e32 v122, v98
	v_cvt_f32_i32_e32 v123, v99
	v_cvt_f32_i32_e32 v124, v100
	v_cvt_f32_i32_e32 v125, v101
	v_cvt_f32_i32_e32 v126, v78
	v_cvt_f32_i32_e32 v127, v79
	v_cvt_f32_i32_e32 v128, v80
	v_cvt_f32_i32_e32 v129, v81
	v_cvt_f32_i32_e32 v148, v74
	v_cvt_f32_i32_e32 v149, v75
	v_cvt_f32_i32_e32 v150, v76
	v_cvt_f32_i32_e32 v151, v77
	v_cvt_f32_i32_e32 v102, v90
	v_cvt_f32_i32_e32 v103, v91
	v_cvt_f32_i32_e32 v104, v92
	v_cvt_f32_i32_e32 v105, v93
	v_cvt_f32_i32_e32 v106, v82
	v_cvt_f32_i32_e32 v107, v83
	v_cvt_f32_i32_e32 v108, v84
	v_cvt_f32_i32_e32 v109, v85
	v_cvt_f32_i32_e32 v110, v70
	v_cvt_f32_i32_e32 v111, v71
	v_cvt_f32_i32_e32 v112, v72
	v_cvt_f32_i32_e32 v113, v73
	v_cvt_f32_i32_e32 v114, v66
	v_cvt_f32_i32_e32 v115, v67
	v_cvt_f32_i32_e32 v116, v68
	v_cvt_f32_i32_e32 v117, v69
	v_cvt_f32_i32_e32 v82, v62
	v_cvt_f32_i32_e32 v83, v63
	v_cvt_f32_i32_e32 v84, v64
	v_cvt_f32_i32_e32 v85, v65
	v_cvt_f32_i32_e32 v86, v58
	v_cvt_f32_i32_e32 v87, v59
	v_cvt_f32_i32_e32 v88, v60
	v_cvt_f32_i32_e32 v89, v61
	v_cvt_f32_i32_e32 v92, v46
	v_cvt_f32_i32_e32 v93, v47
	v_cvt_f32_i32_e32 v94, v48
	v_cvt_f32_i32_e32 v95, v49
	v_cvt_f32_i32_e32 v96, v38
	v_cvt_f32_i32_e32 v97, v39
	v_cvt_f32_i32_e32 v98, v40
	v_cvt_f32_i32_e32 v99, v41
	v_cvt_f32_i32_e32 v66, v54
	v_cvt_f32_i32_e32 v67, v55
	v_cvt_f32_i32_e32 v68, v56
	v_cvt_f32_i32_e32 v69, v57
	v_cvt_f32_i32_e32 v70, v50
	v_cvt_f32_i32_e32 v71, v51
	v_cvt_f32_i32_e32 v72, v52
	v_cvt_f32_i32_e32 v73, v53
	v_cvt_f32_i32_e32 v74, v30
	v_cvt_f32_i32_e32 v75, v31
	v_cvt_f32_i32_e32 v76, v32
	v_cvt_f32_i32_e32 v77, v33
	v_cvt_f32_i32_e32 v78, v22
	v_cvt_f32_i32_e32 v79, v23
	v_cvt_f32_i32_e32 v80, v24
	v_cvt_f32_i32_e32 v81, v25
	v_cvt_f32_i32_e32 v50, v42
	v_cvt_f32_i32_e32 v51, v43
	v_cvt_f32_i32_e32 v52, v44
	v_cvt_f32_i32_e32 v53, v45
	v_cvt_f32_i32_e32 v54, v34
	v_cvt_f32_i32_e32 v55, v35
	v_cvt_f32_i32_e32 v56, v36
	v_cvt_f32_i32_e32 v57, v37
	v_cvt_f32_i32_e32 v58, v14
	v_cvt_f32_i32_e32 v59, v15
	v_cvt_f32_i32_e32 v60, v16
	v_cvt_f32_i32_e32 v61, v17
	v_cvt_f32_i32_e32 v62, v10
	v_cvt_f32_i32_e32 v63, v11
	v_cvt_f32_i32_e32 v64, v12
	v_cvt_f32_i32_e32 v65, v13
	v_cvt_f32_i32_e32 v34, v26
	v_cvt_f32_i32_e32 v35, v27
	v_cvt_f32_i32_e32 v36, v28
	v_cvt_f32_i32_e32 v37, v29
	v_cvt_f32_i32_e32 v38, v18
	v_cvt_f32_i32_e32 v39, v19
	v_cvt_f32_i32_e32 v40, v20
	v_cvt_f32_i32_e32 v41, v21
	v_cvt_f32_i32_e32 v42, v6
	v_cvt_f32_i32_e32 v43, v7
	v_cvt_f32_i32_e32 v44, v8
	v_cvt_f32_i32_e32 v45, v9
	v_cvt_f32_i32_e32 v46, v2
	v_cvt_f32_i32_e32 v47, v3
	v_cvt_f32_i32_e32 v48, v4
	v_cvt_f32_i32_e32 v49, v5

.LBB0_1170:
	s_waitcnt lgkmcnt(0)
	ds_read_b128 v[114:117], v209
	ds_read_b128 v[118:121], v209 offset:1024
	ds_read_b128 v[122:125], v209 offset:2048
	ds_read_b128 v[126:129], v209 offset:3072
	ds_read_b128 v[146:149], v210
	ds_read_b128 v[150:153], v210 offset:1024
	ds_read_b128 v[154:157], v210 offset:2048
	ds_read_b128 v[158:161], v210 offset:3072
	s_add_i32 s92, s42, 2
	s_add_u32 s43, s38, 0x4000
	s_addc_u32 s44, s39, 0
	s_cmp_eq_u32 s81, s42
	s_cselect_b32 s45, s5, s44
	s_cselect_b32 s44, s4, s43
	s_cselect_b32 s94, s36, s90
	s_cselect_b32 s95, s37, s91
	s_add_u32 s42, s44, 0x8000
	s_addc_u32 s43, s45, 0
	v_lshl_add_u64 v[218:219], s[38:39], 0, v[170:171]
	s_add_i32 m0, s55, 0xc000
	ds_read_b128 v[178:181], v211
	ds_read_b128 v[182:185], v211 offset:1024
	ds_read_b128 v[186:189], v211 offset:2048
	ds_read_b128 v[190:193], v211 offset:3072
	ds_read_b128 v[194:197], v211 offset:4096
	ds_read_b128 v[198:201], v211 offset:5120
	ds_read_b128 v[202:205], v211 offset:6144
	ds_read_b128 v[214:217], v211 offset:7168
	global_load_lds_dwordx4 v[218:219], off
	v_lshl_add_u64 v[218:219], s[38:39], 0, v[172:173]
	s_add_i32 m0, s55, 0xe000
	s_nop 0
	global_load_lds_dwordx4 v[218:219], off
	s_waitcnt vmcnt(8)
	s_waitcnt lgkmcnt(0)
	s_waitcnt lgkmcnt(0)
	v_mfma_f32_16x16x32_bf16 v[142:145], v[114:117], v[178:181], v[142:145]
	v_mfma_f32_16x16x32_bf16 v[138:141], v[122:125], v[178:181], v[138:141]
	s_barrier
	v_mfma_f32_16x16x32_bf16 v[110:113], v[114:117], v[186:189], v[110:113]
	v_mfma_f32_16x16x32_bf16 v[106:109], v[122:125], v[186:189], v[106:109]
	v_mfma_f32_16x16x32_bf16 v[94:97], v[114:117], v[194:197], v[94:97]
	v_mfma_f32_16x16x32_bf16 v[90:93], v[122:125], v[194:197], v[90:93]
	v_mfma_f32_16x16x32_bf16 v[78:81], v[114:117], v[202:205], v[78:81]
	v_mfma_f32_16x16x32_bf16 v[74:77], v[122:125], v[202:205], v[74:77]
	v_mfma_f32_16x16x32_bf16 v[142:145], v[118:121], v[182:185], v[142:145]
	v_mfma_f32_16x16x32_bf16 v[138:141], v[126:129], v[182:185], v[138:141]
	v_mfma_f32_16x16x32_bf16 v[110:113], v[118:121], v[190:193], v[110:113]
	v_mfma_f32_16x16x32_bf16 v[106:109], v[126:129], v[190:193], v[106:109]
	v_mfma_f32_16x16x32_bf16 v[94:97], v[118:121], v[198:201], v[94:97]
	v_mfma_f32_16x16x32_bf16 v[90:93], v[126:129], v[198:201], v[90:93]
	v_mfma_f32_16x16x32_bf16 v[78:81], v[118:121], v[214:217], v[78:81]
	v_mfma_f32_16x16x32_bf16 v[74:77], v[126:129], v[214:217], v[74:77]
	v_mfma_f32_16x16x32_bf16 v[134:137], v[146:149], v[178:181], v[134:137]
	v_mfma_f32_16x16x32_bf16 v[130:133], v[154:157], v[178:181], v[130:133]
	v_mfma_f32_16x16x32_bf16 v[102:105], v[146:149], v[186:189], v[102:105]
	v_mfma_f32_16x16x32_bf16 v[98:101], v[154:157], v[186:189], v[98:101]
	v_mfma_f32_16x16x32_bf16 v[86:89], v[146:149], v[194:197], v[86:89]
	v_mfma_f32_16x16x32_bf16 v[82:85], v[154:157], v[194:197], v[82:85]
	v_mfma_f32_16x16x32_bf16 v[70:73], v[146:149], v[202:205], v[70:73]
	v_mfma_f32_16x16x32_bf16 v[66:69], v[154:157], v[202:205], v[66:69]
	v_mfma_f32_16x16x32_bf16 v[134:137], v[150:153], v[182:185], v[134:137]
	v_mfma_f32_16x16x32_bf16 v[130:133], v[158:161], v[182:185], v[130:133]
	v_mfma_f32_16x16x32_bf16 v[102:105], v[150:153], v[190:193], v[102:105]
	v_mfma_f32_16x16x32_bf16 v[98:101], v[158:161], v[190:193], v[98:101]
	v_mfma_f32_16x16x32_bf16 v[86:89], v[150:153], v[198:201], v[86:89]
	v_mfma_f32_16x16x32_bf16 v[82:85], v[158:161], v[198:201], v[82:85]
	v_mfma_f32_16x16x32_bf16 v[70:73], v[150:153], v[214:217], v[70:73]
	v_mfma_f32_16x16x32_bf16 v[66:69], v[158:161], v[214:217], v[66:69]
	s_barrier
	s_add_i32 s93, s84, s54
	v_lshl_add_u64 v[218:219], s[94:95], 0, v[164:165]
	s_mov_b32 m0, s93
	ds_read_b128 v[178:181], v211 offset:16384
	ds_read_b128 v[182:185], v211 offset:17408
	ds_read_b128 v[186:189], v211 offset:18432
	ds_read_b128 v[190:193], v211 offset:19456
	ds_read_b128 v[194:197], v211 offset:20480
	ds_read_b128 v[198:201], v211 offset:21504
	ds_read_b128 v[202:205], v211 offset:22528
	ds_read_b128 v[214:217], v211 offset:23552
	global_load_lds_dwordx4 v[218:219], off
	s_add_i32 m0, s93, 0x2000
	v_lshl_add_u64 v[220:221], s[94:95], 0, v[168:169]
	s_add_u32 s94, s94, s8
	s_addc_u32 s95, s95, s9
	s_add_i32 s93, s85, s54
	global_load_lds_dwordx4 v[220:221], off
	v_lshl_add_u64 v[222:223], s[94:95], 0, v[164:165]
	s_mov_b32 m0, s93
	v_lshl_add_u64 v[224:225], s[94:95], 0, v[168:169]
	global_load_lds_dwordx4 v[222:223], off
	s_add_i32 m0, s93, 0x2000
	v_lshl_add_u64 v[226:227], s[44:45], 0, v[162:163]
	global_load_lds_dwordx4 v[224:225], off
	s_mov_b32 m0, s55
	s_nop 0
	global_load_lds_dwordx4 v[226:227], off
	v_lshl_add_u64 v[226:227], s[44:45], 0, v[166:167]
	s_mov_b32 m0, s56
	s_nop 0
	global_load_lds_dwordx4 v[226:227], off
	s_waitcnt vmcnt(8)
	s_waitcnt lgkmcnt(0)
	s_waitcnt lgkmcnt(0)
	v_mfma_f32_16x16x32_bf16 v[62:65], v[114:117], v[178:181], v[62:65]
	v_mfma_f32_16x16x32_bf16 v[58:61], v[122:125], v[178:181], v[58:61]
	s_barrier
	v_mfma_f32_16x16x32_bf16 v[46:49], v[114:117], v[186:189], v[46:49]
	v_mfma_f32_16x16x32_bf16 v[42:45], v[122:125], v[186:189], v[42:45]
	v_mfma_f32_16x16x32_bf16 v[30:33], v[114:117], v[194:197], v[30:33]
	v_mfma_f32_16x16x32_bf16 v[26:29], v[122:125], v[194:197], v[26:29]
	v_mfma_f32_16x16x32_bf16 v[14:17], v[114:117], v[202:205], v[14:17]
	v_mfma_f32_16x16x32_bf16 v[10:13], v[122:125], v[202:205], v[10:13]
	v_mfma_f32_16x16x32_bf16 v[62:65], v[118:121], v[182:185], v[62:65]
	v_mfma_f32_16x16x32_bf16 v[58:61], v[126:129], v[182:185], v[58:61]
	v_mfma_f32_16x16x32_bf16 v[46:49], v[118:121], v[190:193], v[46:49]
	v_mfma_f32_16x16x32_bf16 v[42:45], v[126:129], v[190:193], v[42:45]
	v_mfma_f32_16x16x32_bf16 v[30:33], v[118:121], v[198:201], v[30:33]
	v_mfma_f32_16x16x32_bf16 v[26:29], v[126:129], v[198:201], v[26:29]
	v_mfma_f32_16x16x32_bf16 v[14:17], v[118:121], v[214:217], v[14:17]
	v_mfma_f32_16x16x32_bf16 v[10:13], v[126:129], v[214:217], v[10:13]
	v_mfma_f32_16x16x32_bf16 v[54:57], v[146:149], v[178:181], v[54:57]
	v_mfma_f32_16x16x32_bf16 v[50:53], v[154:157], v[178:181], v[50:53]
	v_mfma_f32_16x16x32_bf16 v[38:41], v[146:149], v[186:189], v[38:41]
	v_mfma_f32_16x16x32_bf16 v[34:37], v[154:157], v[186:189], v[34:37]
	v_mfma_f32_16x16x32_bf16 v[22:25], v[146:149], v[194:197], v[22:25]
	v_mfma_f32_16x16x32_bf16 v[18:21], v[154:157], v[194:197], v[18:21]
	v_mfma_f32_16x16x32_bf16 v[6:9], v[146:149], v[202:205], v[6:9]
	v_mfma_f32_16x16x32_bf16 v[2:5], v[154:157], v[202:205], v[2:5]
	v_mfma_f32_16x16x32_bf16 v[54:57], v[150:153], v[182:185], v[54:57]
	v_mfma_f32_16x16x32_bf16 v[50:53], v[158:161], v[182:185], v[50:53]
	v_mfma_f32_16x16x32_bf16 v[38:41], v[150:153], v[190:193], v[38:41]
	v_mfma_f32_16x16x32_bf16 v[34:37], v[158:161], v[190:193], v[34:37]
	v_mfma_f32_16x16x32_bf16 v[22:25], v[150:153], v[198:201], v[22:25]
	v_mfma_f32_16x16x32_bf16 v[18:21], v[158:161], v[198:201], v[18:21]
	v_mfma_f32_16x16x32_bf16 v[6:9], v[150:153], v[214:217], v[6:9]
	v_mfma_f32_16x16x32_bf16 v[2:5], v[158:161], v[214:217], v[2:5]
	s_barrier
	s_add_i32 s93, 0, 0x18000
	s_add_i32 s94, 0, 0x1c000
	v_add_u32_e32 v126, s93, v207
	v_add_u32_e32 v158, s94, v207
	ds_read_b128 v[114:117], v126
	ds_read_b128 v[118:121], v126 offset:1024
	ds_read_b128 v[122:125], v126 offset:2048
	ds_read_b128 v[126:129], v126 offset:3072
	ds_read_b128 v[146:149], v158
	ds_read_b128 v[150:153], v158 offset:1024
	ds_read_b128 v[154:157], v158 offset:2048
	ds_read_b128 v[158:161], v158 offset:3072
	s_add_u32 s44, s44, 0x4000
	s_addc_u32 s45, s45, 0
	s_mov_b32 m0, s57
	v_lshl_add_u64 v[226:227], s[44:45], 0, v[162:163]
	ds_read_b128 v[178:181], v211 offset:32768
	ds_read_b128 v[182:185], v211 offset:33792
	ds_read_b128 v[186:189], v211 offset:34816
	ds_read_b128 v[190:193], v211 offset:35840
	ds_read_b128 v[194:197], v211 offset:36864
	ds_read_b128 v[198:201], v211 offset:37888
	ds_read_b128 v[202:205], v211 offset:38912
	ds_read_b128 v[214:217], v211 offset:39936
	global_load_lds_dwordx4 v[226:227], off
	v_lshl_add_u64 v[226:227], s[44:45], 0, v[166:167]
	s_mov_b32 m0, s58
	s_nop 0
	global_load_lds_dwordx4 v[226:227], off
	s_waitcnt vmcnt(8)
	s_waitcnt lgkmcnt(0)
	s_waitcnt lgkmcnt(0)
	v_mfma_f32_16x16x32_bf16 v[142:145], v[114:117], v[178:181], v[142:145]
	v_mfma_f32_16x16x32_bf16 v[138:141], v[122:125], v[178:181], v[138:141]
	s_barrier
	v_mfma_f32_16x16x32_bf16 v[110:113], v[114:117], v[186:189], v[110:113]
	v_mfma_f32_16x16x32_bf16 v[106:109], v[122:125], v[186:189], v[106:109]
	v_mfma_f32_16x16x32_bf16 v[94:97], v[114:117], v[194:197], v[94:97]
	v_mfma_f32_16x16x32_bf16 v[90:93], v[122:125], v[194:197], v[90:93]
	v_mfma_f32_16x16x32_bf16 v[78:81], v[114:117], v[202:205], v[78:81]
	v_mfma_f32_16x16x32_bf16 v[74:77], v[122:125], v[202:205], v[74:77]
	v_mfma_f32_16x16x32_bf16 v[142:145], v[118:121], v[182:185], v[142:145]
	v_mfma_f32_16x16x32_bf16 v[138:141], v[126:129], v[182:185], v[138:141]
	v_mfma_f32_16x16x32_bf16 v[110:113], v[118:121], v[190:193], v[110:113]
	v_mfma_f32_16x16x32_bf16 v[106:109], v[126:129], v[190:193], v[106:109]
	v_mfma_f32_16x16x32_bf16 v[94:97], v[118:121], v[198:201], v[94:97]
	v_mfma_f32_16x16x32_bf16 v[90:93], v[126:129], v[198:201], v[90:93]
	v_mfma_f32_16x16x32_bf16 v[78:81], v[118:121], v[214:217], v[78:81]
	v_mfma_f32_16x16x32_bf16 v[74:77], v[126:129], v[214:217], v[74:77]
	v_mfma_f32_16x16x32_bf16 v[134:137], v[146:149], v[178:181], v[134:137]
	v_mfma_f32_16x16x32_bf16 v[130:133], v[154:157], v[178:181], v[130:133]
	v_mfma_f32_16x16x32_bf16 v[102:105], v[146:149], v[186:189], v[102:105]
	v_mfma_f32_16x16x32_bf16 v[98:101], v[154:157], v[186:189], v[98:101]
	v_mfma_f32_16x16x32_bf16 v[86:89], v[146:149], v[194:197], v[86:89]
	v_mfma_f32_16x16x32_bf16 v[82:85], v[154:157], v[194:197], v[82:85]
	v_mfma_f32_16x16x32_bf16 v[70:73], v[146:149], v[202:205], v[70:73]
	v_mfma_f32_16x16x32_bf16 v[66:69], v[154:157], v[202:205], v[66:69]
	v_mfma_f32_16x16x32_bf16 v[134:137], v[150:153], v[182:185], v[134:137]
	v_mfma_f32_16x16x32_bf16 v[130:133], v[158:161], v[182:185], v[130:133]
	v_mfma_f32_16x16x32_bf16 v[102:105], v[150:153], v[190:193], v[102:105]
	v_mfma_f32_16x16x32_bf16 v[98:101], v[158:161], v[190:193], v[98:101]
	v_mfma_f32_16x16x32_bf16 v[86:89], v[150:153], v[198:201], v[86:89]
	v_mfma_f32_16x16x32_bf16 v[82:85], v[158:161], v[198:201], v[82:85]
	v_mfma_f32_16x16x32_bf16 v[70:73], v[150:153], v[214:217], v[70:73]
	v_mfma_f32_16x16x32_bf16 v[66:69], v[158:161], v[214:217], v[66:69]
	s_barrier
	s_add_i32 s44, s93, s54
	v_lshl_add_u64 v[218:219], v[218:219], 0, s[28:29]
	s_mov_b32 m0, s44
	ds_read_b128 v[178:181], v211 offset:49152
	ds_read_b128 v[182:185], v211 offset:50176
	ds_read_b128 v[186:189], v211 offset:51200
	ds_read_b128 v[190:193], v211 offset:52224
	ds_read_b128 v[194:197], v211 offset:53248
	ds_read_b128 v[198:201], v211 offset:54272
	ds_read_b128 v[202:205], v211 offset:55296
	ds_read_b128 v[214:217], v211 offset:56320
	global_load_lds_dwordx4 v[218:219], off
	v_lshl_add_u64 v[218:219], v[220:221], 0, s[28:29]
	s_add_i32 m0, s44, 0x2000
	s_add_i32 s44, s94, s54
	global_load_lds_dwordx4 v[218:219], off
	v_lshl_add_u64 v[218:219], v[222:223], 0, s[28:29]
	s_mov_b32 m0, s44
	s_nop 0
	global_load_lds_dwordx4 v[218:219], off
	v_lshl_add_u64 v[218:219], v[224:225], 0, s[28:29]
	s_add_i32 m0, s44, 0x2000
	s_nop 0
	global_load_lds_dwordx4 v[218:219], off
	v_lshl_add_u64 v[218:219], s[42:43], 0, v[162:163]
	s_mov_b32 m0, s65
	s_nop 0
	global_load_lds_dwordx4 v[218:219], off
	v_lshl_add_u64 v[218:219], s[42:43], 0, v[166:167]
	s_mov_b32 m0, s80
	s_nop 0
	global_load_lds_dwordx4 v[218:219], off
	s_waitcnt vmcnt(8)
	s_waitcnt lgkmcnt(0)
	s_waitcnt lgkmcnt(0)
	v_mfma_f32_16x16x32_bf16 v[62:65], v[114:117], v[178:181], v[62:65]
	v_mfma_f32_16x16x32_bf16 v[58:61], v[122:125], v[178:181], v[58:61]
	s_barrier
	v_mfma_f32_16x16x32_bf16 v[46:49], v[114:117], v[186:189], v[46:49]
	v_mfma_f32_16x16x32_bf16 v[42:45], v[122:125], v[186:189], v[42:45]
	v_mfma_f32_16x16x32_bf16 v[30:33], v[114:117], v[194:197], v[30:33]
	v_mfma_f32_16x16x32_bf16 v[26:29], v[122:125], v[194:197], v[26:29]
	v_mfma_f32_16x16x32_bf16 v[14:17], v[114:117], v[202:205], v[14:17]
	v_mfma_f32_16x16x32_bf16 v[10:13], v[122:125], v[202:205], v[10:13]
	v_mfma_f32_16x16x32_bf16 v[62:65], v[118:121], v[182:185], v[62:65]
	v_mfma_f32_16x16x32_bf16 v[58:61], v[126:129], v[182:185], v[58:61]
	v_mfma_f32_16x16x32_bf16 v[46:49], v[118:121], v[190:193], v[46:49]
	v_mfma_f32_16x16x32_bf16 v[42:45], v[126:129], v[190:193], v[42:45]
	v_mfma_f32_16x16x32_bf16 v[30:33], v[118:121], v[198:201], v[30:33]
	v_mfma_f32_16x16x32_bf16 v[26:29], v[126:129], v[198:201], v[26:29]
	v_mfma_f32_16x16x32_bf16 v[14:17], v[118:121], v[214:217], v[14:17]
	v_mfma_f32_16x16x32_bf16 v[10:13], v[126:129], v[214:217], v[10:13]
	v_mfma_f32_16x16x32_bf16 v[54:57], v[146:149], v[178:181], v[54:57]
	v_mfma_f32_16x16x32_bf16 v[50:53], v[154:157], v[178:181], v[50:53]
	v_mfma_f32_16x16x32_bf16 v[38:41], v[146:149], v[186:189], v[38:41]
	v_mfma_f32_16x16x32_bf16 v[34:37], v[154:157], v[186:189], v[34:37]
	v_mfma_f32_16x16x32_bf16 v[22:25], v[146:149], v[194:197], v[22:25]
	v_mfma_f32_16x16x32_bf16 v[18:21], v[154:157], v[194:197], v[18:21]
	v_mfma_f32_16x16x32_bf16 v[6:9], v[146:149], v[202:205], v[6:9]
	v_mfma_f32_16x16x32_bf16 v[2:5], v[154:157], v[202:205], v[2:5]
	v_mfma_f32_16x16x32_bf16 v[54:57], v[150:153], v[182:185], v[54:57]
	v_mfma_f32_16x16x32_bf16 v[50:53], v[158:161], v[182:185], v[50:53]
	v_mfma_f32_16x16x32_bf16 v[38:41], v[150:153], v[190:193], v[38:41]
	v_mfma_f32_16x16x32_bf16 v[34:37], v[158:161], v[190:193], v[34:37]
	v_mfma_f32_16x16x32_bf16 v[22:25], v[150:153], v[198:201], v[22:25]
	v_mfma_f32_16x16x32_bf16 v[18:21], v[158:161], v[198:201], v[18:21]
	v_mfma_f32_16x16x32_bf16 v[6:9], v[150:153], v[214:217], v[6:9]
	v_mfma_f32_16x16x32_bf16 v[2:5], v[158:161], v[214:217], v[2:5]
	s_barrier
	s_add_u32 s90, s90, 0x100
	s_addc_u32 s91, s91, 0
	s_add_u32 s38, s38, 0x10000
	s_addc_u32 s39, s39, 0
	s_cmp_ge_i32 s92, s64
	s_mov_b32 s42, s92
	s_cbranch_scc0 .LBB0_1170

.LBB0_1276:
	ds_read_b128 v[114:117], v171
	ds_read_b128 v[118:121], v171 offset:1024
	ds_read_b128 v[122:125], v171 offset:2048
	ds_read_b128 v[130:133], v171 offset:3072
	ds_read_b128 v[162:165], v172
	ds_read_b128 v[176:179], v172 offset:1024
	ds_read_b128 v[180:183], v172 offset:2048
	ds_read_b128 v[184:187], v172 offset:3072
	s_add_i32 s82, s30, 2
	s_add_u32 s83, s2, 0x80
	s_addc_u32 s31, s3, 0
	s_cmp_eq_u32 s58, s30
	s_cselect_b32 s30, s26, s83
	s_cselect_b32 s31, s27, s31
	s_cselect_b32 s85, s29, s35
	s_cselect_b32 s84, s28, s34
	v_lshl_add_u64 v[220:221], s[2:3], 0, v[154:155]
	s_add_i32 m0, s44, 0xc000
	ds_read_b128 v[188:191], v173
	ds_read_b128 v[192:195], v173 offset:1024
	ds_read_b128 v[196:199], v173 offset:2048
	ds_read_b128 v[200:203], v173 offset:3072
	ds_read_b128 v[204:207], v173 offset:4096
	ds_read_b128 v[208:211], v173 offset:5120
	ds_read_b128 v[212:215], v173 offset:6144
	ds_read_b128 v[216:219], v173 offset:7168
	global_load_lds_dwordx4 v[220:221], off
	v_lshl_add_u64 v[220:221], s[2:3], 0, v[156:157]
	s_add_i32 m0, s44, 0xe000
	s_nop 0
	global_load_lds_dwordx4 v[220:221], off
	s_waitcnt vmcnt(8)
	s_waitcnt lgkmcnt(0)
	s_waitcnt lgkmcnt(0)
	v_mfma_f32_16x16x32_bf16 v[142:145], v[114:117], v[188:191], v[142:145]
	v_mfma_f32_16x16x32_bf16 v[138:141], v[122:125], v[188:191], v[138:141]
	s_barrier
	v_mfma_f32_16x16x32_bf16 v[110:113], v[114:117], v[196:199], v[110:113]
	v_mfma_f32_16x16x32_bf16 v[106:109], v[122:125], v[196:199], v[106:109]
	v_mfma_f32_16x16x32_bf16 v[94:97], v[114:117], v[204:207], v[94:97]
	v_mfma_f32_16x16x32_bf16 v[90:93], v[122:125], v[204:207], v[90:93]
	v_mfma_f32_16x16x32_bf16 v[78:81], v[114:117], v[212:215], v[78:81]
	v_mfma_f32_16x16x32_bf16 v[74:77], v[122:125], v[212:215], v[74:77]
	v_mfma_f32_16x16x32_bf16 v[142:145], v[118:121], v[192:195], v[142:145]
	v_mfma_f32_16x16x32_bf16 v[138:141], v[130:133], v[192:195], v[138:141]
	v_mfma_f32_16x16x32_bf16 v[110:113], v[118:121], v[200:203], v[110:113]
	v_mfma_f32_16x16x32_bf16 v[106:109], v[130:133], v[200:203], v[106:109]
	v_mfma_f32_16x16x32_bf16 v[94:97], v[118:121], v[208:211], v[94:97]
	v_mfma_f32_16x16x32_bf16 v[90:93], v[130:133], v[208:211], v[90:93]
	v_mfma_f32_16x16x32_bf16 v[78:81], v[118:121], v[216:219], v[78:81]
	v_mfma_f32_16x16x32_bf16 v[74:77], v[130:133], v[216:219], v[74:77]
	v_mfma_f32_16x16x32_bf16 v[134:137], v[162:165], v[188:191], v[134:137]
	v_mfma_f32_16x16x32_bf16 v[126:129], v[180:183], v[188:191], v[126:129]
	v_mfma_f32_16x16x32_bf16 v[102:105], v[162:165], v[196:199], v[102:105]
	v_mfma_f32_16x16x32_bf16 v[98:101], v[180:183], v[196:199], v[98:101]
	v_mfma_f32_16x16x32_bf16 v[86:89], v[162:165], v[204:207], v[86:89]
	v_mfma_f32_16x16x32_bf16 v[82:85], v[180:183], v[204:207], v[82:85]
	v_mfma_f32_16x16x32_bf16 v[70:73], v[162:165], v[212:215], v[70:73]
	v_mfma_f32_16x16x32_bf16 v[66:69], v[180:183], v[212:215], v[66:69]
	v_mfma_f32_16x16x32_bf16 v[134:137], v[176:179], v[192:195], v[134:137]
	v_mfma_f32_16x16x32_bf16 v[126:129], v[184:187], v[192:195], v[126:129]
	v_mfma_f32_16x16x32_bf16 v[102:105], v[176:179], v[200:203], v[102:105]
	v_mfma_f32_16x16x32_bf16 v[98:101], v[184:187], v[200:203], v[98:101]
	v_mfma_f32_16x16x32_bf16 v[86:89], v[176:179], v[208:211], v[86:89]
	v_mfma_f32_16x16x32_bf16 v[82:85], v[184:187], v[208:211], v[82:85]
	v_mfma_f32_16x16x32_bf16 v[70:73], v[176:179], v[216:219], v[70:73]
	v_mfma_f32_16x16x32_bf16 v[66:69], v[184:187], v[216:219], v[66:69]
	s_barrier
	s_add_i32 s83, s61, s37
	v_lshl_add_u64 v[220:221], s[84:85], 0, v[148:149]
	s_mov_b32 m0, s83
	ds_read_b128 v[188:191], v173 offset:16384
	ds_read_b128 v[192:195], v173 offset:17408
	ds_read_b128 v[196:199], v173 offset:18432
	ds_read_b128 v[200:203], v173 offset:19456
	ds_read_b128 v[204:207], v173 offset:20480
	ds_read_b128 v[208:211], v173 offset:21504
	ds_read_b128 v[212:215], v173 offset:22528
	ds_read_b128 v[216:219], v173 offset:23552
	global_load_lds_dwordx4 v[220:221], off
	s_add_i32 m0, s83, 0x2000
	v_lshl_add_u64 v[222:223], s[84:85], 0, v[152:153]
	s_add_u32 s84, s84, s6
	s_addc_u32 s85, s85, s7
	s_add_i32 s83, s62, s37
	global_load_lds_dwordx4 v[222:223], off
	v_lshl_add_u64 v[224:225], s[84:85], 0, v[148:149]
	s_mov_b32 m0, s83
	v_lshl_add_u64 v[226:227], s[84:85], 0, v[152:153]
	global_load_lds_dwordx4 v[224:225], off
	s_add_i32 m0, s83, 0x2000
	v_lshl_add_u64 v[228:229], s[30:31], 0, v[146:147]
	global_load_lds_dwordx4 v[226:227], off
	s_mov_b32 m0, s44
	v_lshl_add_u64 v[230:231], s[30:31], 0, v[150:151]
	global_load_lds_dwordx4 v[228:229], off
	s_mov_b32 m0, s45
	s_nop 0
	global_load_lds_dwordx4 v[230:231], off
	s_waitcnt vmcnt(8)
	s_waitcnt lgkmcnt(0)
	s_waitcnt lgkmcnt(0)
	v_mfma_f32_16x16x32_bf16 v[62:65], v[114:117], v[188:191], v[62:65]
	v_mfma_f32_16x16x32_bf16 v[58:61], v[122:125], v[188:191], v[58:61]
	s_barrier
	v_mfma_f32_16x16x32_bf16 v[46:49], v[114:117], v[196:199], v[46:49]
	v_mfma_f32_16x16x32_bf16 v[42:45], v[122:125], v[196:199], v[42:45]
	v_mfma_f32_16x16x32_bf16 v[30:33], v[114:117], v[204:207], v[30:33]
	v_mfma_f32_16x16x32_bf16 v[26:29], v[122:125], v[204:207], v[26:29]
	v_mfma_f32_16x16x32_bf16 v[14:17], v[114:117], v[212:215], v[14:17]
	v_mfma_f32_16x16x32_bf16 v[10:13], v[122:125], v[212:215], v[10:13]
	v_mfma_f32_16x16x32_bf16 v[62:65], v[118:121], v[192:195], v[62:65]
	v_mfma_f32_16x16x32_bf16 v[58:61], v[130:133], v[192:195], v[58:61]
	v_mfma_f32_16x16x32_bf16 v[46:49], v[118:121], v[200:203], v[46:49]
	v_mfma_f32_16x16x32_bf16 v[42:45], v[130:133], v[200:203], v[42:45]
	v_mfma_f32_16x16x32_bf16 v[30:33], v[118:121], v[208:211], v[30:33]
	v_mfma_f32_16x16x32_bf16 v[26:29], v[130:133], v[208:211], v[26:29]
	v_mfma_f32_16x16x32_bf16 v[14:17], v[118:121], v[216:219], v[14:17]
	v_mfma_f32_16x16x32_bf16 v[10:13], v[130:133], v[216:219], v[10:13]
	v_mfma_f32_16x16x32_bf16 v[54:57], v[162:165], v[188:191], v[54:57]
	v_mfma_f32_16x16x32_bf16 v[50:53], v[180:183], v[188:191], v[50:53]
	v_mfma_f32_16x16x32_bf16 v[38:41], v[162:165], v[196:199], v[38:41]
	v_mfma_f32_16x16x32_bf16 v[34:37], v[180:183], v[196:199], v[34:37]
	v_mfma_f32_16x16x32_bf16 v[22:25], v[162:165], v[204:207], v[22:25]
	v_mfma_f32_16x16x32_bf16 v[18:21], v[180:183], v[204:207], v[18:21]
	v_mfma_f32_16x16x32_bf16 v[6:9], v[162:165], v[212:215], v[6:9]
	v_mfma_f32_16x16x32_bf16 v[2:5], v[180:183], v[212:215], v[2:5]
	v_mfma_f32_16x16x32_bf16 v[54:57], v[176:179], v[192:195], v[54:57]
	v_mfma_f32_16x16x32_bf16 v[50:53], v[184:187], v[192:195], v[50:53]
	v_mfma_f32_16x16x32_bf16 v[38:41], v[176:179], v[200:203], v[38:41]
	v_mfma_f32_16x16x32_bf16 v[34:37], v[184:187], v[200:203], v[34:37]
	v_mfma_f32_16x16x32_bf16 v[22:25], v[176:179], v[208:211], v[22:25]
	v_mfma_f32_16x16x32_bf16 v[18:21], v[184:187], v[208:211], v[18:21]
	v_mfma_f32_16x16x32_bf16 v[6:9], v[176:179], v[216:219], v[6:9]
	v_mfma_f32_16x16x32_bf16 v[2:5], v[184:187], v[216:219], v[2:5]
	s_barrier
	s_add_i32 s83, 0, 0x18000
	s_add_i32 s84, 0, 0x1c000
	v_add_u32_e32 v130, s83, v168
	v_add_u32_e32 v166, s84, v168
	ds_read_b128 v[114:117], v130
	ds_read_b128 v[118:121], v130 offset:1024
	ds_read_b128 v[122:125], v130 offset:2048
	ds_read_b128 v[130:133], v130 offset:3072
	ds_read_b128 v[162:165], v166
	ds_read_b128 v[176:179], v166 offset:1024
	ds_read_b128 v[180:183], v166 offset:2048
	ds_read_b128 v[184:187], v166 offset:3072
	s_add_u32 s30, s30, s6
	s_addc_u32 s31, s31, s7
	s_mov_b32 m0, s46
	v_lshl_add_u64 v[232:233], s[30:31], 0, v[146:147]
	ds_read_b128 v[188:191], v173 offset:32768
	ds_read_b128 v[192:195], v173 offset:33792
	ds_read_b128 v[196:199], v173 offset:34816
	ds_read_b128 v[200:203], v173 offset:35840
	ds_read_b128 v[204:207], v173 offset:36864
	ds_read_b128 v[208:211], v173 offset:37888
	ds_read_b128 v[212:215], v173 offset:38912
	ds_read_b128 v[216:219], v173 offset:39936
	global_load_lds_dwordx4 v[232:233], off
	v_lshl_add_u64 v[232:233], s[30:31], 0, v[150:151]
	s_mov_b32 m0, s47
	s_nop 0
	global_load_lds_dwordx4 v[232:233], off
	s_waitcnt vmcnt(8)
	s_waitcnt lgkmcnt(0)
	s_waitcnt lgkmcnt(0)
	v_mfma_f32_16x16x32_bf16 v[142:145], v[114:117], v[188:191], v[142:145]
	v_mfma_f32_16x16x32_bf16 v[138:141], v[122:125], v[188:191], v[138:141]
	s_barrier
	v_mfma_f32_16x16x32_bf16 v[110:113], v[114:117], v[196:199], v[110:113]
	v_mfma_f32_16x16x32_bf16 v[106:109], v[122:125], v[196:199], v[106:109]
	v_mfma_f32_16x16x32_bf16 v[94:97], v[114:117], v[204:207], v[94:97]
	v_mfma_f32_16x16x32_bf16 v[90:93], v[122:125], v[204:207], v[90:93]
	v_mfma_f32_16x16x32_bf16 v[78:81], v[114:117], v[212:215], v[78:81]
	v_mfma_f32_16x16x32_bf16 v[74:77], v[122:125], v[212:215], v[74:77]
	v_mfma_f32_16x16x32_bf16 v[142:145], v[118:121], v[192:195], v[142:145]
	v_mfma_f32_16x16x32_bf16 v[138:141], v[130:133], v[192:195], v[138:141]
	v_mfma_f32_16x16x32_bf16 v[110:113], v[118:121], v[200:203], v[110:113]
	v_mfma_f32_16x16x32_bf16 v[106:109], v[130:133], v[200:203], v[106:109]
	v_mfma_f32_16x16x32_bf16 v[94:97], v[118:121], v[208:211], v[94:97]
	v_mfma_f32_16x16x32_bf16 v[90:93], v[130:133], v[208:211], v[90:93]
	v_mfma_f32_16x16x32_bf16 v[78:81], v[118:121], v[216:219], v[78:81]
	v_mfma_f32_16x16x32_bf16 v[74:77], v[130:133], v[216:219], v[74:77]
	v_mfma_f32_16x16x32_bf16 v[134:137], v[162:165], v[188:191], v[134:137]
	v_mfma_f32_16x16x32_bf16 v[126:129], v[180:183], v[188:191], v[126:129]
	v_mfma_f32_16x16x32_bf16 v[102:105], v[162:165], v[196:199], v[102:105]
	v_mfma_f32_16x16x32_bf16 v[98:101], v[180:183], v[196:199], v[98:101]
	v_mfma_f32_16x16x32_bf16 v[86:89], v[162:165], v[204:207], v[86:89]
	v_mfma_f32_16x16x32_bf16 v[82:85], v[180:183], v[204:207], v[82:85]
	v_mfma_f32_16x16x32_bf16 v[70:73], v[162:165], v[212:215], v[70:73]
	v_mfma_f32_16x16x32_bf16 v[66:69], v[180:183], v[212:215], v[66:69]
	v_mfma_f32_16x16x32_bf16 v[134:137], v[176:179], v[192:195], v[134:137]
	v_mfma_f32_16x16x32_bf16 v[126:129], v[184:187], v[192:195], v[126:129]
	v_mfma_f32_16x16x32_bf16 v[102:105], v[176:179], v[200:203], v[102:105]
	v_mfma_f32_16x16x32_bf16 v[98:101], v[184:187], v[200:203], v[98:101]
	v_mfma_f32_16x16x32_bf16 v[86:89], v[176:179], v[208:211], v[86:89]
	v_mfma_f32_16x16x32_bf16 v[82:85], v[184:187], v[208:211], v[82:85]
	v_mfma_f32_16x16x32_bf16 v[70:73], v[176:179], v[216:219], v[70:73]
	v_mfma_f32_16x16x32_bf16 v[66:69], v[184:187], v[216:219], v[66:69]
	s_barrier
	s_add_i32 s30, s83, s37
	v_lshl_add_u64 v[220:221], v[220:221], 0, s[20:21]
	s_mov_b32 m0, s30
	ds_read_b128 v[188:191], v173 offset:49152
	ds_read_b128 v[192:195], v173 offset:50176
	ds_read_b128 v[196:199], v173 offset:51200
	ds_read_b128 v[200:203], v173 offset:52224
	ds_read_b128 v[204:207], v173 offset:53248
	ds_read_b128 v[208:211], v173 offset:54272
	ds_read_b128 v[212:215], v173 offset:55296
	ds_read_b128 v[216:219], v173 offset:56320
	global_load_lds_dwordx4 v[220:221], off
	v_lshl_add_u64 v[220:221], v[222:223], 0, s[20:21]
	s_add_i32 m0, s30, 0x2000
	s_add_i32 s30, s84, s37
	global_load_lds_dwordx4 v[220:221], off
	v_lshl_add_u64 v[220:221], v[224:225], 0, s[20:21]
	s_mov_b32 m0, s30
	s_nop 0
	global_load_lds_dwordx4 v[220:221], off
	v_lshl_add_u64 v[220:221], v[226:227], 0, s[20:21]
	s_add_i32 m0, s30, 0x2000
	s_nop 0
	global_load_lds_dwordx4 v[220:221], off
	v_lshl_add_u64 v[220:221], v[228:229], 0, s[20:21]
	s_mov_b32 m0, s55
	s_nop 0
	global_load_lds_dwordx4 v[220:221], off
	v_lshl_add_u64 v[220:221], v[230:231], 0, s[20:21]
	s_mov_b32 m0, s56
	s_nop 0
	global_load_lds_dwordx4 v[220:221], off
	s_waitcnt vmcnt(8)
	s_waitcnt lgkmcnt(0)
	s_waitcnt lgkmcnt(0)
	v_mfma_f32_16x16x32_bf16 v[62:65], v[114:117], v[188:191], v[62:65]
	v_mfma_f32_16x16x32_bf16 v[58:61], v[122:125], v[188:191], v[58:61]
	s_barrier
	v_mfma_f32_16x16x32_bf16 v[46:49], v[114:117], v[196:199], v[46:49]
	v_mfma_f32_16x16x32_bf16 v[42:45], v[122:125], v[196:199], v[42:45]
	v_mfma_f32_16x16x32_bf16 v[30:33], v[114:117], v[204:207], v[30:33]
	v_mfma_f32_16x16x32_bf16 v[26:29], v[122:125], v[204:207], v[26:29]
	v_mfma_f32_16x16x32_bf16 v[14:17], v[114:117], v[212:215], v[14:17]
	v_mfma_f32_16x16x32_bf16 v[10:13], v[122:125], v[212:215], v[10:13]
	v_mfma_f32_16x16x32_bf16 v[62:65], v[118:121], v[192:195], v[62:65]
	v_mfma_f32_16x16x32_bf16 v[58:61], v[130:133], v[192:195], v[58:61]
	v_mfma_f32_16x16x32_bf16 v[46:49], v[118:121], v[200:203], v[46:49]
	v_mfma_f32_16x16x32_bf16 v[42:45], v[130:133], v[200:203], v[42:45]
	v_mfma_f32_16x16x32_bf16 v[30:33], v[118:121], v[208:211], v[30:33]
	v_mfma_f32_16x16x32_bf16 v[26:29], v[130:133], v[208:211], v[26:29]
	v_mfma_f32_16x16x32_bf16 v[14:17], v[118:121], v[216:219], v[14:17]
	v_mfma_f32_16x16x32_bf16 v[10:13], v[130:133], v[216:219], v[10:13]
	v_mfma_f32_16x16x32_bf16 v[54:57], v[162:165], v[188:191], v[54:57]
	v_mfma_f32_16x16x32_bf16 v[50:53], v[180:183], v[188:191], v[50:53]
	v_mfma_f32_16x16x32_bf16 v[38:41], v[162:165], v[196:199], v[38:41]
	v_mfma_f32_16x16x32_bf16 v[34:37], v[180:183], v[196:199], v[34:37]
	v_mfma_f32_16x16x32_bf16 v[22:25], v[162:165], v[204:207], v[22:25]
	v_mfma_f32_16x16x32_bf16 v[18:21], v[180:183], v[204:207], v[18:21]
	v_mfma_f32_16x16x32_bf16 v[6:9], v[162:165], v[212:215], v[6:9]
	v_mfma_f32_16x16x32_bf16 v[2:5], v[180:183], v[212:215], v[2:5]
	v_mfma_f32_16x16x32_bf16 v[54:57], v[176:179], v[192:195], v[54:57]
	v_mfma_f32_16x16x32_bf16 v[50:53], v[184:187], v[192:195], v[50:53]
	v_mfma_f32_16x16x32_bf16 v[38:41], v[176:179], v[200:203], v[38:41]
	v_mfma_f32_16x16x32_bf16 v[34:37], v[184:187], v[200:203], v[34:37]
	v_mfma_f32_16x16x32_bf16 v[22:25], v[176:179], v[208:211], v[22:25]
	v_mfma_f32_16x16x32_bf16 v[18:21], v[184:187], v[208:211], v[18:21]
	v_mfma_f32_16x16x32_bf16 v[6:9], v[176:179], v[216:219], v[6:9]
	v_mfma_f32_16x16x32_bf16 v[2:5], v[184:187], v[216:219], v[2:5]
	s_barrier
	s_add_u32 s2, s2, 0x100
	s_addc_u32 s3, s3, 0
	s_add_u32 s34, s34, 0x100
	s_addc_u32 s35, s35, 0
	s_cmp_ge_i32 s82, s57
	s_mov_b32 s30, s82
	s_cbranch_scc0 .LBB0_1276

.LBB0_1461:
	ds_read_b128 v[148:151], v168
	ds_read_b128 v[172:175], v168 offset:1024
	ds_read_b128 v[176:179], v168 offset:2048
	ds_read_b128 v[180:183], v168 offset:3072
	ds_read_b128 v[184:187], v169
	ds_read_b128 v[188:191], v169 offset:1024
	ds_read_b128 v[192:195], v169 offset:2048
	ds_read_b128 v[196:199], v169 offset:3072
	s_add_i32 s67, s26, 2
	s_add_u32 s68, s24, 0x80
	s_addc_u32 s27, s25, 0
	s_cmp_eq_u32 s50, s26
	s_cselect_b32 s26, s2, s68
	s_cselect_b32 s27, s3, s27
	s_cselect_b32 s69, s23, s66
	s_cselect_b32 s68, s22, s65
	v_lshl_add_u64 v[232:233], s[24:25], 0, v[140:141]
	s_add_i32 m0, s37, 0xc000
	ds_read_b128 v[200:203], v170
	ds_read_b128 v[204:207], v170 offset:1024
	ds_read_b128 v[208:211], v170 offset:2048
	ds_read_b128 v[212:215], v170 offset:3072
	ds_read_b128 v[216:219], v170 offset:4096
	ds_read_b128 v[220:223], v170 offset:5120
	ds_read_b128 v[224:227], v170 offset:6144
	ds_read_b128 v[228:231], v170 offset:7168
	global_load_lds_dwordx4 v[232:233], off
	v_lshl_add_u64 v[232:233], s[24:25], 0, v[142:143]
	s_add_i32 m0, s37, 0xe000
	s_nop 0
	global_load_lds_dwordx4 v[232:233], off
	s_waitcnt vmcnt(8)
	s_waitcnt lgkmcnt(0)
	s_waitcnt lgkmcnt(0)
	v_mfma_f32_16x16x32_bf16 v[128:131], v[148:151], v[200:203], v[128:131]
	v_mfma_f32_16x16x32_bf16 v[124:127], v[176:179], v[200:203], v[124:127]
	s_barrier
	v_mfma_f32_16x16x32_bf16 v[120:123], v[148:151], v[208:211], v[120:123]
	v_mfma_f32_16x16x32_bf16 v[116:119], v[176:179], v[208:211], v[116:119]
	v_mfma_f32_16x16x32_bf16 v[112:115], v[148:151], v[216:219], v[112:115]
	v_mfma_f32_16x16x32_bf16 v[108:111], v[176:179], v[216:219], v[108:111]
	v_mfma_f32_16x16x32_bf16 v[104:107], v[148:151], v[224:227], v[104:107]
	v_mfma_f32_16x16x32_bf16 v[100:103], v[176:179], v[224:227], v[100:103]
	v_mfma_f32_16x16x32_bf16 v[128:131], v[172:175], v[204:207], v[128:131]
	v_mfma_f32_16x16x32_bf16 v[124:127], v[180:183], v[204:207], v[124:127]
	v_mfma_f32_16x16x32_bf16 v[120:123], v[172:175], v[212:215], v[120:123]
	v_mfma_f32_16x16x32_bf16 v[116:119], v[180:183], v[212:215], v[116:119]
	v_mfma_f32_16x16x32_bf16 v[112:115], v[172:175], v[220:223], v[112:115]
	v_mfma_f32_16x16x32_bf16 v[108:111], v[180:183], v[220:223], v[108:111]
	v_mfma_f32_16x16x32_bf16 v[104:107], v[172:175], v[228:231], v[104:107]
	v_mfma_f32_16x16x32_bf16 v[100:103], v[180:183], v[228:231], v[100:103]
	v_mfma_f32_16x16x32_bf16 v[64:67], v[184:187], v[200:203], v[64:67]
	v_mfma_f32_16x16x32_bf16 v[60:63], v[192:195], v[200:203], v[60:63]
	v_mfma_f32_16x16x32_bf16 v[56:59], v[184:187], v[208:211], v[56:59]
	v_mfma_f32_16x16x32_bf16 v[52:55], v[192:195], v[208:211], v[52:55]
	v_mfma_f32_16x16x32_bf16 v[48:51], v[184:187], v[216:219], v[48:51]
	v_mfma_f32_16x16x32_bf16 v[44:47], v[192:195], v[216:219], v[44:47]
	v_mfma_f32_16x16x32_bf16 v[40:43], v[184:187], v[224:227], v[40:43]
	v_mfma_f32_16x16x32_bf16 v[36:39], v[192:195], v[224:227], v[36:39]
	v_mfma_f32_16x16x32_bf16 v[64:67], v[188:191], v[204:207], v[64:67]
	v_mfma_f32_16x16x32_bf16 v[60:63], v[196:199], v[204:207], v[60:63]
	v_mfma_f32_16x16x32_bf16 v[56:59], v[188:191], v[212:215], v[56:59]
	v_mfma_f32_16x16x32_bf16 v[52:55], v[196:199], v[212:215], v[52:55]
	v_mfma_f32_16x16x32_bf16 v[48:51], v[188:191], v[220:223], v[48:51]
	v_mfma_f32_16x16x32_bf16 v[44:47], v[196:199], v[220:223], v[44:47]
	v_mfma_f32_16x16x32_bf16 v[40:43], v[188:191], v[228:231], v[40:43]
	v_mfma_f32_16x16x32_bf16 v[36:39], v[196:199], v[228:231], v[36:39]
	s_barrier
	s_add_i32 s80, s57, s36
	v_lshl_add_u64 v[232:233], s[68:69], 0, v[134:135]
	s_mov_b32 m0, s80
	ds_read_b128 v[200:203], v170 offset:16384
	ds_read_b128 v[204:207], v170 offset:17408
	ds_read_b128 v[208:211], v170 offset:18432
	ds_read_b128 v[212:215], v170 offset:19456
	ds_read_b128 v[216:219], v170 offset:20480
	ds_read_b128 v[220:223], v170 offset:21504
	ds_read_b128 v[224:227], v170 offset:22528
	ds_read_b128 v[228:231], v170 offset:23552
	global_load_lds_dwordx4 v[232:233], off
	s_add_i32 m0, s80, 0x2000
	v_lshl_add_u64 v[234:235], s[68:69], 0, v[138:139]
	s_add_u32 s68, s68, s6
	s_addc_u32 s69, s69, s7
	s_add_i32 s80, s58, s36
	global_load_lds_dwordx4 v[234:235], off
	v_lshl_add_u64 v[236:237], s[68:69], 0, v[134:135]
	s_mov_b32 m0, s80
	v_lshl_add_u64 v[238:239], s[68:69], 0, v[138:139]
	global_load_lds_dwordx4 v[236:237], off
	s_add_i32 m0, s80, 0x2000
	v_lshl_add_u64 v[240:241], s[26:27], 0, v[132:133]
	global_load_lds_dwordx4 v[238:239], off
	s_mov_b32 m0, s37
	v_lshl_add_u64 v[242:243], s[26:27], 0, v[136:137]
	global_load_lds_dwordx4 v[240:241], off
	s_mov_b32 m0, s38
	s_nop 0
	global_load_lds_dwordx4 v[242:243], off
	s_waitcnt vmcnt(8)
	s_waitcnt lgkmcnt(0)
	s_waitcnt lgkmcnt(0)
	v_mfma_f32_16x16x32_bf16 v[96:99], v[148:151], v[200:203], v[96:99]
	v_mfma_f32_16x16x32_bf16 v[92:95], v[176:179], v[200:203], v[92:95]
	s_barrier
	v_mfma_f32_16x16x32_bf16 v[88:91], v[148:151], v[208:211], v[88:91]
	v_mfma_f32_16x16x32_bf16 v[84:87], v[176:179], v[208:211], v[84:87]
	v_mfma_f32_16x16x32_bf16 v[80:83], v[148:151], v[216:219], v[80:83]
	v_mfma_f32_16x16x32_bf16 v[76:79], v[176:179], v[216:219], v[76:79]
	v_mfma_f32_16x16x32_bf16 v[72:75], v[148:151], v[224:227], v[72:75]
	v_mfma_f32_16x16x32_bf16 v[68:71], v[176:179], v[224:227], v[68:71]
	v_mfma_f32_16x16x32_bf16 v[96:99], v[172:175], v[204:207], v[96:99]
	v_mfma_f32_16x16x32_bf16 v[92:95], v[180:183], v[204:207], v[92:95]
	v_mfma_f32_16x16x32_bf16 v[88:91], v[172:175], v[212:215], v[88:91]
	v_mfma_f32_16x16x32_bf16 v[84:87], v[180:183], v[212:215], v[84:87]
	v_mfma_f32_16x16x32_bf16 v[80:83], v[172:175], v[220:223], v[80:83]
	v_mfma_f32_16x16x32_bf16 v[76:79], v[180:183], v[220:223], v[76:79]
	v_mfma_f32_16x16x32_bf16 v[72:75], v[172:175], v[228:231], v[72:75]
	v_mfma_f32_16x16x32_bf16 v[68:71], v[180:183], v[228:231], v[68:71]
	v_mfma_f32_16x16x32_bf16 v[32:35], v[184:187], v[200:203], v[32:35]
	v_mfma_f32_16x16x32_bf16 v[28:31], v[192:195], v[200:203], v[28:31]
	v_mfma_f32_16x16x32_bf16 v[24:27], v[184:187], v[208:211], v[24:27]
	v_mfma_f32_16x16x32_bf16 v[20:23], v[192:195], v[208:211], v[20:23]
	v_mfma_f32_16x16x32_bf16 v[16:19], v[184:187], v[216:219], v[16:19]
	v_mfma_f32_16x16x32_bf16 v[12:15], v[192:195], v[216:219], v[12:15]
	v_mfma_f32_16x16x32_bf16 v[8:11], v[184:187], v[224:227], v[8:11]
	v_mfma_f32_16x16x32_bf16 v[4:7], v[192:195], v[224:227], v[4:7]
	v_mfma_f32_16x16x32_bf16 v[32:35], v[188:191], v[204:207], v[32:35]
	v_mfma_f32_16x16x32_bf16 v[28:31], v[196:199], v[204:207], v[28:31]
	v_mfma_f32_16x16x32_bf16 v[24:27], v[188:191], v[212:215], v[24:27]
	v_mfma_f32_16x16x32_bf16 v[20:23], v[196:199], v[212:215], v[20:23]
	v_mfma_f32_16x16x32_bf16 v[16:19], v[188:191], v[220:223], v[16:19]
	v_mfma_f32_16x16x32_bf16 v[12:15], v[196:199], v[220:223], v[12:15]
	v_mfma_f32_16x16x32_bf16 v[8:11], v[188:191], v[228:231], v[8:11]
	v_mfma_f32_16x16x32_bf16 v[4:7], v[196:199], v[228:231], v[4:7]
	s_barrier
	s_add_i32 s68, 0, 0x18000
	v_add_u32_e32 v3, s68, v166
	s_add_i32 s69, 0, 0x1c000
	ds_read_b128 v[148:151], v3
	ds_read_b128 v[172:175], v3 offset:1024
	ds_read_b128 v[176:179], v3 offset:2048
	ds_read_b128 v[180:183], v3 offset:3072
	v_add_u32_e32 v3, s69, v166
	ds_read_b128 v[184:187], v3
	ds_read_b128 v[188:191], v3 offset:1024
	ds_read_b128 v[192:195], v3 offset:2048
	ds_read_b128 v[196:199], v3 offset:3072
	s_add_u32 s26, s26, s6
	s_addc_u32 s27, s27, s7
	s_mov_b32 m0, s39
	v_lshl_add_u64 v[244:245], s[26:27], 0, v[132:133]
	ds_read_b128 v[200:203], v170 offset:32768
	ds_read_b128 v[204:207], v170 offset:33792
	ds_read_b128 v[208:211], v170 offset:34816
	ds_read_b128 v[212:215], v170 offset:35840
	ds_read_b128 v[216:219], v170 offset:36864
	ds_read_b128 v[220:223], v170 offset:37888
	ds_read_b128 v[224:227], v170 offset:38912
	ds_read_b128 v[228:231], v170 offset:39936
	global_load_lds_dwordx4 v[244:245], off
	v_lshl_add_u64 v[244:245], s[26:27], 0, v[136:137]
	s_mov_b32 m0, s42
	s_nop 0
	global_load_lds_dwordx4 v[244:245], off
	s_waitcnt vmcnt(8)
	s_waitcnt lgkmcnt(0)
	s_waitcnt lgkmcnt(0)
	v_mfma_f32_16x16x32_bf16 v[128:131], v[148:151], v[200:203], v[128:131]
	v_mfma_f32_16x16x32_bf16 v[124:127], v[176:179], v[200:203], v[124:127]
	s_barrier
	v_mfma_f32_16x16x32_bf16 v[120:123], v[148:151], v[208:211], v[120:123]
	v_mfma_f32_16x16x32_bf16 v[116:119], v[176:179], v[208:211], v[116:119]
	v_mfma_f32_16x16x32_bf16 v[112:115], v[148:151], v[216:219], v[112:115]
	v_mfma_f32_16x16x32_bf16 v[108:111], v[176:179], v[216:219], v[108:111]
	v_mfma_f32_16x16x32_bf16 v[104:107], v[148:151], v[224:227], v[104:107]
	v_mfma_f32_16x16x32_bf16 v[100:103], v[176:179], v[224:227], v[100:103]
	v_mfma_f32_16x16x32_bf16 v[128:131], v[172:175], v[204:207], v[128:131]
	v_mfma_f32_16x16x32_bf16 v[124:127], v[180:183], v[204:207], v[124:127]
	v_mfma_f32_16x16x32_bf16 v[120:123], v[172:175], v[212:215], v[120:123]
	v_mfma_f32_16x16x32_bf16 v[116:119], v[180:183], v[212:215], v[116:119]
	v_mfma_f32_16x16x32_bf16 v[112:115], v[172:175], v[220:223], v[112:115]
	v_mfma_f32_16x16x32_bf16 v[108:111], v[180:183], v[220:223], v[108:111]
	v_mfma_f32_16x16x32_bf16 v[104:107], v[172:175], v[228:231], v[104:107]
	v_mfma_f32_16x16x32_bf16 v[100:103], v[180:183], v[228:231], v[100:103]
	v_mfma_f32_16x16x32_bf16 v[64:67], v[184:187], v[200:203], v[64:67]
	v_mfma_f32_16x16x32_bf16 v[60:63], v[192:195], v[200:203], v[60:63]
	v_mfma_f32_16x16x32_bf16 v[56:59], v[184:187], v[208:211], v[56:59]
	v_mfma_f32_16x16x32_bf16 v[52:55], v[192:195], v[208:211], v[52:55]
	v_mfma_f32_16x16x32_bf16 v[48:51], v[184:187], v[216:219], v[48:51]
	v_mfma_f32_16x16x32_bf16 v[44:47], v[192:195], v[216:219], v[44:47]
	v_mfma_f32_16x16x32_bf16 v[40:43], v[184:187], v[224:227], v[40:43]
	v_mfma_f32_16x16x32_bf16 v[36:39], v[192:195], v[224:227], v[36:39]
	v_mfma_f32_16x16x32_bf16 v[64:67], v[188:191], v[204:207], v[64:67]
	v_mfma_f32_16x16x32_bf16 v[60:63], v[196:199], v[204:207], v[60:63]
	v_mfma_f32_16x16x32_bf16 v[56:59], v[188:191], v[212:215], v[56:59]
	v_mfma_f32_16x16x32_bf16 v[52:55], v[196:199], v[212:215], v[52:55]
	v_mfma_f32_16x16x32_bf16 v[48:51], v[188:191], v[220:223], v[48:51]
	v_mfma_f32_16x16x32_bf16 v[44:47], v[196:199], v[220:223], v[44:47]
	v_mfma_f32_16x16x32_bf16 v[40:43], v[188:191], v[228:231], v[40:43]
	v_mfma_f32_16x16x32_bf16 v[36:39], v[196:199], v[228:231], v[36:39]
	s_barrier
	s_add_i32 s26, s68, s36
	v_lshl_add_u64 v[232:233], v[232:233], 0, s[16:17]
	s_mov_b32 m0, s26
	ds_read_b128 v[200:203], v170 offset:49152
	ds_read_b128 v[204:207], v170 offset:50176
	ds_read_b128 v[208:211], v170 offset:51200
	ds_read_b128 v[212:215], v170 offset:52224
	ds_read_b128 v[216:219], v170 offset:53248
	ds_read_b128 v[220:223], v170 offset:54272
	ds_read_b128 v[224:227], v170 offset:55296
	ds_read_b128 v[228:231], v170 offset:56320
	global_load_lds_dwordx4 v[232:233], off
	v_lshl_add_u64 v[232:233], v[234:235], 0, s[16:17]
	s_add_i32 m0, s26, 0x2000
	s_add_i32 s26, s69, s36
	global_load_lds_dwordx4 v[232:233], off
	v_lshl_add_u64 v[232:233], v[236:237], 0, s[16:17]
	s_mov_b32 m0, s26
	s_nop 0
	global_load_lds_dwordx4 v[232:233], off
	v_lshl_add_u64 v[232:233], v[238:239], 0, s[16:17]
	s_add_i32 m0, s26, 0x2000
	s_nop 0
	global_load_lds_dwordx4 v[232:233], off
	v_lshl_add_u64 v[232:233], v[240:241], 0, s[16:17]
	s_mov_b32 m0, s44
	s_nop 0
	global_load_lds_dwordx4 v[232:233], off
	v_lshl_add_u64 v[232:233], v[242:243], 0, s[16:17]
	s_mov_b32 m0, s45
	s_nop 0
	global_load_lds_dwordx4 v[232:233], off
	s_waitcnt vmcnt(8)
	s_waitcnt lgkmcnt(0)
	s_waitcnt lgkmcnt(0)
	v_mfma_f32_16x16x32_bf16 v[96:99], v[148:151], v[200:203], v[96:99]
	v_mfma_f32_16x16x32_bf16 v[92:95], v[176:179], v[200:203], v[92:95]
	s_barrier
	v_mfma_f32_16x16x32_bf16 v[88:91], v[148:151], v[208:211], v[88:91]
	v_mfma_f32_16x16x32_bf16 v[84:87], v[176:179], v[208:211], v[84:87]
	v_mfma_f32_16x16x32_bf16 v[80:83], v[148:151], v[216:219], v[80:83]
	v_mfma_f32_16x16x32_bf16 v[76:79], v[176:179], v[216:219], v[76:79]
	v_mfma_f32_16x16x32_bf16 v[72:75], v[148:151], v[224:227], v[72:75]
	v_mfma_f32_16x16x32_bf16 v[68:71], v[176:179], v[224:227], v[68:71]
	v_mfma_f32_16x16x32_bf16 v[96:99], v[172:175], v[204:207], v[96:99]
	v_mfma_f32_16x16x32_bf16 v[92:95], v[180:183], v[204:207], v[92:95]
	v_mfma_f32_16x16x32_bf16 v[88:91], v[172:175], v[212:215], v[88:91]
	v_mfma_f32_16x16x32_bf16 v[84:87], v[180:183], v[212:215], v[84:87]
	v_mfma_f32_16x16x32_bf16 v[80:83], v[172:175], v[220:223], v[80:83]
	v_mfma_f32_16x16x32_bf16 v[76:79], v[180:183], v[220:223], v[76:79]
	v_mfma_f32_16x16x32_bf16 v[72:75], v[172:175], v[228:231], v[72:75]
	v_mfma_f32_16x16x32_bf16 v[68:71], v[180:183], v[228:231], v[68:71]
	v_mfma_f32_16x16x32_bf16 v[32:35], v[184:187], v[200:203], v[32:35]
	v_mfma_f32_16x16x32_bf16 v[28:31], v[192:195], v[200:203], v[28:31]
	v_mfma_f32_16x16x32_bf16 v[24:27], v[184:187], v[208:211], v[24:27]
	v_mfma_f32_16x16x32_bf16 v[20:23], v[192:195], v[208:211], v[20:23]
	v_mfma_f32_16x16x32_bf16 v[16:19], v[184:187], v[216:219], v[16:19]
	v_mfma_f32_16x16x32_bf16 v[12:15], v[192:195], v[216:219], v[12:15]
	v_mfma_f32_16x16x32_bf16 v[8:11], v[184:187], v[224:227], v[8:11]
	v_mfma_f32_16x16x32_bf16 v[4:7], v[192:195], v[224:227], v[4:7]
	v_mfma_f32_16x16x32_bf16 v[32:35], v[188:191], v[204:207], v[32:35]
	v_mfma_f32_16x16x32_bf16 v[28:31], v[196:199], v[204:207], v[28:31]
	v_mfma_f32_16x16x32_bf16 v[24:27], v[188:191], v[212:215], v[24:27]
	v_mfma_f32_16x16x32_bf16 v[20:23], v[196:199], v[212:215], v[20:23]
	v_mfma_f32_16x16x32_bf16 v[16:19], v[188:191], v[220:223], v[16:19]
	v_mfma_f32_16x16x32_bf16 v[12:15], v[196:199], v[220:223], v[12:15]
	v_mfma_f32_16x16x32_bf16 v[8:11], v[188:191], v[228:231], v[8:11]
	v_mfma_f32_16x16x32_bf16 v[4:7], v[196:199], v[228:231], v[4:7]
	s_barrier
	s_add_u32 s24, s24, 0x100
	s_addc_u32 s25, s25, 0
	s_add_u32 s65, s65, 0x100
	s_addc_u32 s66, s66, 0
	s_cmp_ge_i32 s67, s46
	s_mov_b32 s26, s67
	s_cbranch_scc0 .LBB0_1461

.LBB0_1514:
	ds_read_b128 v[152:155], v149
	ds_read_b128 v[156:159], v149 offset:1024
	ds_read_b128 v[160:163], v149 offset:2048
	ds_read_b128 v[164:167], v149 offset:3072
	ds_read_b128 v[168:171], v150
	ds_read_b128 v[172:175], v150 offset:1024
	ds_read_b128 v[176:179], v150 offset:2048
	ds_read_b128 v[180:183], v150 offset:3072
	s_add_i32 s69, s36, 2
	s_add_u32 s80, s34, 0x80
	s_addc_u32 s37, s35, 0
	s_cmp_eq_u32 s59, s36
	s_cselect_b32 s36, s2, s80
	s_cselect_b32 s37, s3, s37
	s_cselect_b32 s81, s31, s68
	s_cselect_b32 s80, s30, s67
	v_lshl_add_u64 v[216:217], s[34:35], 0, v[138:139]
	s_add_i32 m0, s47, 0xc000
	ds_read_b128 v[184:187], v151
	ds_read_b128 v[188:191], v151 offset:1024
	ds_read_b128 v[192:195], v151 offset:2048
	ds_read_b128 v[196:199], v151 offset:3072
	ds_read_b128 v[200:203], v151 offset:4096
	ds_read_b128 v[204:207], v151 offset:5120
	ds_read_b128 v[208:211], v151 offset:6144
	ds_read_b128 v[212:215], v151 offset:7168
	global_load_lds_dwordx4 v[216:217], off
	v_lshl_add_u64 v[216:217], s[34:35], 0, v[140:141]
	s_add_i32 m0, s47, 0xe000
	s_nop 0
	global_load_lds_dwordx4 v[216:217], off
	s_waitcnt vmcnt(8)
	s_waitcnt lgkmcnt(0)
	s_waitcnt lgkmcnt(0)
	v_mfma_f32_16x16x32_bf16 v[122:125], v[152:155], v[184:187], v[122:125]
	v_mfma_f32_16x16x32_bf16 v[126:129], v[160:163], v[184:187], v[126:129]
	s_barrier
	v_mfma_f32_16x16x32_bf16 v[110:113], v[152:155], v[192:195], v[110:113]
	v_mfma_f32_16x16x32_bf16 v[106:109], v[160:163], v[192:195], v[106:109]
	v_mfma_f32_16x16x32_bf16 v[94:97], v[152:155], v[200:203], v[94:97]
	v_mfma_f32_16x16x32_bf16 v[90:93], v[160:163], v[200:203], v[90:93]
	v_mfma_f32_16x16x32_bf16 v[78:81], v[152:155], v[208:211], v[78:81]
	v_mfma_f32_16x16x32_bf16 v[74:77], v[160:163], v[208:211], v[74:77]
	v_mfma_f32_16x16x32_bf16 v[122:125], v[156:159], v[188:191], v[122:125]
	v_mfma_f32_16x16x32_bf16 v[126:129], v[164:167], v[188:191], v[126:129]
	v_mfma_f32_16x16x32_bf16 v[110:113], v[156:159], v[196:199], v[110:113]
	v_mfma_f32_16x16x32_bf16 v[106:109], v[164:167], v[196:199], v[106:109]
	v_mfma_f32_16x16x32_bf16 v[94:97], v[156:159], v[204:207], v[94:97]
	v_mfma_f32_16x16x32_bf16 v[90:93], v[164:167], v[204:207], v[90:93]
	v_mfma_f32_16x16x32_bf16 v[78:81], v[156:159], v[212:215], v[78:81]
	v_mfma_f32_16x16x32_bf16 v[74:77], v[164:167], v[212:215], v[74:77]
	v_mfma_f32_16x16x32_bf16 v[118:121], v[168:171], v[184:187], v[118:121]
	v_mfma_f32_16x16x32_bf16 v[114:117], v[176:179], v[184:187], v[114:117]
	v_mfma_f32_16x16x32_bf16 v[102:105], v[168:171], v[192:195], v[102:105]
	v_mfma_f32_16x16x32_bf16 v[98:101], v[176:179], v[192:195], v[98:101]
	v_mfma_f32_16x16x32_bf16 v[86:89], v[168:171], v[200:203], v[86:89]
	v_mfma_f32_16x16x32_bf16 v[82:85], v[176:179], v[200:203], v[82:85]
	v_mfma_f32_16x16x32_bf16 v[70:73], v[168:171], v[208:211], v[70:73]
	v_mfma_f32_16x16x32_bf16 v[66:69], v[176:179], v[208:211], v[66:69]
	v_mfma_f32_16x16x32_bf16 v[118:121], v[172:175], v[188:191], v[118:121]
	v_mfma_f32_16x16x32_bf16 v[114:117], v[180:183], v[188:191], v[114:117]
	v_mfma_f32_16x16x32_bf16 v[102:105], v[172:175], v[196:199], v[102:105]
	v_mfma_f32_16x16x32_bf16 v[98:101], v[180:183], v[196:199], v[98:101]
	v_mfma_f32_16x16x32_bf16 v[86:89], v[172:175], v[204:207], v[86:89]
	v_mfma_f32_16x16x32_bf16 v[82:85], v[180:183], v[204:207], v[82:85]
	v_mfma_f32_16x16x32_bf16 v[70:73], v[172:175], v[212:215], v[70:73]
	v_mfma_f32_16x16x32_bf16 v[66:69], v[180:183], v[212:215], v[66:69]
	s_barrier
	s_add_i32 s82, s61, s44
	v_lshl_add_u64 v[216:217], s[80:81], 0, v[134:135]
	s_mov_b32 m0, s82
	ds_read_b128 v[184:187], v151 offset:16384
	ds_read_b128 v[188:191], v151 offset:17408
	ds_read_b128 v[192:195], v151 offset:18432
	ds_read_b128 v[196:199], v151 offset:19456
	ds_read_b128 v[200:203], v151 offset:20480
	ds_read_b128 v[204:207], v151 offset:21504
	ds_read_b128 v[208:211], v151 offset:22528
	ds_read_b128 v[212:215], v151 offset:23552
	global_load_lds_dwordx4 v[216:217], off
	s_add_i32 m0, s82, 0x2000
	v_lshl_add_u64 v[218:219], s[80:81], 0, v[130:131]
	s_add_u32 s80, s80, s6
	s_addc_u32 s81, s81, s7
	s_add_i32 s82, s62, s44
	global_load_lds_dwordx4 v[218:219], off
	v_lshl_add_u64 v[220:221], s[80:81], 0, v[134:135]
	s_mov_b32 m0, s82
	v_lshl_add_u64 v[222:223], s[80:81], 0, v[130:131]
	global_load_lds_dwordx4 v[220:221], off
	s_add_i32 m0, s82, 0x2000
	v_lshl_add_u64 v[224:225], s[36:37], 0, v[136:137]
	global_load_lds_dwordx4 v[222:223], off
	s_mov_b32 m0, s47
	v_lshl_add_u64 v[226:227], s[36:37], 0, v[132:133]
	global_load_lds_dwordx4 v[224:225], off
	s_mov_b32 m0, s50
	s_nop 0
	global_load_lds_dwordx4 v[226:227], off
	s_waitcnt vmcnt(8)
	s_waitcnt lgkmcnt(0)
	s_waitcnt lgkmcnt(0)
	v_mfma_f32_16x16x32_bf16 v[62:65], v[152:155], v[184:187], v[62:65]
	v_mfma_f32_16x16x32_bf16 v[58:61], v[160:163], v[184:187], v[58:61]
	s_barrier
	v_mfma_f32_16x16x32_bf16 v[46:49], v[152:155], v[192:195], v[46:49]
	v_mfma_f32_16x16x32_bf16 v[42:45], v[160:163], v[192:195], v[42:45]
	v_mfma_f32_16x16x32_bf16 v[30:33], v[152:155], v[200:203], v[30:33]
	v_mfma_f32_16x16x32_bf16 v[26:29], v[160:163], v[200:203], v[26:29]
	v_mfma_f32_16x16x32_bf16 v[14:17], v[152:155], v[208:211], v[14:17]
	v_mfma_f32_16x16x32_bf16 v[10:13], v[160:163], v[208:211], v[10:13]
	v_mfma_f32_16x16x32_bf16 v[62:65], v[156:159], v[188:191], v[62:65]
	v_mfma_f32_16x16x32_bf16 v[58:61], v[164:167], v[188:191], v[58:61]
	v_mfma_f32_16x16x32_bf16 v[46:49], v[156:159], v[196:199], v[46:49]
	v_mfma_f32_16x16x32_bf16 v[42:45], v[164:167], v[196:199], v[42:45]
	v_mfma_f32_16x16x32_bf16 v[30:33], v[156:159], v[204:207], v[30:33]
	v_mfma_f32_16x16x32_bf16 v[26:29], v[164:167], v[204:207], v[26:29]
	v_mfma_f32_16x16x32_bf16 v[14:17], v[156:159], v[212:215], v[14:17]
	v_mfma_f32_16x16x32_bf16 v[10:13], v[164:167], v[212:215], v[10:13]
	v_mfma_f32_16x16x32_bf16 v[54:57], v[168:171], v[184:187], v[54:57]
	v_mfma_f32_16x16x32_bf16 v[50:53], v[176:179], v[184:187], v[50:53]
	v_mfma_f32_16x16x32_bf16 v[38:41], v[168:171], v[192:195], v[38:41]
	v_mfma_f32_16x16x32_bf16 v[34:37], v[176:179], v[192:195], v[34:37]
	v_mfma_f32_16x16x32_bf16 v[22:25], v[168:171], v[200:203], v[22:25]
	v_mfma_f32_16x16x32_bf16 v[18:21], v[176:179], v[200:203], v[18:21]
	v_mfma_f32_16x16x32_bf16 v[6:9], v[168:171], v[208:211], v[6:9]
	v_mfma_f32_16x16x32_bf16 v[2:5], v[176:179], v[208:211], v[2:5]
	v_mfma_f32_16x16x32_bf16 v[54:57], v[172:175], v[188:191], v[54:57]
	v_mfma_f32_16x16x32_bf16 v[50:53], v[180:183], v[188:191], v[50:53]
	v_mfma_f32_16x16x32_bf16 v[38:41], v[172:175], v[196:199], v[38:41]
	v_mfma_f32_16x16x32_bf16 v[34:37], v[180:183], v[196:199], v[34:37]
	v_mfma_f32_16x16x32_bf16 v[22:25], v[172:175], v[204:207], v[22:25]
	v_mfma_f32_16x16x32_bf16 v[18:21], v[180:183], v[204:207], v[18:21]
	v_mfma_f32_16x16x32_bf16 v[6:9], v[172:175], v[212:215], v[6:9]
	v_mfma_f32_16x16x32_bf16 v[2:5], v[180:183], v[212:215], v[2:5]
	s_barrier
	s_add_i32 s80, 0, 0x18000
	s_add_i32 s81, 0, 0x1c000
	v_add_u32_e32 v164, s80, v147
	v_add_u32_e32 v180, s81, v147
	ds_read_b128 v[152:155], v164
	ds_read_b128 v[156:159], v164 offset:1024
	ds_read_b128 v[160:163], v164 offset:2048
	ds_read_b128 v[164:167], v164 offset:3072
	ds_read_b128 v[168:171], v180
	ds_read_b128 v[172:175], v180 offset:1024
	ds_read_b128 v[176:179], v180 offset:2048
	ds_read_b128 v[180:183], v180 offset:3072
	s_add_u32 s36, s36, s6
	s_addc_u32 s37, s37, s7
	s_mov_b32 m0, s51
	v_lshl_add_u64 v[228:229], s[36:37], 0, v[136:137]
	ds_read_b128 v[184:187], v151 offset:32768
	ds_read_b128 v[188:191], v151 offset:33792
	ds_read_b128 v[192:195], v151 offset:34816
	ds_read_b128 v[196:199], v151 offset:35840
	ds_read_b128 v[200:203], v151 offset:36864
	ds_read_b128 v[204:207], v151 offset:37888
	ds_read_b128 v[208:211], v151 offset:38912
	ds_read_b128 v[212:215], v151 offset:39936
	global_load_lds_dwordx4 v[228:229], off
	v_lshl_add_u64 v[228:229], s[36:37], 0, v[132:133]
	s_mov_b32 m0, s54
	s_nop 0
	global_load_lds_dwordx4 v[228:229], off
	s_waitcnt vmcnt(8)
	s_waitcnt lgkmcnt(0)
	s_waitcnt lgkmcnt(0)
	v_mfma_f32_16x16x32_bf16 v[122:125], v[152:155], v[184:187], v[122:125]
	v_mfma_f32_16x16x32_bf16 v[126:129], v[160:163], v[184:187], v[126:129]
	s_barrier
	v_mfma_f32_16x16x32_bf16 v[110:113], v[152:155], v[192:195], v[110:113]
	v_mfma_f32_16x16x32_bf16 v[106:109], v[160:163], v[192:195], v[106:109]
	v_mfma_f32_16x16x32_bf16 v[94:97], v[152:155], v[200:203], v[94:97]
	v_mfma_f32_16x16x32_bf16 v[90:93], v[160:163], v[200:203], v[90:93]
	v_mfma_f32_16x16x32_bf16 v[78:81], v[152:155], v[208:211], v[78:81]
	v_mfma_f32_16x16x32_bf16 v[74:77], v[160:163], v[208:211], v[74:77]
	v_mfma_f32_16x16x32_bf16 v[122:125], v[156:159], v[188:191], v[122:125]
	v_mfma_f32_16x16x32_bf16 v[126:129], v[164:167], v[188:191], v[126:129]
	v_mfma_f32_16x16x32_bf16 v[110:113], v[156:159], v[196:199], v[110:113]
	v_mfma_f32_16x16x32_bf16 v[106:109], v[164:167], v[196:199], v[106:109]
	v_mfma_f32_16x16x32_bf16 v[94:97], v[156:159], v[204:207], v[94:97]
	v_mfma_f32_16x16x32_bf16 v[90:93], v[164:167], v[204:207], v[90:93]
	v_mfma_f32_16x16x32_bf16 v[78:81], v[156:159], v[212:215], v[78:81]
	v_mfma_f32_16x16x32_bf16 v[74:77], v[164:167], v[212:215], v[74:77]
	v_mfma_f32_16x16x32_bf16 v[118:121], v[168:171], v[184:187], v[118:121]
	v_mfma_f32_16x16x32_bf16 v[114:117], v[176:179], v[184:187], v[114:117]
	v_mfma_f32_16x16x32_bf16 v[102:105], v[168:171], v[192:195], v[102:105]
	v_mfma_f32_16x16x32_bf16 v[98:101], v[176:179], v[192:195], v[98:101]
	v_mfma_f32_16x16x32_bf16 v[86:89], v[168:171], v[200:203], v[86:89]
	v_mfma_f32_16x16x32_bf16 v[82:85], v[176:179], v[200:203], v[82:85]
	v_mfma_f32_16x16x32_bf16 v[70:73], v[168:171], v[208:211], v[70:73]
	v_mfma_f32_16x16x32_bf16 v[66:69], v[176:179], v[208:211], v[66:69]
	v_mfma_f32_16x16x32_bf16 v[118:121], v[172:175], v[188:191], v[118:121]
	v_mfma_f32_16x16x32_bf16 v[114:117], v[180:183], v[188:191], v[114:117]
	v_mfma_f32_16x16x32_bf16 v[102:105], v[172:175], v[196:199], v[102:105]
	v_mfma_f32_16x16x32_bf16 v[98:101], v[180:183], v[196:199], v[98:101]
	v_mfma_f32_16x16x32_bf16 v[86:89], v[172:175], v[204:207], v[86:89]
	v_mfma_f32_16x16x32_bf16 v[82:85], v[180:183], v[204:207], v[82:85]
	v_mfma_f32_16x16x32_bf16 v[70:73], v[172:175], v[212:215], v[70:73]
	v_mfma_f32_16x16x32_bf16 v[66:69], v[180:183], v[212:215], v[66:69]
	s_barrier
	s_add_i32 s36, s80, s44
	v_lshl_add_u64 v[216:217], v[216:217], 0, s[16:17]
	s_mov_b32 m0, s36
	ds_read_b128 v[184:187], v151 offset:49152
	ds_read_b128 v[188:191], v151 offset:50176
	ds_read_b128 v[192:195], v151 offset:51200
	ds_read_b128 v[196:199], v151 offset:52224
	ds_read_b128 v[200:203], v151 offset:53248
	ds_read_b128 v[204:207], v151 offset:54272
	ds_read_b128 v[208:211], v151 offset:55296
	ds_read_b128 v[212:215], v151 offset:56320
	global_load_lds_dwordx4 v[216:217], off
	v_lshl_add_u64 v[216:217], v[218:219], 0, s[16:17]
	s_add_i32 m0, s36, 0x2000
	s_add_i32 s36, s81, s44
	global_load_lds_dwordx4 v[216:217], off
	v_lshl_add_u64 v[216:217], v[220:221], 0, s[16:17]
	s_mov_b32 m0, s36
	s_nop 0
	global_load_lds_dwordx4 v[216:217], off
	v_lshl_add_u64 v[216:217], v[222:223], 0, s[16:17]
	s_add_i32 m0, s36, 0x2000
	s_nop 0
	global_load_lds_dwordx4 v[216:217], off
	v_lshl_add_u64 v[216:217], v[224:225], 0, s[16:17]
	s_mov_b32 m0, s56
	s_nop 0
	global_load_lds_dwordx4 v[216:217], off
	v_lshl_add_u64 v[216:217], v[226:227], 0, s[16:17]
	s_mov_b32 m0, s57
	s_nop 0
	global_load_lds_dwordx4 v[216:217], off
	s_waitcnt vmcnt(8)
	s_waitcnt lgkmcnt(0)
	s_waitcnt lgkmcnt(0)
	v_mfma_f32_16x16x32_bf16 v[62:65], v[152:155], v[184:187], v[62:65]
	v_mfma_f32_16x16x32_bf16 v[58:61], v[160:163], v[184:187], v[58:61]
	s_barrier
	v_mfma_f32_16x16x32_bf16 v[46:49], v[152:155], v[192:195], v[46:49]
	v_mfma_f32_16x16x32_bf16 v[42:45], v[160:163], v[192:195], v[42:45]
	v_mfma_f32_16x16x32_bf16 v[30:33], v[152:155], v[200:203], v[30:33]
	v_mfma_f32_16x16x32_bf16 v[26:29], v[160:163], v[200:203], v[26:29]
	v_mfma_f32_16x16x32_bf16 v[14:17], v[152:155], v[208:211], v[14:17]
	v_mfma_f32_16x16x32_bf16 v[10:13], v[160:163], v[208:211], v[10:13]
	v_mfma_f32_16x16x32_bf16 v[62:65], v[156:159], v[188:191], v[62:65]
	v_mfma_f32_16x16x32_bf16 v[58:61], v[164:167], v[188:191], v[58:61]
	v_mfma_f32_16x16x32_bf16 v[46:49], v[156:159], v[196:199], v[46:49]
	v_mfma_f32_16x16x32_bf16 v[42:45], v[164:167], v[196:199], v[42:45]
	v_mfma_f32_16x16x32_bf16 v[30:33], v[156:159], v[204:207], v[30:33]
	v_mfma_f32_16x16x32_bf16 v[26:29], v[164:167], v[204:207], v[26:29]
	v_mfma_f32_16x16x32_bf16 v[14:17], v[156:159], v[212:215], v[14:17]
	v_mfma_f32_16x16x32_bf16 v[10:13], v[164:167], v[212:215], v[10:13]
	v_mfma_f32_16x16x32_bf16 v[54:57], v[168:171], v[184:187], v[54:57]
	v_mfma_f32_16x16x32_bf16 v[50:53], v[176:179], v[184:187], v[50:53]
	v_mfma_f32_16x16x32_bf16 v[38:41], v[168:171], v[192:195], v[38:41]
	v_mfma_f32_16x16x32_bf16 v[34:37], v[176:179], v[192:195], v[34:37]
	v_mfma_f32_16x16x32_bf16 v[22:25], v[168:171], v[200:203], v[22:25]
	v_mfma_f32_16x16x32_bf16 v[18:21], v[176:179], v[200:203], v[18:21]
	v_mfma_f32_16x16x32_bf16 v[6:9], v[168:171], v[208:211], v[6:9]
	v_mfma_f32_16x16x32_bf16 v[2:5], v[176:179], v[208:211], v[2:5]
	v_mfma_f32_16x16x32_bf16 v[54:57], v[172:175], v[188:191], v[54:57]
	v_mfma_f32_16x16x32_bf16 v[50:53], v[180:183], v[188:191], v[50:53]
	v_mfma_f32_16x16x32_bf16 v[38:41], v[172:175], v[196:199], v[38:41]
	v_mfma_f32_16x16x32_bf16 v[34:37], v[180:183], v[196:199], v[34:37]
	v_mfma_f32_16x16x32_bf16 v[22:25], v[172:175], v[204:207], v[22:25]
	v_mfma_f32_16x16x32_bf16 v[18:21], v[180:183], v[204:207], v[18:21]
	v_mfma_f32_16x16x32_bf16 v[6:9], v[172:175], v[212:215], v[6:9]
	v_mfma_f32_16x16x32_bf16 v[2:5], v[180:183], v[212:215], v[2:5]
	s_barrier
	s_add_u32 s34, s34, 0x100
	s_addc_u32 s35, s35, 0
	s_add_u32 s67, s67, 0x100
	s_addc_u32 s68, s68, 0
	s_cmp_ge_i32 s69, s58
	s_mov_b32 s36, s69
	s_cbranch_scc0 .LBB0_1514

.LBB0_1754:
	v_add_u32_e32 v158, s80, v229
	v_add_u32_e32 v174, s81, v229
	ds_read_b128 v[146:149], v158
	ds_read_b128 v[150:153], v158 offset:1024
	ds_read_b128 v[154:157], v158 offset:2048
	ds_read_b128 v[158:161], v158 offset:3072
	ds_read_b128 v[162:165], v174
	ds_read_b128 v[166:169], v174 offset:1024
	ds_read_b128 v[170:173], v174 offset:2048
	ds_read_b128 v[174:177], v174 offset:3072
	s_add_i32 s88, s44, 2
	s_add_u32 s89, s42, 0x80
	s_addc_u32 s45, s43, 0
	s_cmp_eq_u32 s67, s44
	s_cselect_b32 s44, s4, s89
	s_cselect_b32 s45, s5, s45
	s_cselect_b32 s91, s39, s87
	s_cselect_b32 s90, s38, s86
	v_lshl_add_u64 v[210:211], s[42:43], 0, v[138:139]
	s_add_i32 m0, s55, 0xc000
	ds_read_b128 v[178:181], v231
	ds_read_b128 v[182:185], v231 offset:1024
	ds_read_b128 v[186:189], v231 offset:2048
	ds_read_b128 v[190:193], v231 offset:3072
	ds_read_b128 v[194:197], v231 offset:4096
	ds_read_b128 v[198:201], v231 offset:5120
	ds_read_b128 v[202:205], v231 offset:6144
	ds_read_b128 v[206:209], v231 offset:7168
	global_load_lds_dwordx4 v[210:211], off
	v_lshl_add_u64 v[210:211], s[42:43], 0, v[140:141]
	s_add_i32 m0, s55, 0xe000
	s_nop 0
	global_load_lds_dwordx4 v[210:211], off
	s_waitcnt vmcnt(8)
	s_waitcnt lgkmcnt(0)
	s_waitcnt lgkmcnt(0)
	v_mfma_i32_16x16x64_i8 v[126:129], v[146:149], v[178:181], v[126:129]
	v_mfma_i32_16x16x64_i8 v[122:125], v[154:157], v[178:181], v[122:125]
	s_barrier
	v_mfma_i32_16x16x64_i8 v[118:121], v[146:149], v[186:189], v[118:121]
	v_mfma_i32_16x16x64_i8 v[114:117], v[154:157], v[186:189], v[114:117]
	v_mfma_i32_16x16x64_i8 v[106:109], v[146:149], v[194:197], v[106:109]
	v_mfma_i32_16x16x64_i8 v[98:101], v[154:157], v[194:197], v[98:101]
	v_mfma_i32_16x16x64_i8 v[90:93], v[146:149], v[202:205], v[90:93]
	v_mfma_i32_16x16x64_i8 v[82:85], v[154:157], v[202:205], v[82:85]
	v_mfma_i32_16x16x64_i8 v[126:129], v[150:153], v[182:185], v[126:129]
	v_mfma_i32_16x16x64_i8 v[122:125], v[158:161], v[182:185], v[122:125]
	v_mfma_i32_16x16x64_i8 v[118:121], v[150:153], v[190:193], v[118:121]
	v_mfma_i32_16x16x64_i8 v[114:117], v[158:161], v[190:193], v[114:117]
	v_mfma_i32_16x16x64_i8 v[106:109], v[150:153], v[198:201], v[106:109]
	v_mfma_i32_16x16x64_i8 v[98:101], v[158:161], v[198:201], v[98:101]
	v_mfma_i32_16x16x64_i8 v[90:93], v[150:153], v[206:209], v[90:93]
	v_mfma_i32_16x16x64_i8 v[82:85], v[158:161], v[206:209], v[82:85]
	v_mfma_i32_16x16x64_i8 v[110:113], v[162:165], v[178:181], v[110:113]
	v_mfma_i32_16x16x64_i8 v[102:105], v[170:173], v[178:181], v[102:105]
	v_mfma_i32_16x16x64_i8 v[94:97], v[162:165], v[186:189], v[94:97]
	v_mfma_i32_16x16x64_i8 v[86:89], v[170:173], v[186:189], v[86:89]
	v_mfma_i32_16x16x64_i8 v[78:81], v[162:165], v[194:197], v[78:81]
	v_mfma_i32_16x16x64_i8 v[74:77], v[170:173], v[194:197], v[74:77]
	v_mfma_i32_16x16x64_i8 v[70:73], v[162:165], v[202:205], v[70:73]
	v_mfma_i32_16x16x64_i8 v[66:69], v[170:173], v[202:205], v[66:69]
	v_mfma_i32_16x16x64_i8 v[110:113], v[166:169], v[182:185], v[110:113]
	v_mfma_i32_16x16x64_i8 v[102:105], v[174:177], v[182:185], v[102:105]
	v_mfma_i32_16x16x64_i8 v[94:97], v[166:169], v[190:193], v[94:97]
	v_mfma_i32_16x16x64_i8 v[86:89], v[174:177], v[190:193], v[86:89]
	v_mfma_i32_16x16x64_i8 v[78:81], v[166:169], v[198:201], v[78:81]
	v_mfma_i32_16x16x64_i8 v[74:77], v[174:177], v[198:201], v[74:77]
	v_mfma_i32_16x16x64_i8 v[70:73], v[166:169], v[206:209], v[70:73]
	v_mfma_i32_16x16x64_i8 v[66:69], v[174:177], v[206:209], v[66:69]
	s_barrier
	s_add_i32 s89, s80, s54
	v_lshl_add_u64 v[210:211], s[90:91], 0, v[132:133]
	s_mov_b32 m0, s89
	ds_read_b128 v[178:181], v231 offset:16384
	ds_read_b128 v[182:185], v231 offset:17408
	ds_read_b128 v[186:189], v231 offset:18432
	ds_read_b128 v[190:193], v231 offset:19456
	ds_read_b128 v[194:197], v231 offset:20480
	ds_read_b128 v[198:201], v231 offset:21504
	ds_read_b128 v[202:205], v231 offset:22528
	ds_read_b128 v[206:209], v231 offset:23552
	global_load_lds_dwordx4 v[210:211], off
	s_add_i32 m0, s89, 0x2000
	v_lshl_add_u64 v[212:213], s[90:91], 0, v[136:137]
	s_add_u32 s90, s90, s8
	s_addc_u32 s91, s91, s9
	s_add_i32 s89, s81, s54
	global_load_lds_dwordx4 v[212:213], off
	v_lshl_add_u64 v[214:215], s[90:91], 0, v[132:133]
	s_mov_b32 m0, s89
	v_lshl_add_u64 v[216:217], s[90:91], 0, v[136:137]
	global_load_lds_dwordx4 v[214:215], off
	s_add_i32 m0, s89, 0x2000
	v_lshl_add_u64 v[218:219], s[44:45], 0, v[130:131]
	global_load_lds_dwordx4 v[216:217], off
	s_mov_b32 m0, s55
	v_lshl_add_u64 v[220:221], s[44:45], 0, v[134:135]
	global_load_lds_dwordx4 v[218:219], off
	s_mov_b32 m0, s56
	s_nop 0
	global_load_lds_dwordx4 v[220:221], off
	s_waitcnt vmcnt(8)
	s_waitcnt lgkmcnt(0)
	s_waitcnt lgkmcnt(0)
	v_mfma_i32_16x16x64_i8 v[62:65], v[146:149], v[178:181], v[62:65]
	v_mfma_i32_16x16x64_i8 v[58:61], v[154:157], v[178:181], v[58:61]
	s_barrier
	v_mfma_i32_16x16x64_i8 v[54:57], v[146:149], v[186:189], v[54:57]
	v_mfma_i32_16x16x64_i8 v[50:53], v[154:157], v[186:189], v[50:53]
	v_mfma_i32_16x16x64_i8 v[42:45], v[146:149], v[194:197], v[42:45]
	v_mfma_i32_16x16x64_i8 v[34:37], v[154:157], v[194:197], v[34:37]
	v_mfma_i32_16x16x64_i8 v[26:29], v[146:149], v[202:205], v[26:29]
	v_mfma_i32_16x16x64_i8 v[18:21], v[154:157], v[202:205], v[18:21]
	v_mfma_i32_16x16x64_i8 v[62:65], v[150:153], v[182:185], v[62:65]
	v_mfma_i32_16x16x64_i8 v[58:61], v[158:161], v[182:185], v[58:61]
	v_mfma_i32_16x16x64_i8 v[54:57], v[150:153], v[190:193], v[54:57]
	v_mfma_i32_16x16x64_i8 v[50:53], v[158:161], v[190:193], v[50:53]
	v_mfma_i32_16x16x64_i8 v[42:45], v[150:153], v[198:201], v[42:45]
	v_mfma_i32_16x16x64_i8 v[34:37], v[158:161], v[198:201], v[34:37]
	v_mfma_i32_16x16x64_i8 v[26:29], v[150:153], v[206:209], v[26:29]
	v_mfma_i32_16x16x64_i8 v[18:21], v[158:161], v[206:209], v[18:21]
	v_mfma_i32_16x16x64_i8 v[46:49], v[162:165], v[178:181], v[46:49]
	v_mfma_i32_16x16x64_i8 v[38:41], v[170:173], v[178:181], v[38:41]
	v_mfma_i32_16x16x64_i8 v[30:33], v[162:165], v[186:189], v[30:33]
	v_mfma_i32_16x16x64_i8 v[22:25], v[170:173], v[186:189], v[22:25]
	v_mfma_i32_16x16x64_i8 v[14:17], v[162:165], v[194:197], v[14:17]
	v_mfma_i32_16x16x64_i8 v[10:13], v[170:173], v[194:197], v[10:13]
	v_mfma_i32_16x16x64_i8 v[6:9], v[162:165], v[202:205], v[6:9]
	v_mfma_i32_16x16x64_i8 v[2:5], v[170:173], v[202:205], v[2:5]
	v_mfma_i32_16x16x64_i8 v[46:49], v[166:169], v[182:185], v[46:49]
	v_mfma_i32_16x16x64_i8 v[38:41], v[174:177], v[182:185], v[38:41]
	v_mfma_i32_16x16x64_i8 v[30:33], v[166:169], v[190:193], v[30:33]
	v_mfma_i32_16x16x64_i8 v[22:25], v[174:177], v[190:193], v[22:25]
	v_mfma_i32_16x16x64_i8 v[14:17], v[166:169], v[198:201], v[14:17]
	v_mfma_i32_16x16x64_i8 v[10:13], v[174:177], v[198:201], v[10:13]
	v_mfma_i32_16x16x64_i8 v[6:9], v[166:169], v[206:209], v[6:9]
	v_mfma_i32_16x16x64_i8 v[2:5], v[174:177], v[206:209], v[2:5]
	s_barrier
	s_add_i32 s89, 0, 0x18000
	s_add_i32 s90, 0, 0x1c000
	v_add_u32_e32 v158, s89, v229
	v_add_u32_e32 v174, s90, v229
	ds_read_b128 v[146:149], v158
	ds_read_b128 v[150:153], v158 offset:1024
	ds_read_b128 v[154:157], v158 offset:2048
	ds_read_b128 v[158:161], v158 offset:3072
	ds_read_b128 v[162:165], v174
	ds_read_b128 v[166:169], v174 offset:1024
	ds_read_b128 v[170:173], v174 offset:2048
	ds_read_b128 v[174:177], v174 offset:3072
	s_add_u32 s44, s44, s8
	s_addc_u32 s45, s45, s9
	s_mov_b32 m0, s57
	v_lshl_add_u64 v[222:223], s[44:45], 0, v[130:131]
	ds_read_b128 v[178:181], v231 offset:32768
	ds_read_b128 v[182:185], v231 offset:33792
	ds_read_b128 v[186:189], v231 offset:34816
	ds_read_b128 v[190:193], v231 offset:35840
	ds_read_b128 v[194:197], v231 offset:36864
	ds_read_b128 v[198:201], v231 offset:37888
	ds_read_b128 v[202:205], v231 offset:38912
	ds_read_b128 v[206:209], v231 offset:39936
	global_load_lds_dwordx4 v[222:223], off
	v_lshl_add_u64 v[222:223], s[44:45], 0, v[134:135]
	s_mov_b32 m0, s58
	s_nop 0
	global_load_lds_dwordx4 v[222:223], off
	s_waitcnt vmcnt(8)
	s_waitcnt lgkmcnt(0)
	s_waitcnt lgkmcnt(0)
	v_mfma_i32_16x16x64_i8 v[126:129], v[146:149], v[178:181], v[126:129]
	v_mfma_i32_16x16x64_i8 v[122:125], v[154:157], v[178:181], v[122:125]
	s_barrier
	v_mfma_i32_16x16x64_i8 v[118:121], v[146:149], v[186:189], v[118:121]
	v_mfma_i32_16x16x64_i8 v[114:117], v[154:157], v[186:189], v[114:117]
	v_mfma_i32_16x16x64_i8 v[106:109], v[146:149], v[194:197], v[106:109]
	v_mfma_i32_16x16x64_i8 v[98:101], v[154:157], v[194:197], v[98:101]
	v_mfma_i32_16x16x64_i8 v[90:93], v[146:149], v[202:205], v[90:93]
	v_mfma_i32_16x16x64_i8 v[82:85], v[154:157], v[202:205], v[82:85]
	v_mfma_i32_16x16x64_i8 v[126:129], v[150:153], v[182:185], v[126:129]
	v_mfma_i32_16x16x64_i8 v[122:125], v[158:161], v[182:185], v[122:125]
	v_mfma_i32_16x16x64_i8 v[118:121], v[150:153], v[190:193], v[118:121]
	v_mfma_i32_16x16x64_i8 v[114:117], v[158:161], v[190:193], v[114:117]
	v_mfma_i32_16x16x64_i8 v[106:109], v[150:153], v[198:201], v[106:109]
	v_mfma_i32_16x16x64_i8 v[98:101], v[158:161], v[198:201], v[98:101]
	v_mfma_i32_16x16x64_i8 v[90:93], v[150:153], v[206:209], v[90:93]
	v_mfma_i32_16x16x64_i8 v[82:85], v[158:161], v[206:209], v[82:85]
	v_mfma_i32_16x16x64_i8 v[110:113], v[162:165], v[178:181], v[110:113]
	v_mfma_i32_16x16x64_i8 v[102:105], v[170:173], v[178:181], v[102:105]
	v_mfma_i32_16x16x64_i8 v[94:97], v[162:165], v[186:189], v[94:97]
	v_mfma_i32_16x16x64_i8 v[86:89], v[170:173], v[186:189], v[86:89]
	v_mfma_i32_16x16x64_i8 v[78:81], v[162:165], v[194:197], v[78:81]
	v_mfma_i32_16x16x64_i8 v[74:77], v[170:173], v[194:197], v[74:77]
	v_mfma_i32_16x16x64_i8 v[70:73], v[162:165], v[202:205], v[70:73]
	v_mfma_i32_16x16x64_i8 v[66:69], v[170:173], v[202:205], v[66:69]
	v_mfma_i32_16x16x64_i8 v[110:113], v[166:169], v[182:185], v[110:113]
	v_mfma_i32_16x16x64_i8 v[102:105], v[174:177], v[182:185], v[102:105]
	v_mfma_i32_16x16x64_i8 v[94:97], v[166:169], v[190:193], v[94:97]
	v_mfma_i32_16x16x64_i8 v[86:89], v[174:177], v[190:193], v[86:89]
	v_mfma_i32_16x16x64_i8 v[78:81], v[166:169], v[198:201], v[78:81]
	v_mfma_i32_16x16x64_i8 v[74:77], v[174:177], v[198:201], v[74:77]
	v_mfma_i32_16x16x64_i8 v[70:73], v[166:169], v[206:209], v[70:73]
	v_mfma_i32_16x16x64_i8 v[66:69], v[174:177], v[206:209], v[66:69]
	s_barrier
	s_add_i32 s44, s89, s54
	v_lshl_add_u64 v[210:211], v[210:211], 0, s[30:31]
	s_mov_b32 m0, s44
	ds_read_b128 v[178:181], v231 offset:49152
	ds_read_b128 v[182:185], v231 offset:50176
	ds_read_b128 v[186:189], v231 offset:51200
	ds_read_b128 v[190:193], v231 offset:52224
	ds_read_b128 v[194:197], v231 offset:53248
	ds_read_b128 v[198:201], v231 offset:54272
	ds_read_b128 v[202:205], v231 offset:55296
	ds_read_b128 v[206:209], v231 offset:56320
	global_load_lds_dwordx4 v[210:211], off
	v_lshl_add_u64 v[210:211], v[212:213], 0, s[30:31]
	s_add_i32 m0, s44, 0x2000
	s_add_i32 s44, s90, s54
	global_load_lds_dwordx4 v[210:211], off
	v_lshl_add_u64 v[210:211], v[214:215], 0, s[30:31]
	s_mov_b32 m0, s44
	s_nop 0
	global_load_lds_dwordx4 v[210:211], off
	v_lshl_add_u64 v[210:211], v[216:217], 0, s[30:31]
	s_add_i32 m0, s44, 0x2000
	s_nop 0
	global_load_lds_dwordx4 v[210:211], off
	v_lshl_add_u64 v[210:211], v[218:219], 0, s[30:31]
	s_mov_b32 m0, s63
	s_nop 0
	global_load_lds_dwordx4 v[210:211], off
	v_lshl_add_u64 v[210:211], v[220:221], 0, s[30:31]
	s_mov_b32 m0, s64
	s_nop 0
	global_load_lds_dwordx4 v[210:211], off
	s_waitcnt vmcnt(8)
	s_waitcnt lgkmcnt(0)
	s_waitcnt lgkmcnt(0)
	v_mfma_i32_16x16x64_i8 v[62:65], v[146:149], v[178:181], v[62:65]
	v_mfma_i32_16x16x64_i8 v[58:61], v[154:157], v[178:181], v[58:61]
	s_barrier
	v_mfma_i32_16x16x64_i8 v[54:57], v[146:149], v[186:189], v[54:57]
	v_mfma_i32_16x16x64_i8 v[50:53], v[154:157], v[186:189], v[50:53]
	v_mfma_i32_16x16x64_i8 v[42:45], v[146:149], v[194:197], v[42:45]
	v_mfma_i32_16x16x64_i8 v[34:37], v[154:157], v[194:197], v[34:37]
	v_mfma_i32_16x16x64_i8 v[26:29], v[146:149], v[202:205], v[26:29]
	v_mfma_i32_16x16x64_i8 v[18:21], v[154:157], v[202:205], v[18:21]
	v_mfma_i32_16x16x64_i8 v[62:65], v[150:153], v[182:185], v[62:65]
	v_mfma_i32_16x16x64_i8 v[58:61], v[158:161], v[182:185], v[58:61]
	v_mfma_i32_16x16x64_i8 v[54:57], v[150:153], v[190:193], v[54:57]
	v_mfma_i32_16x16x64_i8 v[50:53], v[158:161], v[190:193], v[50:53]
	v_mfma_i32_16x16x64_i8 v[42:45], v[150:153], v[198:201], v[42:45]
	v_mfma_i32_16x16x64_i8 v[34:37], v[158:161], v[198:201], v[34:37]
	v_mfma_i32_16x16x64_i8 v[26:29], v[150:153], v[206:209], v[26:29]
	v_mfma_i32_16x16x64_i8 v[18:21], v[158:161], v[206:209], v[18:21]
	v_mfma_i32_16x16x64_i8 v[46:49], v[162:165], v[178:181], v[46:49]
	v_mfma_i32_16x16x64_i8 v[38:41], v[170:173], v[178:181], v[38:41]
	v_mfma_i32_16x16x64_i8 v[30:33], v[162:165], v[186:189], v[30:33]
	v_mfma_i32_16x16x64_i8 v[22:25], v[170:173], v[186:189], v[22:25]
	v_mfma_i32_16x16x64_i8 v[14:17], v[162:165], v[194:197], v[14:17]
	v_mfma_i32_16x16x64_i8 v[10:13], v[170:173], v[194:197], v[10:13]
	v_mfma_i32_16x16x64_i8 v[6:9], v[162:165], v[202:205], v[6:9]
	v_mfma_i32_16x16x64_i8 v[2:5], v[170:173], v[202:205], v[2:5]
	v_mfma_i32_16x16x64_i8 v[46:49], v[166:169], v[182:185], v[46:49]
	v_mfma_i32_16x16x64_i8 v[38:41], v[174:177], v[182:185], v[38:41]
	v_mfma_i32_16x16x64_i8 v[30:33], v[166:169], v[190:193], v[30:33]
	v_mfma_i32_16x16x64_i8 v[22:25], v[174:177], v[190:193], v[22:25]
	v_mfma_i32_16x16x64_i8 v[14:17], v[166:169], v[198:201], v[14:17]
	v_mfma_i32_16x16x64_i8 v[10:13], v[174:177], v[198:201], v[10:13]
	v_mfma_i32_16x16x64_i8 v[6:9], v[166:169], v[206:209], v[6:9]
	v_mfma_i32_16x16x64_i8 v[2:5], v[174:177], v[206:209], v[2:5]
	s_barrier
	s_add_u32 s42, s42, 0x100
	s_addc_u32 s43, s43, 0
	s_add_u32 s86, s86, 0x100
	s_addc_u32 s87, s87, 0
	s_cmp_ge_i32 s88, s66
	s_mov_b32 s44, s88
	s_cbranch_scc0 .LBB0_1754
	v_cvt_f32_i32_e32 v214, v126
	v_cvt_f32_i32_e32 v215, v127
	v_cvt_f32_i32_e32 v212, v128
	v_cvt_f32_i32_e32 v213, v129
	v_cvt_f32_i32_e32 v218, v122
	v_cvt_f32_i32_e32 v219, v123
	v_cvt_f32_i32_e32 v216, v124
	v_cvt_f32_i32_e32 v217, v125
	v_cvt_f32_i32_e32 v222, v110
	v_cvt_f32_i32_e32 v223, v111
	v_cvt_f32_i32_e32 v220, v112
	v_cvt_f32_i32_e32 v221, v113
	v_cvt_f32_i32_e32 v226, v102
	v_cvt_f32_i32_e32 v227, v103
	v_cvt_f32_i32_e32 v224, v104
	v_cvt_f32_i32_e32 v225, v105
	v_cvt_f32_i32_e32 v194, v118
	v_cvt_f32_i32_e32 v195, v119
	v_cvt_f32_i32_e32 v192, v120
	v_cvt_f32_i32_e32 v193, v121
	v_cvt_f32_i32_e32 v200, v114
	v_cvt_f32_i32_e32 v201, v115
	v_cvt_f32_i32_e32 v198, v116
	v_cvt_f32_i32_e32 v199, v117
	v_cvt_f32_i32_e32 v206, v94
	v_cvt_f32_i32_e32 v207, v95
	v_cvt_f32_i32_e32 v202, v96
	v_cvt_f32_i32_e32 v203, v97
	v_cvt_f32_i32_e32 v208, v86
	v_cvt_f32_i32_e32 v209, v87
	v_cvt_f32_i32_e32 v204, v88
	v_cvt_f32_i32_e32 v205, v89
	v_cvt_f32_i32_e32 v178, v106
	v_cvt_f32_i32_e32 v179, v107
	v_cvt_f32_i32_e32 v176, v108
	v_cvt_f32_i32_e32 v177, v109
	v_cvt_f32_i32_e32 v182, v98
	v_cvt_f32_i32_e32 v183, v99
	v_cvt_f32_i32_e32 v180, v100
	v_cvt_f32_i32_e32 v181, v101
	v_cvt_f32_i32_e32 v188, v78
	v_cvt_f32_i32_e32 v189, v79
	v_cvt_f32_i32_e32 v184, v80
	v_cvt_f32_i32_e32 v185, v81
	v_cvt_f32_i32_e32 v190, v74
	v_cvt_f32_i32_e32 v191, v75
	v_cvt_f32_i32_e32 v186, v76
	v_cvt_f32_i32_e32 v187, v77
	v_cvt_f32_i32_e32 v162, v90
	v_cvt_f32_i32_e32 v163, v91
	v_cvt_f32_i32_e32 v160, v92
	v_cvt_f32_i32_e32 v161, v93
	v_cvt_f32_i32_e32 v166, v82
	v_cvt_f32_i32_e32 v167, v83
	v_cvt_f32_i32_e32 v164, v84
	v_cvt_f32_i32_e32 v165, v85
	v_cvt_f32_i32_e32 v172, v70
	v_cvt_f32_i32_e32 v173, v71
	v_cvt_f32_i32_e32 v168, v72
	v_cvt_f32_i32_e32 v169, v73
	v_cvt_f32_i32_e32 v174, v66
	v_cvt_f32_i32_e32 v175, v67
	v_cvt_f32_i32_e32 v170, v68
	v_cvt_f32_i32_e32 v171, v69
	v_cvt_f32_i32_e32 v146, v62
	v_cvt_f32_i32_e32 v147, v63
	v_cvt_f32_i32_e32 v128, v64
	v_cvt_f32_i32_e32 v129, v65
	v_cvt_f32_i32_e32 v150, v58
	v_cvt_f32_i32_e32 v151, v59
	v_cvt_f32_i32_e32 v148, v60
	v_cvt_f32_i32_e32 v149, v61
	v_cvt_f32_i32_e32 v156, v46
	v_cvt_f32_i32_e32 v157, v47
	v_cvt_f32_i32_e32 v152, v48
	v_cvt_f32_i32_e32 v153, v49
	v_cvt_f32_i32_e32 v158, v38
	v_cvt_f32_i32_e32 v159, v39
	v_cvt_f32_i32_e32 v154, v40
	v_cvt_f32_i32_e32 v155, v41
	v_cvt_f32_i32_e32 v114, v54
	v_cvt_f32_i32_e32 v115, v55
	v_cvt_f32_i32_e32 v112, v56
	v_cvt_f32_i32_e32 v113, v57
	v_cvt_f32_i32_e32 v118, v50
	v_cvt_f32_i32_e32 v119, v51
	v_cvt_f32_i32_e32 v116, v52
	v_cvt_f32_i32_e32 v117, v53
	v_cvt_f32_i32_e32 v124, v30
	v_cvt_f32_i32_e32 v125, v31
	v_cvt_f32_i32_e32 v120, v32
	v_cvt_f32_i32_e32 v121, v33
	v_cvt_f32_i32_e32 v126, v22
	v_cvt_f32_i32_e32 v127, v23
	v_cvt_f32_i32_e32 v122, v24
	v_cvt_f32_i32_e32 v123, v25
	v_cvt_f32_i32_e32 v64, v42
	v_cvt_f32_i32_e32 v65, v43
	v_cvt_f32_i32_e32 v62, v44
	v_cvt_f32_i32_e32 v63, v45
	v_cvt_f32_i32_e32 v68, v34
	v_cvt_f32_i32_e32 v69, v35
	v_cvt_f32_i32_e32 v66, v36
	v_cvt_f32_i32_e32 v67, v37
	v_cvt_f32_i32_e32 v74, v14
	v_cvt_f32_i32_e32 v75, v15
	v_cvt_f32_i32_e32 v70, v16
	v_cvt_f32_i32_e32 v71, v17
	v_cvt_f32_i32_e32 v76, v10
	v_cvt_f32_i32_e32 v77, v11
	v_cvt_f32_i32_e32 v72, v12
	v_cvt_f32_i32_e32 v73, v13
	v_cvt_f32_i32_e32 v48, v26
	v_cvt_f32_i32_e32 v49, v27
	v_cvt_f32_i32_e32 v46, v28
	v_cvt_f32_i32_e32 v47, v29
	v_cvt_f32_i32_e32 v52, v18
	v_cvt_f32_i32_e32 v53, v19
	v_cvt_f32_i32_e32 v50, v20
	v_cvt_f32_i32_e32 v51, v21
	v_cvt_f32_i32_e32 v58, v6
	v_cvt_f32_i32_e32 v59, v7
	v_cvt_f32_i32_e32 v54, v8
	v_cvt_f32_i32_e32 v55, v9
	v_cvt_f32_i32_e32 v60, v2
	v_cvt_f32_i32_e32 v61, v3
	v_cvt_f32_i32_e32 v56, v4
	v_cvt_f32_i32_e32 v57, v5

.LBB0_1939:
	v_add_u32_e32 v138, s62, v188
	ds_read_b128 v[148:151], v138
	ds_read_b128 v[152:155], v138 offset:1024
	ds_read_b128 v[156:159], v138 offset:2048
	ds_read_b128 v[160:163], v138 offset:3072
	v_add_u32_e32 v138, s63, v188
	ds_read_b128 v[164:167], v138
	ds_read_b128 v[168:171], v138 offset:1024
	ds_read_b128 v[172:175], v138 offset:2048
	ds_read_b128 v[176:179], v138 offset:3072
	s_add_i32 s66, s28, 2
	s_add_u32 s67, s26, 0x80
	s_addc_u32 s29, s27, 0
	s_cmp_eq_u32 s60, s28
	s_cselect_b32 s28, s2, s67
	s_cselect_b32 s29, s3, s29
	s_cselect_b32 s69, s25, s35
	s_cselect_b32 s68, s24, s34
	v_lshl_add_u64 v[184:185], s[26:27], 0, v[140:141]
	s_add_i32 m0, s44, 0xc000
	ds_read_b128 v[180:183], v189
	ds_read_b128 v[190:193], v189 offset:1024
	ds_read_b128 v[194:197], v189 offset:2048
	ds_read_b128 v[198:201], v189 offset:3072
	ds_read_b128 v[202:205], v189 offset:4096
	ds_read_b128 v[206:209], v189 offset:5120
	ds_read_b128 v[210:213], v189 offset:6144
	ds_read_b128 v[214:217], v189 offset:7168
	global_load_lds_dwordx4 v[184:185], off
	v_lshl_add_u64 v[184:185], s[26:27], 0, v[142:143]
	s_add_i32 m0, s44, 0xe000
	s_nop 0
	global_load_lds_dwordx4 v[184:185], off
	s_waitcnt vmcnt(8)
	s_waitcnt lgkmcnt(0)
	s_waitcnt lgkmcnt(0)
	v_mfma_i32_16x16x64_i8 v[126:129], v[148:151], v[180:183], v[126:129]
	v_mfma_i32_16x16x64_i8 v[122:125], v[156:159], v[180:183], v[122:125]
	s_barrier
	v_mfma_i32_16x16x64_i8 v[118:121], v[148:151], v[194:197], v[118:121]
	v_mfma_i32_16x16x64_i8 v[114:117], v[156:159], v[194:197], v[114:117]
	v_mfma_i32_16x16x64_i8 v[106:109], v[148:151], v[202:205], v[106:109]
	v_mfma_i32_16x16x64_i8 v[98:101], v[156:159], v[202:205], v[98:101]
	v_mfma_i32_16x16x64_i8 v[90:93], v[148:151], v[210:213], v[90:93]
	v_mfma_i32_16x16x64_i8 v[82:85], v[156:159], v[210:213], v[82:85]
	v_mfma_i32_16x16x64_i8 v[126:129], v[152:155], v[190:193], v[126:129]
	v_mfma_i32_16x16x64_i8 v[122:125], v[160:163], v[190:193], v[122:125]
	v_mfma_i32_16x16x64_i8 v[118:121], v[152:155], v[198:201], v[118:121]
	v_mfma_i32_16x16x64_i8 v[114:117], v[160:163], v[198:201], v[114:117]
	v_mfma_i32_16x16x64_i8 v[106:109], v[152:155], v[206:209], v[106:109]
	v_mfma_i32_16x16x64_i8 v[98:101], v[160:163], v[206:209], v[98:101]
	v_mfma_i32_16x16x64_i8 v[90:93], v[152:155], v[214:217], v[90:93]
	v_mfma_i32_16x16x64_i8 v[82:85], v[160:163], v[214:217], v[82:85]
	v_mfma_i32_16x16x64_i8 v[110:113], v[164:167], v[180:183], v[110:113]
	v_mfma_i32_16x16x64_i8 v[102:105], v[172:175], v[180:183], v[102:105]
	v_mfma_i32_16x16x64_i8 v[94:97], v[164:167], v[194:197], v[94:97]
	v_mfma_i32_16x16x64_i8 v[86:89], v[172:175], v[194:197], v[86:89]
	v_mfma_i32_16x16x64_i8 v[78:81], v[164:167], v[202:205], v[78:81]
	v_mfma_i32_16x16x64_i8 v[74:77], v[172:175], v[202:205], v[74:77]
	v_mfma_i32_16x16x64_i8 v[70:73], v[164:167], v[210:213], v[70:73]
	v_mfma_i32_16x16x64_i8 v[66:69], v[172:175], v[210:213], v[66:69]
	v_mfma_i32_16x16x64_i8 v[110:113], v[168:171], v[190:193], v[110:113]
	v_mfma_i32_16x16x64_i8 v[102:105], v[176:179], v[190:193], v[102:105]
	v_mfma_i32_16x16x64_i8 v[94:97], v[168:171], v[198:201], v[94:97]
	v_mfma_i32_16x16x64_i8 v[86:89], v[176:179], v[198:201], v[86:89]
	v_mfma_i32_16x16x64_i8 v[78:81], v[168:171], v[206:209], v[78:81]
	v_mfma_i32_16x16x64_i8 v[74:77], v[176:179], v[206:209], v[74:77]
	v_mfma_i32_16x16x64_i8 v[70:73], v[168:171], v[214:217], v[70:73]
	v_mfma_i32_16x16x64_i8 v[66:69], v[176:179], v[214:217], v[66:69]
	s_barrier
	s_add_i32 s67, s62, s43
	v_lshl_add_u64 v[184:185], s[68:69], 0, v[132:133]
	s_mov_b32 m0, s67
	ds_read_b128 v[180:183], v189 offset:16384
	ds_read_b128 v[190:193], v189 offset:17408
	ds_read_b128 v[194:197], v189 offset:18432
	ds_read_b128 v[198:201], v189 offset:19456
	ds_read_b128 v[202:205], v189 offset:20480
	ds_read_b128 v[206:209], v189 offset:21504
	ds_read_b128 v[210:213], v189 offset:22528
	ds_read_b128 v[214:217], v189 offset:23552
	global_load_lds_dwordx4 v[184:185], off
	s_add_i32 m0, s67, 0x2000
	v_lshl_add_u64 v[218:219], s[68:69], 0, v[136:137]
	s_add_u32 s68, s68, s6
	s_addc_u32 s69, s69, s7
	s_add_i32 s67, s63, s43
	global_load_lds_dwordx4 v[218:219], off
	v_lshl_add_u64 v[220:221], s[68:69], 0, v[132:133]
	s_mov_b32 m0, s67
	v_lshl_add_u64 v[222:223], s[68:69], 0, v[136:137]
	global_load_lds_dwordx4 v[220:221], off
	s_add_i32 m0, s67, 0x2000
	v_lshl_add_u64 v[224:225], s[28:29], 0, v[130:131]
	global_load_lds_dwordx4 v[222:223], off
	s_mov_b32 m0, s44
	v_lshl_add_u64 v[226:227], s[28:29], 0, v[134:135]
	global_load_lds_dwordx4 v[224:225], off
	s_mov_b32 m0, s45
	s_nop 0
	global_load_lds_dwordx4 v[226:227], off
	s_waitcnt vmcnt(8)
	s_waitcnt lgkmcnt(0)
	s_waitcnt lgkmcnt(0)
	v_mfma_i32_16x16x64_i8 v[62:65], v[148:151], v[180:183], v[62:65]
	v_mfma_i32_16x16x64_i8 v[58:61], v[156:159], v[180:183], v[58:61]
	s_barrier
	v_mfma_i32_16x16x64_i8 v[54:57], v[148:151], v[194:197], v[54:57]
	v_mfma_i32_16x16x64_i8 v[50:53], v[156:159], v[194:197], v[50:53]
	v_mfma_i32_16x16x64_i8 v[42:45], v[148:151], v[202:205], v[42:45]
	v_mfma_i32_16x16x64_i8 v[34:37], v[156:159], v[202:205], v[34:37]
	v_mfma_i32_16x16x64_i8 v[26:29], v[148:151], v[210:213], v[26:29]
	v_mfma_i32_16x16x64_i8 v[18:21], v[156:159], v[210:213], v[18:21]
	v_mfma_i32_16x16x64_i8 v[62:65], v[152:155], v[190:193], v[62:65]
	v_mfma_i32_16x16x64_i8 v[58:61], v[160:163], v[190:193], v[58:61]
	v_mfma_i32_16x16x64_i8 v[54:57], v[152:155], v[198:201], v[54:57]
	v_mfma_i32_16x16x64_i8 v[50:53], v[160:163], v[198:201], v[50:53]
	v_mfma_i32_16x16x64_i8 v[42:45], v[152:155], v[206:209], v[42:45]
	v_mfma_i32_16x16x64_i8 v[34:37], v[160:163], v[206:209], v[34:37]
	v_mfma_i32_16x16x64_i8 v[26:29], v[152:155], v[214:217], v[26:29]
	v_mfma_i32_16x16x64_i8 v[18:21], v[160:163], v[214:217], v[18:21]
	v_mfma_i32_16x16x64_i8 v[46:49], v[164:167], v[180:183], v[46:49]
	v_mfma_i32_16x16x64_i8 v[38:41], v[172:175], v[180:183], v[38:41]
	v_mfma_i32_16x16x64_i8 v[30:33], v[164:167], v[194:197], v[30:33]
	v_mfma_i32_16x16x64_i8 v[22:25], v[172:175], v[194:197], v[22:25]
	v_mfma_i32_16x16x64_i8 v[14:17], v[164:167], v[202:205], v[14:17]
	v_mfma_i32_16x16x64_i8 v[10:13], v[172:175], v[202:205], v[10:13]
	v_mfma_i32_16x16x64_i8 v[6:9], v[164:167], v[210:213], v[6:9]
	v_mfma_i32_16x16x64_i8 v[2:5], v[172:175], v[210:213], v[2:5]
	v_mfma_i32_16x16x64_i8 v[46:49], v[168:171], v[190:193], v[46:49]
	v_mfma_i32_16x16x64_i8 v[38:41], v[176:179], v[190:193], v[38:41]
	v_mfma_i32_16x16x64_i8 v[30:33], v[168:171], v[198:201], v[30:33]
	v_mfma_i32_16x16x64_i8 v[22:25], v[176:179], v[198:201], v[22:25]
	v_mfma_i32_16x16x64_i8 v[14:17], v[168:171], v[206:209], v[14:17]
	v_mfma_i32_16x16x64_i8 v[10:13], v[176:179], v[206:209], v[10:13]
	v_mfma_i32_16x16x64_i8 v[6:9], v[168:171], v[214:217], v[6:9]
	v_mfma_i32_16x16x64_i8 v[2:5], v[176:179], v[214:217], v[2:5]
	s_barrier
	s_add_i32 s67, 0, 0x18000
	v_add_u32_e32 v138, s67, v188
	s_add_i32 s68, 0, 0x1c000
	ds_read_b128 v[148:151], v138
	ds_read_b128 v[152:155], v138 offset:1024
	ds_read_b128 v[156:159], v138 offset:2048
	ds_read_b128 v[160:163], v138 offset:3072
	v_add_u32_e32 v138, s68, v188
	ds_read_b128 v[164:167], v138
	ds_read_b128 v[168:171], v138 offset:1024
	ds_read_b128 v[172:175], v138 offset:2048
	ds_read_b128 v[176:179], v138 offset:3072
	s_add_u32 s28, s28, s6
	s_addc_u32 s29, s29, s7
	s_mov_b32 m0, s46
	v_lshl_add_u64 v[228:229], s[28:29], 0, v[130:131]
	ds_read_b128 v[180:183], v189 offset:32768
	ds_read_b128 v[190:193], v189 offset:33792
	ds_read_b128 v[194:197], v189 offset:34816
	ds_read_b128 v[198:201], v189 offset:35840
	ds_read_b128 v[202:205], v189 offset:36864
	ds_read_b128 v[206:209], v189 offset:37888
	ds_read_b128 v[210:213], v189 offset:38912
	ds_read_b128 v[214:217], v189 offset:39936
	global_load_lds_dwordx4 v[228:229], off
	v_lshl_add_u64 v[228:229], s[28:29], 0, v[134:135]
	s_mov_b32 m0, s47
	s_nop 0
	global_load_lds_dwordx4 v[228:229], off
	s_waitcnt vmcnt(8)
	s_waitcnt lgkmcnt(0)
	s_waitcnt lgkmcnt(0)
	v_mfma_i32_16x16x64_i8 v[126:129], v[148:151], v[180:183], v[126:129]
	v_mfma_i32_16x16x64_i8 v[122:125], v[156:159], v[180:183], v[122:125]
	s_barrier
	v_mfma_i32_16x16x64_i8 v[118:121], v[148:151], v[194:197], v[118:121]
	v_mfma_i32_16x16x64_i8 v[114:117], v[156:159], v[194:197], v[114:117]
	v_mfma_i32_16x16x64_i8 v[106:109], v[148:151], v[202:205], v[106:109]
	v_mfma_i32_16x16x64_i8 v[98:101], v[156:159], v[202:205], v[98:101]
	v_mfma_i32_16x16x64_i8 v[90:93], v[148:151], v[210:213], v[90:93]
	v_mfma_i32_16x16x64_i8 v[82:85], v[156:159], v[210:213], v[82:85]
	v_mfma_i32_16x16x64_i8 v[126:129], v[152:155], v[190:193], v[126:129]
	v_mfma_i32_16x16x64_i8 v[122:125], v[160:163], v[190:193], v[122:125]
	v_mfma_i32_16x16x64_i8 v[118:121], v[152:155], v[198:201], v[118:121]
	v_mfma_i32_16x16x64_i8 v[114:117], v[160:163], v[198:201], v[114:117]
	v_mfma_i32_16x16x64_i8 v[106:109], v[152:155], v[206:209], v[106:109]
	v_mfma_i32_16x16x64_i8 v[98:101], v[160:163], v[206:209], v[98:101]
	v_mfma_i32_16x16x64_i8 v[90:93], v[152:155], v[214:217], v[90:93]
	v_mfma_i32_16x16x64_i8 v[82:85], v[160:163], v[214:217], v[82:85]
	v_mfma_i32_16x16x64_i8 v[110:113], v[164:167], v[180:183], v[110:113]
	v_mfma_i32_16x16x64_i8 v[102:105], v[172:175], v[180:183], v[102:105]
	v_mfma_i32_16x16x64_i8 v[94:97], v[164:167], v[194:197], v[94:97]
	v_mfma_i32_16x16x64_i8 v[86:89], v[172:175], v[194:197], v[86:89]
	v_mfma_i32_16x16x64_i8 v[78:81], v[164:167], v[202:205], v[78:81]
	v_mfma_i32_16x16x64_i8 v[74:77], v[172:175], v[202:205], v[74:77]
	v_mfma_i32_16x16x64_i8 v[70:73], v[164:167], v[210:213], v[70:73]
	v_mfma_i32_16x16x64_i8 v[66:69], v[172:175], v[210:213], v[66:69]
	v_mfma_i32_16x16x64_i8 v[110:113], v[168:171], v[190:193], v[110:113]
	v_mfma_i32_16x16x64_i8 v[102:105], v[176:179], v[190:193], v[102:105]
	v_mfma_i32_16x16x64_i8 v[94:97], v[168:171], v[198:201], v[94:97]
	v_mfma_i32_16x16x64_i8 v[86:89], v[176:179], v[198:201], v[86:89]
	v_mfma_i32_16x16x64_i8 v[78:81], v[168:171], v[206:209], v[78:81]
	v_mfma_i32_16x16x64_i8 v[74:77], v[176:179], v[206:209], v[74:77]
	v_mfma_i32_16x16x64_i8 v[70:73], v[168:171], v[214:217], v[70:73]
	v_mfma_i32_16x16x64_i8 v[66:69], v[176:179], v[214:217], v[66:69]
	s_barrier
	s_add_i32 s28, s67, s43
	v_lshl_add_u64 v[184:185], v[184:185], 0, s[18:19]
	s_mov_b32 m0, s28
	ds_read_b128 v[180:183], v189 offset:49152
	ds_read_b128 v[190:193], v189 offset:50176
	ds_read_b128 v[194:197], v189 offset:51200
	ds_read_b128 v[198:201], v189 offset:52224
	ds_read_b128 v[202:205], v189 offset:53248
	ds_read_b128 v[206:209], v189 offset:54272
	ds_read_b128 v[210:213], v189 offset:55296
	ds_read_b128 v[214:217], v189 offset:56320
	global_load_lds_dwordx4 v[184:185], off
	v_lshl_add_u64 v[184:185], v[218:219], 0, s[18:19]
	s_add_i32 m0, s28, 0x2000
	s_add_i32 s28, s68, s43
	global_load_lds_dwordx4 v[184:185], off
	v_lshl_add_u64 v[184:185], v[220:221], 0, s[18:19]
	s_mov_b32 m0, s28
	s_nop 0
	global_load_lds_dwordx4 v[184:185], off
	v_lshl_add_u64 v[184:185], v[222:223], 0, s[18:19]
	s_add_i32 m0, s28, 0x2000
	s_nop 0
	global_load_lds_dwordx4 v[184:185], off
	v_lshl_add_u64 v[184:185], v[224:225], 0, s[18:19]
	s_mov_b32 m0, s55
	s_nop 0
	global_load_lds_dwordx4 v[184:185], off
	v_lshl_add_u64 v[184:185], v[226:227], 0, s[18:19]
	s_mov_b32 m0, s56
	s_nop 0
	global_load_lds_dwordx4 v[184:185], off
	s_waitcnt vmcnt(8)
	s_waitcnt lgkmcnt(0)
	s_waitcnt lgkmcnt(0)
	v_mfma_i32_16x16x64_i8 v[62:65], v[148:151], v[180:183], v[62:65]
	v_mfma_i32_16x16x64_i8 v[58:61], v[156:159], v[180:183], v[58:61]
	s_barrier
	v_mfma_i32_16x16x64_i8 v[54:57], v[148:151], v[194:197], v[54:57]
	v_mfma_i32_16x16x64_i8 v[50:53], v[156:159], v[194:197], v[50:53]
	v_mfma_i32_16x16x64_i8 v[42:45], v[148:151], v[202:205], v[42:45]
	v_mfma_i32_16x16x64_i8 v[34:37], v[156:159], v[202:205], v[34:37]
	v_mfma_i32_16x16x64_i8 v[26:29], v[148:151], v[210:213], v[26:29]
	v_mfma_i32_16x16x64_i8 v[18:21], v[156:159], v[210:213], v[18:21]
	v_mfma_i32_16x16x64_i8 v[62:65], v[152:155], v[190:193], v[62:65]
	v_mfma_i32_16x16x64_i8 v[58:61], v[160:163], v[190:193], v[58:61]
	v_mfma_i32_16x16x64_i8 v[54:57], v[152:155], v[198:201], v[54:57]
	v_mfma_i32_16x16x64_i8 v[50:53], v[160:163], v[198:201], v[50:53]
	v_mfma_i32_16x16x64_i8 v[42:45], v[152:155], v[206:209], v[42:45]
	v_mfma_i32_16x16x64_i8 v[34:37], v[160:163], v[206:209], v[34:37]
	v_mfma_i32_16x16x64_i8 v[26:29], v[152:155], v[214:217], v[26:29]
	v_mfma_i32_16x16x64_i8 v[18:21], v[160:163], v[214:217], v[18:21]
	v_mfma_i32_16x16x64_i8 v[46:49], v[164:167], v[180:183], v[46:49]
	v_mfma_i32_16x16x64_i8 v[38:41], v[172:175], v[180:183], v[38:41]
	v_mfma_i32_16x16x64_i8 v[30:33], v[164:167], v[194:197], v[30:33]
	v_mfma_i32_16x16x64_i8 v[22:25], v[172:175], v[194:197], v[22:25]
	v_mfma_i32_16x16x64_i8 v[14:17], v[164:167], v[202:205], v[14:17]
	v_mfma_i32_16x16x64_i8 v[10:13], v[172:175], v[202:205], v[10:13]
	v_mfma_i32_16x16x64_i8 v[6:9], v[164:167], v[210:213], v[6:9]
	v_mfma_i32_16x16x64_i8 v[2:5], v[172:175], v[210:213], v[2:5]
	v_mfma_i32_16x16x64_i8 v[46:49], v[168:171], v[190:193], v[46:49]
	v_mfma_i32_16x16x64_i8 v[38:41], v[176:179], v[190:193], v[38:41]
	v_mfma_i32_16x16x64_i8 v[30:33], v[168:171], v[198:201], v[30:33]
	v_mfma_i32_16x16x64_i8 v[22:25], v[176:179], v[198:201], v[22:25]
	v_mfma_i32_16x16x64_i8 v[14:17], v[168:171], v[206:209], v[14:17]
	v_mfma_i32_16x16x64_i8 v[10:13], v[176:179], v[206:209], v[10:13]
	v_mfma_i32_16x16x64_i8 v[6:9], v[168:171], v[214:217], v[6:9]
	v_mfma_i32_16x16x64_i8 v[2:5], v[176:179], v[214:217], v[2:5]
	s_barrier
	s_add_u32 s26, s26, 0x100
	s_addc_u32 s27, s27, 0
	s_add_u32 s34, s34, 0x100
	s_addc_u32 s35, s35, 0
	s_cmp_ge_i32 s66, s57
	s_mov_b32 s28, s66
	s_cbranch_scc0 .LBB0_1939
	v_cvt_f32_i32_e32 v172, v126
	v_cvt_f32_i32_e32 v173, v127
	v_cvt_f32_i32_e32 v170, v128
	v_cvt_f32_i32_e32 v171, v129
	v_cvt_f32_i32_e32 v174, v122
	v_cvt_f32_i32_e32 v175, v123
	v_cvt_f32_i32_e32 v176, v124
	v_cvt_f32_i32_e32 v177, v125
	v_cvt_f32_i32_e32 v180, v110
	v_cvt_f32_i32_e32 v181, v111
	v_cvt_f32_i32_e32 v182, v112
	v_cvt_f32_i32_e32 v183, v113
	v_cvt_f32_i32_e32 v178, v102
	v_cvt_f32_i32_e32 v179, v103
	v_cvt_f32_i32_e32 v184, v104
	v_cvt_f32_i32_e32 v185, v105
	v_cvt_f32_i32_e32 v152, v118
	v_cvt_f32_i32_e32 v153, v119
	v_cvt_f32_i32_e32 v154, v120
	v_cvt_f32_i32_e32 v155, v121
	v_cvt_f32_i32_e32 v156, v114
	v_cvt_f32_i32_e32 v157, v115
	v_cvt_f32_i32_e32 v158, v116
	v_cvt_f32_i32_e32 v159, v117
	v_cvt_f32_i32_e32 v160, v94
	v_cvt_f32_i32_e32 v161, v95
	v_cvt_f32_i32_e32 v162, v96
	v_cvt_f32_i32_e32 v163, v97
	v_cvt_f32_i32_e32 v164, v86
	v_cvt_f32_i32_e32 v165, v87
	v_cvt_f32_i32_e32 v166, v88
	v_cvt_f32_i32_e32 v167, v89
	v_cvt_f32_i32_e32 v118, v106
	v_cvt_f32_i32_e32 v119, v107
	v_cvt_f32_i32_e32 v120, v108
	v_cvt_f32_i32_e32 v121, v109
	v_cvt_f32_i32_e32 v122, v98
	v_cvt_f32_i32_e32 v123, v99
	v_cvt_f32_i32_e32 v124, v100
	v_cvt_f32_i32_e32 v125, v101
	v_cvt_f32_i32_e32 v126, v78
	v_cvt_f32_i32_e32 v127, v79
	v_cvt_f32_i32_e32 v128, v80
	v_cvt_f32_i32_e32 v129, v81
	v_cvt_f32_i32_e32 v148, v74
	v_cvt_f32_i32_e32 v149, v75
	v_cvt_f32_i32_e32 v150, v76
	v_cvt_f32_i32_e32 v151, v77
	v_cvt_f32_i32_e32 v102, v90
	v_cvt_f32_i32_e32 v103, v91
	v_cvt_f32_i32_e32 v104, v92
	v_cvt_f32_i32_e32 v105, v93
	v_cvt_f32_i32_e32 v106, v82
	v_cvt_f32_i32_e32 v107, v83
	v_cvt_f32_i32_e32 v108, v84
	v_cvt_f32_i32_e32 v109, v85
	v_cvt_f32_i32_e32 v110, v70
	v_cvt_f32_i32_e32 v111, v71
	v_cvt_f32_i32_e32 v112, v72
	v_cvt_f32_i32_e32 v113, v73
	v_cvt_f32_i32_e32 v114, v66
	v_cvt_f32_i32_e32 v115, v67
	v_cvt_f32_i32_e32 v116, v68
	v_cvt_f32_i32_e32 v117, v69
	v_cvt_f32_i32_e32 v82, v62
	v_cvt_f32_i32_e32 v83, v63
	v_cvt_f32_i32_e32 v84, v64
	v_cvt_f32_i32_e32 v85, v65
	v_cvt_f32_i32_e32 v86, v58
	v_cvt_f32_i32_e32 v87, v59
	v_cvt_f32_i32_e32 v88, v60
	v_cvt_f32_i32_e32 v89, v61
	v_cvt_f32_i32_e32 v92, v46
	v_cvt_f32_i32_e32 v93, v47
	v_cvt_f32_i32_e32 v94, v48
	v_cvt_f32_i32_e32 v95, v49
	v_cvt_f32_i32_e32 v96, v38
	v_cvt_f32_i32_e32 v97, v39
	v_cvt_f32_i32_e32 v98, v40
	v_cvt_f32_i32_e32 v99, v41
	v_cvt_f32_i32_e32 v66, v54
	v_cvt_f32_i32_e32 v67, v55
	v_cvt_f32_i32_e32 v68, v56
	v_cvt_f32_i32_e32 v69, v57
	v_cvt_f32_i32_e32 v70, v50
	v_cvt_f32_i32_e32 v71, v51
	v_cvt_f32_i32_e32 v72, v52
	v_cvt_f32_i32_e32 v73, v53
	v_cvt_f32_i32_e32 v74, v30
	v_cvt_f32_i32_e32 v75, v31
	v_cvt_f32_i32_e32 v76, v32
	v_cvt_f32_i32_e32 v77, v33
	v_cvt_f32_i32_e32 v78, v22
	v_cvt_f32_i32_e32 v79, v23
	v_cvt_f32_i32_e32 v80, v24
	v_cvt_f32_i32_e32 v81, v25
	v_cvt_f32_i32_e32 v50, v42
	v_cvt_f32_i32_e32 v51, v43
	v_cvt_f32_i32_e32 v52, v44
	v_cvt_f32_i32_e32 v53, v45
	v_cvt_f32_i32_e32 v54, v34
	v_cvt_f32_i32_e32 v55, v35
	v_cvt_f32_i32_e32 v56, v36
	v_cvt_f32_i32_e32 v57, v37
	v_cvt_f32_i32_e32 v58, v14
	v_cvt_f32_i32_e32 v59, v15
	v_cvt_f32_i32_e32 v60, v16
	v_cvt_f32_i32_e32 v61, v17
	v_cvt_f32_i32_e32 v62, v10
	v_cvt_f32_i32_e32 v63, v11
	v_cvt_f32_i32_e32 v64, v12
	v_cvt_f32_i32_e32 v65, v13
	v_cvt_f32_i32_e32 v34, v26
	v_cvt_f32_i32_e32 v35, v27
	v_cvt_f32_i32_e32 v36, v28
	v_cvt_f32_i32_e32 v37, v29
	v_cvt_f32_i32_e32 v38, v18
	v_cvt_f32_i32_e32 v39, v19
	v_cvt_f32_i32_e32 v40, v20
	v_cvt_f32_i32_e32 v41, v21
	v_cvt_f32_i32_e32 v42, v6
	v_cvt_f32_i32_e32 v43, v7
	v_cvt_f32_i32_e32 v44, v8
	v_cvt_f32_i32_e32 v45, v9
	v_cvt_f32_i32_e32 v46, v2
	v_cvt_f32_i32_e32 v47, v3
	v_cvt_f32_i32_e32 v48, v4
	v_cvt_f32_i32_e32 v49, v5

.LBB0_2022:
	ds_read_b128 v[114:117], v209
	ds_read_b128 v[118:121], v209 offset:1024
	ds_read_b128 v[122:125], v209 offset:2048
	ds_read_b128 v[126:129], v209 offset:3072
	ds_read_b128 v[146:149], v210
	ds_read_b128 v[150:153], v210 offset:1024
	ds_read_b128 v[154:157], v210 offset:2048
	ds_read_b128 v[158:161], v210 offset:3072
	s_add_i32 s84, s36, 2
	s_add_u32 s37, s34, 0x4000
	s_addc_u32 s38, s35, 0
	s_cmp_eq_u32 s63, s36
	s_cselect_b32 s39, s5, s38
	s_cselect_b32 s38, s4, s37
	s_cselect_b32 s86, s30, s82
	s_cselect_b32 s87, s31, s83
	s_add_u32 s36, s38, 0x8000
	s_addc_u32 s37, s39, 0
	v_lshl_add_u64 v[218:219], s[34:35], 0, v[170:171]
	s_add_i32 m0, s47, 0xc000
	ds_read_b128 v[178:181], v211
	ds_read_b128 v[182:185], v211 offset:1024
	ds_read_b128 v[186:189], v211 offset:2048
	ds_read_b128 v[190:193], v211 offset:3072
	ds_read_b128 v[194:197], v211 offset:4096
	ds_read_b128 v[198:201], v211 offset:5120
	ds_read_b128 v[202:205], v211 offset:6144
	ds_read_b128 v[214:217], v211 offset:7168
	global_load_lds_dwordx4 v[218:219], off
	v_lshl_add_u64 v[218:219], s[34:35], 0, v[172:173]
	s_add_i32 m0, s47, 0xe000
	s_nop 0
	global_load_lds_dwordx4 v[218:219], off
	s_waitcnt vmcnt(8)
	s_waitcnt lgkmcnt(0)
	s_waitcnt lgkmcnt(0)
	v_mfma_f32_16x16x32_bf16 v[142:145], v[114:117], v[178:181], v[142:145]
	v_mfma_f32_16x16x32_bf16 v[138:141], v[122:125], v[178:181], v[138:141]
	s_barrier
	v_mfma_f32_16x16x32_bf16 v[110:113], v[114:117], v[186:189], v[110:113]
	v_mfma_f32_16x16x32_bf16 v[106:109], v[122:125], v[186:189], v[106:109]
	v_mfma_f32_16x16x32_bf16 v[94:97], v[114:117], v[194:197], v[94:97]
	v_mfma_f32_16x16x32_bf16 v[90:93], v[122:125], v[194:197], v[90:93]
	v_mfma_f32_16x16x32_bf16 v[78:81], v[114:117], v[202:205], v[78:81]
	v_mfma_f32_16x16x32_bf16 v[74:77], v[122:125], v[202:205], v[74:77]
	v_mfma_f32_16x16x32_bf16 v[142:145], v[118:121], v[182:185], v[142:145]
	v_mfma_f32_16x16x32_bf16 v[138:141], v[126:129], v[182:185], v[138:141]
	v_mfma_f32_16x16x32_bf16 v[110:113], v[118:121], v[190:193], v[110:113]
	v_mfma_f32_16x16x32_bf16 v[106:109], v[126:129], v[190:193], v[106:109]
	v_mfma_f32_16x16x32_bf16 v[94:97], v[118:121], v[198:201], v[94:97]
	v_mfma_f32_16x16x32_bf16 v[90:93], v[126:129], v[198:201], v[90:93]
	v_mfma_f32_16x16x32_bf16 v[78:81], v[118:121], v[214:217], v[78:81]
	v_mfma_f32_16x16x32_bf16 v[74:77], v[126:129], v[214:217], v[74:77]
	v_mfma_f32_16x16x32_bf16 v[134:137], v[146:149], v[178:181], v[134:137]
	v_mfma_f32_16x16x32_bf16 v[130:133], v[154:157], v[178:181], v[130:133]
	v_mfma_f32_16x16x32_bf16 v[102:105], v[146:149], v[186:189], v[102:105]
	v_mfma_f32_16x16x32_bf16 v[98:101], v[154:157], v[186:189], v[98:101]
	v_mfma_f32_16x16x32_bf16 v[86:89], v[146:149], v[194:197], v[86:89]
	v_mfma_f32_16x16x32_bf16 v[82:85], v[154:157], v[194:197], v[82:85]
	v_mfma_f32_16x16x32_bf16 v[70:73], v[146:149], v[202:205], v[70:73]
	v_mfma_f32_16x16x32_bf16 v[66:69], v[154:157], v[202:205], v[66:69]
	v_mfma_f32_16x16x32_bf16 v[134:137], v[150:153], v[182:185], v[134:137]
	v_mfma_f32_16x16x32_bf16 v[130:133], v[158:161], v[182:185], v[130:133]
	v_mfma_f32_16x16x32_bf16 v[102:105], v[150:153], v[190:193], v[102:105]
	v_mfma_f32_16x16x32_bf16 v[98:101], v[158:161], v[190:193], v[98:101]
	v_mfma_f32_16x16x32_bf16 v[86:89], v[150:153], v[198:201], v[86:89]
	v_mfma_f32_16x16x32_bf16 v[82:85], v[158:161], v[198:201], v[82:85]
	v_mfma_f32_16x16x32_bf16 v[70:73], v[150:153], v[214:217], v[70:73]
	v_mfma_f32_16x16x32_bf16 v[66:69], v[158:161], v[214:217], v[66:69]
	s_barrier
	s_add_i32 s85, s66, s46
	v_lshl_add_u64 v[218:219], s[86:87], 0, v[164:165]
	s_mov_b32 m0, s85
	ds_read_b128 v[178:181], v211 offset:16384
	ds_read_b128 v[182:185], v211 offset:17408
	ds_read_b128 v[186:189], v211 offset:18432
	ds_read_b128 v[190:193], v211 offset:19456
	ds_read_b128 v[194:197], v211 offset:20480
	ds_read_b128 v[198:201], v211 offset:21504
	ds_read_b128 v[202:205], v211 offset:22528
	ds_read_b128 v[214:217], v211 offset:23552
	global_load_lds_dwordx4 v[218:219], off
	s_add_i32 m0, s85, 0x2000
	v_lshl_add_u64 v[220:221], s[86:87], 0, v[168:169]
	s_add_u32 s86, s86, s8
	s_addc_u32 s87, s87, s9
	s_add_i32 s85, s67, s46
	global_load_lds_dwordx4 v[220:221], off
	v_lshl_add_u64 v[222:223], s[86:87], 0, v[164:165]
	s_mov_b32 m0, s85
	v_lshl_add_u64 v[224:225], s[86:87], 0, v[168:169]
	global_load_lds_dwordx4 v[222:223], off
	s_add_i32 m0, s85, 0x2000
	v_lshl_add_u64 v[226:227], s[38:39], 0, v[162:163]
	global_load_lds_dwordx4 v[224:225], off
	s_mov_b32 m0, s47
	s_nop 0
	global_load_lds_dwordx4 v[226:227], off
	v_lshl_add_u64 v[226:227], s[38:39], 0, v[166:167]
	s_mov_b32 m0, s50
	s_nop 0
	global_load_lds_dwordx4 v[226:227], off
	s_waitcnt vmcnt(8)
	s_waitcnt lgkmcnt(0)
	s_waitcnt lgkmcnt(0)
	v_mfma_f32_16x16x32_bf16 v[62:65], v[114:117], v[178:181], v[62:65]
	v_mfma_f32_16x16x32_bf16 v[58:61], v[122:125], v[178:181], v[58:61]
	s_barrier
	v_mfma_f32_16x16x32_bf16 v[46:49], v[114:117], v[186:189], v[46:49]
	v_mfma_f32_16x16x32_bf16 v[42:45], v[122:125], v[186:189], v[42:45]
	v_mfma_f32_16x16x32_bf16 v[30:33], v[114:117], v[194:197], v[30:33]
	v_mfma_f32_16x16x32_bf16 v[26:29], v[122:125], v[194:197], v[26:29]
	v_mfma_f32_16x16x32_bf16 v[14:17], v[114:117], v[202:205], v[14:17]
	v_mfma_f32_16x16x32_bf16 v[10:13], v[122:125], v[202:205], v[10:13]
	v_mfma_f32_16x16x32_bf16 v[62:65], v[118:121], v[182:185], v[62:65]
	v_mfma_f32_16x16x32_bf16 v[58:61], v[126:129], v[182:185], v[58:61]
	v_mfma_f32_16x16x32_bf16 v[46:49], v[118:121], v[190:193], v[46:49]
	v_mfma_f32_16x16x32_bf16 v[42:45], v[126:129], v[190:193], v[42:45]
	v_mfma_f32_16x16x32_bf16 v[30:33], v[118:121], v[198:201], v[30:33]
	v_mfma_f32_16x16x32_bf16 v[26:29], v[126:129], v[198:201], v[26:29]
	v_mfma_f32_16x16x32_bf16 v[14:17], v[118:121], v[214:217], v[14:17]
	v_mfma_f32_16x16x32_bf16 v[10:13], v[126:129], v[214:217], v[10:13]
	v_mfma_f32_16x16x32_bf16 v[54:57], v[146:149], v[178:181], v[54:57]
	v_mfma_f32_16x16x32_bf16 v[50:53], v[154:157], v[178:181], v[50:53]
	v_mfma_f32_16x16x32_bf16 v[38:41], v[146:149], v[186:189], v[38:41]
	v_mfma_f32_16x16x32_bf16 v[34:37], v[154:157], v[186:189], v[34:37]
	v_mfma_f32_16x16x32_bf16 v[22:25], v[146:149], v[194:197], v[22:25]
	v_mfma_f32_16x16x32_bf16 v[18:21], v[154:157], v[194:197], v[18:21]
	v_mfma_f32_16x16x32_bf16 v[6:9], v[146:149], v[202:205], v[6:9]
	v_mfma_f32_16x16x32_bf16 v[2:5], v[154:157], v[202:205], v[2:5]
	v_mfma_f32_16x16x32_bf16 v[54:57], v[150:153], v[182:185], v[54:57]
	v_mfma_f32_16x16x32_bf16 v[50:53], v[158:161], v[182:185], v[50:53]
	v_mfma_f32_16x16x32_bf16 v[38:41], v[150:153], v[190:193], v[38:41]
	v_mfma_f32_16x16x32_bf16 v[34:37], v[158:161], v[190:193], v[34:37]
	v_mfma_f32_16x16x32_bf16 v[22:25], v[150:153], v[198:201], v[22:25]
	v_mfma_f32_16x16x32_bf16 v[18:21], v[158:161], v[198:201], v[18:21]
	v_mfma_f32_16x16x32_bf16 v[6:9], v[150:153], v[214:217], v[6:9]
	v_mfma_f32_16x16x32_bf16 v[2:5], v[158:161], v[214:217], v[2:5]
	s_barrier
	s_add_i32 s85, 0, 0x18000
	s_add_i32 s86, 0, 0x1c000
	v_add_u32_e32 v126, s85, v207
	v_add_u32_e32 v158, s86, v207
	ds_read_b128 v[114:117], v126
	ds_read_b128 v[118:121], v126 offset:1024
	ds_read_b128 v[122:125], v126 offset:2048
	ds_read_b128 v[126:129], v126 offset:3072
	ds_read_b128 v[146:149], v158
	ds_read_b128 v[150:153], v158 offset:1024
	ds_read_b128 v[154:157], v158 offset:2048
	ds_read_b128 v[158:161], v158 offset:3072
	s_add_u32 s38, s38, 0x4000
	s_addc_u32 s39, s39, 0
	s_mov_b32 m0, s51
	v_lshl_add_u64 v[226:227], s[38:39], 0, v[162:163]
	ds_read_b128 v[178:181], v211 offset:32768
	ds_read_b128 v[182:185], v211 offset:33792
	ds_read_b128 v[186:189], v211 offset:34816
	ds_read_b128 v[190:193], v211 offset:35840
	ds_read_b128 v[194:197], v211 offset:36864
	ds_read_b128 v[198:201], v211 offset:37888
	ds_read_b128 v[202:205], v211 offset:38912
	ds_read_b128 v[214:217], v211 offset:39936
	global_load_lds_dwordx4 v[226:227], off
	v_lshl_add_u64 v[226:227], s[38:39], 0, v[166:167]
	s_mov_b32 m0, s54
	s_nop 0
	global_load_lds_dwordx4 v[226:227], off
	s_waitcnt vmcnt(8)
	s_waitcnt lgkmcnt(0)
	s_waitcnt lgkmcnt(0)
	v_mfma_f32_16x16x32_bf16 v[142:145], v[114:117], v[178:181], v[142:145]
	v_mfma_f32_16x16x32_bf16 v[138:141], v[122:125], v[178:181], v[138:141]
	s_barrier
	v_mfma_f32_16x16x32_bf16 v[110:113], v[114:117], v[186:189], v[110:113]
	v_mfma_f32_16x16x32_bf16 v[106:109], v[122:125], v[186:189], v[106:109]
	v_mfma_f32_16x16x32_bf16 v[94:97], v[114:117], v[194:197], v[94:97]
	v_mfma_f32_16x16x32_bf16 v[90:93], v[122:125], v[194:197], v[90:93]
	v_mfma_f32_16x16x32_bf16 v[78:81], v[114:117], v[202:205], v[78:81]
	v_mfma_f32_16x16x32_bf16 v[74:77], v[122:125], v[202:205], v[74:77]
	v_mfma_f32_16x16x32_bf16 v[142:145], v[118:121], v[182:185], v[142:145]
	v_mfma_f32_16x16x32_bf16 v[138:141], v[126:129], v[182:185], v[138:141]
	v_mfma_f32_16x16x32_bf16 v[110:113], v[118:121], v[190:193], v[110:113]
	v_mfma_f32_16x16x32_bf16 v[106:109], v[126:129], v[190:193], v[106:109]
	v_mfma_f32_16x16x32_bf16 v[94:97], v[118:121], v[198:201], v[94:97]
	v_mfma_f32_16x16x32_bf16 v[90:93], v[126:129], v[198:201], v[90:93]
	v_mfma_f32_16x16x32_bf16 v[78:81], v[118:121], v[214:217], v[78:81]
	v_mfma_f32_16x16x32_bf16 v[74:77], v[126:129], v[214:217], v[74:77]
	v_mfma_f32_16x16x32_bf16 v[134:137], v[146:149], v[178:181], v[134:137]
	v_mfma_f32_16x16x32_bf16 v[130:133], v[154:157], v[178:181], v[130:133]
	v_mfma_f32_16x16x32_bf16 v[102:105], v[146:149], v[186:189], v[102:105]
	v_mfma_f32_16x16x32_bf16 v[98:101], v[154:157], v[186:189], v[98:101]
	v_mfma_f32_16x16x32_bf16 v[86:89], v[146:149], v[194:197], v[86:89]
	v_mfma_f32_16x16x32_bf16 v[82:85], v[154:157], v[194:197], v[82:85]
	v_mfma_f32_16x16x32_bf16 v[70:73], v[146:149], v[202:205], v[70:73]
	v_mfma_f32_16x16x32_bf16 v[66:69], v[154:157], v[202:205], v[66:69]
	v_mfma_f32_16x16x32_bf16 v[134:137], v[150:153], v[182:185], v[134:137]
	v_mfma_f32_16x16x32_bf16 v[130:133], v[158:161], v[182:185], v[130:133]
	v_mfma_f32_16x16x32_bf16 v[102:105], v[150:153], v[190:193], v[102:105]
	v_mfma_f32_16x16x32_bf16 v[98:101], v[158:161], v[190:193], v[98:101]
	v_mfma_f32_16x16x32_bf16 v[86:89], v[150:153], v[198:201], v[86:89]
	v_mfma_f32_16x16x32_bf16 v[82:85], v[158:161], v[198:201], v[82:85]
	v_mfma_f32_16x16x32_bf16 v[70:73], v[150:153], v[214:217], v[70:73]
	v_mfma_f32_16x16x32_bf16 v[66:69], v[158:161], v[214:217], v[66:69]
	s_barrier
	s_add_i32 s38, s85, s46
	v_lshl_add_u64 v[218:219], v[218:219], 0, s[24:25]
	s_mov_b32 m0, s38
	ds_read_b128 v[178:181], v211 offset:49152
	ds_read_b128 v[182:185], v211 offset:50176
	ds_read_b128 v[186:189], v211 offset:51200
	ds_read_b128 v[190:193], v211 offset:52224
	ds_read_b128 v[194:197], v211 offset:53248
	ds_read_b128 v[198:201], v211 offset:54272
	ds_read_b128 v[202:205], v211 offset:55296
	ds_read_b128 v[214:217], v211 offset:56320
	global_load_lds_dwordx4 v[218:219], off
	v_lshl_add_u64 v[218:219], v[220:221], 0, s[24:25]
	s_add_i32 m0, s38, 0x2000
	s_add_i32 s38, s86, s46
	global_load_lds_dwordx4 v[218:219], off
	v_lshl_add_u64 v[218:219], v[222:223], 0, s[24:25]
	s_mov_b32 m0, s38
	s_nop 0
	global_load_lds_dwordx4 v[218:219], off
	v_lshl_add_u64 v[218:219], v[224:225], 0, s[24:25]
	s_add_i32 m0, s38, 0x2000
	s_nop 0
	global_load_lds_dwordx4 v[218:219], off
	v_lshl_add_u64 v[218:219], s[36:37], 0, v[162:163]
	s_mov_b32 m0, s61
	s_nop 0
	global_load_lds_dwordx4 v[218:219], off
	v_lshl_add_u64 v[218:219], s[36:37], 0, v[166:167]
	s_mov_b32 m0, s62
	s_nop 0
	global_load_lds_dwordx4 v[218:219], off
	s_waitcnt vmcnt(8)
	s_waitcnt lgkmcnt(0)
	s_waitcnt lgkmcnt(0)
	v_mfma_f32_16x16x32_bf16 v[62:65], v[114:117], v[178:181], v[62:65]
	v_mfma_f32_16x16x32_bf16 v[58:61], v[122:125], v[178:181], v[58:61]
	s_barrier
	v_mfma_f32_16x16x32_bf16 v[46:49], v[114:117], v[186:189], v[46:49]
	v_mfma_f32_16x16x32_bf16 v[42:45], v[122:125], v[186:189], v[42:45]
	v_mfma_f32_16x16x32_bf16 v[30:33], v[114:117], v[194:197], v[30:33]
	v_mfma_f32_16x16x32_bf16 v[26:29], v[122:125], v[194:197], v[26:29]
	v_mfma_f32_16x16x32_bf16 v[14:17], v[114:117], v[202:205], v[14:17]
	v_mfma_f32_16x16x32_bf16 v[10:13], v[122:125], v[202:205], v[10:13]
	v_mfma_f32_16x16x32_bf16 v[62:65], v[118:121], v[182:185], v[62:65]
	v_mfma_f32_16x16x32_bf16 v[58:61], v[126:129], v[182:185], v[58:61]
	v_mfma_f32_16x16x32_bf16 v[46:49], v[118:121], v[190:193], v[46:49]
	v_mfma_f32_16x16x32_bf16 v[42:45], v[126:129], v[190:193], v[42:45]
	v_mfma_f32_16x16x32_bf16 v[30:33], v[118:121], v[198:201], v[30:33]
	v_mfma_f32_16x16x32_bf16 v[26:29], v[126:129], v[198:201], v[26:29]
	v_mfma_f32_16x16x32_bf16 v[14:17], v[118:121], v[214:217], v[14:17]
	v_mfma_f32_16x16x32_bf16 v[10:13], v[126:129], v[214:217], v[10:13]
	v_mfma_f32_16x16x32_bf16 v[54:57], v[146:149], v[178:181], v[54:57]
	v_mfma_f32_16x16x32_bf16 v[50:53], v[154:157], v[178:181], v[50:53]
	v_mfma_f32_16x16x32_bf16 v[38:41], v[146:149], v[186:189], v[38:41]
	v_mfma_f32_16x16x32_bf16 v[34:37], v[154:157], v[186:189], v[34:37]
	v_mfma_f32_16x16x32_bf16 v[22:25], v[146:149], v[194:197], v[22:25]
	v_mfma_f32_16x16x32_bf16 v[18:21], v[154:157], v[194:197], v[18:21]
	v_mfma_f32_16x16x32_bf16 v[6:9], v[146:149], v[202:205], v[6:9]
	v_mfma_f32_16x16x32_bf16 v[2:5], v[154:157], v[202:205], v[2:5]
	v_mfma_f32_16x16x32_bf16 v[54:57], v[150:153], v[182:185], v[54:57]
	v_mfma_f32_16x16x32_bf16 v[50:53], v[158:161], v[182:185], v[50:53]
	v_mfma_f32_16x16x32_bf16 v[38:41], v[150:153], v[190:193], v[38:41]
	v_mfma_f32_16x16x32_bf16 v[34:37], v[158:161], v[190:193], v[34:37]
	v_mfma_f32_16x16x32_bf16 v[22:25], v[150:153], v[198:201], v[22:25]
	v_mfma_f32_16x16x32_bf16 v[18:21], v[158:161], v[198:201], v[18:21]
	v_mfma_f32_16x16x32_bf16 v[6:9], v[150:153], v[214:217], v[6:9]
	v_mfma_f32_16x16x32_bf16 v[2:5], v[158:161], v[214:217], v[2:5]
	s_barrier
	s_add_u32 s82, s82, 0x100
	s_addc_u32 s83, s83, 0
	s_add_u32 s34, s34, 0x10000
	s_addc_u32 s35, s35, 0
	s_cmp_ge_i32 s84, s60
	s_mov_b32 s36, s84
	s_cbranch_scc0 .LBB0_2022

.LBB0_2116:
	ds_read_b128 v[34:37], v186
	ds_read_b128 v[38:41], v186 offset:1024
	ds_read_b128 v[50:53], v186 offset:2048
	ds_read_b128 v[54:57], v186 offset:3072
	ds_read_b128 v[168:171], v187
	ds_read_b128 v[172:175], v187 offset:1024
	ds_read_b128 v[176:179], v187 offset:2048
	ds_read_b128 v[192:195], v187 offset:3072
	s_add_i32 s47, s4, 2
	s_add_u32 s50, s2, 0x80
	s_addc_u32 s5, s3, 0
	s_cmp_eq_u32 s85, s4
	s_cselect_b32 s4, s42, s50
	s_cselect_b32 s5, s43, s5
	s_cselect_b32 s51, s45, s7
	s_cselect_b32 s50, s44, s6
	v_lshl_add_u64 v[228:229], s[2:3], 0, v[160:161]
	s_add_i32 m0, s65, 0xc000
	ds_read_b128 v[196:199], v188
	ds_read_b128 v[200:203], v188 offset:1024
	ds_read_b128 v[204:207], v188 offset:2048
	ds_read_b128 v[208:211], v188 offset:3072
	ds_read_b128 v[212:215], v188 offset:4096
	ds_read_b128 v[216:219], v188 offset:5120
	ds_read_b128 v[220:223], v188 offset:6144
	ds_read_b128 v[224:227], v188 offset:7168
	global_load_lds_dwordx4 v[228:229], off
	v_lshl_add_u64 v[228:229], s[2:3], 0, v[162:163]
	s_add_i32 m0, s65, 0xe000
	s_nop 0
	global_load_lds_dwordx4 v[228:229], off
	s_waitcnt vmcnt(8)
	s_waitcnt lgkmcnt(0)
	s_waitcnt lgkmcnt(0)
	v_mfma_f32_16x16x32_bf16 v[142:145], v[34:37], v[196:199], v[142:145]
	v_mfma_f32_16x16x32_bf16 v[138:141], v[50:53], v[196:199], v[138:141]
	s_barrier
	v_mfma_f32_16x16x32_bf16 v[126:129], v[34:37], v[204:207], v[126:129]
	v_mfma_f32_16x16x32_bf16 v[122:125], v[50:53], v[204:207], v[122:125]
	v_mfma_f32_16x16x32_bf16 v[110:113], v[34:37], v[212:215], v[110:113]
	v_mfma_f32_16x16x32_bf16 v[106:109], v[50:53], v[212:215], v[106:109]
	v_mfma_f32_16x16x32_bf16 v[94:97], v[34:37], v[220:223], v[94:97]
	v_mfma_f32_16x16x32_bf16 v[90:93], v[50:53], v[220:223], v[90:93]
	v_mfma_f32_16x16x32_bf16 v[142:145], v[38:41], v[200:203], v[142:145]
	v_mfma_f32_16x16x32_bf16 v[138:141], v[54:57], v[200:203], v[138:141]
	v_mfma_f32_16x16x32_bf16 v[126:129], v[38:41], v[208:211], v[126:129]
	v_mfma_f32_16x16x32_bf16 v[122:125], v[54:57], v[208:211], v[122:125]
	v_mfma_f32_16x16x32_bf16 v[110:113], v[38:41], v[216:219], v[110:113]
	v_mfma_f32_16x16x32_bf16 v[106:109], v[54:57], v[216:219], v[106:109]
	v_mfma_f32_16x16x32_bf16 v[94:97], v[38:41], v[224:227], v[94:97]
	v_mfma_f32_16x16x32_bf16 v[90:93], v[54:57], v[224:227], v[90:93]
	v_mfma_f32_16x16x32_bf16 v[134:137], v[168:171], v[196:199], v[134:137]
	v_mfma_f32_16x16x32_bf16 v[130:133], v[176:179], v[196:199], v[130:133]
	v_mfma_f32_16x16x32_bf16 v[118:121], v[168:171], v[204:207], v[118:121]
	v_mfma_f32_16x16x32_bf16 v[114:117], v[176:179], v[204:207], v[114:117]
	v_mfma_f32_16x16x32_bf16 v[102:105], v[168:171], v[212:215], v[102:105]
	v_mfma_f32_16x16x32_bf16 v[98:101], v[176:179], v[212:215], v[98:101]
	v_mfma_f32_16x16x32_bf16 v[86:89], v[168:171], v[220:223], v[86:89]
	v_mfma_f32_16x16x32_bf16 v[82:85], v[176:179], v[220:223], v[82:85]
	v_mfma_f32_16x16x32_bf16 v[134:137], v[172:175], v[200:203], v[134:137]
	v_mfma_f32_16x16x32_bf16 v[130:133], v[192:195], v[200:203], v[130:133]
	v_mfma_f32_16x16x32_bf16 v[118:121], v[172:175], v[208:211], v[118:121]
	v_mfma_f32_16x16x32_bf16 v[114:117], v[192:195], v[208:211], v[114:117]
	v_mfma_f32_16x16x32_bf16 v[102:105], v[172:175], v[216:219], v[102:105]
	v_mfma_f32_16x16x32_bf16 v[98:101], v[192:195], v[216:219], v[98:101]
	v_mfma_f32_16x16x32_bf16 v[86:89], v[172:175], v[224:227], v[86:89]
	v_mfma_f32_16x16x32_bf16 v[82:85], v[192:195], v[224:227], v[82:85]
	s_barrier
	s_add_i32 s55, s88, s62
	v_lshl_add_u64 v[228:229], s[50:51], 0, v[148:149]
	s_mov_b32 m0, s55
	ds_read_b128 v[196:199], v188 offset:16384
	ds_read_b128 v[200:203], v188 offset:17408
	ds_read_b128 v[204:207], v188 offset:18432
	ds_read_b128 v[208:211], v188 offset:19456
	ds_read_b128 v[212:215], v188 offset:20480
	ds_read_b128 v[216:219], v188 offset:21504
	ds_read_b128 v[220:223], v188 offset:22528
	ds_read_b128 v[224:227], v188 offset:23552
	global_load_lds_dwordx4 v[228:229], off
	s_add_i32 m0, s55, 0x2000
	v_lshl_add_u64 v[230:231], s[50:51], 0, v[152:153]
	s_add_u32 s50, s50, s14
	s_addc_u32 s51, s51, s15
	s_add_i32 s55, s89, s62
	global_load_lds_dwordx4 v[230:231], off
	v_lshl_add_u64 v[232:233], s[50:51], 0, v[148:149]
	s_mov_b32 m0, s55
	v_lshl_add_u64 v[234:235], s[50:51], 0, v[152:153]
	global_load_lds_dwordx4 v[232:233], off
	s_add_i32 m0, s55, 0x2000
	v_lshl_add_u64 v[236:237], s[4:5], 0, v[146:147]
	global_load_lds_dwordx4 v[234:235], off
	s_mov_b32 m0, s65
	v_lshl_add_u64 v[238:239], s[4:5], 0, v[150:151]
	global_load_lds_dwordx4 v[236:237], off
	s_mov_b32 m0, s66
	s_nop 0
	global_load_lds_dwordx4 v[238:239], off
	s_waitcnt vmcnt(8)
	s_waitcnt lgkmcnt(0)
	s_waitcnt lgkmcnt(0)
	v_mfma_f32_16x16x32_bf16 v[78:81], v[34:37], v[196:199], v[78:81]
	v_mfma_f32_16x16x32_bf16 v[74:77], v[50:53], v[196:199], v[74:77]
	s_barrier
	v_mfma_f32_16x16x32_bf16 v[62:65], v[34:37], v[204:207], v[62:65]
	v_mfma_f32_16x16x32_bf16 v[58:61], v[50:53], v[204:207], v[58:61]
	v_mfma_f32_16x16x32_bf16 v[30:33], v[34:37], v[212:215], v[30:33]
	v_mfma_f32_16x16x32_bf16 v[26:29], v[50:53], v[212:215], v[26:29]
	v_mfma_f32_16x16x32_bf16 v[14:17], v[34:37], v[220:223], v[14:17]
	v_mfma_f32_16x16x32_bf16 v[10:13], v[50:53], v[220:223], v[10:13]
	v_mfma_f32_16x16x32_bf16 v[78:81], v[38:41], v[200:203], v[78:81]
	v_mfma_f32_16x16x32_bf16 v[74:77], v[54:57], v[200:203], v[74:77]
	v_mfma_f32_16x16x32_bf16 v[62:65], v[38:41], v[208:211], v[62:65]
	v_mfma_f32_16x16x32_bf16 v[58:61], v[54:57], v[208:211], v[58:61]
	v_mfma_f32_16x16x32_bf16 v[30:33], v[38:41], v[216:219], v[30:33]
	v_mfma_f32_16x16x32_bf16 v[26:29], v[54:57], v[216:219], v[26:29]
	v_mfma_f32_16x16x32_bf16 v[14:17], v[38:41], v[224:227], v[14:17]
	v_mfma_f32_16x16x32_bf16 v[10:13], v[54:57], v[224:227], v[10:13]
	v_mfma_f32_16x16x32_bf16 v[46:49], v[168:171], v[204:207], v[46:49]
	v_mfma_f32_16x16x32_bf16 v[42:45], v[176:179], v[204:207], v[42:45]
	v_mfma_f32_16x16x32_bf16 v[22:25], v[168:171], v[212:215], v[22:25]
	v_mfma_f32_16x16x32_bf16 v[18:21], v[176:179], v[212:215], v[18:21]
	v_mfma_f32_16x16x32_bf16 v[6:9], v[168:171], v[220:223], v[6:9]
	v_mfma_f32_16x16x32_bf16 v[2:5], v[176:179], v[220:223], v[2:5]
	v_mfma_f32_16x16x32_bf16 v[34:37], v[168:171], v[196:199], v[70:73]
	v_mfma_f32_16x16x32_bf16 v[38:41], v[176:179], v[196:199], v[66:69]
	v_mfma_f32_16x16x32_bf16 v[46:49], v[172:175], v[208:211], v[46:49]
	v_mfma_f32_16x16x32_bf16 v[42:45], v[192:195], v[208:211], v[42:45]
	v_mfma_f32_16x16x32_bf16 v[22:25], v[172:175], v[216:219], v[22:25]
	v_mfma_f32_16x16x32_bf16 v[18:21], v[192:195], v[216:219], v[18:21]
	v_mfma_f32_16x16x32_bf16 v[6:9], v[172:175], v[224:227], v[6:9]
	v_mfma_f32_16x16x32_bf16 v[2:5], v[192:195], v[224:227], v[2:5]
	v_mfma_f32_16x16x32_bf16 v[34:37], v[172:175], v[200:203], v[34:37]
	v_mfma_f32_16x16x32_bf16 v[38:41], v[192:195], v[200:203], v[38:41]
	s_barrier
	s_add_i32 s50, 0, 0x18000
	s_add_i32 s51, 0, 0x1c000
	v_add_u32_e32 v70, s50, v184
	v_add_u32_e32 v154, s51, v184
	ds_read_b128 v[50:53], v70
	ds_read_b128 v[54:57], v70 offset:1024
	ds_read_b128 v[66:69], v70 offset:2048
	ds_read_b128 v[70:73], v70 offset:3072
	ds_read_b128 v[168:171], v154
	ds_read_b128 v[172:175], v154 offset:1024
	ds_read_b128 v[176:179], v154 offset:2048
	ds_read_b128 v[192:195], v154 offset:3072
	s_add_u32 s4, s4, s14
	s_addc_u32 s5, s5, s15
	s_mov_b32 m0, s67
	v_lshl_add_u64 v[240:241], s[4:5], 0, v[146:147]
	ds_read_b128 v[196:199], v188 offset:32768
	ds_read_b128 v[200:203], v188 offset:33792
	ds_read_b128 v[204:207], v188 offset:34816
	ds_read_b128 v[208:211], v188 offset:35840
	ds_read_b128 v[212:215], v188 offset:36864
	ds_read_b128 v[216:219], v188 offset:37888
	ds_read_b128 v[220:223], v188 offset:38912
	ds_read_b128 v[224:227], v188 offset:39936
	global_load_lds_dwordx4 v[240:241], off
	v_lshl_add_u64 v[240:241], s[4:5], 0, v[150:151]
	s_mov_b32 m0, s68
	s_nop 0
	global_load_lds_dwordx4 v[240:241], off
	s_waitcnt vmcnt(8)
	s_waitcnt lgkmcnt(0)
	s_waitcnt lgkmcnt(0)
	v_mfma_f32_16x16x32_bf16 v[142:145], v[50:53], v[196:199], v[142:145]
	v_mfma_f32_16x16x32_bf16 v[138:141], v[66:69], v[196:199], v[138:141]
	s_barrier
	v_mfma_f32_16x16x32_bf16 v[126:129], v[50:53], v[204:207], v[126:129]
	v_mfma_f32_16x16x32_bf16 v[122:125], v[66:69], v[204:207], v[122:125]
	v_mfma_f32_16x16x32_bf16 v[110:113], v[50:53], v[212:215], v[110:113]
	v_mfma_f32_16x16x32_bf16 v[106:109], v[66:69], v[212:215], v[106:109]
	v_mfma_f32_16x16x32_bf16 v[94:97], v[50:53], v[220:223], v[94:97]
	v_mfma_f32_16x16x32_bf16 v[90:93], v[66:69], v[220:223], v[90:93]
	v_mfma_f32_16x16x32_bf16 v[142:145], v[54:57], v[200:203], v[142:145]
	v_mfma_f32_16x16x32_bf16 v[138:141], v[70:73], v[200:203], v[138:141]
	v_mfma_f32_16x16x32_bf16 v[126:129], v[54:57], v[208:211], v[126:129]
	v_mfma_f32_16x16x32_bf16 v[122:125], v[70:73], v[208:211], v[122:125]
	v_mfma_f32_16x16x32_bf16 v[110:113], v[54:57], v[216:219], v[110:113]
	v_mfma_f32_16x16x32_bf16 v[106:109], v[70:73], v[216:219], v[106:109]
	v_mfma_f32_16x16x32_bf16 v[94:97], v[54:57], v[224:227], v[94:97]
	v_mfma_f32_16x16x32_bf16 v[90:93], v[70:73], v[224:227], v[90:93]
	v_mfma_f32_16x16x32_bf16 v[134:137], v[168:171], v[196:199], v[134:137]
	v_mfma_f32_16x16x32_bf16 v[130:133], v[176:179], v[196:199], v[130:133]
	v_mfma_f32_16x16x32_bf16 v[118:121], v[168:171], v[204:207], v[118:121]
	v_mfma_f32_16x16x32_bf16 v[114:117], v[176:179], v[204:207], v[114:117]
	v_mfma_f32_16x16x32_bf16 v[102:105], v[168:171], v[212:215], v[102:105]
	v_mfma_f32_16x16x32_bf16 v[98:101], v[176:179], v[212:215], v[98:101]
	v_mfma_f32_16x16x32_bf16 v[86:89], v[168:171], v[220:223], v[86:89]
	v_mfma_f32_16x16x32_bf16 v[82:85], v[176:179], v[220:223], v[82:85]
	v_mfma_f32_16x16x32_bf16 v[134:137], v[172:175], v[200:203], v[134:137]
	v_mfma_f32_16x16x32_bf16 v[130:133], v[192:195], v[200:203], v[130:133]
	v_mfma_f32_16x16x32_bf16 v[118:121], v[172:175], v[208:211], v[118:121]
	v_mfma_f32_16x16x32_bf16 v[114:117], v[192:195], v[208:211], v[114:117]
	v_mfma_f32_16x16x32_bf16 v[102:105], v[172:175], v[216:219], v[102:105]
	v_mfma_f32_16x16x32_bf16 v[98:101], v[192:195], v[216:219], v[98:101]
	v_mfma_f32_16x16x32_bf16 v[86:89], v[172:175], v[224:227], v[86:89]
	v_mfma_f32_16x16x32_bf16 v[82:85], v[192:195], v[224:227], v[82:85]
	s_barrier
	s_add_i32 s4, s50, s62
	v_lshl_add_u64 v[228:229], v[228:229], 0, s[28:29]
	s_mov_b32 m0, s4
	ds_read_b128 v[196:199], v188 offset:49152
	ds_read_b128 v[200:203], v188 offset:50176
	ds_read_b128 v[204:207], v188 offset:51200
	ds_read_b128 v[208:211], v188 offset:52224
	ds_read_b128 v[212:215], v188 offset:53248
	ds_read_b128 v[216:219], v188 offset:54272
	ds_read_b128 v[220:223], v188 offset:55296
	ds_read_b128 v[224:227], v188 offset:56320
	global_load_lds_dwordx4 v[228:229], off
	v_lshl_add_u64 v[228:229], v[230:231], 0, s[28:29]
	s_add_i32 m0, s4, 0x2000
	s_add_i32 s4, s51, s62
	global_load_lds_dwordx4 v[228:229], off
	v_lshl_add_u64 v[228:229], v[232:233], 0, s[28:29]
	s_mov_b32 m0, s4
	s_nop 0
	global_load_lds_dwordx4 v[228:229], off
	v_lshl_add_u64 v[228:229], v[234:235], 0, s[28:29]
	s_add_i32 m0, s4, 0x2000
	s_nop 0
	global_load_lds_dwordx4 v[228:229], off
	v_lshl_add_u64 v[228:229], v[236:237], 0, s[28:29]
	s_mov_b32 m0, s82
	s_nop 0
	global_load_lds_dwordx4 v[228:229], off
	v_lshl_add_u64 v[228:229], v[238:239], 0, s[28:29]
	s_mov_b32 m0, s83
	s_nop 0
	global_load_lds_dwordx4 v[228:229], off
	s_waitcnt vmcnt(8)
	s_waitcnt lgkmcnt(0)
	s_waitcnt lgkmcnt(0)
	v_mfma_f32_16x16x32_bf16 v[78:81], v[50:53], v[196:199], v[78:81]
	v_mfma_f32_16x16x32_bf16 v[74:77], v[66:69], v[196:199], v[74:77]
	s_barrier
	v_mfma_f32_16x16x32_bf16 v[62:65], v[50:53], v[204:207], v[62:65]
	v_mfma_f32_16x16x32_bf16 v[58:61], v[66:69], v[204:207], v[58:61]
	v_mfma_f32_16x16x32_bf16 v[30:33], v[50:53], v[212:215], v[30:33]
	v_mfma_f32_16x16x32_bf16 v[26:29], v[66:69], v[212:215], v[26:29]
	v_mfma_f32_16x16x32_bf16 v[14:17], v[50:53], v[220:223], v[14:17]
	v_mfma_f32_16x16x32_bf16 v[10:13], v[66:69], v[220:223], v[10:13]
	v_mfma_f32_16x16x32_bf16 v[78:81], v[54:57], v[200:203], v[78:81]
	v_mfma_f32_16x16x32_bf16 v[74:77], v[70:73], v[200:203], v[74:77]
	v_mfma_f32_16x16x32_bf16 v[62:65], v[54:57], v[208:211], v[62:65]
	v_mfma_f32_16x16x32_bf16 v[58:61], v[70:73], v[208:211], v[58:61]
	v_mfma_f32_16x16x32_bf16 v[30:33], v[54:57], v[216:219], v[30:33]
	v_mfma_f32_16x16x32_bf16 v[26:29], v[70:73], v[216:219], v[26:29]
	v_mfma_f32_16x16x32_bf16 v[14:17], v[54:57], v[224:227], v[14:17]
	v_mfma_f32_16x16x32_bf16 v[10:13], v[70:73], v[224:227], v[10:13]
	v_mfma_f32_16x16x32_bf16 v[34:37], v[168:171], v[196:199], v[34:37]
	v_mfma_f32_16x16x32_bf16 v[70:73], v[172:175], v[200:203], v[34:37]
	v_mfma_f32_16x16x32_bf16 v[34:37], v[176:179], v[196:199], v[38:41]
	v_mfma_f32_16x16x32_bf16 v[66:69], v[192:195], v[200:203], v[34:37]
	v_mfma_f32_16x16x32_bf16 v[34:37], v[168:171], v[204:207], v[46:49]
	v_mfma_f32_16x16x32_bf16 v[46:49], v[172:175], v[208:211], v[34:37]
	v_mfma_f32_16x16x32_bf16 v[34:37], v[176:179], v[204:207], v[42:45]
	v_mfma_f32_16x16x32_bf16 v[22:25], v[168:171], v[212:215], v[22:25]
	v_mfma_f32_16x16x32_bf16 v[18:21], v[176:179], v[212:215], v[18:21]
	v_mfma_f32_16x16x32_bf16 v[6:9], v[168:171], v[220:223], v[6:9]
	v_mfma_f32_16x16x32_bf16 v[2:5], v[176:179], v[220:223], v[2:5]
	v_mfma_f32_16x16x32_bf16 v[42:45], v[192:195], v[208:211], v[34:37]
	v_mfma_f32_16x16x32_bf16 v[22:25], v[172:175], v[216:219], v[22:25]
	v_mfma_f32_16x16x32_bf16 v[18:21], v[192:195], v[216:219], v[18:21]
	v_mfma_f32_16x16x32_bf16 v[6:9], v[172:175], v[224:227], v[6:9]
	v_mfma_f32_16x16x32_bf16 v[2:5], v[192:195], v[224:227], v[2:5]
	s_barrier
	s_add_u32 s2, s2, 0x100
	s_addc_u32 s3, s3, 0
	s_add_u32 s6, s6, 0x100
	s_addc_u32 s7, s7, 0
	s_cmp_ge_i32 s47, s84
	s_mov_b32 s4, s47
	s_cbranch_scc0 .LBB0_2116

.LBB0_2764:
	v_add_u32_e32 v158, s68, v229
	v_add_u32_e32 v174, s69, v229
	ds_read_b128 v[146:149], v158
	ds_read_b128 v[150:153], v158 offset:1024
	ds_read_b128 v[154:157], v158 offset:2048
	ds_read_b128 v[158:161], v158 offset:3072
	ds_read_b128 v[162:165], v174
	ds_read_b128 v[166:169], v174 offset:1024
	ds_read_b128 v[170:173], v174 offset:2048
	ds_read_b128 v[174:177], v174 offset:3072
	s_add_i32 s84, s42, 2
	s_add_u32 s85, s40, 0x80
	s_addc_u32 s43, s41, 0
	s_cmp_eq_u32 s65, s42
	s_cselect_b32 s42, s4, s85
	s_cselect_b32 s43, s5, s43
	s_cselect_b32 s87, s39, s83
	s_cselect_b32 s86, s38, s82
	v_lshl_add_u64 v[210:211], s[40:41], 0, v[138:139]
	s_add_i32 m0, s51, 0xc000
	ds_read_b128 v[178:181], v231
	ds_read_b128 v[182:185], v231 offset:1024
	ds_read_b128 v[186:189], v231 offset:2048
	ds_read_b128 v[190:193], v231 offset:3072
	ds_read_b128 v[194:197], v231 offset:4096
	ds_read_b128 v[198:201], v231 offset:5120
	ds_read_b128 v[202:205], v231 offset:6144
	ds_read_b128 v[206:209], v231 offset:7168
	global_load_lds_dwordx4 v[210:211], off
	v_lshl_add_u64 v[210:211], s[40:41], 0, v[140:141]
	s_add_i32 m0, s51, 0xe000
	s_nop 0
	global_load_lds_dwordx4 v[210:211], off
	s_waitcnt vmcnt(8)
	s_waitcnt lgkmcnt(0)
	s_waitcnt lgkmcnt(0)
	v_mfma_i32_16x16x64_i8 v[126:129], v[146:149], v[178:181], v[126:129]
	v_mfma_i32_16x16x64_i8 v[122:125], v[154:157], v[178:181], v[122:125]
	s_barrier
	v_mfma_i32_16x16x64_i8 v[118:121], v[146:149], v[186:189], v[118:121]
	v_mfma_i32_16x16x64_i8 v[114:117], v[154:157], v[186:189], v[114:117]
	v_mfma_i32_16x16x64_i8 v[106:109], v[146:149], v[194:197], v[106:109]
	v_mfma_i32_16x16x64_i8 v[98:101], v[154:157], v[194:197], v[98:101]
	v_mfma_i32_16x16x64_i8 v[90:93], v[146:149], v[202:205], v[90:93]
	v_mfma_i32_16x16x64_i8 v[82:85], v[154:157], v[202:205], v[82:85]
	v_mfma_i32_16x16x64_i8 v[126:129], v[150:153], v[182:185], v[126:129]
	v_mfma_i32_16x16x64_i8 v[122:125], v[158:161], v[182:185], v[122:125]
	v_mfma_i32_16x16x64_i8 v[118:121], v[150:153], v[190:193], v[118:121]
	v_mfma_i32_16x16x64_i8 v[114:117], v[158:161], v[190:193], v[114:117]
	v_mfma_i32_16x16x64_i8 v[106:109], v[150:153], v[198:201], v[106:109]
	v_mfma_i32_16x16x64_i8 v[98:101], v[158:161], v[198:201], v[98:101]
	v_mfma_i32_16x16x64_i8 v[90:93], v[150:153], v[206:209], v[90:93]
	v_mfma_i32_16x16x64_i8 v[82:85], v[158:161], v[206:209], v[82:85]
	v_mfma_i32_16x16x64_i8 v[110:113], v[162:165], v[178:181], v[110:113]
	v_mfma_i32_16x16x64_i8 v[102:105], v[170:173], v[178:181], v[102:105]
	v_mfma_i32_16x16x64_i8 v[94:97], v[162:165], v[186:189], v[94:97]
	v_mfma_i32_16x16x64_i8 v[86:89], v[170:173], v[186:189], v[86:89]
	v_mfma_i32_16x16x64_i8 v[78:81], v[162:165], v[194:197], v[78:81]
	v_mfma_i32_16x16x64_i8 v[74:77], v[170:173], v[194:197], v[74:77]
	v_mfma_i32_16x16x64_i8 v[70:73], v[162:165], v[202:205], v[70:73]
	v_mfma_i32_16x16x64_i8 v[66:69], v[170:173], v[202:205], v[66:69]
	v_mfma_i32_16x16x64_i8 v[110:113], v[166:169], v[182:185], v[110:113]
	v_mfma_i32_16x16x64_i8 v[102:105], v[174:177], v[182:185], v[102:105]
	v_mfma_i32_16x16x64_i8 v[94:97], v[166:169], v[190:193], v[94:97]
	v_mfma_i32_16x16x64_i8 v[86:89], v[174:177], v[190:193], v[86:89]
	v_mfma_i32_16x16x64_i8 v[78:81], v[166:169], v[198:201], v[78:81]
	v_mfma_i32_16x16x64_i8 v[74:77], v[174:177], v[198:201], v[74:77]
	v_mfma_i32_16x16x64_i8 v[70:73], v[166:169], v[206:209], v[70:73]
	v_mfma_i32_16x16x64_i8 v[66:69], v[174:177], v[206:209], v[66:69]
	s_barrier
	s_add_i32 s85, s68, s50
	v_lshl_add_u64 v[210:211], s[86:87], 0, v[132:133]
	s_mov_b32 m0, s85
	ds_read_b128 v[178:181], v231 offset:16384
	ds_read_b128 v[182:185], v231 offset:17408
	ds_read_b128 v[186:189], v231 offset:18432
	ds_read_b128 v[190:193], v231 offset:19456
	ds_read_b128 v[194:197], v231 offset:20480
	ds_read_b128 v[198:201], v231 offset:21504
	ds_read_b128 v[202:205], v231 offset:22528
	ds_read_b128 v[206:209], v231 offset:23552
	global_load_lds_dwordx4 v[210:211], off
	s_add_i32 m0, s85, 0x2000
	v_lshl_add_u64 v[212:213], s[86:87], 0, v[136:137]
	s_add_u32 s86, s86, s8
	s_addc_u32 s87, s87, s9
	s_add_i32 s85, s69, s50
	global_load_lds_dwordx4 v[212:213], off
	v_lshl_add_u64 v[214:215], s[86:87], 0, v[132:133]
	s_mov_b32 m0, s85
	v_lshl_add_u64 v[216:217], s[86:87], 0, v[136:137]
	global_load_lds_dwordx4 v[214:215], off
	s_add_i32 m0, s85, 0x2000
	v_lshl_add_u64 v[218:219], s[42:43], 0, v[130:131]
	global_load_lds_dwordx4 v[216:217], off
	s_mov_b32 m0, s51
	v_lshl_add_u64 v[220:221], s[42:43], 0, v[134:135]
	global_load_lds_dwordx4 v[218:219], off
	s_mov_b32 m0, s54
	s_nop 0
	global_load_lds_dwordx4 v[220:221], off
	s_waitcnt vmcnt(8)
	s_waitcnt lgkmcnt(0)
	s_waitcnt lgkmcnt(0)
	v_mfma_i32_16x16x64_i8 v[62:65], v[146:149], v[178:181], v[62:65]
	v_mfma_i32_16x16x64_i8 v[58:61], v[154:157], v[178:181], v[58:61]
	s_barrier
	v_mfma_i32_16x16x64_i8 v[54:57], v[146:149], v[186:189], v[54:57]
	v_mfma_i32_16x16x64_i8 v[50:53], v[154:157], v[186:189], v[50:53]
	v_mfma_i32_16x16x64_i8 v[42:45], v[146:149], v[194:197], v[42:45]
	v_mfma_i32_16x16x64_i8 v[34:37], v[154:157], v[194:197], v[34:37]
	v_mfma_i32_16x16x64_i8 v[26:29], v[146:149], v[202:205], v[26:29]
	v_mfma_i32_16x16x64_i8 v[18:21], v[154:157], v[202:205], v[18:21]
	v_mfma_i32_16x16x64_i8 v[62:65], v[150:153], v[182:185], v[62:65]
	v_mfma_i32_16x16x64_i8 v[58:61], v[158:161], v[182:185], v[58:61]
	v_mfma_i32_16x16x64_i8 v[54:57], v[150:153], v[190:193], v[54:57]
	v_mfma_i32_16x16x64_i8 v[50:53], v[158:161], v[190:193], v[50:53]
	v_mfma_i32_16x16x64_i8 v[42:45], v[150:153], v[198:201], v[42:45]
	v_mfma_i32_16x16x64_i8 v[34:37], v[158:161], v[198:201], v[34:37]
	v_mfma_i32_16x16x64_i8 v[26:29], v[150:153], v[206:209], v[26:29]
	v_mfma_i32_16x16x64_i8 v[18:21], v[158:161], v[206:209], v[18:21]
	v_mfma_i32_16x16x64_i8 v[46:49], v[162:165], v[178:181], v[46:49]
	v_mfma_i32_16x16x64_i8 v[38:41], v[170:173], v[178:181], v[38:41]
	v_mfma_i32_16x16x64_i8 v[30:33], v[162:165], v[186:189], v[30:33]
	v_mfma_i32_16x16x64_i8 v[22:25], v[170:173], v[186:189], v[22:25]
	v_mfma_i32_16x16x64_i8 v[14:17], v[162:165], v[194:197], v[14:17]
	v_mfma_i32_16x16x64_i8 v[10:13], v[170:173], v[194:197], v[10:13]
	v_mfma_i32_16x16x64_i8 v[6:9], v[162:165], v[202:205], v[6:9]
	v_mfma_i32_16x16x64_i8 v[2:5], v[170:173], v[202:205], v[2:5]
	v_mfma_i32_16x16x64_i8 v[46:49], v[166:169], v[182:185], v[46:49]
	v_mfma_i32_16x16x64_i8 v[38:41], v[174:177], v[182:185], v[38:41]
	v_mfma_i32_16x16x64_i8 v[30:33], v[166:169], v[190:193], v[30:33]
	v_mfma_i32_16x16x64_i8 v[22:25], v[174:177], v[190:193], v[22:25]
	v_mfma_i32_16x16x64_i8 v[14:17], v[166:169], v[198:201], v[14:17]
	v_mfma_i32_16x16x64_i8 v[10:13], v[174:177], v[198:201], v[10:13]
	v_mfma_i32_16x16x64_i8 v[6:9], v[166:169], v[206:209], v[6:9]
	v_mfma_i32_16x16x64_i8 v[2:5], v[174:177], v[206:209], v[2:5]
	s_barrier
	s_add_i32 s85, 0, 0x18000
	s_add_i32 s86, 0, 0x1c000
	v_add_u32_e32 v158, s85, v229
	v_add_u32_e32 v174, s86, v229
	ds_read_b128 v[146:149], v158
	ds_read_b128 v[150:153], v158 offset:1024
	ds_read_b128 v[154:157], v158 offset:2048
	ds_read_b128 v[158:161], v158 offset:3072
	ds_read_b128 v[162:165], v174
	ds_read_b128 v[166:169], v174 offset:1024
	ds_read_b128 v[170:173], v174 offset:2048
	ds_read_b128 v[174:177], v174 offset:3072
	s_add_u32 s42, s42, s8
	s_addc_u32 s43, s43, s9
	s_mov_b32 m0, s55
	v_lshl_add_u64 v[222:223], s[42:43], 0, v[130:131]
	ds_read_b128 v[178:181], v231 offset:32768
	ds_read_b128 v[182:185], v231 offset:33792
	ds_read_b128 v[186:189], v231 offset:34816
	ds_read_b128 v[190:193], v231 offset:35840
	ds_read_b128 v[194:197], v231 offset:36864
	ds_read_b128 v[198:201], v231 offset:37888
	ds_read_b128 v[202:205], v231 offset:38912
	ds_read_b128 v[206:209], v231 offset:39936
	global_load_lds_dwordx4 v[222:223], off
	v_lshl_add_u64 v[222:223], s[42:43], 0, v[134:135]
	s_mov_b32 m0, s56
	s_nop 0
	global_load_lds_dwordx4 v[222:223], off
	s_waitcnt vmcnt(8)
	s_waitcnt lgkmcnt(0)
	s_waitcnt lgkmcnt(0)
	v_mfma_i32_16x16x64_i8 v[126:129], v[146:149], v[178:181], v[126:129]
	v_mfma_i32_16x16x64_i8 v[122:125], v[154:157], v[178:181], v[122:125]
	s_barrier
	v_mfma_i32_16x16x64_i8 v[118:121], v[146:149], v[186:189], v[118:121]
	v_mfma_i32_16x16x64_i8 v[114:117], v[154:157], v[186:189], v[114:117]
	v_mfma_i32_16x16x64_i8 v[106:109], v[146:149], v[194:197], v[106:109]
	v_mfma_i32_16x16x64_i8 v[98:101], v[154:157], v[194:197], v[98:101]
	v_mfma_i32_16x16x64_i8 v[90:93], v[146:149], v[202:205], v[90:93]
	v_mfma_i32_16x16x64_i8 v[82:85], v[154:157], v[202:205], v[82:85]
	v_mfma_i32_16x16x64_i8 v[126:129], v[150:153], v[182:185], v[126:129]
	v_mfma_i32_16x16x64_i8 v[122:125], v[158:161], v[182:185], v[122:125]
	v_mfma_i32_16x16x64_i8 v[118:121], v[150:153], v[190:193], v[118:121]
	v_mfma_i32_16x16x64_i8 v[114:117], v[158:161], v[190:193], v[114:117]
	v_mfma_i32_16x16x64_i8 v[106:109], v[150:153], v[198:201], v[106:109]
	v_mfma_i32_16x16x64_i8 v[98:101], v[158:161], v[198:201], v[98:101]
	v_mfma_i32_16x16x64_i8 v[90:93], v[150:153], v[206:209], v[90:93]
	v_mfma_i32_16x16x64_i8 v[82:85], v[158:161], v[206:209], v[82:85]
	v_mfma_i32_16x16x64_i8 v[110:113], v[162:165], v[178:181], v[110:113]
	v_mfma_i32_16x16x64_i8 v[102:105], v[170:173], v[178:181], v[102:105]
	v_mfma_i32_16x16x64_i8 v[94:97], v[162:165], v[186:189], v[94:97]
	v_mfma_i32_16x16x64_i8 v[86:89], v[170:173], v[186:189], v[86:89]
	v_mfma_i32_16x16x64_i8 v[78:81], v[162:165], v[194:197], v[78:81]
	v_mfma_i32_16x16x64_i8 v[74:77], v[170:173], v[194:197], v[74:77]
	v_mfma_i32_16x16x64_i8 v[70:73], v[162:165], v[202:205], v[70:73]
	v_mfma_i32_16x16x64_i8 v[66:69], v[170:173], v[202:205], v[66:69]
	v_mfma_i32_16x16x64_i8 v[110:113], v[166:169], v[182:185], v[110:113]
	v_mfma_i32_16x16x64_i8 v[102:105], v[174:177], v[182:185], v[102:105]
	v_mfma_i32_16x16x64_i8 v[94:97], v[166:169], v[190:193], v[94:97]
	v_mfma_i32_16x16x64_i8 v[86:89], v[174:177], v[190:193], v[86:89]
	v_mfma_i32_16x16x64_i8 v[78:81], v[166:169], v[198:201], v[78:81]
	v_mfma_i32_16x16x64_i8 v[74:77], v[174:177], v[198:201], v[74:77]
	v_mfma_i32_16x16x64_i8 v[70:73], v[166:169], v[206:209], v[70:73]
	v_mfma_i32_16x16x64_i8 v[66:69], v[174:177], v[206:209], v[66:69]
	s_barrier
	s_add_i32 s42, s85, s50
	v_lshl_add_u64 v[210:211], v[210:211], 0, s[30:31]
	s_mov_b32 m0, s42
	ds_read_b128 v[178:181], v231 offset:49152
	ds_read_b128 v[182:185], v231 offset:50176
	ds_read_b128 v[186:189], v231 offset:51200
	ds_read_b128 v[190:193], v231 offset:52224
	ds_read_b128 v[194:197], v231 offset:53248
	ds_read_b128 v[198:201], v231 offset:54272
	ds_read_b128 v[202:205], v231 offset:55296
	ds_read_b128 v[206:209], v231 offset:56320
	global_load_lds_dwordx4 v[210:211], off
	v_lshl_add_u64 v[210:211], v[212:213], 0, s[30:31]
	s_add_i32 m0, s42, 0x2000
	s_add_i32 s42, s86, s50
	global_load_lds_dwordx4 v[210:211], off
	v_lshl_add_u64 v[210:211], v[214:215], 0, s[30:31]
	s_mov_b32 m0, s42
	s_nop 0
	global_load_lds_dwordx4 v[210:211], off
	v_lshl_add_u64 v[210:211], v[216:217], 0, s[30:31]
	s_add_i32 m0, s42, 0x2000
	s_nop 0
	global_load_lds_dwordx4 v[210:211], off
	v_lshl_add_u64 v[210:211], v[218:219], 0, s[30:31]
	s_mov_b32 m0, s61
	s_nop 0
	global_load_lds_dwordx4 v[210:211], off
	v_lshl_add_u64 v[210:211], v[220:221], 0, s[30:31]
	s_mov_b32 m0, s62
	s_nop 0
	global_load_lds_dwordx4 v[210:211], off
	s_waitcnt vmcnt(8)
	s_waitcnt lgkmcnt(0)
	s_waitcnt lgkmcnt(0)
	v_mfma_i32_16x16x64_i8 v[62:65], v[146:149], v[178:181], v[62:65]
	v_mfma_i32_16x16x64_i8 v[58:61], v[154:157], v[178:181], v[58:61]
	s_barrier
	v_mfma_i32_16x16x64_i8 v[54:57], v[146:149], v[186:189], v[54:57]
	v_mfma_i32_16x16x64_i8 v[50:53], v[154:157], v[186:189], v[50:53]
	v_mfma_i32_16x16x64_i8 v[42:45], v[146:149], v[194:197], v[42:45]
	v_mfma_i32_16x16x64_i8 v[34:37], v[154:157], v[194:197], v[34:37]
	v_mfma_i32_16x16x64_i8 v[26:29], v[146:149], v[202:205], v[26:29]
	v_mfma_i32_16x16x64_i8 v[18:21], v[154:157], v[202:205], v[18:21]
	v_mfma_i32_16x16x64_i8 v[62:65], v[150:153], v[182:185], v[62:65]
	v_mfma_i32_16x16x64_i8 v[58:61], v[158:161], v[182:185], v[58:61]
	v_mfma_i32_16x16x64_i8 v[54:57], v[150:153], v[190:193], v[54:57]
	v_mfma_i32_16x16x64_i8 v[50:53], v[158:161], v[190:193], v[50:53]
	v_mfma_i32_16x16x64_i8 v[42:45], v[150:153], v[198:201], v[42:45]
	v_mfma_i32_16x16x64_i8 v[34:37], v[158:161], v[198:201], v[34:37]
	v_mfma_i32_16x16x64_i8 v[26:29], v[150:153], v[206:209], v[26:29]
	v_mfma_i32_16x16x64_i8 v[18:21], v[158:161], v[206:209], v[18:21]
	v_mfma_i32_16x16x64_i8 v[46:49], v[162:165], v[178:181], v[46:49]
	v_mfma_i32_16x16x64_i8 v[38:41], v[170:173], v[178:181], v[38:41]
	v_mfma_i32_16x16x64_i8 v[30:33], v[162:165], v[186:189], v[30:33]
	v_mfma_i32_16x16x64_i8 v[22:25], v[170:173], v[186:189], v[22:25]
	v_mfma_i32_16x16x64_i8 v[14:17], v[162:165], v[194:197], v[14:17]
	v_mfma_i32_16x16x64_i8 v[10:13], v[170:173], v[194:197], v[10:13]
	v_mfma_i32_16x16x64_i8 v[6:9], v[162:165], v[202:205], v[6:9]
	v_mfma_i32_16x16x64_i8 v[2:5], v[170:173], v[202:205], v[2:5]
	v_mfma_i32_16x16x64_i8 v[46:49], v[166:169], v[182:185], v[46:49]
	v_mfma_i32_16x16x64_i8 v[38:41], v[174:177], v[182:185], v[38:41]
	v_mfma_i32_16x16x64_i8 v[30:33], v[166:169], v[190:193], v[30:33]
	v_mfma_i32_16x16x64_i8 v[22:25], v[174:177], v[190:193], v[22:25]
	v_mfma_i32_16x16x64_i8 v[14:17], v[166:169], v[198:201], v[14:17]
	v_mfma_i32_16x16x64_i8 v[10:13], v[174:177], v[198:201], v[10:13]
	v_mfma_i32_16x16x64_i8 v[6:9], v[166:169], v[206:209], v[6:9]
	v_mfma_i32_16x16x64_i8 v[2:5], v[174:177], v[206:209], v[2:5]
	s_barrier
	s_add_u32 s40, s40, 0x100
	s_addc_u32 s41, s41, 0
	s_add_u32 s82, s82, 0x100
	s_addc_u32 s83, s83, 0
	s_cmp_ge_i32 s84, s64
	s_mov_b32 s42, s84
	s_cbranch_scc0 .LBB0_2764
	v_cvt_f32_i32_e32 v214, v126
	v_cvt_f32_i32_e32 v215, v127
	v_cvt_f32_i32_e32 v212, v128
	v_cvt_f32_i32_e32 v213, v129
	v_cvt_f32_i32_e32 v218, v122
	v_cvt_f32_i32_e32 v219, v123
	v_cvt_f32_i32_e32 v216, v124
	v_cvt_f32_i32_e32 v217, v125
	v_cvt_f32_i32_e32 v222, v110
	v_cvt_f32_i32_e32 v223, v111
	v_cvt_f32_i32_e32 v220, v112
	v_cvt_f32_i32_e32 v221, v113
	v_cvt_f32_i32_e32 v226, v102
	v_cvt_f32_i32_e32 v227, v103
	v_cvt_f32_i32_e32 v224, v104
	v_cvt_f32_i32_e32 v225, v105
	v_cvt_f32_i32_e32 v194, v118
	v_cvt_f32_i32_e32 v195, v119
	v_cvt_f32_i32_e32 v192, v120
	v_cvt_f32_i32_e32 v193, v121
	v_cvt_f32_i32_e32 v200, v114
	v_cvt_f32_i32_e32 v201, v115
	v_cvt_f32_i32_e32 v198, v116
	v_cvt_f32_i32_e32 v199, v117
	v_cvt_f32_i32_e32 v206, v94
	v_cvt_f32_i32_e32 v207, v95
	v_cvt_f32_i32_e32 v202, v96
	v_cvt_f32_i32_e32 v203, v97
	v_cvt_f32_i32_e32 v208, v86
	v_cvt_f32_i32_e32 v209, v87
	v_cvt_f32_i32_e32 v204, v88
	v_cvt_f32_i32_e32 v205, v89
	v_cvt_f32_i32_e32 v178, v106
	v_cvt_f32_i32_e32 v179, v107
	v_cvt_f32_i32_e32 v176, v108
	v_cvt_f32_i32_e32 v177, v109
	v_cvt_f32_i32_e32 v182, v98
	v_cvt_f32_i32_e32 v183, v99
	v_cvt_f32_i32_e32 v180, v100
	v_cvt_f32_i32_e32 v181, v101
	v_cvt_f32_i32_e32 v188, v78
	v_cvt_f32_i32_e32 v189, v79
	v_cvt_f32_i32_e32 v184, v80
	v_cvt_f32_i32_e32 v185, v81
	v_cvt_f32_i32_e32 v190, v74
	v_cvt_f32_i32_e32 v191, v75
	v_cvt_f32_i32_e32 v186, v76
	v_cvt_f32_i32_e32 v187, v77
	v_cvt_f32_i32_e32 v162, v90
	v_cvt_f32_i32_e32 v163, v91
	v_cvt_f32_i32_e32 v160, v92
	v_cvt_f32_i32_e32 v161, v93
	v_cvt_f32_i32_e32 v166, v82
	v_cvt_f32_i32_e32 v167, v83
	v_cvt_f32_i32_e32 v164, v84
	v_cvt_f32_i32_e32 v165, v85
	v_cvt_f32_i32_e32 v172, v70
	v_cvt_f32_i32_e32 v173, v71
	v_cvt_f32_i32_e32 v168, v72
	v_cvt_f32_i32_e32 v169, v73
	v_cvt_f32_i32_e32 v174, v66
	v_cvt_f32_i32_e32 v175, v67
	v_cvt_f32_i32_e32 v170, v68
	v_cvt_f32_i32_e32 v171, v69
	v_cvt_f32_i32_e32 v146, v62
	v_cvt_f32_i32_e32 v147, v63
	v_cvt_f32_i32_e32 v128, v64
	v_cvt_f32_i32_e32 v129, v65
	v_cvt_f32_i32_e32 v150, v58
	v_cvt_f32_i32_e32 v151, v59
	v_cvt_f32_i32_e32 v148, v60
	v_cvt_f32_i32_e32 v149, v61
	v_cvt_f32_i32_e32 v156, v46
	v_cvt_f32_i32_e32 v157, v47
	v_cvt_f32_i32_e32 v152, v48
	v_cvt_f32_i32_e32 v153, v49
	v_cvt_f32_i32_e32 v158, v38
	v_cvt_f32_i32_e32 v159, v39
	v_cvt_f32_i32_e32 v154, v40
	v_cvt_f32_i32_e32 v155, v41
	v_cvt_f32_i32_e32 v114, v54
	v_cvt_f32_i32_e32 v115, v55
	v_cvt_f32_i32_e32 v112, v56
	v_cvt_f32_i32_e32 v113, v57
	v_cvt_f32_i32_e32 v118, v50
	v_cvt_f32_i32_e32 v119, v51
	v_cvt_f32_i32_e32 v116, v52
	v_cvt_f32_i32_e32 v117, v53
	v_cvt_f32_i32_e32 v124, v30
	v_cvt_f32_i32_e32 v125, v31
	v_cvt_f32_i32_e32 v120, v32
	v_cvt_f32_i32_e32 v121, v33
	v_cvt_f32_i32_e32 v126, v22
	v_cvt_f32_i32_e32 v127, v23
	v_cvt_f32_i32_e32 v122, v24
	v_cvt_f32_i32_e32 v123, v25
	v_cvt_f32_i32_e32 v64, v42
	v_cvt_f32_i32_e32 v65, v43
	v_cvt_f32_i32_e32 v62, v44
	v_cvt_f32_i32_e32 v63, v45
	v_cvt_f32_i32_e32 v68, v34
	v_cvt_f32_i32_e32 v69, v35
	v_cvt_f32_i32_e32 v66, v36
	v_cvt_f32_i32_e32 v67, v37
	v_cvt_f32_i32_e32 v74, v14
	v_cvt_f32_i32_e32 v75, v15
	v_cvt_f32_i32_e32 v70, v16
	v_cvt_f32_i32_e32 v71, v17
	v_cvt_f32_i32_e32 v76, v10
	v_cvt_f32_i32_e32 v77, v11
	v_cvt_f32_i32_e32 v72, v12
	v_cvt_f32_i32_e32 v73, v13
	v_cvt_f32_i32_e32 v48, v26
	v_cvt_f32_i32_e32 v49, v27
	v_cvt_f32_i32_e32 v46, v28
	v_cvt_f32_i32_e32 v47, v29
	v_cvt_f32_i32_e32 v52, v18
	v_cvt_f32_i32_e32 v53, v19
	v_cvt_f32_i32_e32 v50, v20
	v_cvt_f32_i32_e32 v51, v21
	v_cvt_f32_i32_e32 v58, v6
	v_cvt_f32_i32_e32 v59, v7
	v_cvt_f32_i32_e32 v54, v8
	v_cvt_f32_i32_e32 v55, v9
	v_cvt_f32_i32_e32 v60, v2
	v_cvt_f32_i32_e32 v61, v3
	v_cvt_f32_i32_e32 v56, v4
	v_cvt_f32_i32_e32 v57, v5

.LBB0_2949:
	v_add_u32_e32 v138, s60, v188
	ds_read_b128 v[148:151], v138
	ds_read_b128 v[152:155], v138 offset:1024
	ds_read_b128 v[156:159], v138 offset:2048
	ds_read_b128 v[160:163], v138 offset:3072
	v_add_u32_e32 v138, s61, v188
	ds_read_b128 v[164:167], v138
	ds_read_b128 v[168:171], v138 offset:1024
	ds_read_b128 v[172:175], v138 offset:2048
	ds_read_b128 v[176:179], v138 offset:3072
	s_add_i32 s64, s28, 2
	s_add_u32 s65, s26, 0x80
	s_addc_u32 s29, s27, 0
	s_cmp_eq_u32 s58, s28
	s_cselect_b32 s28, s2, s65
	s_cselect_b32 s29, s3, s29
	s_cselect_b32 s67, s25, s35
	s_cselect_b32 s66, s24, s34
	v_lshl_add_u64 v[184:185], s[26:27], 0, v[140:141]
	s_add_i32 m0, s42, 0xc000
	ds_read_b128 v[180:183], v189
	ds_read_b128 v[190:193], v189 offset:1024
	ds_read_b128 v[194:197], v189 offset:2048
	ds_read_b128 v[198:201], v189 offset:3072
	ds_read_b128 v[202:205], v189 offset:4096
	ds_read_b128 v[206:209], v189 offset:5120
	ds_read_b128 v[210:213], v189 offset:6144
	ds_read_b128 v[214:217], v189 offset:7168
	global_load_lds_dwordx4 v[184:185], off
	v_lshl_add_u64 v[184:185], s[26:27], 0, v[142:143]
	s_add_i32 m0, s42, 0xe000
	s_nop 0
	global_load_lds_dwordx4 v[184:185], off
	s_waitcnt vmcnt(8)
	s_waitcnt lgkmcnt(0)
	s_waitcnt lgkmcnt(0)
	v_mfma_i32_16x16x64_i8 v[126:129], v[148:151], v[180:183], v[126:129]
	v_mfma_i32_16x16x64_i8 v[122:125], v[156:159], v[180:183], v[122:125]
	s_barrier
	v_mfma_i32_16x16x64_i8 v[118:121], v[148:151], v[194:197], v[118:121]
	v_mfma_i32_16x16x64_i8 v[114:117], v[156:159], v[194:197], v[114:117]
	v_mfma_i32_16x16x64_i8 v[106:109], v[148:151], v[202:205], v[106:109]
	v_mfma_i32_16x16x64_i8 v[98:101], v[156:159], v[202:205], v[98:101]
	v_mfma_i32_16x16x64_i8 v[90:93], v[148:151], v[210:213], v[90:93]
	v_mfma_i32_16x16x64_i8 v[82:85], v[156:159], v[210:213], v[82:85]
	v_mfma_i32_16x16x64_i8 v[126:129], v[152:155], v[190:193], v[126:129]
	v_mfma_i32_16x16x64_i8 v[122:125], v[160:163], v[190:193], v[122:125]
	v_mfma_i32_16x16x64_i8 v[118:121], v[152:155], v[198:201], v[118:121]
	v_mfma_i32_16x16x64_i8 v[114:117], v[160:163], v[198:201], v[114:117]
	v_mfma_i32_16x16x64_i8 v[106:109], v[152:155], v[206:209], v[106:109]
	v_mfma_i32_16x16x64_i8 v[98:101], v[160:163], v[206:209], v[98:101]
	v_mfma_i32_16x16x64_i8 v[90:93], v[152:155], v[214:217], v[90:93]
	v_mfma_i32_16x16x64_i8 v[82:85], v[160:163], v[214:217], v[82:85]
	v_mfma_i32_16x16x64_i8 v[110:113], v[164:167], v[180:183], v[110:113]
	v_mfma_i32_16x16x64_i8 v[102:105], v[172:175], v[180:183], v[102:105]
	v_mfma_i32_16x16x64_i8 v[94:97], v[164:167], v[194:197], v[94:97]
	v_mfma_i32_16x16x64_i8 v[86:89], v[172:175], v[194:197], v[86:89]
	v_mfma_i32_16x16x64_i8 v[78:81], v[164:167], v[202:205], v[78:81]
	v_mfma_i32_16x16x64_i8 v[74:77], v[172:175], v[202:205], v[74:77]
	v_mfma_i32_16x16x64_i8 v[70:73], v[164:167], v[210:213], v[70:73]
	v_mfma_i32_16x16x64_i8 v[66:69], v[172:175], v[210:213], v[66:69]
	v_mfma_i32_16x16x64_i8 v[110:113], v[168:171], v[190:193], v[110:113]
	v_mfma_i32_16x16x64_i8 v[102:105], v[176:179], v[190:193], v[102:105]
	v_mfma_i32_16x16x64_i8 v[94:97], v[168:171], v[198:201], v[94:97]
	v_mfma_i32_16x16x64_i8 v[86:89], v[176:179], v[198:201], v[86:89]
	v_mfma_i32_16x16x64_i8 v[78:81], v[168:171], v[206:209], v[78:81]
	v_mfma_i32_16x16x64_i8 v[74:77], v[176:179], v[206:209], v[74:77]
	v_mfma_i32_16x16x64_i8 v[70:73], v[168:171], v[214:217], v[70:73]
	v_mfma_i32_16x16x64_i8 v[66:69], v[176:179], v[214:217], v[66:69]
	s_barrier
	s_add_i32 s65, s60, s41
	v_lshl_add_u64 v[184:185], s[66:67], 0, v[132:133]
	s_mov_b32 m0, s65
	ds_read_b128 v[180:183], v189 offset:16384
	ds_read_b128 v[190:193], v189 offset:17408
	ds_read_b128 v[194:197], v189 offset:18432
	ds_read_b128 v[198:201], v189 offset:19456
	ds_read_b128 v[202:205], v189 offset:20480
	ds_read_b128 v[206:209], v189 offset:21504
	ds_read_b128 v[210:213], v189 offset:22528
	ds_read_b128 v[214:217], v189 offset:23552
	global_load_lds_dwordx4 v[184:185], off
	s_add_i32 m0, s65, 0x2000
	v_lshl_add_u64 v[218:219], s[66:67], 0, v[136:137]
	s_add_u32 s66, s66, s6
	s_addc_u32 s67, s67, s7
	s_add_i32 s65, s61, s41
	global_load_lds_dwordx4 v[218:219], off
	v_lshl_add_u64 v[220:221], s[66:67], 0, v[132:133]
	s_mov_b32 m0, s65
	v_lshl_add_u64 v[222:223], s[66:67], 0, v[136:137]
	global_load_lds_dwordx4 v[220:221], off
	s_add_i32 m0, s65, 0x2000
	v_lshl_add_u64 v[224:225], s[28:29], 0, v[130:131]
	global_load_lds_dwordx4 v[222:223], off
	s_mov_b32 m0, s42
	v_lshl_add_u64 v[226:227], s[28:29], 0, v[134:135]
	global_load_lds_dwordx4 v[224:225], off
	s_mov_b32 m0, s43
	s_nop 0
	global_load_lds_dwordx4 v[226:227], off
	s_waitcnt vmcnt(8)
	s_waitcnt lgkmcnt(0)
	s_waitcnt lgkmcnt(0)
	v_mfma_i32_16x16x64_i8 v[62:65], v[148:151], v[180:183], v[62:65]
	v_mfma_i32_16x16x64_i8 v[58:61], v[156:159], v[180:183], v[58:61]
	s_barrier
	v_mfma_i32_16x16x64_i8 v[54:57], v[148:151], v[194:197], v[54:57]
	v_mfma_i32_16x16x64_i8 v[50:53], v[156:159], v[194:197], v[50:53]
	v_mfma_i32_16x16x64_i8 v[42:45], v[148:151], v[202:205], v[42:45]
	v_mfma_i32_16x16x64_i8 v[34:37], v[156:159], v[202:205], v[34:37]
	v_mfma_i32_16x16x64_i8 v[26:29], v[148:151], v[210:213], v[26:29]
	v_mfma_i32_16x16x64_i8 v[18:21], v[156:159], v[210:213], v[18:21]
	v_mfma_i32_16x16x64_i8 v[62:65], v[152:155], v[190:193], v[62:65]
	v_mfma_i32_16x16x64_i8 v[58:61], v[160:163], v[190:193], v[58:61]
	v_mfma_i32_16x16x64_i8 v[54:57], v[152:155], v[198:201], v[54:57]
	v_mfma_i32_16x16x64_i8 v[50:53], v[160:163], v[198:201], v[50:53]
	v_mfma_i32_16x16x64_i8 v[42:45], v[152:155], v[206:209], v[42:45]
	v_mfma_i32_16x16x64_i8 v[34:37], v[160:163], v[206:209], v[34:37]
	v_mfma_i32_16x16x64_i8 v[26:29], v[152:155], v[214:217], v[26:29]
	v_mfma_i32_16x16x64_i8 v[18:21], v[160:163], v[214:217], v[18:21]
	v_mfma_i32_16x16x64_i8 v[46:49], v[164:167], v[180:183], v[46:49]
	v_mfma_i32_16x16x64_i8 v[38:41], v[172:175], v[180:183], v[38:41]
	v_mfma_i32_16x16x64_i8 v[30:33], v[164:167], v[194:197], v[30:33]
	v_mfma_i32_16x16x64_i8 v[22:25], v[172:175], v[194:197], v[22:25]
	v_mfma_i32_16x16x64_i8 v[14:17], v[164:167], v[202:205], v[14:17]
	v_mfma_i32_16x16x64_i8 v[10:13], v[172:175], v[202:205], v[10:13]
	v_mfma_i32_16x16x64_i8 v[6:9], v[164:167], v[210:213], v[6:9]
	v_mfma_i32_16x16x64_i8 v[2:5], v[172:175], v[210:213], v[2:5]
	v_mfma_i32_16x16x64_i8 v[46:49], v[168:171], v[190:193], v[46:49]
	v_mfma_i32_16x16x64_i8 v[38:41], v[176:179], v[190:193], v[38:41]
	v_mfma_i32_16x16x64_i8 v[30:33], v[168:171], v[198:201], v[30:33]
	v_mfma_i32_16x16x64_i8 v[22:25], v[176:179], v[198:201], v[22:25]
	v_mfma_i32_16x16x64_i8 v[14:17], v[168:171], v[206:209], v[14:17]
	v_mfma_i32_16x16x64_i8 v[10:13], v[176:179], v[206:209], v[10:13]
	v_mfma_i32_16x16x64_i8 v[6:9], v[168:171], v[214:217], v[6:9]
	v_mfma_i32_16x16x64_i8 v[2:5], v[176:179], v[214:217], v[2:5]
	s_barrier
	s_add_i32 s65, 0, 0x18000
	v_add_u32_e32 v138, s65, v188
	s_add_i32 s66, 0, 0x1c000
	ds_read_b128 v[148:151], v138
	ds_read_b128 v[152:155], v138 offset:1024
	ds_read_b128 v[156:159], v138 offset:2048
	ds_read_b128 v[160:163], v138 offset:3072
	v_add_u32_e32 v138, s66, v188
	ds_read_b128 v[164:167], v138
	ds_read_b128 v[168:171], v138 offset:1024
	ds_read_b128 v[172:175], v138 offset:2048
	ds_read_b128 v[176:179], v138 offset:3072
	s_add_u32 s28, s28, s6
	s_addc_u32 s29, s29, s7
	s_mov_b32 m0, s44
	v_lshl_add_u64 v[228:229], s[28:29], 0, v[130:131]
	ds_read_b128 v[180:183], v189 offset:32768
	ds_read_b128 v[190:193], v189 offset:33792
	ds_read_b128 v[194:197], v189 offset:34816
	ds_read_b128 v[198:201], v189 offset:35840
	ds_read_b128 v[202:205], v189 offset:36864
	ds_read_b128 v[206:209], v189 offset:37888
	ds_read_b128 v[210:213], v189 offset:38912
	ds_read_b128 v[214:217], v189 offset:39936
	global_load_lds_dwordx4 v[228:229], off
	v_lshl_add_u64 v[228:229], s[28:29], 0, v[134:135]
	s_mov_b32 m0, s45
	s_nop 0
	global_load_lds_dwordx4 v[228:229], off
	s_waitcnt vmcnt(8)
	s_waitcnt lgkmcnt(0)
	s_waitcnt lgkmcnt(0)
	v_mfma_i32_16x16x64_i8 v[126:129], v[148:151], v[180:183], v[126:129]
	v_mfma_i32_16x16x64_i8 v[122:125], v[156:159], v[180:183], v[122:125]
	s_barrier
	v_mfma_i32_16x16x64_i8 v[118:121], v[148:151], v[194:197], v[118:121]
	v_mfma_i32_16x16x64_i8 v[114:117], v[156:159], v[194:197], v[114:117]
	v_mfma_i32_16x16x64_i8 v[106:109], v[148:151], v[202:205], v[106:109]
	v_mfma_i32_16x16x64_i8 v[98:101], v[156:159], v[202:205], v[98:101]
	v_mfma_i32_16x16x64_i8 v[90:93], v[148:151], v[210:213], v[90:93]
	v_mfma_i32_16x16x64_i8 v[82:85], v[156:159], v[210:213], v[82:85]
	v_mfma_i32_16x16x64_i8 v[126:129], v[152:155], v[190:193], v[126:129]
	v_mfma_i32_16x16x64_i8 v[122:125], v[160:163], v[190:193], v[122:125]
	v_mfma_i32_16x16x64_i8 v[118:121], v[152:155], v[198:201], v[118:121]
	v_mfma_i32_16x16x64_i8 v[114:117], v[160:163], v[198:201], v[114:117]
	v_mfma_i32_16x16x64_i8 v[106:109], v[152:155], v[206:209], v[106:109]
	v_mfma_i32_16x16x64_i8 v[98:101], v[160:163], v[206:209], v[98:101]
	v_mfma_i32_16x16x64_i8 v[90:93], v[152:155], v[214:217], v[90:93]
	v_mfma_i32_16x16x64_i8 v[82:85], v[160:163], v[214:217], v[82:85]
	v_mfma_i32_16x16x64_i8 v[110:113], v[164:167], v[180:183], v[110:113]
	v_mfma_i32_16x16x64_i8 v[102:105], v[172:175], v[180:183], v[102:105]
	v_mfma_i32_16x16x64_i8 v[94:97], v[164:167], v[194:197], v[94:97]
	v_mfma_i32_16x16x64_i8 v[86:89], v[172:175], v[194:197], v[86:89]
	v_mfma_i32_16x16x64_i8 v[78:81], v[164:167], v[202:205], v[78:81]
	v_mfma_i32_16x16x64_i8 v[74:77], v[172:175], v[202:205], v[74:77]
	v_mfma_i32_16x16x64_i8 v[70:73], v[164:167], v[210:213], v[70:73]
	v_mfma_i32_16x16x64_i8 v[66:69], v[172:175], v[210:213], v[66:69]
	v_mfma_i32_16x16x64_i8 v[110:113], v[168:171], v[190:193], v[110:113]
	v_mfma_i32_16x16x64_i8 v[102:105], v[176:179], v[190:193], v[102:105]
	v_mfma_i32_16x16x64_i8 v[94:97], v[168:171], v[198:201], v[94:97]
	v_mfma_i32_16x16x64_i8 v[86:89], v[176:179], v[198:201], v[86:89]
	v_mfma_i32_16x16x64_i8 v[78:81], v[168:171], v[206:209], v[78:81]
	v_mfma_i32_16x16x64_i8 v[74:77], v[176:179], v[206:209], v[74:77]
	v_mfma_i32_16x16x64_i8 v[70:73], v[168:171], v[214:217], v[70:73]
	v_mfma_i32_16x16x64_i8 v[66:69], v[176:179], v[214:217], v[66:69]
	s_barrier
	s_add_i32 s28, s65, s41
	v_lshl_add_u64 v[184:185], v[184:185], 0, s[18:19]
	s_mov_b32 m0, s28
	ds_read_b128 v[180:183], v189 offset:49152
	ds_read_b128 v[190:193], v189 offset:50176
	ds_read_b128 v[194:197], v189 offset:51200
	ds_read_b128 v[198:201], v189 offset:52224
	ds_read_b128 v[202:205], v189 offset:53248
	ds_read_b128 v[206:209], v189 offset:54272
	ds_read_b128 v[210:213], v189 offset:55296
	ds_read_b128 v[214:217], v189 offset:56320
	global_load_lds_dwordx4 v[184:185], off
	v_lshl_add_u64 v[184:185], v[218:219], 0, s[18:19]
	s_add_i32 m0, s28, 0x2000
	s_add_i32 s28, s66, s41
	global_load_lds_dwordx4 v[184:185], off
	v_lshl_add_u64 v[184:185], v[220:221], 0, s[18:19]
	s_mov_b32 m0, s28
	s_nop 0
	global_load_lds_dwordx4 v[184:185], off
	v_lshl_add_u64 v[184:185], v[222:223], 0, s[18:19]
	s_add_i32 m0, s28, 0x2000
	s_nop 0
	global_load_lds_dwordx4 v[184:185], off
	v_lshl_add_u64 v[184:185], v[224:225], 0, s[18:19]
	s_mov_b32 m0, s51
	s_nop 0
	global_load_lds_dwordx4 v[184:185], off
	v_lshl_add_u64 v[184:185], v[226:227], 0, s[18:19]
	s_mov_b32 m0, s54
	s_nop 0
	global_load_lds_dwordx4 v[184:185], off
	s_waitcnt vmcnt(8)
	s_waitcnt lgkmcnt(0)
	s_waitcnt lgkmcnt(0)
	v_mfma_i32_16x16x64_i8 v[62:65], v[148:151], v[180:183], v[62:65]
	v_mfma_i32_16x16x64_i8 v[58:61], v[156:159], v[180:183], v[58:61]
	s_barrier
	v_mfma_i32_16x16x64_i8 v[54:57], v[148:151], v[194:197], v[54:57]
	v_mfma_i32_16x16x64_i8 v[50:53], v[156:159], v[194:197], v[50:53]
	v_mfma_i32_16x16x64_i8 v[42:45], v[148:151], v[202:205], v[42:45]
	v_mfma_i32_16x16x64_i8 v[34:37], v[156:159], v[202:205], v[34:37]
	v_mfma_i32_16x16x64_i8 v[26:29], v[148:151], v[210:213], v[26:29]
	v_mfma_i32_16x16x64_i8 v[18:21], v[156:159], v[210:213], v[18:21]
	v_mfma_i32_16x16x64_i8 v[62:65], v[152:155], v[190:193], v[62:65]
	v_mfma_i32_16x16x64_i8 v[58:61], v[160:163], v[190:193], v[58:61]
	v_mfma_i32_16x16x64_i8 v[54:57], v[152:155], v[198:201], v[54:57]
	v_mfma_i32_16x16x64_i8 v[50:53], v[160:163], v[198:201], v[50:53]
	v_mfma_i32_16x16x64_i8 v[42:45], v[152:155], v[206:209], v[42:45]
	v_mfma_i32_16x16x64_i8 v[34:37], v[160:163], v[206:209], v[34:37]
	v_mfma_i32_16x16x64_i8 v[26:29], v[152:155], v[214:217], v[26:29]
	v_mfma_i32_16x16x64_i8 v[18:21], v[160:163], v[214:217], v[18:21]
	v_mfma_i32_16x16x64_i8 v[46:49], v[164:167], v[180:183], v[46:49]
	v_mfma_i32_16x16x64_i8 v[38:41], v[172:175], v[180:183], v[38:41]
	v_mfma_i32_16x16x64_i8 v[30:33], v[164:167], v[194:197], v[30:33]
	v_mfma_i32_16x16x64_i8 v[22:25], v[172:175], v[194:197], v[22:25]
	v_mfma_i32_16x16x64_i8 v[14:17], v[164:167], v[202:205], v[14:17]
	v_mfma_i32_16x16x64_i8 v[10:13], v[172:175], v[202:205], v[10:13]
	v_mfma_i32_16x16x64_i8 v[6:9], v[164:167], v[210:213], v[6:9]
	v_mfma_i32_16x16x64_i8 v[2:5], v[172:175], v[210:213], v[2:5]
	v_mfma_i32_16x16x64_i8 v[46:49], v[168:171], v[190:193], v[46:49]
	v_mfma_i32_16x16x64_i8 v[38:41], v[176:179], v[190:193], v[38:41]
	v_mfma_i32_16x16x64_i8 v[30:33], v[168:171], v[198:201], v[30:33]
	v_mfma_i32_16x16x64_i8 v[22:25], v[176:179], v[198:201], v[22:25]
	v_mfma_i32_16x16x64_i8 v[14:17], v[168:171], v[206:209], v[14:17]
	v_mfma_i32_16x16x64_i8 v[10:13], v[176:179], v[206:209], v[10:13]
	v_mfma_i32_16x16x64_i8 v[6:9], v[168:171], v[214:217], v[6:9]
	v_mfma_i32_16x16x64_i8 v[2:5], v[176:179], v[214:217], v[2:5]
	s_barrier
	s_add_u32 s26, s26, 0x100
	s_addc_u32 s27, s27, 0
	s_add_u32 s34, s34, 0x100
	s_addc_u32 s35, s35, 0
	s_cmp_ge_i32 s64, s55
	s_mov_b32 s28, s64
	s_cbranch_scc0 .LBB0_2949
	v_cvt_f32_i32_e32 v172, v126
	v_cvt_f32_i32_e32 v173, v127
	v_cvt_f32_i32_e32 v170, v128
	v_cvt_f32_i32_e32 v171, v129
	v_cvt_f32_i32_e32 v174, v122
	v_cvt_f32_i32_e32 v175, v123
	v_cvt_f32_i32_e32 v176, v124
	v_cvt_f32_i32_e32 v177, v125
	v_cvt_f32_i32_e32 v180, v110
	v_cvt_f32_i32_e32 v181, v111
	v_cvt_f32_i32_e32 v182, v112
	v_cvt_f32_i32_e32 v183, v113
	v_cvt_f32_i32_e32 v178, v102
	v_cvt_f32_i32_e32 v179, v103
	v_cvt_f32_i32_e32 v184, v104
	v_cvt_f32_i32_e32 v185, v105
	v_cvt_f32_i32_e32 v152, v118
	v_cvt_f32_i32_e32 v153, v119
	v_cvt_f32_i32_e32 v154, v120
	v_cvt_f32_i32_e32 v155, v121
	v_cvt_f32_i32_e32 v156, v114
	v_cvt_f32_i32_e32 v157, v115
	v_cvt_f32_i32_e32 v158, v116
	v_cvt_f32_i32_e32 v159, v117
	v_cvt_f32_i32_e32 v160, v94
	v_cvt_f32_i32_e32 v161, v95
	v_cvt_f32_i32_e32 v162, v96
	v_cvt_f32_i32_e32 v163, v97
	v_cvt_f32_i32_e32 v164, v86
	v_cvt_f32_i32_e32 v165, v87
	v_cvt_f32_i32_e32 v166, v88
	v_cvt_f32_i32_e32 v167, v89
	v_cvt_f32_i32_e32 v118, v106
	v_cvt_f32_i32_e32 v119, v107
	v_cvt_f32_i32_e32 v120, v108
	v_cvt_f32_i32_e32 v121, v109
	v_cvt_f32_i32_e32 v122, v98
	v_cvt_f32_i32_e32 v123, v99
	v_cvt_f32_i32_e32 v124, v100
	v_cvt_f32_i32_e32 v125, v101
	v_cvt_f32_i32_e32 v126, v78
	v_cvt_f32_i32_e32 v127, v79
	v_cvt_f32_i32_e32 v128, v80
	v_cvt_f32_i32_e32 v129, v81
	v_cvt_f32_i32_e32 v148, v74
	v_cvt_f32_i32_e32 v149, v75
	v_cvt_f32_i32_e32 v150, v76
	v_cvt_f32_i32_e32 v151, v77
	v_cvt_f32_i32_e32 v102, v90
	v_cvt_f32_i32_e32 v103, v91
	v_cvt_f32_i32_e32 v104, v92
	v_cvt_f32_i32_e32 v105, v93
	v_cvt_f32_i32_e32 v106, v82
	v_cvt_f32_i32_e32 v107, v83
	v_cvt_f32_i32_e32 v108, v84
	v_cvt_f32_i32_e32 v109, v85
	v_cvt_f32_i32_e32 v110, v70
	v_cvt_f32_i32_e32 v111, v71
	v_cvt_f32_i32_e32 v112, v72
	v_cvt_f32_i32_e32 v113, v73
	v_cvt_f32_i32_e32 v114, v66
	v_cvt_f32_i32_e32 v115, v67
	v_cvt_f32_i32_e32 v116, v68
	v_cvt_f32_i32_e32 v117, v69
	v_cvt_f32_i32_e32 v82, v62
	v_cvt_f32_i32_e32 v83, v63
	v_cvt_f32_i32_e32 v84, v64
	v_cvt_f32_i32_e32 v85, v65
	v_cvt_f32_i32_e32 v86, v58
	v_cvt_f32_i32_e32 v87, v59
	v_cvt_f32_i32_e32 v88, v60
	v_cvt_f32_i32_e32 v89, v61
	v_cvt_f32_i32_e32 v92, v46
	v_cvt_f32_i32_e32 v93, v47
	v_cvt_f32_i32_e32 v94, v48
	v_cvt_f32_i32_e32 v95, v49
	v_cvt_f32_i32_e32 v96, v38
	v_cvt_f32_i32_e32 v97, v39
	v_cvt_f32_i32_e32 v98, v40
	v_cvt_f32_i32_e32 v99, v41
	v_cvt_f32_i32_e32 v66, v54
	v_cvt_f32_i32_e32 v67, v55
	v_cvt_f32_i32_e32 v68, v56
	v_cvt_f32_i32_e32 v69, v57
	v_cvt_f32_i32_e32 v70, v50
	v_cvt_f32_i32_e32 v71, v51
	v_cvt_f32_i32_e32 v72, v52
	v_cvt_f32_i32_e32 v73, v53
	v_cvt_f32_i32_e32 v74, v30
	v_cvt_f32_i32_e32 v75, v31
	v_cvt_f32_i32_e32 v76, v32
	v_cvt_f32_i32_e32 v77, v33
	v_cvt_f32_i32_e32 v78, v22
	v_cvt_f32_i32_e32 v79, v23
	v_cvt_f32_i32_e32 v80, v24
	v_cvt_f32_i32_e32 v81, v25
	v_cvt_f32_i32_e32 v50, v42
	v_cvt_f32_i32_e32 v51, v43
	v_cvt_f32_i32_e32 v52, v44
	v_cvt_f32_i32_e32 v53, v45
	v_cvt_f32_i32_e32 v54, v34
	v_cvt_f32_i32_e32 v55, v35
	v_cvt_f32_i32_e32 v56, v36
	v_cvt_f32_i32_e32 v57, v37
	v_cvt_f32_i32_e32 v58, v14
	v_cvt_f32_i32_e32 v59, v15
	v_cvt_f32_i32_e32 v60, v16
	v_cvt_f32_i32_e32 v61, v17
	v_cvt_f32_i32_e32 v62, v10
	v_cvt_f32_i32_e32 v63, v11
	v_cvt_f32_i32_e32 v64, v12
	v_cvt_f32_i32_e32 v65, v13
	v_cvt_f32_i32_e32 v34, v26
	v_cvt_f32_i32_e32 v35, v27
	v_cvt_f32_i32_e32 v36, v28
	v_cvt_f32_i32_e32 v37, v29
	v_cvt_f32_i32_e32 v38, v18
	v_cvt_f32_i32_e32 v39, v19
	v_cvt_f32_i32_e32 v40, v20
	v_cvt_f32_i32_e32 v41, v21
	v_cvt_f32_i32_e32 v42, v6
	v_cvt_f32_i32_e32 v43, v7
	v_cvt_f32_i32_e32 v44, v8
	v_cvt_f32_i32_e32 v45, v9
	v_cvt_f32_i32_e32 v46, v2
	v_cvt_f32_i32_e32 v47, v3
	v_cvt_f32_i32_e32 v48, v4
	v_cvt_f32_i32_e32 v49, v5

.LBB0_3032:
	ds_read_b128 v[114:117], v209
	ds_read_b128 v[118:121], v209 offset:1024
	ds_read_b128 v[122:125], v209 offset:2048
	ds_read_b128 v[126:129], v209 offset:3072
	ds_read_b128 v[146:149], v210
	ds_read_b128 v[150:153], v210 offset:1024
	ds_read_b128 v[154:157], v210 offset:2048
	ds_read_b128 v[158:161], v210 offset:3072
	s_add_i32 s80, s36, 2
	s_add_u32 s37, s34, 0x4000
	s_addc_u32 s38, s35, 0
	s_cmp_eq_u32 s61, s36
	s_cselect_b32 s39, s5, s38
	s_cselect_b32 s38, s4, s37
	s_cselect_b32 s82, s30, s70
	s_cselect_b32 s83, s31, s71
	s_add_u32 s36, s38, 0x8000
	s_addc_u32 s37, s39, 0
	v_lshl_add_u64 v[218:219], s[34:35], 0, v[170:171]
	s_add_i32 m0, s45, 0xc000
	ds_read_b128 v[178:181], v211
	ds_read_b128 v[182:185], v211 offset:1024
	ds_read_b128 v[186:189], v211 offset:2048
	ds_read_b128 v[190:193], v211 offset:3072
	ds_read_b128 v[194:197], v211 offset:4096
	ds_read_b128 v[198:201], v211 offset:5120
	ds_read_b128 v[202:205], v211 offset:6144
	ds_read_b128 v[214:217], v211 offset:7168
	global_load_lds_dwordx4 v[218:219], off
	v_lshl_add_u64 v[218:219], s[34:35], 0, v[172:173]
	s_add_i32 m0, s45, 0xe000
	s_nop 0
	global_load_lds_dwordx4 v[218:219], off
	s_waitcnt vmcnt(8)
	s_waitcnt lgkmcnt(0)
	s_waitcnt lgkmcnt(0)
	v_mfma_f32_16x16x32_bf16 v[142:145], v[114:117], v[178:181], v[142:145]
	v_mfma_f32_16x16x32_bf16 v[138:141], v[122:125], v[178:181], v[138:141]
	s_barrier
	v_mfma_f32_16x16x32_bf16 v[110:113], v[114:117], v[186:189], v[110:113]
	v_mfma_f32_16x16x32_bf16 v[106:109], v[122:125], v[186:189], v[106:109]
	v_mfma_f32_16x16x32_bf16 v[94:97], v[114:117], v[194:197], v[94:97]
	v_mfma_f32_16x16x32_bf16 v[90:93], v[122:125], v[194:197], v[90:93]
	v_mfma_f32_16x16x32_bf16 v[78:81], v[114:117], v[202:205], v[78:81]
	v_mfma_f32_16x16x32_bf16 v[74:77], v[122:125], v[202:205], v[74:77]
	v_mfma_f32_16x16x32_bf16 v[142:145], v[118:121], v[182:185], v[142:145]
	v_mfma_f32_16x16x32_bf16 v[138:141], v[126:129], v[182:185], v[138:141]
	v_mfma_f32_16x16x32_bf16 v[110:113], v[118:121], v[190:193], v[110:113]
	v_mfma_f32_16x16x32_bf16 v[106:109], v[126:129], v[190:193], v[106:109]
	v_mfma_f32_16x16x32_bf16 v[94:97], v[118:121], v[198:201], v[94:97]
	v_mfma_f32_16x16x32_bf16 v[90:93], v[126:129], v[198:201], v[90:93]
	v_mfma_f32_16x16x32_bf16 v[78:81], v[118:121], v[214:217], v[78:81]
	v_mfma_f32_16x16x32_bf16 v[74:77], v[126:129], v[214:217], v[74:77]
	v_mfma_f32_16x16x32_bf16 v[134:137], v[146:149], v[178:181], v[134:137]
	v_mfma_f32_16x16x32_bf16 v[130:133], v[154:157], v[178:181], v[130:133]
	v_mfma_f32_16x16x32_bf16 v[102:105], v[146:149], v[186:189], v[102:105]
	v_mfma_f32_16x16x32_bf16 v[98:101], v[154:157], v[186:189], v[98:101]
	v_mfma_f32_16x16x32_bf16 v[86:89], v[146:149], v[194:197], v[86:89]
	v_mfma_f32_16x16x32_bf16 v[82:85], v[154:157], v[194:197], v[82:85]
	v_mfma_f32_16x16x32_bf16 v[70:73], v[146:149], v[202:205], v[70:73]
	v_mfma_f32_16x16x32_bf16 v[66:69], v[154:157], v[202:205], v[66:69]
	v_mfma_f32_16x16x32_bf16 v[134:137], v[150:153], v[182:185], v[134:137]
	v_mfma_f32_16x16x32_bf16 v[130:133], v[158:161], v[182:185], v[130:133]
	v_mfma_f32_16x16x32_bf16 v[102:105], v[150:153], v[190:193], v[102:105]
	v_mfma_f32_16x16x32_bf16 v[98:101], v[158:161], v[190:193], v[98:101]
	v_mfma_f32_16x16x32_bf16 v[86:89], v[150:153], v[198:201], v[86:89]
	v_mfma_f32_16x16x32_bf16 v[82:85], v[158:161], v[198:201], v[82:85]
	v_mfma_f32_16x16x32_bf16 v[70:73], v[150:153], v[214:217], v[70:73]
	v_mfma_f32_16x16x32_bf16 v[66:69], v[158:161], v[214:217], v[66:69]
	s_barrier
	s_add_i32 s81, s64, s44
	v_lshl_add_u64 v[218:219], s[82:83], 0, v[164:165]
	s_mov_b32 m0, s81
	ds_read_b128 v[178:181], v211 offset:16384
	ds_read_b128 v[182:185], v211 offset:17408
	ds_read_b128 v[186:189], v211 offset:18432
	ds_read_b128 v[190:193], v211 offset:19456
	ds_read_b128 v[194:197], v211 offset:20480
	ds_read_b128 v[198:201], v211 offset:21504
	ds_read_b128 v[202:205], v211 offset:22528
	ds_read_b128 v[214:217], v211 offset:23552
	global_load_lds_dwordx4 v[218:219], off
	s_add_i32 m0, s81, 0x2000
	v_lshl_add_u64 v[220:221], s[82:83], 0, v[168:169]
	s_add_u32 s82, s82, s8
	s_addc_u32 s83, s83, s9
	s_add_i32 s81, s65, s44
	global_load_lds_dwordx4 v[220:221], off
	v_lshl_add_u64 v[222:223], s[82:83], 0, v[164:165]
	s_mov_b32 m0, s81
	v_lshl_add_u64 v[224:225], s[82:83], 0, v[168:169]
	global_load_lds_dwordx4 v[222:223], off
	s_add_i32 m0, s81, 0x2000
	v_lshl_add_u64 v[226:227], s[38:39], 0, v[162:163]
	global_load_lds_dwordx4 v[224:225], off
	s_mov_b32 m0, s45
	s_nop 0
	global_load_lds_dwordx4 v[226:227], off
	v_lshl_add_u64 v[226:227], s[38:39], 0, v[166:167]
	s_mov_b32 m0, s46
	s_nop 0
	global_load_lds_dwordx4 v[226:227], off
	s_waitcnt vmcnt(8)
	s_waitcnt lgkmcnt(0)
	s_waitcnt lgkmcnt(0)
	v_mfma_f32_16x16x32_bf16 v[62:65], v[114:117], v[178:181], v[62:65]
	v_mfma_f32_16x16x32_bf16 v[58:61], v[122:125], v[178:181], v[58:61]
	s_barrier
	v_mfma_f32_16x16x32_bf16 v[46:49], v[114:117], v[186:189], v[46:49]
	v_mfma_f32_16x16x32_bf16 v[42:45], v[122:125], v[186:189], v[42:45]
	v_mfma_f32_16x16x32_bf16 v[30:33], v[114:117], v[194:197], v[30:33]
	v_mfma_f32_16x16x32_bf16 v[26:29], v[122:125], v[194:197], v[26:29]
	v_mfma_f32_16x16x32_bf16 v[14:17], v[114:117], v[202:205], v[14:17]
	v_mfma_f32_16x16x32_bf16 v[10:13], v[122:125], v[202:205], v[10:13]
	v_mfma_f32_16x16x32_bf16 v[62:65], v[118:121], v[182:185], v[62:65]
	v_mfma_f32_16x16x32_bf16 v[58:61], v[126:129], v[182:185], v[58:61]
	v_mfma_f32_16x16x32_bf16 v[46:49], v[118:121], v[190:193], v[46:49]
	v_mfma_f32_16x16x32_bf16 v[42:45], v[126:129], v[190:193], v[42:45]
	v_mfma_f32_16x16x32_bf16 v[30:33], v[118:121], v[198:201], v[30:33]
	v_mfma_f32_16x16x32_bf16 v[26:29], v[126:129], v[198:201], v[26:29]
	v_mfma_f32_16x16x32_bf16 v[14:17], v[118:121], v[214:217], v[14:17]
	v_mfma_f32_16x16x32_bf16 v[10:13], v[126:129], v[214:217], v[10:13]
	v_mfma_f32_16x16x32_bf16 v[54:57], v[146:149], v[178:181], v[54:57]
	v_mfma_f32_16x16x32_bf16 v[50:53], v[154:157], v[178:181], v[50:53]
	v_mfma_f32_16x16x32_bf16 v[38:41], v[146:149], v[186:189], v[38:41]
	v_mfma_f32_16x16x32_bf16 v[34:37], v[154:157], v[186:189], v[34:37]
	v_mfma_f32_16x16x32_bf16 v[22:25], v[146:149], v[194:197], v[22:25]
	v_mfma_f32_16x16x32_bf16 v[18:21], v[154:157], v[194:197], v[18:21]
	v_mfma_f32_16x16x32_bf16 v[6:9], v[146:149], v[202:205], v[6:9]
	v_mfma_f32_16x16x32_bf16 v[2:5], v[154:157], v[202:205], v[2:5]
	v_mfma_f32_16x16x32_bf16 v[54:57], v[150:153], v[182:185], v[54:57]
	v_mfma_f32_16x16x32_bf16 v[50:53], v[158:161], v[182:185], v[50:53]
	v_mfma_f32_16x16x32_bf16 v[38:41], v[150:153], v[190:193], v[38:41]
	v_mfma_f32_16x16x32_bf16 v[34:37], v[158:161], v[190:193], v[34:37]
	v_mfma_f32_16x16x32_bf16 v[22:25], v[150:153], v[198:201], v[22:25]
	v_mfma_f32_16x16x32_bf16 v[18:21], v[158:161], v[198:201], v[18:21]
	v_mfma_f32_16x16x32_bf16 v[6:9], v[150:153], v[214:217], v[6:9]
	v_mfma_f32_16x16x32_bf16 v[2:5], v[158:161], v[214:217], v[2:5]
	s_barrier
	s_add_i32 s81, 0, 0x18000
	s_add_i32 s82, 0, 0x1c000
	v_add_u32_e32 v126, s81, v207
	v_add_u32_e32 v158, s82, v207
	ds_read_b128 v[114:117], v126
	ds_read_b128 v[118:121], v126 offset:1024
	ds_read_b128 v[122:125], v126 offset:2048
	ds_read_b128 v[126:129], v126 offset:3072
	ds_read_b128 v[146:149], v158
	ds_read_b128 v[150:153], v158 offset:1024
	ds_read_b128 v[154:157], v158 offset:2048
	ds_read_b128 v[158:161], v158 offset:3072
	s_add_u32 s38, s38, 0x4000
	s_addc_u32 s39, s39, 0
	s_mov_b32 m0, s47
	v_lshl_add_u64 v[226:227], s[38:39], 0, v[162:163]
	ds_read_b128 v[178:181], v211 offset:32768
	ds_read_b128 v[182:185], v211 offset:33792
	ds_read_b128 v[186:189], v211 offset:34816
	ds_read_b128 v[190:193], v211 offset:35840
	ds_read_b128 v[194:197], v211 offset:36864
	ds_read_b128 v[198:201], v211 offset:37888
	ds_read_b128 v[202:205], v211 offset:38912
	ds_read_b128 v[214:217], v211 offset:39936
	global_load_lds_dwordx4 v[226:227], off
	v_lshl_add_u64 v[226:227], s[38:39], 0, v[166:167]
	s_mov_b32 m0, s50
	s_nop 0
	global_load_lds_dwordx4 v[226:227], off
	s_waitcnt vmcnt(8)
	s_waitcnt lgkmcnt(0)
	s_waitcnt lgkmcnt(0)
	v_mfma_f32_16x16x32_bf16 v[142:145], v[114:117], v[178:181], v[142:145]
	v_mfma_f32_16x16x32_bf16 v[138:141], v[122:125], v[178:181], v[138:141]
	s_barrier
	v_mfma_f32_16x16x32_bf16 v[110:113], v[114:117], v[186:189], v[110:113]
	v_mfma_f32_16x16x32_bf16 v[106:109], v[122:125], v[186:189], v[106:109]
	v_mfma_f32_16x16x32_bf16 v[94:97], v[114:117], v[194:197], v[94:97]
	v_mfma_f32_16x16x32_bf16 v[90:93], v[122:125], v[194:197], v[90:93]
	v_mfma_f32_16x16x32_bf16 v[78:81], v[114:117], v[202:205], v[78:81]
	v_mfma_f32_16x16x32_bf16 v[74:77], v[122:125], v[202:205], v[74:77]
	v_mfma_f32_16x16x32_bf16 v[142:145], v[118:121], v[182:185], v[142:145]
	v_mfma_f32_16x16x32_bf16 v[138:141], v[126:129], v[182:185], v[138:141]
	v_mfma_f32_16x16x32_bf16 v[110:113], v[118:121], v[190:193], v[110:113]
	v_mfma_f32_16x16x32_bf16 v[106:109], v[126:129], v[190:193], v[106:109]
	v_mfma_f32_16x16x32_bf16 v[94:97], v[118:121], v[198:201], v[94:97]
	v_mfma_f32_16x16x32_bf16 v[90:93], v[126:129], v[198:201], v[90:93]
	v_mfma_f32_16x16x32_bf16 v[78:81], v[118:121], v[214:217], v[78:81]
	v_mfma_f32_16x16x32_bf16 v[74:77], v[126:129], v[214:217], v[74:77]
	v_mfma_f32_16x16x32_bf16 v[134:137], v[146:149], v[178:181], v[134:137]
	v_mfma_f32_16x16x32_bf16 v[130:133], v[154:157], v[178:181], v[130:133]
	v_mfma_f32_16x16x32_bf16 v[102:105], v[146:149], v[186:189], v[102:105]
	v_mfma_f32_16x16x32_bf16 v[98:101], v[154:157], v[186:189], v[98:101]
	v_mfma_f32_16x16x32_bf16 v[86:89], v[146:149], v[194:197], v[86:89]
	v_mfma_f32_16x16x32_bf16 v[82:85], v[154:157], v[194:197], v[82:85]
	v_mfma_f32_16x16x32_bf16 v[70:73], v[146:149], v[202:205], v[70:73]
	v_mfma_f32_16x16x32_bf16 v[66:69], v[154:157], v[202:205], v[66:69]
	v_mfma_f32_16x16x32_bf16 v[134:137], v[150:153], v[182:185], v[134:137]
	v_mfma_f32_16x16x32_bf16 v[130:133], v[158:161], v[182:185], v[130:133]
	v_mfma_f32_16x16x32_bf16 v[102:105], v[150:153], v[190:193], v[102:105]
	v_mfma_f32_16x16x32_bf16 v[98:101], v[158:161], v[190:193], v[98:101]
	v_mfma_f32_16x16x32_bf16 v[86:89], v[150:153], v[198:201], v[86:89]
	v_mfma_f32_16x16x32_bf16 v[82:85], v[158:161], v[198:201], v[82:85]
	v_mfma_f32_16x16x32_bf16 v[70:73], v[150:153], v[214:217], v[70:73]
	v_mfma_f32_16x16x32_bf16 v[66:69], v[158:161], v[214:217], v[66:69]
	s_barrier
	s_add_i32 s38, s81, s44
	v_lshl_add_u64 v[218:219], v[218:219], 0, s[24:25]
	s_mov_b32 m0, s38
	ds_read_b128 v[178:181], v211 offset:49152
	ds_read_b128 v[182:185], v211 offset:50176
	ds_read_b128 v[186:189], v211 offset:51200
	ds_read_b128 v[190:193], v211 offset:52224
	ds_read_b128 v[194:197], v211 offset:53248
	ds_read_b128 v[198:201], v211 offset:54272
	ds_read_b128 v[202:205], v211 offset:55296
	ds_read_b128 v[214:217], v211 offset:56320
	global_load_lds_dwordx4 v[218:219], off
	v_lshl_add_u64 v[218:219], v[220:221], 0, s[24:25]
	s_add_i32 m0, s38, 0x2000
	s_add_i32 s38, s82, s44
	global_load_lds_dwordx4 v[218:219], off
	v_lshl_add_u64 v[218:219], v[222:223], 0, s[24:25]
	s_mov_b32 m0, s38
	s_nop 0
	global_load_lds_dwordx4 v[218:219], off
	v_lshl_add_u64 v[218:219], v[224:225], 0, s[24:25]
	s_add_i32 m0, s38, 0x2000
	s_nop 0
	global_load_lds_dwordx4 v[218:219], off
	v_lshl_add_u64 v[218:219], s[36:37], 0, v[162:163]
	s_mov_b32 m0, s59
	s_nop 0
	global_load_lds_dwordx4 v[218:219], off
	v_lshl_add_u64 v[218:219], s[36:37], 0, v[166:167]
	s_mov_b32 m0, s60
	s_nop 0
	global_load_lds_dwordx4 v[218:219], off
	s_waitcnt vmcnt(8)
	s_waitcnt lgkmcnt(0)
	s_waitcnt lgkmcnt(0)
	v_mfma_f32_16x16x32_bf16 v[62:65], v[114:117], v[178:181], v[62:65]
	v_mfma_f32_16x16x32_bf16 v[58:61], v[122:125], v[178:181], v[58:61]
	s_barrier
	v_mfma_f32_16x16x32_bf16 v[46:49], v[114:117], v[186:189], v[46:49]
	v_mfma_f32_16x16x32_bf16 v[42:45], v[122:125], v[186:189], v[42:45]
	v_mfma_f32_16x16x32_bf16 v[30:33], v[114:117], v[194:197], v[30:33]
	v_mfma_f32_16x16x32_bf16 v[26:29], v[122:125], v[194:197], v[26:29]
	v_mfma_f32_16x16x32_bf16 v[14:17], v[114:117], v[202:205], v[14:17]
	v_mfma_f32_16x16x32_bf16 v[10:13], v[122:125], v[202:205], v[10:13]
	v_mfma_f32_16x16x32_bf16 v[62:65], v[118:121], v[182:185], v[62:65]
	v_mfma_f32_16x16x32_bf16 v[58:61], v[126:129], v[182:185], v[58:61]
	v_mfma_f32_16x16x32_bf16 v[46:49], v[118:121], v[190:193], v[46:49]
	v_mfma_f32_16x16x32_bf16 v[42:45], v[126:129], v[190:193], v[42:45]
	v_mfma_f32_16x16x32_bf16 v[30:33], v[118:121], v[198:201], v[30:33]
	v_mfma_f32_16x16x32_bf16 v[26:29], v[126:129], v[198:201], v[26:29]
	v_mfma_f32_16x16x32_bf16 v[14:17], v[118:121], v[214:217], v[14:17]
	v_mfma_f32_16x16x32_bf16 v[10:13], v[126:129], v[214:217], v[10:13]
	v_mfma_f32_16x16x32_bf16 v[54:57], v[146:149], v[178:181], v[54:57]
	v_mfma_f32_16x16x32_bf16 v[50:53], v[154:157], v[178:181], v[50:53]
	v_mfma_f32_16x16x32_bf16 v[38:41], v[146:149], v[186:189], v[38:41]
	v_mfma_f32_16x16x32_bf16 v[34:37], v[154:157], v[186:189], v[34:37]
	v_mfma_f32_16x16x32_bf16 v[22:25], v[146:149], v[194:197], v[22:25]
	v_mfma_f32_16x16x32_bf16 v[18:21], v[154:157], v[194:197], v[18:21]
	v_mfma_f32_16x16x32_bf16 v[6:9], v[146:149], v[202:205], v[6:9]
	v_mfma_f32_16x16x32_bf16 v[2:5], v[154:157], v[202:205], v[2:5]
	v_mfma_f32_16x16x32_bf16 v[54:57], v[150:153], v[182:185], v[54:57]
	v_mfma_f32_16x16x32_bf16 v[50:53], v[158:161], v[182:185], v[50:53]
	v_mfma_f32_16x16x32_bf16 v[38:41], v[150:153], v[190:193], v[38:41]
	v_mfma_f32_16x16x32_bf16 v[34:37], v[158:161], v[190:193], v[34:37]
	v_mfma_f32_16x16x32_bf16 v[22:25], v[150:153], v[198:201], v[22:25]
	v_mfma_f32_16x16x32_bf16 v[18:21], v[158:161], v[198:201], v[18:21]
	v_mfma_f32_16x16x32_bf16 v[6:9], v[150:153], v[214:217], v[6:9]
	v_mfma_f32_16x16x32_bf16 v[2:5], v[158:161], v[214:217], v[2:5]
	s_barrier
	s_add_u32 s70, s70, 0x100
	s_addc_u32 s71, s71, 0
	s_add_u32 s34, s34, 0x10000
	s_addc_u32 s35, s35, 0
	s_cmp_ge_i32 s80, s58
	s_mov_b32 s36, s80
	s_cbranch_scc0 .LBB0_3032

.LBB0_3126:
	ds_read_b128 v[34:37], v196
	ds_read_b128 v[38:41], v196 offset:1024
	ds_read_b128 v[50:53], v196 offset:2048
	ds_read_b128 v[54:57], v196 offset:3072
	ds_read_b128 v[146:149], v197
	ds_read_b128 v[150:153], v197 offset:1024
	ds_read_b128 v[184:187], v197 offset:2048
	ds_read_b128 v[188:191], v197 offset:3072
	s_add_i32 s11, s6, 2
	s_add_u32 s12, s4, 0x80
	s_addc_u32 s7, s5, 0
	s_cmp_eq_u32 s84, s6
	s_cselect_b32 s6, s44, s12
	s_cselect_b32 s7, s45, s7
	s_cselect_b32 s13, s47, s9
	s_cselect_b32 s12, s46, s8
	v_lshl_add_u64 v[192:193], s[4:5], 0, v[174:175]
	s_add_i32 m0, s66, 0xc000
	ds_read_b128 v[200:203], v198
	ds_read_b128 v[204:207], v198 offset:1024
	ds_read_b128 v[208:211], v198 offset:2048
	ds_read_b128 v[212:215], v198 offset:3072
	ds_read_b128 v[216:219], v198 offset:4096
	ds_read_b128 v[220:223], v198 offset:5120
	ds_read_b128 v[224:227], v198 offset:6144
	ds_read_b128 v[228:231], v198 offset:7168
	global_load_lds_dwordx4 v[192:193], off
	v_lshl_add_u64 v[192:193], s[4:5], 0, v[176:177]
	s_add_i32 m0, s66, 0xe000
	s_nop 0
	global_load_lds_dwordx4 v[192:193], off
	s_waitcnt vmcnt(8)
	s_waitcnt lgkmcnt(0)
	s_waitcnt lgkmcnt(0)
	v_mfma_f32_16x16x32_bf16 v[142:145], v[34:37], v[200:203], v[142:145]
	v_mfma_f32_16x16x32_bf16 v[138:141], v[50:53], v[200:203], v[138:141]
	s_barrier
	v_mfma_f32_16x16x32_bf16 v[126:129], v[34:37], v[208:211], v[126:129]
	v_mfma_f32_16x16x32_bf16 v[122:125], v[50:53], v[208:211], v[122:125]
	v_mfma_f32_16x16x32_bf16 v[110:113], v[34:37], v[216:219], v[110:113]
	v_mfma_f32_16x16x32_bf16 v[106:109], v[50:53], v[216:219], v[106:109]
	v_mfma_f32_16x16x32_bf16 v[94:97], v[34:37], v[224:227], v[94:97]
	v_mfma_f32_16x16x32_bf16 v[90:93], v[50:53], v[224:227], v[90:93]
	v_mfma_f32_16x16x32_bf16 v[142:145], v[38:41], v[204:207], v[142:145]
	v_mfma_f32_16x16x32_bf16 v[138:141], v[54:57], v[204:207], v[138:141]
	v_mfma_f32_16x16x32_bf16 v[126:129], v[38:41], v[212:215], v[126:129]
	v_mfma_f32_16x16x32_bf16 v[122:125], v[54:57], v[212:215], v[122:125]
	v_mfma_f32_16x16x32_bf16 v[110:113], v[38:41], v[220:223], v[110:113]
	v_mfma_f32_16x16x32_bf16 v[106:109], v[54:57], v[220:223], v[106:109]
	v_mfma_f32_16x16x32_bf16 v[94:97], v[38:41], v[228:231], v[94:97]
	v_mfma_f32_16x16x32_bf16 v[90:93], v[54:57], v[228:231], v[90:93]
	v_mfma_f32_16x16x32_bf16 v[134:137], v[146:149], v[200:203], v[134:137]
	v_mfma_f32_16x16x32_bf16 v[130:133], v[184:187], v[200:203], v[130:133]
	v_mfma_f32_16x16x32_bf16 v[118:121], v[146:149], v[208:211], v[118:121]
	v_mfma_f32_16x16x32_bf16 v[114:117], v[184:187], v[208:211], v[114:117]
	v_mfma_f32_16x16x32_bf16 v[102:105], v[146:149], v[216:219], v[102:105]
	v_mfma_f32_16x16x32_bf16 v[98:101], v[184:187], v[216:219], v[98:101]
	v_mfma_f32_16x16x32_bf16 v[86:89], v[146:149], v[224:227], v[86:89]
	v_mfma_f32_16x16x32_bf16 v[82:85], v[184:187], v[224:227], v[82:85]
	v_mfma_f32_16x16x32_bf16 v[134:137], v[150:153], v[204:207], v[134:137]
	v_mfma_f32_16x16x32_bf16 v[130:133], v[188:191], v[204:207], v[130:133]
	v_mfma_f32_16x16x32_bf16 v[118:121], v[150:153], v[212:215], v[118:121]
	v_mfma_f32_16x16x32_bf16 v[114:117], v[188:191], v[212:215], v[114:117]
	v_mfma_f32_16x16x32_bf16 v[102:105], v[150:153], v[220:223], v[102:105]
	v_mfma_f32_16x16x32_bf16 v[98:101], v[188:191], v[220:223], v[98:101]
	v_mfma_f32_16x16x32_bf16 v[86:89], v[150:153], v[228:231], v[86:89]
	v_mfma_f32_16x16x32_bf16 v[82:85], v[188:191], v[228:231], v[82:85]
	s_barrier
	s_add_i32 s20, s88, s61
	v_lshl_add_u64 v[192:193], s[12:13], 0, v[156:157]
	s_mov_b32 m0, s20
	ds_read_b128 v[200:203], v198 offset:16384
	ds_read_b128 v[204:207], v198 offset:17408
	ds_read_b128 v[208:211], v198 offset:18432
	ds_read_b128 v[212:215], v198 offset:19456
	ds_read_b128 v[216:219], v198 offset:20480
	ds_read_b128 v[220:223], v198 offset:21504
	ds_read_b128 v[224:227], v198 offset:22528
	ds_read_b128 v[228:231], v198 offset:23552
	global_load_lds_dwordx4 v[192:193], off
	s_add_i32 m0, s20, 0x2000
	v_lshl_add_u64 v[232:233], s[12:13], 0, v[160:161]
	s_add_u32 s12, s12, s16
	s_addc_u32 s13, s13, s17
	s_add_i32 s20, s89, s61
	global_load_lds_dwordx4 v[232:233], off
	v_lshl_add_u64 v[234:235], s[12:13], 0, v[156:157]
	s_mov_b32 m0, s20
	v_lshl_add_u64 v[236:237], s[12:13], 0, v[160:161]
	global_load_lds_dwordx4 v[234:235], off
	s_add_i32 m0, s20, 0x2000
	v_lshl_add_u64 v[238:239], s[6:7], 0, v[154:155]
	global_load_lds_dwordx4 v[236:237], off
	s_mov_b32 m0, s66
	v_lshl_add_u64 v[240:241], s[6:7], 0, v[158:159]
	global_load_lds_dwordx4 v[238:239], off
	s_mov_b32 m0, s68
	s_nop 0
	global_load_lds_dwordx4 v[240:241], off
	s_waitcnt vmcnt(8)
	s_waitcnt lgkmcnt(0)
	s_waitcnt lgkmcnt(0)
	v_mfma_f32_16x16x32_bf16 v[78:81], v[34:37], v[200:203], v[78:81]
	v_mfma_f32_16x16x32_bf16 v[74:77], v[50:53], v[200:203], v[74:77]
	s_barrier
	v_mfma_f32_16x16x32_bf16 v[62:65], v[34:37], v[208:211], v[62:65]
	v_mfma_f32_16x16x32_bf16 v[58:61], v[50:53], v[208:211], v[58:61]
	v_mfma_f32_16x16x32_bf16 v[30:33], v[34:37], v[216:219], v[30:33]
	v_mfma_f32_16x16x32_bf16 v[26:29], v[50:53], v[216:219], v[26:29]
	v_mfma_f32_16x16x32_bf16 v[14:17], v[34:37], v[224:227], v[14:17]
	v_mfma_f32_16x16x32_bf16 v[10:13], v[50:53], v[224:227], v[10:13]
	v_mfma_f32_16x16x32_bf16 v[78:81], v[38:41], v[204:207], v[78:81]
	v_mfma_f32_16x16x32_bf16 v[74:77], v[54:57], v[204:207], v[74:77]
	v_mfma_f32_16x16x32_bf16 v[62:65], v[38:41], v[212:215], v[62:65]
	v_mfma_f32_16x16x32_bf16 v[58:61], v[54:57], v[212:215], v[58:61]
	v_mfma_f32_16x16x32_bf16 v[30:33], v[38:41], v[220:223], v[30:33]
	v_mfma_f32_16x16x32_bf16 v[26:29], v[54:57], v[220:223], v[26:29]
	v_mfma_f32_16x16x32_bf16 v[14:17], v[38:41], v[228:231], v[14:17]
	v_mfma_f32_16x16x32_bf16 v[10:13], v[54:57], v[228:231], v[10:13]
	v_mfma_f32_16x16x32_bf16 v[46:49], v[146:149], v[208:211], v[46:49]
	v_mfma_f32_16x16x32_bf16 v[42:45], v[184:187], v[208:211], v[42:45]
	v_mfma_f32_16x16x32_bf16 v[22:25], v[146:149], v[216:219], v[22:25]
	v_mfma_f32_16x16x32_bf16 v[18:21], v[184:187], v[216:219], v[18:21]
	v_mfma_f32_16x16x32_bf16 v[6:9], v[146:149], v[224:227], v[6:9]
	v_mfma_f32_16x16x32_bf16 v[2:5], v[184:187], v[224:227], v[2:5]
	v_mfma_f32_16x16x32_bf16 v[34:37], v[146:149], v[200:203], v[70:73]
	v_mfma_f32_16x16x32_bf16 v[38:41], v[184:187], v[200:203], v[66:69]
	v_mfma_f32_16x16x32_bf16 v[46:49], v[150:153], v[212:215], v[46:49]
	v_mfma_f32_16x16x32_bf16 v[42:45], v[188:191], v[212:215], v[42:45]
	v_mfma_f32_16x16x32_bf16 v[22:25], v[150:153], v[220:223], v[22:25]
	v_mfma_f32_16x16x32_bf16 v[18:21], v[188:191], v[220:223], v[18:21]
	v_mfma_f32_16x16x32_bf16 v[6:9], v[150:153], v[228:231], v[6:9]
	v_mfma_f32_16x16x32_bf16 v[2:5], v[188:191], v[228:231], v[2:5]
	v_mfma_f32_16x16x32_bf16 v[34:37], v[150:153], v[204:207], v[34:37]
	v_mfma_f32_16x16x32_bf16 v[38:41], v[188:191], v[204:207], v[38:41]
	s_barrier
	s_add_i32 s12, 0, 0x18000
	s_add_i32 s13, 0, 0x1c000
	v_add_u32_e32 v70, s12, v194
	v_add_u32_e32 v162, s13, v194
	ds_read_b128 v[50:53], v70
	ds_read_b128 v[54:57], v70 offset:1024
	ds_read_b128 v[66:69], v70 offset:2048
	ds_read_b128 v[70:73], v70 offset:3072
	ds_read_b128 v[146:149], v162
	ds_read_b128 v[150:153], v162 offset:1024
	ds_read_b128 v[184:187], v162 offset:2048
	ds_read_b128 v[188:191], v162 offset:3072
	s_add_u32 s6, s6, s16
	s_addc_u32 s7, s7, s17
	s_mov_b32 m0, s69
	v_lshl_add_u64 v[242:243], s[6:7], 0, v[154:155]
	ds_read_b128 v[200:203], v198 offset:32768
	ds_read_b128 v[204:207], v198 offset:33792
	ds_read_b128 v[208:211], v198 offset:34816
	ds_read_b128 v[212:215], v198 offset:35840
	ds_read_b128 v[216:219], v198 offset:36864
	ds_read_b128 v[220:223], v198 offset:37888
	ds_read_b128 v[224:227], v198 offset:38912
	ds_read_b128 v[228:231], v198 offset:39936
	global_load_lds_dwordx4 v[242:243], off
	v_lshl_add_u64 v[242:243], s[6:7], 0, v[158:159]
	s_mov_b32 m0, s70
	s_nop 0
	global_load_lds_dwordx4 v[242:243], off
	s_waitcnt vmcnt(8)
	s_waitcnt lgkmcnt(0)
	s_waitcnt lgkmcnt(0)
	v_mfma_f32_16x16x32_bf16 v[142:145], v[50:53], v[200:203], v[142:145]
	v_mfma_f32_16x16x32_bf16 v[138:141], v[66:69], v[200:203], v[138:141]
	s_barrier
	v_mfma_f32_16x16x32_bf16 v[126:129], v[50:53], v[208:211], v[126:129]
	v_mfma_f32_16x16x32_bf16 v[122:125], v[66:69], v[208:211], v[122:125]
	v_mfma_f32_16x16x32_bf16 v[110:113], v[50:53], v[216:219], v[110:113]
	v_mfma_f32_16x16x32_bf16 v[106:109], v[66:69], v[216:219], v[106:109]
	v_mfma_f32_16x16x32_bf16 v[94:97], v[50:53], v[224:227], v[94:97]
	v_mfma_f32_16x16x32_bf16 v[90:93], v[66:69], v[224:227], v[90:93]
	v_mfma_f32_16x16x32_bf16 v[142:145], v[54:57], v[204:207], v[142:145]
	v_mfma_f32_16x16x32_bf16 v[138:141], v[70:73], v[204:207], v[138:141]
	v_mfma_f32_16x16x32_bf16 v[126:129], v[54:57], v[212:215], v[126:129]
	v_mfma_f32_16x16x32_bf16 v[122:125], v[70:73], v[212:215], v[122:125]
	v_mfma_f32_16x16x32_bf16 v[110:113], v[54:57], v[220:223], v[110:113]
	v_mfma_f32_16x16x32_bf16 v[106:109], v[70:73], v[220:223], v[106:109]
	v_mfma_f32_16x16x32_bf16 v[94:97], v[54:57], v[228:231], v[94:97]
	v_mfma_f32_16x16x32_bf16 v[90:93], v[70:73], v[228:231], v[90:93]
	v_mfma_f32_16x16x32_bf16 v[134:137], v[146:149], v[200:203], v[134:137]
	v_mfma_f32_16x16x32_bf16 v[130:133], v[184:187], v[200:203], v[130:133]
	v_mfma_f32_16x16x32_bf16 v[118:121], v[146:149], v[208:211], v[118:121]
	v_mfma_f32_16x16x32_bf16 v[114:117], v[184:187], v[208:211], v[114:117]
	v_mfma_f32_16x16x32_bf16 v[102:105], v[146:149], v[216:219], v[102:105]
	v_mfma_f32_16x16x32_bf16 v[98:101], v[184:187], v[216:219], v[98:101]
	v_mfma_f32_16x16x32_bf16 v[86:89], v[146:149], v[224:227], v[86:89]
	v_mfma_f32_16x16x32_bf16 v[82:85], v[184:187], v[224:227], v[82:85]
	v_mfma_f32_16x16x32_bf16 v[134:137], v[150:153], v[204:207], v[134:137]
	v_mfma_f32_16x16x32_bf16 v[130:133], v[188:191], v[204:207], v[130:133]
	v_mfma_f32_16x16x32_bf16 v[118:121], v[150:153], v[212:215], v[118:121]
	v_mfma_f32_16x16x32_bf16 v[114:117], v[188:191], v[212:215], v[114:117]
	v_mfma_f32_16x16x32_bf16 v[102:105], v[150:153], v[220:223], v[102:105]
	v_mfma_f32_16x16x32_bf16 v[98:101], v[188:191], v[220:223], v[98:101]
	v_mfma_f32_16x16x32_bf16 v[86:89], v[150:153], v[228:231], v[86:89]
	v_mfma_f32_16x16x32_bf16 v[82:85], v[188:191], v[228:231], v[82:85]
	s_barrier
	s_add_i32 s6, s12, s61
	v_lshl_add_u64 v[192:193], v[192:193], 0, s[38:39]
	s_mov_b32 m0, s6
	ds_read_b128 v[200:203], v198 offset:49152
	ds_read_b128 v[204:207], v198 offset:50176
	ds_read_b128 v[208:211], v198 offset:51200
	ds_read_b128 v[212:215], v198 offset:52224
	ds_read_b128 v[216:219], v198 offset:53248
	ds_read_b128 v[220:223], v198 offset:54272
	ds_read_b128 v[224:227], v198 offset:55296
	ds_read_b128 v[228:231], v198 offset:56320
	global_load_lds_dwordx4 v[192:193], off
	v_lshl_add_u64 v[192:193], v[232:233], 0, s[38:39]
	s_add_i32 m0, s6, 0x2000
	s_add_i32 s6, s13, s61
	global_load_lds_dwordx4 v[192:193], off
	v_lshl_add_u64 v[192:193], v[234:235], 0, s[38:39]
	s_mov_b32 m0, s6
	s_nop 0
	global_load_lds_dwordx4 v[192:193], off
	v_lshl_add_u64 v[192:193], v[236:237], 0, s[38:39]
	s_add_i32 m0, s6, 0x2000
	s_nop 0
	global_load_lds_dwordx4 v[192:193], off
	v_lshl_add_u64 v[192:193], v[238:239], 0, s[38:39]
	s_mov_b32 m0, s81
	s_nop 0
	global_load_lds_dwordx4 v[192:193], off
	v_lshl_add_u64 v[192:193], v[240:241], 0, s[38:39]
	s_mov_b32 m0, s82
	s_nop 0
	global_load_lds_dwordx4 v[192:193], off
	s_waitcnt vmcnt(8)
	s_waitcnt lgkmcnt(0)
	s_waitcnt lgkmcnt(0)
	v_mfma_f32_16x16x32_bf16 v[78:81], v[50:53], v[200:203], v[78:81]
	v_mfma_f32_16x16x32_bf16 v[74:77], v[66:69], v[200:203], v[74:77]
	s_barrier
	v_mfma_f32_16x16x32_bf16 v[62:65], v[50:53], v[208:211], v[62:65]
	v_mfma_f32_16x16x32_bf16 v[58:61], v[66:69], v[208:211], v[58:61]
	v_mfma_f32_16x16x32_bf16 v[30:33], v[50:53], v[216:219], v[30:33]
	v_mfma_f32_16x16x32_bf16 v[26:29], v[66:69], v[216:219], v[26:29]
	v_mfma_f32_16x16x32_bf16 v[14:17], v[50:53], v[224:227], v[14:17]
	v_mfma_f32_16x16x32_bf16 v[10:13], v[66:69], v[224:227], v[10:13]
	v_mfma_f32_16x16x32_bf16 v[78:81], v[54:57], v[204:207], v[78:81]
	v_mfma_f32_16x16x32_bf16 v[74:77], v[70:73], v[204:207], v[74:77]
	v_mfma_f32_16x16x32_bf16 v[62:65], v[54:57], v[212:215], v[62:65]
	v_mfma_f32_16x16x32_bf16 v[58:61], v[70:73], v[212:215], v[58:61]
	v_mfma_f32_16x16x32_bf16 v[30:33], v[54:57], v[220:223], v[30:33]
	v_mfma_f32_16x16x32_bf16 v[26:29], v[70:73], v[220:223], v[26:29]
	v_mfma_f32_16x16x32_bf16 v[14:17], v[54:57], v[228:231], v[14:17]
	v_mfma_f32_16x16x32_bf16 v[10:13], v[70:73], v[228:231], v[10:13]
	v_mfma_f32_16x16x32_bf16 v[34:37], v[146:149], v[200:203], v[34:37]
	v_mfma_f32_16x16x32_bf16 v[70:73], v[150:153], v[204:207], v[34:37]
	v_mfma_f32_16x16x32_bf16 v[34:37], v[184:187], v[200:203], v[38:41]
	v_mfma_f32_16x16x32_bf16 v[66:69], v[188:191], v[204:207], v[34:37]
	v_mfma_f32_16x16x32_bf16 v[34:37], v[146:149], v[208:211], v[46:49]
	v_mfma_f32_16x16x32_bf16 v[46:49], v[150:153], v[212:215], v[34:37]
	v_mfma_f32_16x16x32_bf16 v[34:37], v[184:187], v[208:211], v[42:45]
	v_mfma_f32_16x16x32_bf16 v[22:25], v[146:149], v[216:219], v[22:25]
	v_mfma_f32_16x16x32_bf16 v[18:21], v[184:187], v[216:219], v[18:21]
	v_mfma_f32_16x16x32_bf16 v[6:9], v[146:149], v[224:227], v[6:9]
	v_mfma_f32_16x16x32_bf16 v[2:5], v[184:187], v[224:227], v[2:5]
	v_mfma_f32_16x16x32_bf16 v[42:45], v[188:191], v[212:215], v[34:37]
	v_mfma_f32_16x16x32_bf16 v[22:25], v[150:153], v[220:223], v[22:25]
	v_mfma_f32_16x16x32_bf16 v[18:21], v[188:191], v[220:223], v[18:21]
	v_mfma_f32_16x16x32_bf16 v[6:9], v[150:153], v[228:231], v[6:9]
	v_mfma_f32_16x16x32_bf16 v[2:5], v[188:191], v[228:231], v[2:5]
	s_barrier
	s_add_u32 s4, s4, 0x100
	s_addc_u32 s5, s5, 0
	s_add_u32 s8, s8, 0x100
	s_addc_u32 s9, s9, 0
	s_cmp_ge_i32 s11, s83
	s_mov_b32 s6, s11
	s_cbranch_scc0 .LBB0_3126

.LBB0_3613:
	v_add_u32_e32 v158, s64, v229
	v_add_u32_e32 v174, s65, v229
	ds_read_b128 v[146:149], v158
	ds_read_b128 v[150:153], v158 offset:1024
	ds_read_b128 v[154:157], v158 offset:2048
	ds_read_b128 v[158:161], v158 offset:3072
	ds_read_b128 v[162:165], v174
	ds_read_b128 v[166:169], v174 offset:1024
	ds_read_b128 v[170:173], v174 offset:2048
	ds_read_b128 v[174:177], v174 offset:3072
	s_add_i32 s80, s42, 2
	s_add_u32 s81, s40, 0x80
	s_addc_u32 s43, s41, 0
	s_cmp_eq_u32 s61, s42
	s_cselect_b32 s42, s4, s81
	s_cselect_b32 s43, s5, s43
	s_cselect_b32 s83, s39, s71
	s_cselect_b32 s82, s38, s70
	v_lshl_add_u64 v[210:211], s[40:41], 0, v[138:139]
	s_add_i32 m0, s51, 0xc000
	ds_read_b128 v[178:181], v231
	ds_read_b128 v[182:185], v231 offset:1024
	ds_read_b128 v[186:189], v231 offset:2048
	ds_read_b128 v[190:193], v231 offset:3072
	ds_read_b128 v[194:197], v231 offset:4096
	ds_read_b128 v[198:201], v231 offset:5120
	ds_read_b128 v[202:205], v231 offset:6144
	ds_read_b128 v[206:209], v231 offset:7168
	global_load_lds_dwordx4 v[210:211], off
	v_lshl_add_u64 v[210:211], s[40:41], 0, v[140:141]
	s_add_i32 m0, s51, 0xe000
	s_nop 0
	global_load_lds_dwordx4 v[210:211], off
	s_waitcnt vmcnt(8)
	s_waitcnt lgkmcnt(0)
	s_waitcnt lgkmcnt(0)
	v_mfma_i32_16x16x64_i8 v[126:129], v[146:149], v[178:181], v[126:129]
	v_mfma_i32_16x16x64_i8 v[122:125], v[154:157], v[178:181], v[122:125]
	s_barrier
	v_mfma_i32_16x16x64_i8 v[118:121], v[146:149], v[186:189], v[118:121]
	v_mfma_i32_16x16x64_i8 v[114:117], v[154:157], v[186:189], v[114:117]
	v_mfma_i32_16x16x64_i8 v[106:109], v[146:149], v[194:197], v[106:109]
	v_mfma_i32_16x16x64_i8 v[98:101], v[154:157], v[194:197], v[98:101]
	v_mfma_i32_16x16x64_i8 v[90:93], v[146:149], v[202:205], v[90:93]
	v_mfma_i32_16x16x64_i8 v[82:85], v[154:157], v[202:205], v[82:85]
	v_mfma_i32_16x16x64_i8 v[126:129], v[150:153], v[182:185], v[126:129]
	v_mfma_i32_16x16x64_i8 v[122:125], v[158:161], v[182:185], v[122:125]
	v_mfma_i32_16x16x64_i8 v[118:121], v[150:153], v[190:193], v[118:121]
	v_mfma_i32_16x16x64_i8 v[114:117], v[158:161], v[190:193], v[114:117]
	v_mfma_i32_16x16x64_i8 v[106:109], v[150:153], v[198:201], v[106:109]
	v_mfma_i32_16x16x64_i8 v[98:101], v[158:161], v[198:201], v[98:101]
	v_mfma_i32_16x16x64_i8 v[90:93], v[150:153], v[206:209], v[90:93]
	v_mfma_i32_16x16x64_i8 v[82:85], v[158:161], v[206:209], v[82:85]
	v_mfma_i32_16x16x64_i8 v[110:113], v[162:165], v[178:181], v[110:113]
	v_mfma_i32_16x16x64_i8 v[102:105], v[170:173], v[178:181], v[102:105]
	v_mfma_i32_16x16x64_i8 v[94:97], v[162:165], v[186:189], v[94:97]
	v_mfma_i32_16x16x64_i8 v[86:89], v[170:173], v[186:189], v[86:89]
	v_mfma_i32_16x16x64_i8 v[78:81], v[162:165], v[194:197], v[78:81]
	v_mfma_i32_16x16x64_i8 v[74:77], v[170:173], v[194:197], v[74:77]
	v_mfma_i32_16x16x64_i8 v[70:73], v[162:165], v[202:205], v[70:73]
	v_mfma_i32_16x16x64_i8 v[66:69], v[170:173], v[202:205], v[66:69]
	v_mfma_i32_16x16x64_i8 v[110:113], v[166:169], v[182:185], v[110:113]
	v_mfma_i32_16x16x64_i8 v[102:105], v[174:177], v[182:185], v[102:105]
	v_mfma_i32_16x16x64_i8 v[94:97], v[166:169], v[190:193], v[94:97]
	v_mfma_i32_16x16x64_i8 v[86:89], v[174:177], v[190:193], v[86:89]
	v_mfma_i32_16x16x64_i8 v[78:81], v[166:169], v[198:201], v[78:81]
	v_mfma_i32_16x16x64_i8 v[74:77], v[174:177], v[198:201], v[74:77]
	v_mfma_i32_16x16x64_i8 v[70:73], v[166:169], v[206:209], v[70:73]
	v_mfma_i32_16x16x64_i8 v[66:69], v[174:177], v[206:209], v[66:69]
	s_barrier
	s_add_i32 s81, s64, s50
	v_lshl_add_u64 v[210:211], s[82:83], 0, v[132:133]
	s_mov_b32 m0, s81
	ds_read_b128 v[178:181], v231 offset:16384
	ds_read_b128 v[182:185], v231 offset:17408
	ds_read_b128 v[186:189], v231 offset:18432
	ds_read_b128 v[190:193], v231 offset:19456
	ds_read_b128 v[194:197], v231 offset:20480
	ds_read_b128 v[198:201], v231 offset:21504
	ds_read_b128 v[202:205], v231 offset:22528
	ds_read_b128 v[206:209], v231 offset:23552
	global_load_lds_dwordx4 v[210:211], off
	s_add_i32 m0, s81, 0x2000
	v_lshl_add_u64 v[212:213], s[82:83], 0, v[136:137]
	s_add_u32 s82, s82, s8
	s_addc_u32 s83, s83, s9
	s_add_i32 s81, s65, s50
	global_load_lds_dwordx4 v[212:213], off
	v_lshl_add_u64 v[214:215], s[82:83], 0, v[132:133]
	s_mov_b32 m0, s81
	v_lshl_add_u64 v[216:217], s[82:83], 0, v[136:137]
	global_load_lds_dwordx4 v[214:215], off
	s_add_i32 m0, s81, 0x2000
	v_lshl_add_u64 v[218:219], s[42:43], 0, v[130:131]
	global_load_lds_dwordx4 v[216:217], off
	s_mov_b32 m0, s51
	v_lshl_add_u64 v[220:221], s[42:43], 0, v[134:135]
	global_load_lds_dwordx4 v[218:219], off
	s_mov_b32 m0, s52
	s_nop 0
	global_load_lds_dwordx4 v[220:221], off
	s_waitcnt vmcnt(8)
	s_waitcnt lgkmcnt(0)
	s_waitcnt lgkmcnt(0)
	v_mfma_i32_16x16x64_i8 v[62:65], v[146:149], v[178:181], v[62:65]
	v_mfma_i32_16x16x64_i8 v[58:61], v[154:157], v[178:181], v[58:61]
	s_barrier
	v_mfma_i32_16x16x64_i8 v[54:57], v[146:149], v[186:189], v[54:57]
	v_mfma_i32_16x16x64_i8 v[50:53], v[154:157], v[186:189], v[50:53]
	v_mfma_i32_16x16x64_i8 v[42:45], v[146:149], v[194:197], v[42:45]
	v_mfma_i32_16x16x64_i8 v[34:37], v[154:157], v[194:197], v[34:37]
	v_mfma_i32_16x16x64_i8 v[26:29], v[146:149], v[202:205], v[26:29]
	v_mfma_i32_16x16x64_i8 v[18:21], v[154:157], v[202:205], v[18:21]
	v_mfma_i32_16x16x64_i8 v[62:65], v[150:153], v[182:185], v[62:65]
	v_mfma_i32_16x16x64_i8 v[58:61], v[158:161], v[182:185], v[58:61]
	v_mfma_i32_16x16x64_i8 v[54:57], v[150:153], v[190:193], v[54:57]
	v_mfma_i32_16x16x64_i8 v[50:53], v[158:161], v[190:193], v[50:53]
	v_mfma_i32_16x16x64_i8 v[42:45], v[150:153], v[198:201], v[42:45]
	v_mfma_i32_16x16x64_i8 v[34:37], v[158:161], v[198:201], v[34:37]
	v_mfma_i32_16x16x64_i8 v[26:29], v[150:153], v[206:209], v[26:29]
	v_mfma_i32_16x16x64_i8 v[18:21], v[158:161], v[206:209], v[18:21]
	v_mfma_i32_16x16x64_i8 v[46:49], v[162:165], v[178:181], v[46:49]
	v_mfma_i32_16x16x64_i8 v[38:41], v[170:173], v[178:181], v[38:41]
	v_mfma_i32_16x16x64_i8 v[30:33], v[162:165], v[186:189], v[30:33]
	v_mfma_i32_16x16x64_i8 v[22:25], v[170:173], v[186:189], v[22:25]
	v_mfma_i32_16x16x64_i8 v[14:17], v[162:165], v[194:197], v[14:17]
	v_mfma_i32_16x16x64_i8 v[10:13], v[170:173], v[194:197], v[10:13]
	v_mfma_i32_16x16x64_i8 v[6:9], v[162:165], v[202:205], v[6:9]
	v_mfma_i32_16x16x64_i8 v[2:5], v[170:173], v[202:205], v[2:5]
	v_mfma_i32_16x16x64_i8 v[46:49], v[166:169], v[182:185], v[46:49]
	v_mfma_i32_16x16x64_i8 v[38:41], v[174:177], v[182:185], v[38:41]
	v_mfma_i32_16x16x64_i8 v[30:33], v[166:169], v[190:193], v[30:33]
	v_mfma_i32_16x16x64_i8 v[22:25], v[174:177], v[190:193], v[22:25]
	v_mfma_i32_16x16x64_i8 v[14:17], v[166:169], v[198:201], v[14:17]
	v_mfma_i32_16x16x64_i8 v[10:13], v[174:177], v[198:201], v[10:13]
	v_mfma_i32_16x16x64_i8 v[6:9], v[166:169], v[206:209], v[6:9]
	v_mfma_i32_16x16x64_i8 v[2:5], v[174:177], v[206:209], v[2:5]
	s_barrier
	s_add_i32 s81, 0, 0x18000
	s_add_i32 s82, 0, 0x1c000
	v_add_u32_e32 v158, s81, v229
	v_add_u32_e32 v174, s82, v229
	ds_read_b128 v[146:149], v158
	ds_read_b128 v[150:153], v158 offset:1024
	ds_read_b128 v[154:157], v158 offset:2048
	ds_read_b128 v[158:161], v158 offset:3072
	ds_read_b128 v[162:165], v174
	ds_read_b128 v[166:169], v174 offset:1024
	ds_read_b128 v[170:173], v174 offset:2048
	ds_read_b128 v[174:177], v174 offset:3072
	s_add_u32 s42, s42, s8
	s_addc_u32 s43, s43, s9
	s_mov_b32 m0, s53
	v_lshl_add_u64 v[222:223], s[42:43], 0, v[130:131]
	ds_read_b128 v[178:181], v231 offset:32768
	ds_read_b128 v[182:185], v231 offset:33792
	ds_read_b128 v[186:189], v231 offset:34816
	ds_read_b128 v[190:193], v231 offset:35840
	ds_read_b128 v[194:197], v231 offset:36864
	ds_read_b128 v[198:201], v231 offset:37888
	ds_read_b128 v[202:205], v231 offset:38912
	ds_read_b128 v[206:209], v231 offset:39936
	global_load_lds_dwordx4 v[222:223], off
	v_lshl_add_u64 v[222:223], s[42:43], 0, v[134:135]
	s_mov_b32 m0, s54
	s_nop 0
	global_load_lds_dwordx4 v[222:223], off
	s_waitcnt vmcnt(8)
	s_waitcnt lgkmcnt(0)
	s_waitcnt lgkmcnt(0)
	v_mfma_i32_16x16x64_i8 v[126:129], v[146:149], v[178:181], v[126:129]
	v_mfma_i32_16x16x64_i8 v[122:125], v[154:157], v[178:181], v[122:125]
	s_barrier
	v_mfma_i32_16x16x64_i8 v[118:121], v[146:149], v[186:189], v[118:121]
	v_mfma_i32_16x16x64_i8 v[114:117], v[154:157], v[186:189], v[114:117]
	v_mfma_i32_16x16x64_i8 v[106:109], v[146:149], v[194:197], v[106:109]
	v_mfma_i32_16x16x64_i8 v[98:101], v[154:157], v[194:197], v[98:101]
	v_mfma_i32_16x16x64_i8 v[90:93], v[146:149], v[202:205], v[90:93]
	v_mfma_i32_16x16x64_i8 v[82:85], v[154:157], v[202:205], v[82:85]
	v_mfma_i32_16x16x64_i8 v[126:129], v[150:153], v[182:185], v[126:129]
	v_mfma_i32_16x16x64_i8 v[122:125], v[158:161], v[182:185], v[122:125]
	v_mfma_i32_16x16x64_i8 v[118:121], v[150:153], v[190:193], v[118:121]
	v_mfma_i32_16x16x64_i8 v[114:117], v[158:161], v[190:193], v[114:117]
	v_mfma_i32_16x16x64_i8 v[106:109], v[150:153], v[198:201], v[106:109]
	v_mfma_i32_16x16x64_i8 v[98:101], v[158:161], v[198:201], v[98:101]
	v_mfma_i32_16x16x64_i8 v[90:93], v[150:153], v[206:209], v[90:93]
	v_mfma_i32_16x16x64_i8 v[82:85], v[158:161], v[206:209], v[82:85]
	v_mfma_i32_16x16x64_i8 v[110:113], v[162:165], v[178:181], v[110:113]
	v_mfma_i32_16x16x64_i8 v[102:105], v[170:173], v[178:181], v[102:105]
	v_mfma_i32_16x16x64_i8 v[94:97], v[162:165], v[186:189], v[94:97]
	v_mfma_i32_16x16x64_i8 v[86:89], v[170:173], v[186:189], v[86:89]
	v_mfma_i32_16x16x64_i8 v[78:81], v[162:165], v[194:197], v[78:81]
	v_mfma_i32_16x16x64_i8 v[74:77], v[170:173], v[194:197], v[74:77]
	v_mfma_i32_16x16x64_i8 v[70:73], v[162:165], v[202:205], v[70:73]
	v_mfma_i32_16x16x64_i8 v[66:69], v[170:173], v[202:205], v[66:69]
	v_mfma_i32_16x16x64_i8 v[110:113], v[166:169], v[182:185], v[110:113]
	v_mfma_i32_16x16x64_i8 v[102:105], v[174:177], v[182:185], v[102:105]
	v_mfma_i32_16x16x64_i8 v[94:97], v[166:169], v[190:193], v[94:97]
	v_mfma_i32_16x16x64_i8 v[86:89], v[174:177], v[190:193], v[86:89]
	v_mfma_i32_16x16x64_i8 v[78:81], v[166:169], v[198:201], v[78:81]
	v_mfma_i32_16x16x64_i8 v[74:77], v[174:177], v[198:201], v[74:77]
	v_mfma_i32_16x16x64_i8 v[70:73], v[166:169], v[206:209], v[70:73]
	v_mfma_i32_16x16x64_i8 v[66:69], v[174:177], v[206:209], v[66:69]
	s_barrier
	s_add_i32 s42, s81, s50
	v_lshl_add_u64 v[210:211], v[210:211], 0, s[30:31]
	s_mov_b32 m0, s42
	ds_read_b128 v[178:181], v231 offset:49152
	ds_read_b128 v[182:185], v231 offset:50176
	ds_read_b128 v[186:189], v231 offset:51200
	ds_read_b128 v[190:193], v231 offset:52224
	ds_read_b128 v[194:197], v231 offset:53248
	ds_read_b128 v[198:201], v231 offset:54272
	ds_read_b128 v[202:205], v231 offset:55296
	ds_read_b128 v[206:209], v231 offset:56320
	global_load_lds_dwordx4 v[210:211], off
	v_lshl_add_u64 v[210:211], v[212:213], 0, s[30:31]
	s_add_i32 m0, s42, 0x2000
	s_add_i32 s42, s82, s50
	global_load_lds_dwordx4 v[210:211], off
	v_lshl_add_u64 v[210:211], v[214:215], 0, s[30:31]
	s_mov_b32 m0, s42
	s_nop 0
	global_load_lds_dwordx4 v[210:211], off
	v_lshl_add_u64 v[210:211], v[216:217], 0, s[30:31]
	s_add_i32 m0, s42, 0x2000
	s_nop 0
	global_load_lds_dwordx4 v[210:211], off
	v_lshl_add_u64 v[210:211], v[218:219], 0, s[30:31]
	s_mov_b32 m0, s57
	s_nop 0
	global_load_lds_dwordx4 v[210:211], off
	v_lshl_add_u64 v[210:211], v[220:221], 0, s[30:31]
	s_mov_b32 m0, s58
	s_nop 0
	global_load_lds_dwordx4 v[210:211], off
	s_waitcnt vmcnt(8)
	s_waitcnt lgkmcnt(0)
	s_waitcnt lgkmcnt(0)
	v_mfma_i32_16x16x64_i8 v[62:65], v[146:149], v[178:181], v[62:65]
	v_mfma_i32_16x16x64_i8 v[58:61], v[154:157], v[178:181], v[58:61]
	s_barrier
	v_mfma_i32_16x16x64_i8 v[54:57], v[146:149], v[186:189], v[54:57]
	v_mfma_i32_16x16x64_i8 v[50:53], v[154:157], v[186:189], v[50:53]
	v_mfma_i32_16x16x64_i8 v[42:45], v[146:149], v[194:197], v[42:45]
	v_mfma_i32_16x16x64_i8 v[34:37], v[154:157], v[194:197], v[34:37]
	v_mfma_i32_16x16x64_i8 v[26:29], v[146:149], v[202:205], v[26:29]
	v_mfma_i32_16x16x64_i8 v[18:21], v[154:157], v[202:205], v[18:21]
	v_mfma_i32_16x16x64_i8 v[62:65], v[150:153], v[182:185], v[62:65]
	v_mfma_i32_16x16x64_i8 v[58:61], v[158:161], v[182:185], v[58:61]
	v_mfma_i32_16x16x64_i8 v[54:57], v[150:153], v[190:193], v[54:57]
	v_mfma_i32_16x16x64_i8 v[50:53], v[158:161], v[190:193], v[50:53]
	v_mfma_i32_16x16x64_i8 v[42:45], v[150:153], v[198:201], v[42:45]
	v_mfma_i32_16x16x64_i8 v[34:37], v[158:161], v[198:201], v[34:37]
	v_mfma_i32_16x16x64_i8 v[26:29], v[150:153], v[206:209], v[26:29]
	v_mfma_i32_16x16x64_i8 v[18:21], v[158:161], v[206:209], v[18:21]
	v_mfma_i32_16x16x64_i8 v[46:49], v[162:165], v[178:181], v[46:49]
	v_mfma_i32_16x16x64_i8 v[38:41], v[170:173], v[178:181], v[38:41]
	v_mfma_i32_16x16x64_i8 v[30:33], v[162:165], v[186:189], v[30:33]
	v_mfma_i32_16x16x64_i8 v[22:25], v[170:173], v[186:189], v[22:25]
	v_mfma_i32_16x16x64_i8 v[14:17], v[162:165], v[194:197], v[14:17]
	v_mfma_i32_16x16x64_i8 v[10:13], v[170:173], v[194:197], v[10:13]
	v_mfma_i32_16x16x64_i8 v[6:9], v[162:165], v[202:205], v[6:9]
	v_mfma_i32_16x16x64_i8 v[2:5], v[170:173], v[202:205], v[2:5]
	v_mfma_i32_16x16x64_i8 v[46:49], v[166:169], v[182:185], v[46:49]
	v_mfma_i32_16x16x64_i8 v[38:41], v[174:177], v[182:185], v[38:41]
	v_mfma_i32_16x16x64_i8 v[30:33], v[166:169], v[190:193], v[30:33]
	v_mfma_i32_16x16x64_i8 v[22:25], v[174:177], v[190:193], v[22:25]
	v_mfma_i32_16x16x64_i8 v[14:17], v[166:169], v[198:201], v[14:17]
	v_mfma_i32_16x16x64_i8 v[10:13], v[174:177], v[198:201], v[10:13]
	v_mfma_i32_16x16x64_i8 v[6:9], v[166:169], v[206:209], v[6:9]
	v_mfma_i32_16x16x64_i8 v[2:5], v[174:177], v[206:209], v[2:5]
	s_barrier
	s_add_u32 s40, s40, 0x100
	s_addc_u32 s41, s41, 0
	s_add_u32 s70, s70, 0x100
	s_addc_u32 s71, s71, 0
	s_cmp_ge_i32 s80, s60
	s_mov_b32 s42, s80
	s_cbranch_scc0 .LBB0_3613
	v_cvt_f32_i32_e32 v214, v126
	v_cvt_f32_i32_e32 v215, v127
	v_cvt_f32_i32_e32 v212, v128
	v_cvt_f32_i32_e32 v213, v129
	v_cvt_f32_i32_e32 v218, v122
	v_cvt_f32_i32_e32 v219, v123
	v_cvt_f32_i32_e32 v216, v124
	v_cvt_f32_i32_e32 v217, v125
	v_cvt_f32_i32_e32 v222, v110
	v_cvt_f32_i32_e32 v223, v111
	v_cvt_f32_i32_e32 v220, v112
	v_cvt_f32_i32_e32 v221, v113
	v_cvt_f32_i32_e32 v226, v102
	v_cvt_f32_i32_e32 v227, v103
	v_cvt_f32_i32_e32 v224, v104
	v_cvt_f32_i32_e32 v225, v105
	v_cvt_f32_i32_e32 v194, v118
	v_cvt_f32_i32_e32 v195, v119
	v_cvt_f32_i32_e32 v192, v120
	v_cvt_f32_i32_e32 v193, v121
	v_cvt_f32_i32_e32 v200, v114
	v_cvt_f32_i32_e32 v201, v115
	v_cvt_f32_i32_e32 v198, v116
	v_cvt_f32_i32_e32 v199, v117
	v_cvt_f32_i32_e32 v206, v94
	v_cvt_f32_i32_e32 v207, v95
	v_cvt_f32_i32_e32 v202, v96
	v_cvt_f32_i32_e32 v203, v97
	v_cvt_f32_i32_e32 v208, v86
	v_cvt_f32_i32_e32 v209, v87
	v_cvt_f32_i32_e32 v204, v88
	v_cvt_f32_i32_e32 v205, v89
	v_cvt_f32_i32_e32 v178, v106
	v_cvt_f32_i32_e32 v179, v107
	v_cvt_f32_i32_e32 v176, v108
	v_cvt_f32_i32_e32 v177, v109
	v_cvt_f32_i32_e32 v182, v98
	v_cvt_f32_i32_e32 v183, v99
	v_cvt_f32_i32_e32 v180, v100
	v_cvt_f32_i32_e32 v181, v101
	v_cvt_f32_i32_e32 v188, v78
	v_cvt_f32_i32_e32 v189, v79
	v_cvt_f32_i32_e32 v184, v80
	v_cvt_f32_i32_e32 v185, v81
	v_cvt_f32_i32_e32 v190, v74
	v_cvt_f32_i32_e32 v191, v75
	v_cvt_f32_i32_e32 v186, v76
	v_cvt_f32_i32_e32 v187, v77
	v_cvt_f32_i32_e32 v162, v90
	v_cvt_f32_i32_e32 v163, v91
	v_cvt_f32_i32_e32 v160, v92
	v_cvt_f32_i32_e32 v161, v93
	v_cvt_f32_i32_e32 v166, v82
	v_cvt_f32_i32_e32 v167, v83
	v_cvt_f32_i32_e32 v164, v84
	v_cvt_f32_i32_e32 v165, v85
	v_cvt_f32_i32_e32 v172, v70
	v_cvt_f32_i32_e32 v173, v71
	v_cvt_f32_i32_e32 v168, v72
	v_cvt_f32_i32_e32 v169, v73
	v_cvt_f32_i32_e32 v174, v66
	v_cvt_f32_i32_e32 v175, v67
	v_cvt_f32_i32_e32 v170, v68
	v_cvt_f32_i32_e32 v171, v69
	v_cvt_f32_i32_e32 v146, v62
	v_cvt_f32_i32_e32 v147, v63
	v_cvt_f32_i32_e32 v128, v64
	v_cvt_f32_i32_e32 v129, v65
	v_cvt_f32_i32_e32 v150, v58
	v_cvt_f32_i32_e32 v151, v59
	v_cvt_f32_i32_e32 v148, v60
	v_cvt_f32_i32_e32 v149, v61
	v_cvt_f32_i32_e32 v156, v46
	v_cvt_f32_i32_e32 v157, v47
	v_cvt_f32_i32_e32 v152, v48
	v_cvt_f32_i32_e32 v153, v49
	v_cvt_f32_i32_e32 v158, v38
	v_cvt_f32_i32_e32 v159, v39
	v_cvt_f32_i32_e32 v154, v40
	v_cvt_f32_i32_e32 v155, v41
	v_cvt_f32_i32_e32 v114, v54
	v_cvt_f32_i32_e32 v115, v55
	v_cvt_f32_i32_e32 v112, v56
	v_cvt_f32_i32_e32 v113, v57
	v_cvt_f32_i32_e32 v118, v50
	v_cvt_f32_i32_e32 v119, v51
	v_cvt_f32_i32_e32 v116, v52
	v_cvt_f32_i32_e32 v117, v53
	v_cvt_f32_i32_e32 v124, v30
	v_cvt_f32_i32_e32 v125, v31
	v_cvt_f32_i32_e32 v120, v32
	v_cvt_f32_i32_e32 v121, v33
	v_cvt_f32_i32_e32 v126, v22
	v_cvt_f32_i32_e32 v127, v23
	v_cvt_f32_i32_e32 v122, v24
	v_cvt_f32_i32_e32 v123, v25
	v_cvt_f32_i32_e32 v64, v42
	v_cvt_f32_i32_e32 v65, v43
	v_cvt_f32_i32_e32 v62, v44
	v_cvt_f32_i32_e32 v63, v45
	v_cvt_f32_i32_e32 v68, v34
	v_cvt_f32_i32_e32 v69, v35
	v_cvt_f32_i32_e32 v66, v36
	v_cvt_f32_i32_e32 v67, v37
	v_cvt_f32_i32_e32 v74, v14
	v_cvt_f32_i32_e32 v75, v15
	v_cvt_f32_i32_e32 v70, v16
	v_cvt_f32_i32_e32 v71, v17
	v_cvt_f32_i32_e32 v76, v10
	v_cvt_f32_i32_e32 v77, v11
	v_cvt_f32_i32_e32 v72, v12
	v_cvt_f32_i32_e32 v73, v13
	v_cvt_f32_i32_e32 v48, v26
	v_cvt_f32_i32_e32 v49, v27
	v_cvt_f32_i32_e32 v46, v28
	v_cvt_f32_i32_e32 v47, v29
	v_cvt_f32_i32_e32 v52, v18
	v_cvt_f32_i32_e32 v53, v19
	v_cvt_f32_i32_e32 v50, v20
	v_cvt_f32_i32_e32 v51, v21
	v_cvt_f32_i32_e32 v58, v6
	v_cvt_f32_i32_e32 v59, v7
	v_cvt_f32_i32_e32 v54, v8
	v_cvt_f32_i32_e32 v55, v9
	v_cvt_f32_i32_e32 v60, v2
	v_cvt_f32_i32_e32 v61, v3
	v_cvt_f32_i32_e32 v56, v4
	v_cvt_f32_i32_e32 v57, v5

.LBB0_3798:
	v_add_u32_e32 v138, s56, v188
	ds_read_b128 v[148:151], v138
	ds_read_b128 v[152:155], v138 offset:1024
	ds_read_b128 v[156:159], v138 offset:2048
	ds_read_b128 v[160:163], v138 offset:3072
	v_add_u32_e32 v138, s57, v188
	ds_read_b128 v[164:167], v138
	ds_read_b128 v[168:171], v138 offset:1024
	ds_read_b128 v[172:175], v138 offset:2048
	ds_read_b128 v[176:179], v138 offset:3072
	s_add_i32 s60, s28, 2
	s_add_u32 s61, s26, 0x80
	s_addc_u32 s29, s27, 0
	s_cmp_eq_u32 s54, s28
	s_cselect_b32 s28, s2, s61
	s_cselect_b32 s29, s3, s29
	s_cselect_b32 s63, s25, s35
	s_cselect_b32 s62, s24, s34
	v_lshl_add_u64 v[184:185], s[26:27], 0, v[140:141]
	s_add_i32 m0, s42, 0xc000
	ds_read_b128 v[180:183], v189
	ds_read_b128 v[190:193], v189 offset:1024
	ds_read_b128 v[194:197], v189 offset:2048
	ds_read_b128 v[198:201], v189 offset:3072
	ds_read_b128 v[202:205], v189 offset:4096
	ds_read_b128 v[206:209], v189 offset:5120
	ds_read_b128 v[210:213], v189 offset:6144
	ds_read_b128 v[214:217], v189 offset:7168
	global_load_lds_dwordx4 v[184:185], off
	v_lshl_add_u64 v[184:185], s[26:27], 0, v[142:143]
	s_add_i32 m0, s42, 0xe000
	s_nop 0
	global_load_lds_dwordx4 v[184:185], off
	s_waitcnt vmcnt(8)
	s_waitcnt lgkmcnt(0)
	s_waitcnt lgkmcnt(0)
	v_mfma_i32_16x16x64_i8 v[126:129], v[148:151], v[180:183], v[126:129]
	v_mfma_i32_16x16x64_i8 v[122:125], v[156:159], v[180:183], v[122:125]
	s_barrier
	v_mfma_i32_16x16x64_i8 v[118:121], v[148:151], v[194:197], v[118:121]
	v_mfma_i32_16x16x64_i8 v[114:117], v[156:159], v[194:197], v[114:117]
	v_mfma_i32_16x16x64_i8 v[106:109], v[148:151], v[202:205], v[106:109]
	v_mfma_i32_16x16x64_i8 v[98:101], v[156:159], v[202:205], v[98:101]
	v_mfma_i32_16x16x64_i8 v[90:93], v[148:151], v[210:213], v[90:93]
	v_mfma_i32_16x16x64_i8 v[82:85], v[156:159], v[210:213], v[82:85]
	v_mfma_i32_16x16x64_i8 v[126:129], v[152:155], v[190:193], v[126:129]
	v_mfma_i32_16x16x64_i8 v[122:125], v[160:163], v[190:193], v[122:125]
	v_mfma_i32_16x16x64_i8 v[118:121], v[152:155], v[198:201], v[118:121]
	v_mfma_i32_16x16x64_i8 v[114:117], v[160:163], v[198:201], v[114:117]
	v_mfma_i32_16x16x64_i8 v[106:109], v[152:155], v[206:209], v[106:109]
	v_mfma_i32_16x16x64_i8 v[98:101], v[160:163], v[206:209], v[98:101]
	v_mfma_i32_16x16x64_i8 v[90:93], v[152:155], v[214:217], v[90:93]
	v_mfma_i32_16x16x64_i8 v[82:85], v[160:163], v[214:217], v[82:85]
	v_mfma_i32_16x16x64_i8 v[110:113], v[164:167], v[180:183], v[110:113]
	v_mfma_i32_16x16x64_i8 v[102:105], v[172:175], v[180:183], v[102:105]
	v_mfma_i32_16x16x64_i8 v[94:97], v[164:167], v[194:197], v[94:97]
	v_mfma_i32_16x16x64_i8 v[86:89], v[172:175], v[194:197], v[86:89]
	v_mfma_i32_16x16x64_i8 v[78:81], v[164:167], v[202:205], v[78:81]
	v_mfma_i32_16x16x64_i8 v[74:77], v[172:175], v[202:205], v[74:77]
	v_mfma_i32_16x16x64_i8 v[70:73], v[164:167], v[210:213], v[70:73]
	v_mfma_i32_16x16x64_i8 v[66:69], v[172:175], v[210:213], v[66:69]
	v_mfma_i32_16x16x64_i8 v[110:113], v[168:171], v[190:193], v[110:113]
	v_mfma_i32_16x16x64_i8 v[102:105], v[176:179], v[190:193], v[102:105]
	v_mfma_i32_16x16x64_i8 v[94:97], v[168:171], v[198:201], v[94:97]
	v_mfma_i32_16x16x64_i8 v[86:89], v[176:179], v[198:201], v[86:89]
	v_mfma_i32_16x16x64_i8 v[78:81], v[168:171], v[206:209], v[78:81]
	v_mfma_i32_16x16x64_i8 v[74:77], v[176:179], v[206:209], v[74:77]
	v_mfma_i32_16x16x64_i8 v[70:73], v[168:171], v[214:217], v[70:73]
	v_mfma_i32_16x16x64_i8 v[66:69], v[176:179], v[214:217], v[66:69]
	s_barrier
	s_add_i32 s61, s56, s41
	v_lshl_add_u64 v[184:185], s[62:63], 0, v[132:133]
	s_mov_b32 m0, s61
	ds_read_b128 v[180:183], v189 offset:16384
	ds_read_b128 v[190:193], v189 offset:17408
	ds_read_b128 v[194:197], v189 offset:18432
	ds_read_b128 v[198:201], v189 offset:19456
	ds_read_b128 v[202:205], v189 offset:20480
	ds_read_b128 v[206:209], v189 offset:21504
	ds_read_b128 v[210:213], v189 offset:22528
	ds_read_b128 v[214:217], v189 offset:23552
	global_load_lds_dwordx4 v[184:185], off
	s_add_i32 m0, s61, 0x2000
	v_lshl_add_u64 v[218:219], s[62:63], 0, v[136:137]
	s_add_u32 s62, s62, s6
	s_addc_u32 s63, s63, s7
	s_add_i32 s61, s57, s41
	global_load_lds_dwordx4 v[218:219], off
	v_lshl_add_u64 v[220:221], s[62:63], 0, v[132:133]
	s_mov_b32 m0, s61
	v_lshl_add_u64 v[222:223], s[62:63], 0, v[136:137]
	global_load_lds_dwordx4 v[220:221], off
	s_add_i32 m0, s61, 0x2000
	v_lshl_add_u64 v[224:225], s[28:29], 0, v[130:131]
	global_load_lds_dwordx4 v[222:223], off
	s_mov_b32 m0, s42
	v_lshl_add_u64 v[226:227], s[28:29], 0, v[134:135]
	global_load_lds_dwordx4 v[224:225], off
	s_mov_b32 m0, s43
	s_nop 0
	global_load_lds_dwordx4 v[226:227], off
	s_waitcnt vmcnt(8)
	s_waitcnt lgkmcnt(0)
	s_waitcnt lgkmcnt(0)
	v_mfma_i32_16x16x64_i8 v[62:65], v[148:151], v[180:183], v[62:65]
	v_mfma_i32_16x16x64_i8 v[58:61], v[156:159], v[180:183], v[58:61]
	s_barrier
	v_mfma_i32_16x16x64_i8 v[54:57], v[148:151], v[194:197], v[54:57]
	v_mfma_i32_16x16x64_i8 v[50:53], v[156:159], v[194:197], v[50:53]
	v_mfma_i32_16x16x64_i8 v[42:45], v[148:151], v[202:205], v[42:45]
	v_mfma_i32_16x16x64_i8 v[34:37], v[156:159], v[202:205], v[34:37]
	v_mfma_i32_16x16x64_i8 v[26:29], v[148:151], v[210:213], v[26:29]
	v_mfma_i32_16x16x64_i8 v[18:21], v[156:159], v[210:213], v[18:21]
	v_mfma_i32_16x16x64_i8 v[62:65], v[152:155], v[190:193], v[62:65]
	v_mfma_i32_16x16x64_i8 v[58:61], v[160:163], v[190:193], v[58:61]
	v_mfma_i32_16x16x64_i8 v[54:57], v[152:155], v[198:201], v[54:57]
	v_mfma_i32_16x16x64_i8 v[50:53], v[160:163], v[198:201], v[50:53]
	v_mfma_i32_16x16x64_i8 v[42:45], v[152:155], v[206:209], v[42:45]
	v_mfma_i32_16x16x64_i8 v[34:37], v[160:163], v[206:209], v[34:37]
	v_mfma_i32_16x16x64_i8 v[26:29], v[152:155], v[214:217], v[26:29]
	v_mfma_i32_16x16x64_i8 v[18:21], v[160:163], v[214:217], v[18:21]
	v_mfma_i32_16x16x64_i8 v[46:49], v[164:167], v[180:183], v[46:49]
	v_mfma_i32_16x16x64_i8 v[38:41], v[172:175], v[180:183], v[38:41]
	v_mfma_i32_16x16x64_i8 v[30:33], v[164:167], v[194:197], v[30:33]
	v_mfma_i32_16x16x64_i8 v[22:25], v[172:175], v[194:197], v[22:25]
	v_mfma_i32_16x16x64_i8 v[14:17], v[164:167], v[202:205], v[14:17]
	v_mfma_i32_16x16x64_i8 v[10:13], v[172:175], v[202:205], v[10:13]
	v_mfma_i32_16x16x64_i8 v[6:9], v[164:167], v[210:213], v[6:9]
	v_mfma_i32_16x16x64_i8 v[2:5], v[172:175], v[210:213], v[2:5]
	v_mfma_i32_16x16x64_i8 v[46:49], v[168:171], v[190:193], v[46:49]
	v_mfma_i32_16x16x64_i8 v[38:41], v[176:179], v[190:193], v[38:41]
	v_mfma_i32_16x16x64_i8 v[30:33], v[168:171], v[198:201], v[30:33]
	v_mfma_i32_16x16x64_i8 v[22:25], v[176:179], v[198:201], v[22:25]
	v_mfma_i32_16x16x64_i8 v[14:17], v[168:171], v[206:209], v[14:17]
	v_mfma_i32_16x16x64_i8 v[10:13], v[176:179], v[206:209], v[10:13]
	v_mfma_i32_16x16x64_i8 v[6:9], v[168:171], v[214:217], v[6:9]
	v_mfma_i32_16x16x64_i8 v[2:5], v[176:179], v[214:217], v[2:5]
	s_barrier
	s_add_i32 s61, 0, 0x18000
	v_add_u32_e32 v138, s61, v188
	s_add_i32 s62, 0, 0x1c000
	ds_read_b128 v[148:151], v138
	ds_read_b128 v[152:155], v138 offset:1024
	ds_read_b128 v[156:159], v138 offset:2048
	ds_read_b128 v[160:163], v138 offset:3072
	v_add_u32_e32 v138, s62, v188
	ds_read_b128 v[164:167], v138
	ds_read_b128 v[168:171], v138 offset:1024
	ds_read_b128 v[172:175], v138 offset:2048
	ds_read_b128 v[176:179], v138 offset:3072
	s_add_u32 s28, s28, s6
	s_addc_u32 s29, s29, s7
	s_mov_b32 m0, s44
	v_lshl_add_u64 v[228:229], s[28:29], 0, v[130:131]
	ds_read_b128 v[180:183], v189 offset:32768
	ds_read_b128 v[190:193], v189 offset:33792
	ds_read_b128 v[194:197], v189 offset:34816
	ds_read_b128 v[198:201], v189 offset:35840
	ds_read_b128 v[202:205], v189 offset:36864
	ds_read_b128 v[206:209], v189 offset:37888
	ds_read_b128 v[210:213], v189 offset:38912
	ds_read_b128 v[214:217], v189 offset:39936
	global_load_lds_dwordx4 v[228:229], off
	v_lshl_add_u64 v[228:229], s[28:29], 0, v[134:135]
	s_mov_b32 m0, s45
	s_nop 0
	global_load_lds_dwordx4 v[228:229], off
	s_waitcnt vmcnt(8)
	s_waitcnt lgkmcnt(0)
	s_waitcnt lgkmcnt(0)
	v_mfma_i32_16x16x64_i8 v[126:129], v[148:151], v[180:183], v[126:129]
	v_mfma_i32_16x16x64_i8 v[122:125], v[156:159], v[180:183], v[122:125]
	s_barrier
	v_mfma_i32_16x16x64_i8 v[118:121], v[148:151], v[194:197], v[118:121]
	v_mfma_i32_16x16x64_i8 v[114:117], v[156:159], v[194:197], v[114:117]
	v_mfma_i32_16x16x64_i8 v[106:109], v[148:151], v[202:205], v[106:109]
	v_mfma_i32_16x16x64_i8 v[98:101], v[156:159], v[202:205], v[98:101]
	v_mfma_i32_16x16x64_i8 v[90:93], v[148:151], v[210:213], v[90:93]
	v_mfma_i32_16x16x64_i8 v[82:85], v[156:159], v[210:213], v[82:85]
	v_mfma_i32_16x16x64_i8 v[126:129], v[152:155], v[190:193], v[126:129]
	v_mfma_i32_16x16x64_i8 v[122:125], v[160:163], v[190:193], v[122:125]
	v_mfma_i32_16x16x64_i8 v[118:121], v[152:155], v[198:201], v[118:121]
	v_mfma_i32_16x16x64_i8 v[114:117], v[160:163], v[198:201], v[114:117]
	v_mfma_i32_16x16x64_i8 v[106:109], v[152:155], v[206:209], v[106:109]
	v_mfma_i32_16x16x64_i8 v[98:101], v[160:163], v[206:209], v[98:101]
	v_mfma_i32_16x16x64_i8 v[90:93], v[152:155], v[214:217], v[90:93]
	v_mfma_i32_16x16x64_i8 v[82:85], v[160:163], v[214:217], v[82:85]
	v_mfma_i32_16x16x64_i8 v[110:113], v[164:167], v[180:183], v[110:113]
	v_mfma_i32_16x16x64_i8 v[102:105], v[172:175], v[180:183], v[102:105]
	v_mfma_i32_16x16x64_i8 v[94:97], v[164:167], v[194:197], v[94:97]
	v_mfma_i32_16x16x64_i8 v[86:89], v[172:175], v[194:197], v[86:89]
	v_mfma_i32_16x16x64_i8 v[78:81], v[164:167], v[202:205], v[78:81]
	v_mfma_i32_16x16x64_i8 v[74:77], v[172:175], v[202:205], v[74:77]
	v_mfma_i32_16x16x64_i8 v[70:73], v[164:167], v[210:213], v[70:73]
	v_mfma_i32_16x16x64_i8 v[66:69], v[172:175], v[210:213], v[66:69]
	v_mfma_i32_16x16x64_i8 v[110:113], v[168:171], v[190:193], v[110:113]
	v_mfma_i32_16x16x64_i8 v[102:105], v[176:179], v[190:193], v[102:105]
	v_mfma_i32_16x16x64_i8 v[94:97], v[168:171], v[198:201], v[94:97]
	v_mfma_i32_16x16x64_i8 v[86:89], v[176:179], v[198:201], v[86:89]
	v_mfma_i32_16x16x64_i8 v[78:81], v[168:171], v[206:209], v[78:81]
	v_mfma_i32_16x16x64_i8 v[74:77], v[176:179], v[206:209], v[74:77]
	v_mfma_i32_16x16x64_i8 v[70:73], v[168:171], v[214:217], v[70:73]
	v_mfma_i32_16x16x64_i8 v[66:69], v[176:179], v[214:217], v[66:69]
	s_barrier
	s_add_i32 s28, s61, s41
	v_lshl_add_u64 v[184:185], v[184:185], 0, s[18:19]
	s_mov_b32 m0, s28
	ds_read_b128 v[180:183], v189 offset:49152
	ds_read_b128 v[190:193], v189 offset:50176
	ds_read_b128 v[194:197], v189 offset:51200
	ds_read_b128 v[198:201], v189 offset:52224
	ds_read_b128 v[202:205], v189 offset:53248
	ds_read_b128 v[206:209], v189 offset:54272
	ds_read_b128 v[210:213], v189 offset:55296
	ds_read_b128 v[214:217], v189 offset:56320
	global_load_lds_dwordx4 v[184:185], off
	v_lshl_add_u64 v[184:185], v[218:219], 0, s[18:19]
	s_add_i32 m0, s28, 0x2000
	s_add_i32 s28, s62, s41
	global_load_lds_dwordx4 v[184:185], off
	v_lshl_add_u64 v[184:185], v[220:221], 0, s[18:19]
	s_mov_b32 m0, s28
	s_nop 0
	global_load_lds_dwordx4 v[184:185], off
	v_lshl_add_u64 v[184:185], v[222:223], 0, s[18:19]
	s_add_i32 m0, s28, 0x2000
	s_nop 0
	global_load_lds_dwordx4 v[184:185], off
	v_lshl_add_u64 v[184:185], v[224:225], 0, s[18:19]
	s_mov_b32 m0, s49
	s_nop 0
	global_load_lds_dwordx4 v[184:185], off
	v_lshl_add_u64 v[184:185], v[226:227], 0, s[18:19]
	s_mov_b32 m0, s50
	s_nop 0
	global_load_lds_dwordx4 v[184:185], off
	s_waitcnt vmcnt(8)
	s_waitcnt lgkmcnt(0)
	s_waitcnt lgkmcnt(0)
	v_mfma_i32_16x16x64_i8 v[62:65], v[148:151], v[180:183], v[62:65]
	v_mfma_i32_16x16x64_i8 v[58:61], v[156:159], v[180:183], v[58:61]
	s_barrier
	v_mfma_i32_16x16x64_i8 v[54:57], v[148:151], v[194:197], v[54:57]
	v_mfma_i32_16x16x64_i8 v[50:53], v[156:159], v[194:197], v[50:53]
	v_mfma_i32_16x16x64_i8 v[42:45], v[148:151], v[202:205], v[42:45]
	v_mfma_i32_16x16x64_i8 v[34:37], v[156:159], v[202:205], v[34:37]
	v_mfma_i32_16x16x64_i8 v[26:29], v[148:151], v[210:213], v[26:29]
	v_mfma_i32_16x16x64_i8 v[18:21], v[156:159], v[210:213], v[18:21]
	v_mfma_i32_16x16x64_i8 v[62:65], v[152:155], v[190:193], v[62:65]
	v_mfma_i32_16x16x64_i8 v[58:61], v[160:163], v[190:193], v[58:61]
	v_mfma_i32_16x16x64_i8 v[54:57], v[152:155], v[198:201], v[54:57]
	v_mfma_i32_16x16x64_i8 v[50:53], v[160:163], v[198:201], v[50:53]
	v_mfma_i32_16x16x64_i8 v[42:45], v[152:155], v[206:209], v[42:45]
	v_mfma_i32_16x16x64_i8 v[34:37], v[160:163], v[206:209], v[34:37]
	v_mfma_i32_16x16x64_i8 v[26:29], v[152:155], v[214:217], v[26:29]
	v_mfma_i32_16x16x64_i8 v[18:21], v[160:163], v[214:217], v[18:21]
	v_mfma_i32_16x16x64_i8 v[46:49], v[164:167], v[180:183], v[46:49]
	v_mfma_i32_16x16x64_i8 v[38:41], v[172:175], v[180:183], v[38:41]
	v_mfma_i32_16x16x64_i8 v[30:33], v[164:167], v[194:197], v[30:33]
	v_mfma_i32_16x16x64_i8 v[22:25], v[172:175], v[194:197], v[22:25]
	v_mfma_i32_16x16x64_i8 v[14:17], v[164:167], v[202:205], v[14:17]
	v_mfma_i32_16x16x64_i8 v[10:13], v[172:175], v[202:205], v[10:13]
	v_mfma_i32_16x16x64_i8 v[6:9], v[164:167], v[210:213], v[6:9]
	v_mfma_i32_16x16x64_i8 v[2:5], v[172:175], v[210:213], v[2:5]
	v_mfma_i32_16x16x64_i8 v[46:49], v[168:171], v[190:193], v[46:49]
	v_mfma_i32_16x16x64_i8 v[38:41], v[176:179], v[190:193], v[38:41]
	v_mfma_i32_16x16x64_i8 v[30:33], v[168:171], v[198:201], v[30:33]
	v_mfma_i32_16x16x64_i8 v[22:25], v[176:179], v[198:201], v[22:25]
	v_mfma_i32_16x16x64_i8 v[14:17], v[168:171], v[206:209], v[14:17]
	v_mfma_i32_16x16x64_i8 v[10:13], v[176:179], v[206:209], v[10:13]
	v_mfma_i32_16x16x64_i8 v[6:9], v[168:171], v[214:217], v[6:9]
	v_mfma_i32_16x16x64_i8 v[2:5], v[176:179], v[214:217], v[2:5]
	s_barrier
	s_add_u32 s26, s26, 0x100
	s_addc_u32 s27, s27, 0
	s_add_u32 s34, s34, 0x100
	s_addc_u32 s35, s35, 0
	s_cmp_ge_i32 s60, s51
	s_mov_b32 s28, s60
	s_cbranch_scc0 .LBB0_3798
	v_cvt_f32_i32_e32 v172, v126
	v_cvt_f32_i32_e32 v173, v127
	v_cvt_f32_i32_e32 v170, v128
	v_cvt_f32_i32_e32 v171, v129
	v_cvt_f32_i32_e32 v174, v122
	v_cvt_f32_i32_e32 v175, v123
	v_cvt_f32_i32_e32 v176, v124
	v_cvt_f32_i32_e32 v177, v125
	v_cvt_f32_i32_e32 v180, v110
	v_cvt_f32_i32_e32 v181, v111
	v_cvt_f32_i32_e32 v182, v112
	v_cvt_f32_i32_e32 v183, v113
	v_cvt_f32_i32_e32 v178, v102
	v_cvt_f32_i32_e32 v179, v103
	v_cvt_f32_i32_e32 v184, v104
	v_cvt_f32_i32_e32 v185, v105
	v_cvt_f32_i32_e32 v152, v118
	v_cvt_f32_i32_e32 v153, v119
	v_cvt_f32_i32_e32 v154, v120
	v_cvt_f32_i32_e32 v155, v121
	v_cvt_f32_i32_e32 v156, v114
	v_cvt_f32_i32_e32 v157, v115
	v_cvt_f32_i32_e32 v158, v116
	v_cvt_f32_i32_e32 v159, v117
	v_cvt_f32_i32_e32 v160, v94
	v_cvt_f32_i32_e32 v161, v95
	v_cvt_f32_i32_e32 v162, v96
	v_cvt_f32_i32_e32 v163, v97
	v_cvt_f32_i32_e32 v164, v86
	v_cvt_f32_i32_e32 v165, v87
	v_cvt_f32_i32_e32 v166, v88
	v_cvt_f32_i32_e32 v167, v89
	v_cvt_f32_i32_e32 v118, v106
	v_cvt_f32_i32_e32 v119, v107
	v_cvt_f32_i32_e32 v120, v108
	v_cvt_f32_i32_e32 v121, v109
	v_cvt_f32_i32_e32 v122, v98
	v_cvt_f32_i32_e32 v123, v99
	v_cvt_f32_i32_e32 v124, v100
	v_cvt_f32_i32_e32 v125, v101
	v_cvt_f32_i32_e32 v126, v78
	v_cvt_f32_i32_e32 v127, v79
	v_cvt_f32_i32_e32 v128, v80
	v_cvt_f32_i32_e32 v129, v81
	v_cvt_f32_i32_e32 v148, v74
	v_cvt_f32_i32_e32 v149, v75
	v_cvt_f32_i32_e32 v150, v76
	v_cvt_f32_i32_e32 v151, v77
	v_cvt_f32_i32_e32 v102, v90
	v_cvt_f32_i32_e32 v103, v91
	v_cvt_f32_i32_e32 v104, v92
	v_cvt_f32_i32_e32 v105, v93
	v_cvt_f32_i32_e32 v106, v82
	v_cvt_f32_i32_e32 v107, v83
	v_cvt_f32_i32_e32 v108, v84
	v_cvt_f32_i32_e32 v109, v85
	v_cvt_f32_i32_e32 v110, v70
	v_cvt_f32_i32_e32 v111, v71
	v_cvt_f32_i32_e32 v112, v72
	v_cvt_f32_i32_e32 v113, v73
	v_cvt_f32_i32_e32 v114, v66
	v_cvt_f32_i32_e32 v115, v67
	v_cvt_f32_i32_e32 v116, v68
	v_cvt_f32_i32_e32 v117, v69
	v_cvt_f32_i32_e32 v82, v62
	v_cvt_f32_i32_e32 v83, v63
	v_cvt_f32_i32_e32 v84, v64
	v_cvt_f32_i32_e32 v85, v65
	v_cvt_f32_i32_e32 v86, v58
	v_cvt_f32_i32_e32 v87, v59
	v_cvt_f32_i32_e32 v88, v60
	v_cvt_f32_i32_e32 v89, v61
	v_cvt_f32_i32_e32 v92, v46
	v_cvt_f32_i32_e32 v93, v47
	v_cvt_f32_i32_e32 v94, v48
	v_cvt_f32_i32_e32 v95, v49
	v_cvt_f32_i32_e32 v96, v38
	v_cvt_f32_i32_e32 v97, v39
	v_cvt_f32_i32_e32 v98, v40
	v_cvt_f32_i32_e32 v99, v41
	v_cvt_f32_i32_e32 v66, v54
	v_cvt_f32_i32_e32 v67, v55
	v_cvt_f32_i32_e32 v68, v56
	v_cvt_f32_i32_e32 v69, v57
	v_cvt_f32_i32_e32 v70, v50
	v_cvt_f32_i32_e32 v71, v51
	v_cvt_f32_i32_e32 v72, v52
	v_cvt_f32_i32_e32 v73, v53
	v_cvt_f32_i32_e32 v74, v30
	v_cvt_f32_i32_e32 v75, v31
	v_cvt_f32_i32_e32 v76, v32
	v_cvt_f32_i32_e32 v77, v33
	v_cvt_f32_i32_e32 v78, v22
	v_cvt_f32_i32_e32 v79, v23
	v_cvt_f32_i32_e32 v80, v24
	v_cvt_f32_i32_e32 v81, v25
	v_cvt_f32_i32_e32 v50, v42
	v_cvt_f32_i32_e32 v51, v43
	v_cvt_f32_i32_e32 v52, v44
	v_cvt_f32_i32_e32 v53, v45
	v_cvt_f32_i32_e32 v54, v34
	v_cvt_f32_i32_e32 v55, v35
	v_cvt_f32_i32_e32 v56, v36
	v_cvt_f32_i32_e32 v57, v37
	v_cvt_f32_i32_e32 v58, v14
	v_cvt_f32_i32_e32 v59, v15
	v_cvt_f32_i32_e32 v60, v16
	v_cvt_f32_i32_e32 v61, v17
	v_cvt_f32_i32_e32 v62, v10
	v_cvt_f32_i32_e32 v63, v11
	v_cvt_f32_i32_e32 v64, v12
	v_cvt_f32_i32_e32 v65, v13
	v_cvt_f32_i32_e32 v34, v26
	v_cvt_f32_i32_e32 v35, v27
	v_cvt_f32_i32_e32 v36, v28
	v_cvt_f32_i32_e32 v37, v29
	v_cvt_f32_i32_e32 v38, v18
	v_cvt_f32_i32_e32 v39, v19
	v_cvt_f32_i32_e32 v40, v20
	v_cvt_f32_i32_e32 v41, v21
	v_cvt_f32_i32_e32 v42, v6
	v_cvt_f32_i32_e32 v43, v7
	v_cvt_f32_i32_e32 v44, v8
	v_cvt_f32_i32_e32 v45, v9
	v_cvt_f32_i32_e32 v46, v2
	v_cvt_f32_i32_e32 v47, v3
	v_cvt_f32_i32_e32 v48, v4
	v_cvt_f32_i32_e32 v49, v5

.LBB0_3879:
	ds_read_b128 v[130:133], v169
	ds_read_b128 v[134:137], v169 offset:1024
	ds_read_b128 v[138:141], v169 offset:2048
	ds_read_b128 v[142:145], v169 offset:3072
	ds_read_b128 v[162:165], v170
	ds_read_b128 v[172:175], v170 offset:1024
	ds_read_b128 v[176:179], v170 offset:2048
	ds_read_b128 v[180:183], v170 offset:3072
	s_add_i32 s59, s26, 2
	s_add_u32 s27, s24, 0x4000
	s_addc_u32 s28, s25, 0
	s_cmp_eq_u32 s48, s26
	s_cselect_b32 s29, s3, s28
	s_cselect_b32 s28, s2, s27
	s_cselect_b32 s60, s22, s57
	s_cselect_b32 s61, s23, s58
	s_add_u32 s26, s28, 0x8000
	s_addc_u32 s27, s29, 0
	v_lshl_add_u64 v[216:217], s[24:25], 0, v[154:155]
	s_add_i32 m0, s38, 0xc000
	ds_read_b128 v[184:187], v171
	ds_read_b128 v[188:191], v171 offset:1024
	ds_read_b128 v[192:195], v171 offset:2048
	ds_read_b128 v[196:199], v171 offset:3072
	ds_read_b128 v[200:203], v171 offset:4096
	ds_read_b128 v[204:207], v171 offset:5120
	ds_read_b128 v[208:211], v171 offset:6144
	ds_read_b128 v[212:215], v171 offset:7168
	global_load_lds_dwordx4 v[216:217], off
	v_lshl_add_u64 v[216:217], s[24:25], 0, v[156:157]
	s_add_i32 m0, s38, 0xe000
	s_nop 0
	global_load_lds_dwordx4 v[216:217], off
	s_waitcnt vmcnt(8)
	s_waitcnt lgkmcnt(0)
	s_waitcnt lgkmcnt(0)
	v_mfma_f32_16x16x32_bf16 v[126:129], v[130:133], v[184:187], v[126:129]
	v_mfma_f32_16x16x32_bf16 v[122:125], v[138:141], v[184:187], v[122:125]
	s_barrier
	v_mfma_f32_16x16x32_bf16 v[110:113], v[130:133], v[192:195], v[110:113]
	v_mfma_f32_16x16x32_bf16 v[106:109], v[138:141], v[192:195], v[106:109]
	v_mfma_f32_16x16x32_bf16 v[94:97], v[130:133], v[200:203], v[94:97]
	v_mfma_f32_16x16x32_bf16 v[90:93], v[138:141], v[200:203], v[90:93]
	v_mfma_f32_16x16x32_bf16 v[78:81], v[130:133], v[208:211], v[78:81]
	v_mfma_f32_16x16x32_bf16 v[74:77], v[138:141], v[208:211], v[74:77]
	v_mfma_f32_16x16x32_bf16 v[126:129], v[134:137], v[188:191], v[126:129]
	v_mfma_f32_16x16x32_bf16 v[122:125], v[142:145], v[188:191], v[122:125]
	v_mfma_f32_16x16x32_bf16 v[110:113], v[134:137], v[196:199], v[110:113]
	v_mfma_f32_16x16x32_bf16 v[106:109], v[142:145], v[196:199], v[106:109]
	v_mfma_f32_16x16x32_bf16 v[94:97], v[134:137], v[204:207], v[94:97]
	v_mfma_f32_16x16x32_bf16 v[90:93], v[142:145], v[204:207], v[90:93]
	v_mfma_f32_16x16x32_bf16 v[78:81], v[134:137], v[212:215], v[78:81]
	v_mfma_f32_16x16x32_bf16 v[74:77], v[142:145], v[212:215], v[74:77]
	v_mfma_f32_16x16x32_bf16 v[118:121], v[162:165], v[184:187], v[118:121]
	v_mfma_f32_16x16x32_bf16 v[114:117], v[176:179], v[184:187], v[114:117]
	v_mfma_f32_16x16x32_bf16 v[102:105], v[162:165], v[192:195], v[102:105]
	v_mfma_f32_16x16x32_bf16 v[98:101], v[176:179], v[192:195], v[98:101]
	v_mfma_f32_16x16x32_bf16 v[86:89], v[162:165], v[200:203], v[86:89]
	v_mfma_f32_16x16x32_bf16 v[82:85], v[176:179], v[200:203], v[82:85]
	v_mfma_f32_16x16x32_bf16 v[70:73], v[162:165], v[208:211], v[70:73]
	v_mfma_f32_16x16x32_bf16 v[66:69], v[176:179], v[208:211], v[66:69]
	v_mfma_f32_16x16x32_bf16 v[118:121], v[172:175], v[188:191], v[118:121]
	v_mfma_f32_16x16x32_bf16 v[114:117], v[180:183], v[188:191], v[114:117]
	v_mfma_f32_16x16x32_bf16 v[102:105], v[172:175], v[196:199], v[102:105]
	v_mfma_f32_16x16x32_bf16 v[98:101], v[180:183], v[196:199], v[98:101]
	v_mfma_f32_16x16x32_bf16 v[86:89], v[172:175], v[204:207], v[86:89]
	v_mfma_f32_16x16x32_bf16 v[82:85], v[180:183], v[204:207], v[82:85]
	v_mfma_f32_16x16x32_bf16 v[70:73], v[172:175], v[212:215], v[70:73]
	v_mfma_f32_16x16x32_bf16 v[66:69], v[180:183], v[212:215], v[66:69]
	s_barrier
	s_add_i32 s62, s50, s37
	v_lshl_add_u64 v[216:217], s[60:61], 0, v[148:149]
	s_mov_b32 m0, s62
	ds_read_b128 v[184:187], v171 offset:16384
	ds_read_b128 v[188:191], v171 offset:17408
	ds_read_b128 v[192:195], v171 offset:18432
	ds_read_b128 v[196:199], v171 offset:19456
	ds_read_b128 v[200:203], v171 offset:20480
	ds_read_b128 v[204:207], v171 offset:21504
	ds_read_b128 v[208:211], v171 offset:22528
	ds_read_b128 v[212:215], v171 offset:23552
	global_load_lds_dwordx4 v[216:217], off
	s_add_i32 m0, s62, 0x2000
	v_lshl_add_u64 v[218:219], s[60:61], 0, v[152:153]
	s_add_u32 s60, s60, s6
	s_addc_u32 s61, s61, s7
	s_add_i32 s62, s51, s37
	global_load_lds_dwordx4 v[218:219], off
	v_lshl_add_u64 v[220:221], s[60:61], 0, v[148:149]
	s_mov_b32 m0, s62
	v_lshl_add_u64 v[222:223], s[60:61], 0, v[152:153]
	global_load_lds_dwordx4 v[220:221], off
	s_add_i32 m0, s62, 0x2000
	v_lshl_add_u64 v[224:225], s[28:29], 0, v[146:147]
	global_load_lds_dwordx4 v[222:223], off
	s_mov_b32 m0, s38
	s_nop 0
	global_load_lds_dwordx4 v[224:225], off
	v_lshl_add_u64 v[224:225], s[28:29], 0, v[150:151]
	s_mov_b32 m0, s39
	s_nop 0
	global_load_lds_dwordx4 v[224:225], off
	s_waitcnt vmcnt(8)
	s_waitcnt lgkmcnt(0)
	s_waitcnt lgkmcnt(0)
	v_mfma_f32_16x16x32_bf16 v[62:65], v[130:133], v[184:187], v[62:65]
	v_mfma_f32_16x16x32_bf16 v[58:61], v[138:141], v[184:187], v[58:61]
	s_barrier
	v_mfma_f32_16x16x32_bf16 v[46:49], v[130:133], v[192:195], v[46:49]
	v_mfma_f32_16x16x32_bf16 v[42:45], v[138:141], v[192:195], v[42:45]
	v_mfma_f32_16x16x32_bf16 v[30:33], v[130:133], v[200:203], v[30:33]
	v_mfma_f32_16x16x32_bf16 v[26:29], v[138:141], v[200:203], v[26:29]
	v_mfma_f32_16x16x32_bf16 v[14:17], v[130:133], v[208:211], v[14:17]
	v_mfma_f32_16x16x32_bf16 v[10:13], v[138:141], v[208:211], v[10:13]
	v_mfma_f32_16x16x32_bf16 v[62:65], v[134:137], v[188:191], v[62:65]
	v_mfma_f32_16x16x32_bf16 v[58:61], v[142:145], v[188:191], v[58:61]
	v_mfma_f32_16x16x32_bf16 v[46:49], v[134:137], v[196:199], v[46:49]
	v_mfma_f32_16x16x32_bf16 v[42:45], v[142:145], v[196:199], v[42:45]
	v_mfma_f32_16x16x32_bf16 v[30:33], v[134:137], v[204:207], v[30:33]
	v_mfma_f32_16x16x32_bf16 v[26:29], v[142:145], v[204:207], v[26:29]
	v_mfma_f32_16x16x32_bf16 v[14:17], v[134:137], v[212:215], v[14:17]
	v_mfma_f32_16x16x32_bf16 v[10:13], v[142:145], v[212:215], v[10:13]
	v_mfma_f32_16x16x32_bf16 v[54:57], v[162:165], v[184:187], v[54:57]
	v_mfma_f32_16x16x32_bf16 v[50:53], v[176:179], v[184:187], v[50:53]
	v_mfma_f32_16x16x32_bf16 v[38:41], v[162:165], v[192:195], v[38:41]
	v_mfma_f32_16x16x32_bf16 v[34:37], v[176:179], v[192:195], v[34:37]
	v_mfma_f32_16x16x32_bf16 v[22:25], v[162:165], v[200:203], v[22:25]
	v_mfma_f32_16x16x32_bf16 v[18:21], v[176:179], v[200:203], v[18:21]
	v_mfma_f32_16x16x32_bf16 v[6:9], v[162:165], v[208:211], v[6:9]
	v_mfma_f32_16x16x32_bf16 v[2:5], v[176:179], v[208:211], v[2:5]
	v_mfma_f32_16x16x32_bf16 v[54:57], v[172:175], v[188:191], v[54:57]
	v_mfma_f32_16x16x32_bf16 v[50:53], v[180:183], v[188:191], v[50:53]
	v_mfma_f32_16x16x32_bf16 v[38:41], v[172:175], v[196:199], v[38:41]
	v_mfma_f32_16x16x32_bf16 v[34:37], v[180:183], v[196:199], v[34:37]
	v_mfma_f32_16x16x32_bf16 v[22:25], v[172:175], v[204:207], v[22:25]
	v_mfma_f32_16x16x32_bf16 v[18:21], v[180:183], v[204:207], v[18:21]
	v_mfma_f32_16x16x32_bf16 v[6:9], v[172:175], v[212:215], v[6:9]
	v_mfma_f32_16x16x32_bf16 v[2:5], v[180:183], v[212:215], v[2:5]
	s_barrier
	s_add_i32 s60, 0, 0x18000
	s_add_i32 s61, 0, 0x1c000
	v_add_u32_e32 v142, s60, v167
	v_add_u32_e32 v180, s61, v167
	ds_read_b128 v[130:133], v142
	ds_read_b128 v[134:137], v142 offset:1024
	ds_read_b128 v[138:141], v142 offset:2048
	ds_read_b128 v[142:145], v142 offset:3072
	ds_read_b128 v[162:165], v180
	ds_read_b128 v[172:175], v180 offset:1024
	ds_read_b128 v[176:179], v180 offset:2048
	ds_read_b128 v[180:183], v180 offset:3072
	s_add_u32 s28, s28, 0x4000
	s_addc_u32 s29, s29, 0
	s_mov_b32 m0, s40
	v_lshl_add_u64 v[224:225], s[28:29], 0, v[146:147]
	ds_read_b128 v[184:187], v171 offset:32768
	ds_read_b128 v[188:191], v171 offset:33792
	ds_read_b128 v[192:195], v171 offset:34816
	ds_read_b128 v[196:199], v171 offset:35840
	ds_read_b128 v[200:203], v171 offset:36864
	ds_read_b128 v[204:207], v171 offset:37888
	ds_read_b128 v[208:211], v171 offset:38912
	ds_read_b128 v[212:215], v171 offset:39936
	global_load_lds_dwordx4 v[224:225], off
	v_lshl_add_u64 v[224:225], s[28:29], 0, v[150:151]
	s_mov_b32 m0, s41
	s_nop 0
	global_load_lds_dwordx4 v[224:225], off
	s_waitcnt vmcnt(8)
	s_waitcnt lgkmcnt(0)
	s_waitcnt lgkmcnt(0)
	v_mfma_f32_16x16x32_bf16 v[126:129], v[130:133], v[184:187], v[126:129]
	v_mfma_f32_16x16x32_bf16 v[122:125], v[138:141], v[184:187], v[122:125]
	s_barrier
	v_mfma_f32_16x16x32_bf16 v[110:113], v[130:133], v[192:195], v[110:113]
	v_mfma_f32_16x16x32_bf16 v[106:109], v[138:141], v[192:195], v[106:109]
	v_mfma_f32_16x16x32_bf16 v[94:97], v[130:133], v[200:203], v[94:97]
	v_mfma_f32_16x16x32_bf16 v[90:93], v[138:141], v[200:203], v[90:93]
	v_mfma_f32_16x16x32_bf16 v[78:81], v[130:133], v[208:211], v[78:81]
	v_mfma_f32_16x16x32_bf16 v[74:77], v[138:141], v[208:211], v[74:77]
	v_mfma_f32_16x16x32_bf16 v[126:129], v[134:137], v[188:191], v[126:129]
	v_mfma_f32_16x16x32_bf16 v[122:125], v[142:145], v[188:191], v[122:125]
	v_mfma_f32_16x16x32_bf16 v[110:113], v[134:137], v[196:199], v[110:113]
	v_mfma_f32_16x16x32_bf16 v[106:109], v[142:145], v[196:199], v[106:109]
	v_mfma_f32_16x16x32_bf16 v[94:97], v[134:137], v[204:207], v[94:97]
	v_mfma_f32_16x16x32_bf16 v[90:93], v[142:145], v[204:207], v[90:93]
	v_mfma_f32_16x16x32_bf16 v[78:81], v[134:137], v[212:215], v[78:81]
	v_mfma_f32_16x16x32_bf16 v[74:77], v[142:145], v[212:215], v[74:77]
	v_mfma_f32_16x16x32_bf16 v[118:121], v[162:165], v[184:187], v[118:121]
	v_mfma_f32_16x16x32_bf16 v[114:117], v[176:179], v[184:187], v[114:117]
	v_mfma_f32_16x16x32_bf16 v[102:105], v[162:165], v[192:195], v[102:105]
	v_mfma_f32_16x16x32_bf16 v[98:101], v[176:179], v[192:195], v[98:101]
	v_mfma_f32_16x16x32_bf16 v[86:89], v[162:165], v[200:203], v[86:89]
	v_mfma_f32_16x16x32_bf16 v[82:85], v[176:179], v[200:203], v[82:85]
	v_mfma_f32_16x16x32_bf16 v[70:73], v[162:165], v[208:211], v[70:73]
	v_mfma_f32_16x16x32_bf16 v[66:69], v[176:179], v[208:211], v[66:69]
	v_mfma_f32_16x16x32_bf16 v[118:121], v[172:175], v[188:191], v[118:121]
	v_mfma_f32_16x16x32_bf16 v[114:117], v[180:183], v[188:191], v[114:117]
	v_mfma_f32_16x16x32_bf16 v[102:105], v[172:175], v[196:199], v[102:105]
	v_mfma_f32_16x16x32_bf16 v[98:101], v[180:183], v[196:199], v[98:101]
	v_mfma_f32_16x16x32_bf16 v[86:89], v[172:175], v[204:207], v[86:89]
	v_mfma_f32_16x16x32_bf16 v[82:85], v[180:183], v[204:207], v[82:85]
	v_mfma_f32_16x16x32_bf16 v[70:73], v[172:175], v[212:215], v[70:73]
	v_mfma_f32_16x16x32_bf16 v[66:69], v[180:183], v[212:215], v[66:69]
	s_barrier
	s_add_i32 s28, s60, s37
	v_lshl_add_u64 v[216:217], v[216:217], 0, s[14:15]
	s_mov_b32 m0, s28
	ds_read_b128 v[184:187], v171 offset:49152
	ds_read_b128 v[188:191], v171 offset:50176
	ds_read_b128 v[192:195], v171 offset:51200
	ds_read_b128 v[196:199], v171 offset:52224
	ds_read_b128 v[200:203], v171 offset:53248
	ds_read_b128 v[204:207], v171 offset:54272
	ds_read_b128 v[208:211], v171 offset:55296
	ds_read_b128 v[212:215], v171 offset:56320
	global_load_lds_dwordx4 v[216:217], off
	v_lshl_add_u64 v[216:217], v[218:219], 0, s[14:15]
	s_add_i32 m0, s28, 0x2000
	s_add_i32 s28, s61, s37
	global_load_lds_dwordx4 v[216:217], off
	v_lshl_add_u64 v[216:217], v[220:221], 0, s[14:15]
	s_mov_b32 m0, s28
	s_nop 0
	global_load_lds_dwordx4 v[216:217], off
	v_lshl_add_u64 v[216:217], v[222:223], 0, s[14:15]
	s_add_i32 m0, s28, 0x2000
	s_nop 0
	global_load_lds_dwordx4 v[216:217], off
	v_lshl_add_u64 v[216:217], s[26:27], 0, v[146:147]
	s_mov_b32 m0, s46
	s_nop 0
	global_load_lds_dwordx4 v[216:217], off
	v_lshl_add_u64 v[216:217], s[26:27], 0, v[150:151]
	s_mov_b32 m0, s47
	s_nop 0
	global_load_lds_dwordx4 v[216:217], off
	s_waitcnt vmcnt(8)
	s_waitcnt lgkmcnt(0)
	s_waitcnt lgkmcnt(0)
	v_mfma_f32_16x16x32_bf16 v[62:65], v[130:133], v[184:187], v[62:65]
	v_mfma_f32_16x16x32_bf16 v[58:61], v[138:141], v[184:187], v[58:61]
	s_barrier
	v_mfma_f32_16x16x32_bf16 v[46:49], v[130:133], v[192:195], v[46:49]
	v_mfma_f32_16x16x32_bf16 v[42:45], v[138:141], v[192:195], v[42:45]
	v_mfma_f32_16x16x32_bf16 v[30:33], v[130:133], v[200:203], v[30:33]
	v_mfma_f32_16x16x32_bf16 v[26:29], v[138:141], v[200:203], v[26:29]
	v_mfma_f32_16x16x32_bf16 v[14:17], v[130:133], v[208:211], v[14:17]
	v_mfma_f32_16x16x32_bf16 v[10:13], v[138:141], v[208:211], v[10:13]
	v_mfma_f32_16x16x32_bf16 v[62:65], v[134:137], v[188:191], v[62:65]
	v_mfma_f32_16x16x32_bf16 v[58:61], v[142:145], v[188:191], v[58:61]
	v_mfma_f32_16x16x32_bf16 v[46:49], v[134:137], v[196:199], v[46:49]
	v_mfma_f32_16x16x32_bf16 v[42:45], v[142:145], v[196:199], v[42:45]
	v_mfma_f32_16x16x32_bf16 v[30:33], v[134:137], v[204:207], v[30:33]
	v_mfma_f32_16x16x32_bf16 v[26:29], v[142:145], v[204:207], v[26:29]
	v_mfma_f32_16x16x32_bf16 v[14:17], v[134:137], v[212:215], v[14:17]
	v_mfma_f32_16x16x32_bf16 v[10:13], v[142:145], v[212:215], v[10:13]
	v_mfma_f32_16x16x32_bf16 v[54:57], v[162:165], v[184:187], v[54:57]
	v_mfma_f32_16x16x32_bf16 v[50:53], v[176:179], v[184:187], v[50:53]
	v_mfma_f32_16x16x32_bf16 v[38:41], v[162:165], v[192:195], v[38:41]
	v_mfma_f32_16x16x32_bf16 v[34:37], v[176:179], v[192:195], v[34:37]
	v_mfma_f32_16x16x32_bf16 v[22:25], v[162:165], v[200:203], v[22:25]
	v_mfma_f32_16x16x32_bf16 v[18:21], v[176:179], v[200:203], v[18:21]
	v_mfma_f32_16x16x32_bf16 v[6:9], v[162:165], v[208:211], v[6:9]
	v_mfma_f32_16x16x32_bf16 v[2:5], v[176:179], v[208:211], v[2:5]
	v_mfma_f32_16x16x32_bf16 v[54:57], v[172:175], v[188:191], v[54:57]
	v_mfma_f32_16x16x32_bf16 v[50:53], v[180:183], v[188:191], v[50:53]
	v_mfma_f32_16x16x32_bf16 v[38:41], v[172:175], v[196:199], v[38:41]
	v_mfma_f32_16x16x32_bf16 v[34:37], v[180:183], v[196:199], v[34:37]
	v_mfma_f32_16x16x32_bf16 v[22:25], v[172:175], v[204:207], v[22:25]
	v_mfma_f32_16x16x32_bf16 v[18:21], v[180:183], v[204:207], v[18:21]
	v_mfma_f32_16x16x32_bf16 v[6:9], v[172:175], v[212:215], v[6:9]
	v_mfma_f32_16x16x32_bf16 v[2:5], v[180:183], v[212:215], v[2:5]
	s_barrier
	s_add_u32 s57, s57, 0x100
	s_addc_u32 s58, s58, 0
	s_add_u32 s24, s24, 0x10000
	s_addc_u32 s25, s25, 0
	s_cmp_ge_i32 s59, s45
	s_mov_b32 s26, s59
	s_cbranch_scc0 .LBB0_3879
